# xor 16 / xor 32 butterfly sum steps via v_permlane16/32_swap (copy, swap, add) instead of ds_bpermute_b32 (118 sites)
# baseline (speedup 1.0000x reference)
.LBB0_730:
	v_pk_mul_f32 v[24:25], v[80:81], v[80:81]
	v_pk_mul_f32 v[26:27], v[78:79], v[78:79]
	s_ashr_i32 s27, s10, 13
	v_pk_mov_b32 v[28:29], v[26:27], v[24:25] op_sel:[1,0]
	v_mov_b32_e32 v27, v25
	v_pk_add_f32 v[24:25], v[28:29], v[26:27]
	v_pk_mul_f32 v[26:27], v[76:77], v[76:77]
	v_pk_mul_f32 v[28:29], v[74:75], v[74:75]
	s_and_b64 s[6:7], s[6:7], exec
	v_pk_mov_b32 v[34:35], v[28:29], v[26:27] op_sel:[1,0]
	v_mov_b32_e32 v29, v27
	v_pk_add_f32 v[26:27], v[34:35], v[28:29]
	v_mul_f32_e32 v28, v66, v66
	v_mul_f32_e32 v29, v67, v67
	v_pk_add_f32 v[24:25], v[24:25], v[24:25] op_sel:[0,1] op_sel_hi:[1,0]
	v_pk_add_f32 v[26:27], v[26:27], v[26:27] op_sel:[0,1] op_sel_hi:[1,0]
	s_cselect_b32 s6, s27, s28
	v_mov_b32_e32 v25, v28
	v_mov_b32_e32 v27, v29
	s_mul_hi_i32 s7, s6, 0x9000
	s_mul_i32 s6, s6, 0x9000
	v_pk_add_f32 v[24:25], v[24:25], v[26:27]
	v_mul_f32_e32 v26, v71, v71
	v_mul_f32_e32 v28, v73, v73
	s_add_u32 s6, s42, s6
	v_mul_f32_e32 v34, v68, v68
	v_mul_f32_e32 v35, v69, v69
	v_pk_fma_f32 v[26:27], v[70:71], v[70:71], v[26:27] op_sel_hi:[1,1,0]
	v_pk_fma_f32 v[28:29], v[72:73], v[72:73], v[28:29] op_sel_hi:[1,1,0]
	s_addc_u32 s7, s43, s7
	v_mov_b32_e32 v27, v34
	v_mov_b32_e32 v29, v35
	s_add_u32 s50, s6, 0x1000
	v_mov_b32_e32 v89, v83
	v_pk_add_f32 v[26:27], v[26:27], v[28:29]
	s_addc_u32 s51, s7, 0
	v_lshl_add_u64 v[112:113], s[6:7], 0, v[88:89]
	v_pk_add_f32 v[24:25], v[24:25], v[26:27]
	v_lshl_add_u64 v[26:27], s[50:51], 0, v[88:89]
	global_load_dwordx4 v[104:107], v[112:113], off
	global_load_dwordx4 v[108:111], v[26:27], off
	v_add_f32_e32 v24, v24, v25
	v_lshl_add_u64 v[22:23], v[22:23], 0, v[82:83]
	v_mul_f32_e32 v116, v53, v53
	s_waitcnt lgkmcnt(0)
	s_nop 1
	v_add_f32_dpp v24, v24, v24 quad_perm:[1,0,3,2] row_mask:0xf bank_mask:0xf
	s_waitcnt lgkmcnt(0)
	s_nop 1
	v_add_f32_dpp v24, v24, v24 quad_perm:[2,3,0,1] row_mask:0xf bank_mask:0xf
	s_waitcnt lgkmcnt(0)
	s_nop 1
	v_add_f32_dpp v24, v24, v24 row_half_mirror row_mask:0xf bank_mask:0xf
	s_waitcnt lgkmcnt(0)
	s_nop 1
	v_add_f32_dpp v24, v24, v24 row_mirror row_mask:0xf bank_mask:0xf
	s_waitcnt lgkmcnt(0)
	v_mov_b32_e32 v25, v24
	s_nop 1
	v_permlane16_swap_b32_e32 v24, v25
	v_add_f32_e32 v24, v24, v25
	s_waitcnt lgkmcnt(0)
	v_mov_b32_e32 v25, v24
	s_nop 1
	v_permlane32_swap_b32_e32 v24, v25
	v_add_f32_e32 v24, v24, v25
	v_fmamk_f32 v24, v24, 0x3a800000, v102
	v_mul_f32_e32 v25, 0x4f800000, v24
	v_cmp_gt_f32_e32 vcc, s4, v24
	s_waitcnt vmcnt(0)
	v_pk_add_f32 v[108:109], v[108:109], 1.0 op_sel_hi:[1,0]
	v_cndmask_b32_e32 v24, v24, v25, vcc
	v_sqrt_f32_e32 v25, v24
	v_pk_add_f32 v[110:111], v[110:111], 1.0 op_sel_hi:[1,0]
	v_add_u32_e32 v26, -1, v25
	v_fma_f32 v27, -v26, v25, v24
	v_cmp_ge_f32_e64 s[6:7], 0, v27
	v_add_u32_e32 v27, 1, v25
	s_nop 0
	v_cndmask_b32_e64 v26, v25, v26, s[6:7]
	v_fma_f32 v25, -v27, v25, v24
	v_cmp_lt_f32_e64 s[6:7], 0, v25
	s_nop 1
	v_cndmask_b32_e64 v25, v26, v27, s[6:7]
	v_mul_f32_e32 v26, 0x37800000, v25
	v_cndmask_b32_e32 v25, v25, v26, vcc
	v_cmp_class_f32_e32 vcc, v24, v103
	s_and_b64 s[6:7], s[48:49], exec
	s_nop 0
	v_cndmask_b32_e32 v91, v25, v24, vcc
	v_div_scale_f32 v93, s[6:7], v91, v91, 1.0
	v_rcp_f32_e32 v95, v93
	global_load_dwordx4 v[42:45], v[22:23], off
	global_load_dwordx4 v[34:37], v[22:23], off offset:1024
	global_load_dwordx4 v[26:29], v[22:23], off offset:2048
	s_nop 0
	global_load_dwordx4 v[22:25], v[22:23], off offset:3072
	s_cselect_b32 s6, s27, s14
	s_mul_hi_i32 s7, s6, 0x9000
	v_fma_f32 v96, -v93, v95, 1.0
	v_fmac_f32_e32 v95, v96, v95
	v_div_scale_f32 v96, vcc, 1.0, v91, 1.0
	v_mul_f32_e32 v114, v96, v95
	v_fma_f32 v115, -v93, v114, v96
	v_fmac_f32_e32 v114, v115, v95
	v_fma_f32 v93, -v93, v114, v96
	v_div_fmas_f32 v93, v93, v95, v114
	v_div_fixup_f32 v96, v93, v91, 1.0
	v_pk_mul_f32 v[78:79], v[78:79], v[96:97] op_sel_hi:[1,0]
	v_pk_mul_f32 v[80:81], v[80:81], v[96:97] op_sel_hi:[1,0]
	v_pk_mul_f32 v[78:79], v[2:3], v[78:79]
	v_pk_mul_f32 v[80:81], v[4:5], v[80:81]
	v_pk_fma_f32 v[78:79], v[108:109], v[78:79], v[104:105]
	v_pk_fma_f32 v[80:81], v[110:111], v[80:81], v[106:107]
	v_cvt_pk_bf16_f32 v78, v78, v79
	v_cvt_pk_bf16_f32 v79, v80, v81
	v_mov_b32_e32 v91, v83
	global_store_dwordx2 v[86:87], v[78:79], off
	v_lshl_add_u64 v[78:79], s[50:51], 0, v[90:91]
	global_load_dwordx4 v[78:81], v[78:79], off
	s_nop 0
	global_load_dwordx4 v[104:107], v[112:113], off offset:1024
	v_pk_mul_f32 v[76:77], v[76:77], v[96:97] op_sel_hi:[1,0]
	v_pk_mul_f32 v[74:75], v[74:75], v[96:97] op_sel_hi:[1,0]
	v_pk_mul_f32 v[76:77], v[8:9], v[76:77]
	v_pk_mul_f32 v[74:75], v[6:7], v[74:75]
	v_mov_b32_e32 v93, v83
	v_lshl_add_u64 v[108:109], s[50:51], 0, v[92:93]
	v_pk_mul_f32 v[72:73], v[72:73], v[96:97] op_sel_hi:[1,0]
	v_pk_mul_f32 v[70:71], v[70:71], v[96:97] op_sel_hi:[1,0]
	v_pk_mul_f32 v[72:73], v[12:13], v[72:73]
	v_pk_mul_f32 v[70:71], v[10:11], v[70:71]
	v_mov_b32_e32 v95, v83
	v_pk_mul_f32 v[68:69], v[68:69], v[96:97] op_sel_hi:[1,0]
	v_pk_mul_f32 v[66:67], v[66:67], v[96:97] op_sel_hi:[1,0]
	v_pk_mul_f32 v[68:69], v[68:69], v[16:17]
	v_pk_mul_f32 v[66:67], v[66:67], v[14:15]
	s_mul_i32 s6, s6, 0x9000
	s_add_u32 s6, s42, s6
	v_mul_f32_e32 v111, v50, v50
	v_mul_f32_e32 v110, v57, v57
	s_addc_u32 s7, s43, s7
	v_mul_f32_e32 v115, v52, v52
	s_add_u32 s48, s6, 0x1000
	s_addc_u32 s49, s7, 0
	v_mul_f32_e32 v114, v51, v51
	s_add_i32 s14, s10, 0xffffc004
	s_waitcnt vmcnt(0) lgkmcnt(0)
	v_pk_add_f32 v[80:81], v[80:81], 1.0 op_sel_hi:[1,0]
	v_pk_add_f32 v[78:79], v[78:79], 1.0 op_sel_hi:[1,0]
	v_pk_fma_f32 v[76:77], v[80:81], v[76:77], v[106:107]
	v_pk_fma_f32 v[74:75], v[78:79], v[74:75], v[104:105]
	v_cvt_pk_bf16_f32 v74, v74, v75
	v_cvt_pk_bf16_f32 v75, v76, v77
	global_store_dwordx2 v[86:87], v[74:75], off offset:512
	global_load_dwordx4 v[74:77], v[108:109], off
	s_nop 0
	global_load_dwordx4 v[78:81], v[112:113], off offset:2048
	v_lshl_add_u64 v[104:105], s[50:51], 0, v[94:95]
	v_pk_mul_f32 v[106:107], v[58:59], v[58:59]
	v_mul_f32_e32 v108, v55, v55
	s_waitcnt vmcnt(0) lgkmcnt(0)
	v_pk_add_f32 v[76:77], v[76:77], 1.0 op_sel_hi:[1,0]
	v_pk_add_f32 v[74:75], v[74:75], 1.0 op_sel_hi:[1,0]
	v_pk_fma_f32 v[72:73], v[72:73], v[76:77], v[80:81]
	v_pk_fma_f32 v[70:71], v[70:71], v[74:75], v[78:79]
	v_cvt_pk_bf16_f32 v70, v70, v71
	v_cvt_pk_bf16_f32 v71, v72, v73
	global_store_dwordx2 v[86:87], v[70:71], off offset:1024
	global_load_dwordx4 v[70:73], v[104:105], off
	s_nop 0
	global_load_dwordx4 v[74:77], v[112:113], off offset:3072
	v_pk_mul_f32 v[78:79], v[64:65], v[64:65]
	v_pk_mul_f32 v[80:81], v[62:63], v[62:63]
	v_pk_mul_f32 v[104:105], v[60:61], v[60:61]
	v_pk_mov_b32 v[112:113], v[80:81], v[78:79] op_sel:[1,0]
	v_mov_b32_e32 v81, v79
	v_pk_mov_b32 v[78:79], v[106:107], v[104:105] op_sel:[1,0]
	v_mov_b32_e32 v107, v105
	v_pk_fma_f32 v[104:105], v[54:55], v[54:55], v[108:109] op_sel_hi:[1,1,0]
	v_pk_fma_f32 v[108:109], v[56:57], v[56:57], v[110:111] op_sel_hi:[1,1,0]
	v_pk_add_f32 v[78:79], v[78:79], v[106:107]
	v_mov_b32_e32 v105, v115
	v_mov_b32_e32 v109, v116
	v_lshl_add_u64 v[106:107], s[6:7], 0, v[88:89]
	v_pk_add_f32 v[104:105], v[104:105], v[108:109]
	v_lshl_add_u64 v[108:109], s[48:49], 0, v[88:89]
	v_pk_add_f32 v[80:81], v[112:113], v[80:81]
	v_pk_add_f32 v[78:79], v[78:79], v[78:79] op_sel:[0,1] op_sel_hi:[1,0]
	v_pk_add_f32 v[80:81], v[80:81], v[80:81] op_sel:[0,1] op_sel_hi:[1,0]
	v_mov_b32_e32 v79, v114
	v_mov_b32_e32 v81, v111
	s_waitcnt vmcnt(0) lgkmcnt(0)
	v_pk_add_f32 v[72:73], v[72:73], 1.0 op_sel_hi:[1,0]
	v_pk_add_f32 v[70:71], v[70:71], 1.0 op_sel_hi:[1,0]
	v_pk_fma_f32 v[68:69], v[68:69], v[72:73], v[76:77]
	v_pk_fma_f32 v[66:67], v[66:67], v[70:71], v[74:75]
	v_cvt_pk_bf16_f32 v66, v66, v67
	v_cvt_pk_bf16_f32 v67, v68, v69
	global_store_dwordx2 v[86:87], v[66:67], off offset:1536
	global_load_dwordx4 v[66:69], v[106:107], off
	s_nop 0
	global_load_dwordx4 v[70:73], v[108:109], off
	v_pk_add_f32 v[74:75], v[80:81], v[78:79]
	s_waitcnt vmcnt(0) lgkmcnt(0)
	v_pk_add_f32 v[72:73], v[72:73], 1.0 op_sel_hi:[1,0]
	v_pk_add_f32 v[74:75], v[74:75], v[104:105]
	v_pk_add_f32 v[70:71], v[70:71], 1.0 op_sel_hi:[1,0]
	v_add_f32_e32 v74, v74, v75
	s_waitcnt lgkmcnt(0)
	s_nop 1
	v_add_f32_dpp v74, v74, v74 quad_perm:[1,0,3,2] row_mask:0xf bank_mask:0xf
	s_waitcnt lgkmcnt(0)
	s_nop 1
	v_add_f32_dpp v74, v74, v74 quad_perm:[2,3,0,1] row_mask:0xf bank_mask:0xf
	s_waitcnt lgkmcnt(0)
	s_nop 1
	v_add_f32_dpp v74, v74, v74 row_half_mirror row_mask:0xf bank_mask:0xf
	s_waitcnt lgkmcnt(0)
	s_nop 1
	v_add_f32_dpp v74, v74, v74 row_mirror row_mask:0xf bank_mask:0xf
	s_waitcnt lgkmcnt(0)
	v_mov_b32_e32 v75, v74
	s_nop 1
	v_permlane16_swap_b32_e32 v74, v75
	v_add_f32_e32 v74, v74, v75
	s_waitcnt lgkmcnt(0)
	v_mov_b32_e32 v75, v74
	s_nop 1
	v_permlane32_swap_b32_e32 v74, v75
	v_add_f32_e32 v74, v74, v75
	v_fmamk_f32 v74, v74, 0x3a800000, v102
	v_mul_f32_e32 v75, 0x4f800000, v74
	v_cmp_gt_f32_e32 vcc, s4, v74
	s_nop 1
	v_cndmask_b32_e32 v74, v74, v75, vcc
	v_sqrt_f32_e32 v75, v74
	s_nop 0
	v_add_u32_e32 v76, -1, v75
	v_add_u32_e32 v77, 1, v75
	v_fma_f32 v78, -v76, v75, v74
	v_fma_f32 v79, -v77, v75, v74
	v_cmp_ge_f32_e64 s[6:7], 0, v78
	s_nop 1
	v_cndmask_b32_e64 v75, v75, v76, s[6:7]
	v_cmp_lt_f32_e64 s[6:7], 0, v79
	s_nop 1
	v_cndmask_b32_e64 v75, v75, v77, s[6:7]
	v_mul_f32_e32 v76, 0x37800000, v75
	v_cndmask_b32_e32 v75, v75, v76, vcc
	v_cmp_class_f32_e32 vcc, v74, v103
	s_and_b64 s[6:7], s[46:47], exec
	s_nop 0
	v_cndmask_b32_e32 v76, v75, v74, vcc
	v_div_scale_f32 v77, s[6:7], v76, v76, 1.0
	v_rcp_f32_e32 v78, v77
	v_div_scale_f32 v79, vcc, 1.0, v76, 1.0
	v_lshl_add_u64 v[74:75], s[48:49], 0, v[90:91]
	v_fma_f32 v80, -v77, v78, 1.0
	v_fmac_f32_e32 v78, v80, v78
	v_mul_f32_e32 v80, v79, v78
	v_fma_f32 v81, -v77, v80, v79
	v_fmac_f32_e32 v80, v81, v78
	v_fma_f32 v77, -v77, v80, v79
	v_div_fmas_f32 v77, v77, v78, v80
	v_div_fixup_f32 v76, v77, v76, 1.0
	v_pk_mul_f32 v[64:65], v[64:65], v[76:77] op_sel_hi:[1,0]
	v_pk_mul_f32 v[62:63], v[62:63], v[76:77] op_sel_hi:[1,0]
	v_pk_mul_f32 v[64:65], v[4:5], v[64:65]
	v_pk_mul_f32 v[62:63], v[2:3], v[62:63]
	v_pk_fma_f32 v[64:65], v[72:73], v[64:65], v[68:69]
	v_pk_fma_f32 v[62:63], v[70:71], v[62:63], v[66:67]
	v_cvt_pk_bf16_f32 v62, v62, v63
	v_cvt_pk_bf16_f32 v63, v64, v65
	global_store_dwordx2 v[86:87], v[62:63], off offset:2048
	global_load_dwordx4 v[62:65], v[74:75], off
	s_nop 0
	global_load_dwordx4 v[66:69], v[106:107], off offset:1024
	v_pk_mul_f32 v[60:61], v[60:61], v[76:77] op_sel_hi:[1,0]
	v_pk_mul_f32 v[58:59], v[58:59], v[76:77] op_sel_hi:[1,0]
	v_pk_mul_f32 v[60:61], v[8:9], v[60:61]
	v_pk_mul_f32 v[58:59], v[6:7], v[58:59]
	v_lshl_add_u64 v[70:71], s[48:49], 0, v[92:93]
	v_pk_mul_f32 v[56:57], v[56:57], v[76:77] op_sel_hi:[1,0]
	v_pk_mul_f32 v[54:55], v[54:55], v[76:77] op_sel_hi:[1,0]
	v_pk_mul_f32 v[56:57], v[12:13], v[56:57]
	v_pk_mul_f32 v[54:55], v[10:11], v[54:55]
	v_mul_f32_e32 v77, v19, v19
	v_pk_mul_f32 v[52:53], v[52:53], v[76:77] op_sel_hi:[1,0]
	v_pk_mul_f32 v[50:51], v[50:51], v[76:77] op_sel_hi:[1,0]
	v_pk_mul_f32 v[52:53], v[16:17], v[52:53]
	v_pk_mul_f32 v[50:51], v[14:15], v[50:51]
	s_cselect_b32 s6, s27, s14
	s_mul_hi_i32 s7, s6, 0x9000
	s_mul_i32 s6, s6, 0x9000
	s_add_u32 s6, s42, s6
	v_mul_f32_e32 v73, v18, v18
	v_mul_f32_e32 v72, v33, v33
	s_addc_u32 s7, s43, s7
	v_mul_f32_e32 v78, v20, v20
	v_mul_f32_e32 v79, v21, v21
	s_add_u32 s46, s6, 0x1000
	s_addc_u32 s47, s7, 0
	s_add_i32 s14, s10, 0xffffc005
	s_waitcnt vmcnt(0) lgkmcnt(0)
	v_pk_add_f32 v[64:65], v[64:65], 1.0 op_sel_hi:[1,0]
	v_pk_add_f32 v[62:63], v[62:63], 1.0 op_sel_hi:[1,0]
	v_pk_fma_f32 v[60:61], v[64:65], v[60:61], v[68:69]
	v_pk_fma_f32 v[58:59], v[62:63], v[58:59], v[66:67]
	v_cvt_pk_bf16_f32 v58, v58, v59
	v_cvt_pk_bf16_f32 v59, v60, v61
	global_store_dwordx2 v[86:87], v[58:59], off offset:2560
	global_load_dwordx4 v[58:61], v[70:71], off
	s_nop 0
	global_load_dwordx4 v[62:65], v[106:107], off offset:2048
	v_lshl_add_u64 v[66:67], s[48:49], 0, v[94:95]
	v_pk_mul_f32 v[68:69], v[38:39], v[38:39]
	v_mul_f32_e32 v70, v31, v31
	s_waitcnt vmcnt(0) lgkmcnt(0)
	v_pk_add_f32 v[60:61], v[60:61], 1.0 op_sel_hi:[1,0]
	v_pk_add_f32 v[58:59], v[58:59], 1.0 op_sel_hi:[1,0]
	v_pk_fma_f32 v[56:57], v[60:61], v[56:57], v[64:65]
	v_pk_fma_f32 v[54:55], v[58:59], v[54:55], v[62:63]
	v_cvt_pk_bf16_f32 v54, v54, v55
	v_cvt_pk_bf16_f32 v55, v56, v57
	global_store_dwordx2 v[86:87], v[54:55], off offset:3072
	global_load_dwordx4 v[54:57], v[66:67], off
	s_nop 0
	global_load_dwordx4 v[58:61], v[106:107], off offset:3072
	v_pk_mul_f32 v[62:63], v[48:49], v[48:49]
	v_pk_mul_f32 v[64:65], v[46:47], v[46:47]
	v_pk_mul_f32 v[66:67], v[40:41], v[40:41]
	v_pk_mov_b32 v[74:75], v[64:65], v[62:63] op_sel:[1,0]
	v_mov_b32_e32 v65, v63
	v_pk_mov_b32 v[62:63], v[68:69], v[66:67] op_sel:[1,0]
	v_mov_b32_e32 v69, v67
	v_pk_fma_f32 v[66:67], v[30:31], v[30:31], v[70:71] op_sel_hi:[1,1,0]
	v_pk_fma_f32 v[70:71], v[32:33], v[32:33], v[72:73] op_sel_hi:[1,1,0]
	v_pk_add_f32 v[62:63], v[62:63], v[68:69]
	v_mov_b32_e32 v67, v78
	v_mov_b32_e32 v71, v79
	v_lshl_add_u64 v[68:69], s[6:7], 0, v[88:89]
	v_pk_add_f32 v[66:67], v[66:67], v[70:71]
	v_lshl_add_u64 v[70:71], s[46:47], 0, v[88:89]
	v_pk_add_f32 v[64:65], v[74:75], v[64:65]
	v_pk_add_f32 v[62:63], v[62:63], v[62:63] op_sel:[0,1] op_sel_hi:[1,0]
	v_pk_add_f32 v[64:65], v[64:65], v[64:65] op_sel:[0,1] op_sel_hi:[1,0]
	v_mov_b32_e32 v63, v77
	v_mov_b32_e32 v65, v73
	s_waitcnt vmcnt(0) lgkmcnt(0)
	v_pk_add_f32 v[56:57], v[56:57], 1.0 op_sel_hi:[1,0]
	v_pk_add_f32 v[54:55], v[54:55], 1.0 op_sel_hi:[1,0]
	v_pk_fma_f32 v[52:53], v[52:53], v[56:57], v[60:61]
	v_pk_fma_f32 v[50:51], v[50:51], v[54:55], v[58:59]
	v_cvt_pk_bf16_f32 v50, v50, v51
	v_cvt_pk_bf16_f32 v51, v52, v53
	global_store_dwordx2 v[86:87], v[50:51], off offset:3584
	global_load_dwordx4 v[52:55], v[68:69], off
	global_load_dwordx4 v[56:59], v[70:71], off
	v_pk_add_f32 v[50:51], v[64:65], v[62:63]
	s_waitcnt vmcnt(0) lgkmcnt(0)
	v_pk_add_f32 v[58:59], v[58:59], 1.0 op_sel_hi:[1,0]
	v_pk_add_f32 v[50:51], v[50:51], v[66:67]
	v_pk_add_f32 v[56:57], v[56:57], 1.0 op_sel_hi:[1,0]
	v_add_f32_e32 v50, v50, v51
	s_waitcnt lgkmcnt(0)
	s_nop 1
	v_add_f32_dpp v50, v50, v50 quad_perm:[1,0,3,2] row_mask:0xf bank_mask:0xf
	s_waitcnt lgkmcnt(0)
	s_nop 1
	v_add_f32_dpp v50, v50, v50 quad_perm:[2,3,0,1] row_mask:0xf bank_mask:0xf
	s_waitcnt lgkmcnt(0)
	s_nop 1
	v_add_f32_dpp v50, v50, v50 row_half_mirror row_mask:0xf bank_mask:0xf
	s_waitcnt lgkmcnt(0)
	s_nop 1
	v_add_f32_dpp v50, v50, v50 row_mirror row_mask:0xf bank_mask:0xf
	s_waitcnt lgkmcnt(0)
	v_mov_b32_e32 v51, v50
	s_nop 1
	v_permlane16_swap_b32_e32 v50, v51
	v_add_f32_e32 v50, v50, v51
	s_waitcnt lgkmcnt(0)
	v_mov_b32_e32 v51, v50
	s_nop 1
	v_permlane32_swap_b32_e32 v50, v51
	v_add_f32_e32 v50, v50, v51
	v_fmamk_f32 v50, v50, 0x3a800000, v102
	v_mul_f32_e32 v51, 0x4f800000, v50
	v_cmp_gt_f32_e32 vcc, s4, v50
	s_nop 1
	v_cndmask_b32_e32 v60, v50, v51, vcc
	v_sqrt_f32_e32 v61, v60
	v_add_co_u32_e64 v50, s[6:7], s26, v86
	v_add_u32_e32 v62, -1, v61
	s_nop 0
	v_addc_co_u32_e64 v51, s[6:7], 0, v87, s[6:7]
	v_add_u32_e32 v63, 1, v61
	v_fma_f32 v64, -v62, v61, v60
	v_fma_f32 v65, -v63, v61, v60
	v_cmp_ge_f32_e64 s[6:7], 0, v64
	v_lshl_add_u64 v[86:87], v[86:87], 0, s[18:19]
	s_nop 0
	v_cndmask_b32_e64 v61, v61, v62, s[6:7]
	v_cmp_lt_f32_e64 s[6:7], 0, v65
	s_nop 1
	v_cndmask_b32_e64 v61, v61, v63, s[6:7]
	v_mul_f32_e32 v62, 0x37800000, v61
	v_cndmask_b32_e32 v61, v61, v62, vcc
	v_cmp_class_f32_e32 vcc, v60, v103
	s_and_b64 s[6:7], exec, s[24:25]
	s_nop 0
	v_cndmask_b32_e32 v62, v61, v60, vcc
	v_div_scale_f32 v63, s[6:7], v62, v62, 1.0
	v_rcp_f32_e32 v64, v63
	v_div_scale_f32 v65, vcc, 1.0, v62, 1.0
	v_lshl_add_u64 v[60:61], s[46:47], 0, v[90:91]
	v_fma_f32 v66, -v63, v64, 1.0
	v_fmac_f32_e32 v64, v66, v64
	v_mul_f32_e32 v66, v65, v64
	v_fma_f32 v67, -v63, v66, v65
	v_fmac_f32_e32 v66, v67, v64
	v_fma_f32 v63, -v63, v66, v65
	v_div_fmas_f32 v63, v63, v64, v66
	v_div_fixup_f32 v62, v63, v62, 1.0
	v_pk_mul_f32 v[48:49], v[48:49], v[62:63] op_sel_hi:[1,0]
	v_pk_mul_f32 v[46:47], v[46:47], v[62:63] op_sel_hi:[1,0]
	v_pk_mul_f32 v[48:49], v[4:5], v[48:49]
	v_pk_mul_f32 v[46:47], v[2:3], v[46:47]
	v_pk_fma_f32 v[48:49], v[58:59], v[48:49], v[54:55]
	v_pk_fma_f32 v[46:47], v[56:57], v[46:47], v[52:53]
	v_cvt_pk_bf16_f32 v46, v46, v47
	v_cvt_pk_bf16_f32 v47, v48, v49
	global_store_dwordx2 v[50:51], v[46:47], off
	global_load_dwordx4 v[46:49], v[60:61], off
	s_nop 0
	global_load_dwordx4 v[52:55], v[68:69], off offset:1024
	v_pk_mul_f32 v[40:41], v[40:41], v[62:63] op_sel_hi:[1,0]
	v_pk_mul_f32 v[38:39], v[38:39], v[62:63] op_sel_hi:[1,0]
	v_pk_mul_f32 v[40:41], v[8:9], v[40:41]
	v_pk_mul_f32 v[38:39], v[6:7], v[38:39]
	v_lshl_add_u64 v[56:57], s[46:47], 0, v[92:93]
	v_pk_mul_f32 v[32:33], v[32:33], v[62:63] op_sel_hi:[1,0]
	v_pk_mul_f32 v[30:31], v[30:31], v[62:63] op_sel_hi:[1,0]
	v_pk_mul_f32 v[32:33], v[12:13], v[32:33]
	v_pk_mul_f32 v[30:31], v[10:11], v[30:31]
	v_pk_mul_f32 v[20:21], v[20:21], v[62:63] op_sel_hi:[1,0]
	v_pk_mul_f32 v[18:19], v[18:19], v[62:63] op_sel_hi:[1,0]
	v_pk_mul_f32 v[20:21], v[16:17], v[20:21]
	v_pk_mul_f32 v[18:19], v[14:15], v[18:19]
	s_cselect_b32 s6, s27, s14
	s_mul_hi_i32 s7, s6, 0x9000
	s_mul_i32 s6, s6, 0x9000
	s_add_u32 s6, s42, s6
	s_addc_u32 s7, s43, s7
	s_lshl_b64 s[28:29], s[44:45], 11
	s_add_u32 s24, s6, 0x1000
	s_addc_u32 s25, s7, 0
	v_pk_mul_f32 v[58:59], v[34:35], v[34:35]
	v_mul_f32_e32 v63, v22, v22
	v_mul_f32_e32 v60, v27, v27
	v_mul_f32_e32 v62, v29, v29
	v_mul_f32_e32 v66, v23, v23
	v_mul_f32_e32 v67, v24, v24
	s_add_u32 s10, s10, s16
	s_addc_u32 s11, s11, s17
	s_add_u32 s20, s20, s22
	s_addc_u32 s21, s21, s23
	s_cmpk_lt_i32 s10, 0x4080
	s_waitcnt vmcnt(0) lgkmcnt(0)
	v_pk_add_f32 v[48:49], v[48:49], 1.0 op_sel_hi:[1,0]
	v_pk_add_f32 v[46:47], v[46:47], 1.0 op_sel_hi:[1,0]
	v_pk_fma_f32 v[40:41], v[48:49], v[40:41], v[54:55]
	v_pk_fma_f32 v[38:39], v[46:47], v[38:39], v[52:53]
	v_cvt_pk_bf16_f32 v38, v38, v39
	v_cvt_pk_bf16_f32 v39, v40, v41
	global_store_dwordx2 v[50:51], v[38:39], off offset:512
	global_load_dwordx4 v[38:41], v[56:57], off
	s_nop 0
	global_load_dwordx4 v[46:49], v[68:69], off offset:2048
	v_lshl_add_u64 v[52:53], s[46:47], 0, v[94:95]
	v_pk_mul_f32 v[54:55], v[42:43], v[42:43]
	v_pk_mul_f32 v[56:57], v[36:37], v[36:37]
	s_waitcnt vmcnt(0) lgkmcnt(0)
	v_pk_add_f32 v[40:41], v[40:41], 1.0 op_sel_hi:[1,0]
	v_pk_add_f32 v[38:39], v[38:39], 1.0 op_sel_hi:[1,0]
	v_pk_fma_f32 v[32:33], v[40:41], v[32:33], v[48:49]
	v_pk_fma_f32 v[30:31], v[38:39], v[30:31], v[46:47]
	v_cvt_pk_bf16_f32 v30, v30, v31
	v_cvt_pk_bf16_f32 v31, v32, v33
	global_store_dwordx2 v[50:51], v[30:31], off offset:1024
	global_load_dwordx4 v[38:41], v[52:53], off
	global_load_dwordx4 v[46:49], v[68:69], off offset:3072
	v_lshl_add_u64 v[30:31], s[6:7], 0, v[88:89]
	v_lshl_add_u64 v[32:33], s[24:25], 0, v[88:89]
	v_pk_mul_f32 v[52:53], v[44:45], v[44:45]
	v_mul_f32_e32 v68, v25, v25
	v_pk_mov_b32 v[64:65], v[54:55], v[52:53] op_sel:[1,0]
	v_mov_b32_e32 v55, v53
	v_pk_mov_b32 v[52:53], v[58:59], v[56:57] op_sel:[1,0]
	v_mov_b32_e32 v59, v57
	v_pk_add_f32 v[54:55], v[64:65], v[54:55]
	v_pk_add_f32 v[52:53], v[52:53], v[58:59]
	v_pk_fma_f32 v[56:57], v[26:27], v[26:27], v[60:61] op_sel_hi:[1,1,0]
	v_pk_fma_f32 v[60:61], v[28:29], v[28:29], v[62:63] op_sel_hi:[1,1,0]
	v_pk_add_f32 v[54:55], v[54:55], v[54:55] op_sel:[0,1] op_sel_hi:[1,0]
	v_pk_add_f32 v[52:53], v[52:53], v[52:53] op_sel:[0,1] op_sel_hi:[1,0]
	v_mov_b32_e32 v57, v67
	v_mov_b32_e32 v61, v68
	v_mov_b32_e32 v55, v63
	v_mov_b32_e32 v53, v66
	v_pk_add_f32 v[56:57], v[56:57], v[60:61]
	s_waitcnt vmcnt(0) lgkmcnt(0)
	v_pk_add_f32 v[40:41], v[40:41], 1.0 op_sel_hi:[1,0]
	v_pk_add_f32 v[38:39], v[38:39], 1.0 op_sel_hi:[1,0]
	v_pk_fma_f32 v[20:21], v[20:21], v[40:41], v[48:49]
	v_pk_fma_f32 v[18:19], v[18:19], v[38:39], v[46:47]
	v_cvt_pk_bf16_f32 v18, v18, v19
	v_cvt_pk_bf16_f32 v19, v20, v21
	global_store_dwordx2 v[50:51], v[18:19], off offset:1536
	global_load_dwordx4 v[18:21], v[30:31], off
	s_nop 0
	global_load_dwordx4 v[38:41], v[32:33], off
	v_pk_add_f32 v[32:33], v[54:55], v[52:53]
	v_lshl_add_u64 v[46:47], v[84:85], 0, s[28:29]
	v_pk_add_f32 v[32:33], v[32:33], v[56:57]
	s_waitcnt vmcnt(0) lgkmcnt(0)
	v_pk_add_f32 v[40:41], v[40:41], 1.0 op_sel_hi:[1,0]
	v_add_f32_e32 v32, v32, v33
	v_pk_add_f32 v[38:39], v[38:39], 1.0 op_sel_hi:[1,0]
	s_waitcnt lgkmcnt(0)
	s_nop 1
	v_add_f32_dpp v32, v32, v32 quad_perm:[1,0,3,2] row_mask:0xf bank_mask:0xf
	s_waitcnt lgkmcnt(0)
	s_nop 1
	v_add_f32_dpp v32, v32, v32 quad_perm:[2,3,0,1] row_mask:0xf bank_mask:0xf
	s_waitcnt lgkmcnt(0)
	s_nop 1
	v_add_f32_dpp v32, v32, v32 row_half_mirror row_mask:0xf bank_mask:0xf
	s_waitcnt lgkmcnt(0)
	s_nop 1
	v_add_f32_dpp v32, v32, v32 row_mirror row_mask:0xf bank_mask:0xf
	s_waitcnt lgkmcnt(0)
	v_mov_b32_e32 v33, v32
	s_nop 1
	v_permlane16_swap_b32_e32 v32, v33
	v_add_f32_e32 v32, v32, v33
	s_waitcnt lgkmcnt(0)
	v_mov_b32_e32 v33, v32
	s_nop 1
	v_permlane32_swap_b32_e32 v32, v33
	v_add_f32_e32 v32, v32, v33
	v_fmamk_f32 v32, v32, 0x3a800000, v102
	v_mul_f32_e32 v33, 0x4f800000, v32
	v_cmp_gt_f32_e32 vcc, s4, v32
	s_nop 1
	v_cndmask_b32_e32 v32, v32, v33, vcc
	v_sqrt_f32_e32 v33, v32
	s_nop 0
	v_add_u32_e32 v48, -1, v33
	v_add_u32_e32 v49, 1, v33
	v_fma_f32 v50, -v48, v33, v32
	v_fma_f32 v51, -v49, v33, v32
	v_cmp_ge_f32_e64 s[6:7], 0, v50
	s_nop 1
	v_cndmask_b32_e64 v33, v33, v48, s[6:7]
	v_cmp_lt_f32_e64 s[6:7], 0, v51
	s_nop 1
	v_cndmask_b32_e64 v33, v33, v49, s[6:7]
	v_mul_f32_e32 v48, 0x37800000, v33
	v_cndmask_b32_e32 v33, v33, v48, vcc
	v_cmp_class_f32_e32 vcc, v32, v103
	s_nop 1
	v_cndmask_b32_e32 v48, v33, v32, vcc
	v_div_scale_f32 v49, s[6:7], v48, v48, 1.0
	v_rcp_f32_e32 v50, v49
	v_div_scale_f32 v51, vcc, 1.0, v48, 1.0
	v_lshl_add_u64 v[32:33], s[24:25], 0, v[90:91]
	v_fma_f32 v52, -v49, v50, 1.0
	v_fmac_f32_e32 v50, v52, v50
	v_mul_f32_e32 v52, v51, v50
	v_fma_f32 v53, -v49, v52, v51
	v_fmac_f32_e32 v52, v53, v50
	v_fma_f32 v49, -v49, v52, v51
	v_div_fmas_f32 v49, v49, v50, v52
	v_div_fixup_f32 v48, v49, v48, 1.0
	v_pk_mul_f32 v[44:45], v[44:45], v[48:49] op_sel_hi:[1,0]
	v_pk_mul_f32 v[42:43], v[42:43], v[48:49] op_sel_hi:[1,0]
	v_pk_mul_f32 v[44:45], v[4:5], v[44:45]
	v_pk_mul_f32 v[42:43], v[2:3], v[42:43]
	v_pk_fma_f32 v[20:21], v[40:41], v[44:45], v[20:21]
	v_pk_fma_f32 v[18:19], v[38:39], v[42:43], v[18:19]
	v_cvt_pk_bf16_f32 v18, v18, v19
	v_cvt_pk_bf16_f32 v19, v20, v21
	global_store_dwordx2 v[46:47], v[18:19], off
	global_load_dwordx4 v[18:21], v[32:33], off
	s_nop 0
	global_load_dwordx4 v[38:41], v[30:31], off offset:1024
	v_pk_mul_f32 v[32:33], v[36:37], v[48:49] op_sel_hi:[1,0]
	v_pk_mul_f32 v[34:35], v[34:35], v[48:49] op_sel_hi:[1,0]
	v_pk_mul_f32 v[32:33], v[8:9], v[32:33]
	v_pk_mul_f32 v[34:35], v[6:7], v[34:35]
	v_lshl_add_u64 v[42:43], s[24:25], 0, v[92:93]
	v_pk_mul_f32 v[28:29], v[28:29], v[48:49] op_sel_hi:[1,0]
	v_pk_mul_f32 v[26:27], v[26:27], v[48:49] op_sel_hi:[1,0]
	v_pk_mul_f32 v[28:29], v[12:13], v[28:29]
	v_pk_mul_f32 v[26:27], v[10:11], v[26:27]
	v_lshl_add_u64 v[36:37], s[24:25], 0, v[94:95]
	v_pk_mul_f32 v[24:25], v[24:25], v[48:49] op_sel_hi:[1,0]
	v_pk_mul_f32 v[22:23], v[22:23], v[48:49] op_sel_hi:[1,0]
	v_pk_mul_f32 v[24:25], v[16:17], v[24:25]
	v_pk_mul_f32 v[22:23], v[14:15], v[22:23]
	s_waitcnt vmcnt(0) lgkmcnt(0)
	v_pk_add_f32 v[20:21], v[20:21], 1.0 op_sel_hi:[1,0]
	v_pk_add_f32 v[18:19], v[18:19], 1.0 op_sel_hi:[1,0]
	v_pk_fma_f32 v[20:21], v[20:21], v[32:33], v[40:41]
	v_pk_fma_f32 v[18:19], v[18:19], v[34:35], v[38:39]
	v_cvt_pk_bf16_f32 v18, v18, v19
	v_cvt_pk_bf16_f32 v19, v20, v21
	global_store_dwordx2 v[46:47], v[18:19], off offset:512
	global_load_dwordx4 v[18:21], v[42:43], off
	s_nop 0
	global_load_dwordx4 v[32:35], v[30:31], off offset:2048
	s_waitcnt vmcnt(0) lgkmcnt(0)
	v_pk_add_f32 v[20:21], v[20:21], 1.0 op_sel_hi:[1,0]
	v_pk_add_f32 v[18:19], v[18:19], 1.0 op_sel_hi:[1,0]
	v_pk_fma_f32 v[20:21], v[20:21], v[28:29], v[34:35]
	v_pk_fma_f32 v[18:19], v[18:19], v[26:27], v[32:33]
	v_cvt_pk_bf16_f32 v18, v18, v19
	v_cvt_pk_bf16_f32 v19, v20, v21
	global_store_dwordx2 v[46:47], v[18:19], off offset:1024
	global_load_dwordx4 v[18:21], v[36:37], off
	s_nop 0
	global_load_dwordx4 v[26:29], v[30:31], off offset:3072
	s_waitcnt vmcnt(0) lgkmcnt(0)
	v_pk_add_f32 v[20:21], v[20:21], 1.0 op_sel_hi:[1,0]
	v_pk_add_f32 v[18:19], v[18:19], 1.0 op_sel_hi:[1,0]
	v_pk_fma_f32 v[20:21], v[24:25], v[20:21], v[28:29]
	v_pk_fma_f32 v[18:19], v[22:23], v[18:19], v[26:27]
	v_cvt_pk_bf16_f32 v18, v18, v19
	v_cvt_pk_bf16_f32 v19, v20, v21
	global_store_dwordx2 v[46:47], v[18:19], off offset:1536
	s_cbranch_scc0 .LBB0_735

.LBB0_842:
	v_lshl_add_u64 v[18:19], s[38:39], 0, v[94:95]
	v_lshl_add_u64 v[22:23], s[38:39], 0, v[92:93]
	v_add_co_u32_e32 v20, vcc, 0x7800000, v18
	v_add_co_u32_e64 v102, s[6:7], s31, v22
	s_nop 0
	v_addc_co_u32_e32 v21, vcc, 0, v19, vcc
	v_addc_co_u32_e64 v103, s[6:7], 0, v23, s[6:7]
	v_add_co_u32_e64 v104, s[6:7], s33, v22
	v_add_co_u32_e32 v22, vcc, 0x7801000, v18
	s_nop 0
	v_addc_co_u32_e64 v105, s[6:7], 0, v23, s[6:7]
	global_load_dwordx4 v[78:81], v[20:21], off
	global_load_dwordx4 v[74:77], v[20:21], off offset:1024
	global_load_dwordx4 v[70:73], v[20:21], off offset:2048
	global_load_dwordx4 v[66:69], v[20:21], off offset:3072
	v_addc_co_u32_e32 v23, vcc, 0, v19, vcc
	v_add_co_u32_e32 v20, vcc, 0x7802000, v18
	global_load_dwordx4 v[62:65], v[22:23], off
	global_load_dwordx4 v[58:61], v[22:23], off offset:1024
	global_load_dwordx4 v[54:57], v[22:23], off offset:2048
	global_load_dwordx4 v[50:53], v[22:23], off offset:3072
	v_addc_co_u32_e32 v21, vcc, 0, v19, vcc
	global_load_dwordx4 v[46:49], v[20:21], off
	global_load_dwordx4 v[42:45], v[20:21], off offset:1024
	global_load_dwordx4 v[38:41], v[20:21], off offset:2048
	global_load_dwordx4 v[34:37], v[20:21], off offset:3072
	v_add_co_u32_e32 v18, vcc, 0x7803000, v18
	s_ashr_i32 s8, s18, 13
	s_nop 0
	v_addc_co_u32_e32 v19, vcc, 0, v19, vcc
	global_load_dwordx4 v[30:33], v[18:19], off
	global_load_dwordx4 v[26:29], v[18:19], off offset:1024
	global_load_dwordx4 v[22:25], v[18:19], off offset:2048
	s_nop 0
	global_load_dwordx4 v[18:21], v[18:19], off offset:3072
	s_add_i32 s9, s18, 0xffffc002
	s_cmpk_lt_i32 s18, 0x4000
	s_cselect_b32 s6, s8, s9
	s_mul_hi_i32 s7, s6, 0x9000
	s_mul_i32 s6, s6, 0x9000
	s_add_u32 s6, s27, s6
	s_addc_u32 s7, s28, s7
	s_add_u32 s10, s6, 0x1000
	s_addc_u32 s11, s7, 0
	v_lshl_add_u64 v[122:123], s[6:7], 0, v[90:91]
	v_lshl_add_u64 v[86:87], s[10:11], 0, v[90:91]
	global_load_dwordx4 v[82:85], v[122:123], off
	s_add_i32 s6, s18, 0xffffc003
	global_load_dwordx4 v[86:89], v[86:87], off
	s_cmpk_lt_i32 s18, 0x3fff
	s_cselect_b32 s6, s8, s6
	s_mul_hi_i32 s7, s6, 0x9000
	s_mul_i32 s6, s6, 0x9000
	s_add_u32 s6, s27, s6
	s_addc_u32 s7, s28, s7
	v_lshl_add_u64 v[142:143], s[10:11], 0, v[96:97]
	v_lshl_add_u64 v[138:139], s[10:11], 0, v[98:99]
	v_lshl_add_u64 v[128:129], s[10:11], 0, v[100:101]
	s_add_u32 s10, s6, 0x1000
	v_lshl_add_u64 v[110:111], s[6:7], 0, v[90:91]
	s_addc_u32 s11, s7, 0
	s_add_i32 s6, s18, 0xffffc004
	s_cmpk_lt_i32 s18, 0x3ffe
	s_cselect_b32 s6, s8, s6
	s_mul_hi_i32 s7, s6, 0x9000
	s_mul_i32 s6, s6, 0x9000
	v_lshl_add_u64 v[124:125], s[10:11], 0, v[90:91]
	v_lshl_add_u64 v[118:119], s[10:11], 0, v[96:97]
	v_lshl_add_u64 v[114:115], s[10:11], 0, v[98:99]
	v_lshl_add_u64 v[112:113], s[10:11], 0, v[100:101]
	s_add_u32 s10, s27, s6
	s_addc_u32 s11, s28, s7
	s_add_u32 s6, s10, 0x1000
	s_addc_u32 s7, s11, 0
	s_add_i32 s9, s18, 0xffffc005
	s_cmpk_lt_i32 s18, 0x3ffd
	v_lshl_add_u64 v[146:147], s[6:7], 0, v[90:91]
	v_lshl_add_u64 v[144:145], s[6:7], 0, v[96:97]
	v_lshl_add_u64 v[140:141], s[6:7], 0, v[98:99]
	v_lshl_add_u64 v[126:127], s[6:7], 0, v[100:101]
	s_cselect_b32 s6, s8, s9
	s_mul_hi_i32 s7, s6, 0x9000
	s_mul_i32 s6, s6, 0x9000
	s_add_u32 s6, s27, s6
	s_addc_u32 s7, s28, s7
	s_add_u32 s24, s6, 0x1000
	v_lshl_add_u64 v[106:107], s[6:7], 0, v[90:91]
	s_addc_u32 s25, s7, 0
	v_lshl_add_u64 v[108:109], s[10:11], 0, v[90:91]
	v_lshl_add_u64 v[120:121], s[24:25], 0, v[90:91]
	v_lshl_add_u64 v[116:117], s[24:25], 0, v[96:97]
	s_add_i32 s18, s18, 32
	v_lshl_add_u64 v[92:93], v[92:93], 0, s[20:21]
	v_lshl_add_u64 v[94:95], v[94:95], 0, s[22:23]
	s_cmp_lt_i32 s18, s26
	s_waitcnt vmcnt(0) lgkmcnt(0)
	v_pk_mul_f32 v[148:149], v[80:81], v[80:81]
	v_pk_mul_f32 v[150:151], v[78:79], v[78:79]
	v_pk_mul_f32 v[152:153], v[76:77], v[76:77]
	v_pk_mul_f32 v[154:155], v[74:75], v[74:75]
	v_mul_f32_e32 v164, v71, v71
	v_mul_f32_e32 v166, v73, v73
	v_pk_mov_b32 v[168:169], v[150:151], v[148:149] op_sel:[1,0]
	v_mov_b32_e32 v151, v149
	v_pk_mov_b32 v[148:149], v[154:155], v[152:153] op_sel:[1,0]
	v_mov_b32_e32 v155, v153
	v_mul_f32_e32 v177, v68, v68
	v_mul_f32_e32 v179, v69, v69
	v_pk_fma_f32 v[152:153], v[70:71], v[70:71], v[164:165] op_sel_hi:[1,1,0]
	v_pk_fma_f32 v[164:165], v[72:73], v[72:73], v[166:167] op_sel_hi:[1,1,0]
	v_pk_mul_f32 v[166:167], v[64:65], v[64:65]
	v_pk_mul_f32 v[170:171], v[62:63], v[62:63]
	v_pk_mul_f32 v[172:173], v[60:61], v[60:61]
	v_pk_mul_f32 v[174:175], v[58:59], v[58:59]
	v_mul_f32_e32 v176, v55, v55
	v_mul_f32_e32 v178, v57, v57
	v_pk_add_f32 v[150:151], v[168:169], v[150:151]
	v_pk_add_f32 v[148:149], v[148:149], v[154:155]
	v_mul_f32_e32 v163, v66, v66
	v_mul_f32_e32 v187, v67, v67
	v_mov_b32_e32 v153, v177
	v_mov_b32_e32 v165, v179
	v_pk_mov_b32 v[154:155], v[170:171], v[166:167] op_sel:[1,0]
	v_mov_b32_e32 v171, v167
	v_pk_mov_b32 v[166:167], v[174:175], v[172:173] op_sel:[1,0]
	v_mov_b32_e32 v175, v173
	v_pk_fma_f32 v[168:169], v[54:55], v[54:55], v[176:177] op_sel_hi:[1,1,0]
	v_pk_fma_f32 v[172:173], v[56:57], v[56:57], v[178:179] op_sel_hi:[1,1,0]
	v_pk_mul_f32 v[176:177], v[48:49], v[48:49]
	v_pk_mul_f32 v[178:179], v[46:47], v[46:47]
	v_pk_add_f32 v[188:189], v[150:151], v[150:151] op_sel:[0,1] op_sel_hi:[1,0]
	v_pk_add_f32 v[190:191], v[148:149], v[148:149] op_sel:[0,1] op_sel_hi:[1,0]
	v_mul_f32_e32 v185, v52, v52
	v_pk_mul_f32 v[180:181], v[44:45], v[44:45]
	v_pk_mul_f32 v[182:183], v[42:43], v[42:43]
	v_mul_f32_e32 v184, v39, v39
	v_mul_f32_e32 v186, v41, v41
	v_pk_add_f32 v[164:165], v[152:153], v[164:165]
	v_pk_add_f32 v[148:149], v[154:155], v[170:171]
	v_pk_add_f32 v[150:151], v[166:167], v[174:175]
	v_pk_mov_b32 v[152:153], v[178:179], v[176:177] op_sel:[1,0]
	v_mov_b32_e32 v179, v177
	v_mov_b32_e32 v189, v163
	v_mov_b32_e32 v191, v187
	v_mul_f32_e32 v193, v50, v50
	v_mul_f32_e32 v198, v51, v51
	v_mul_f32_e32 v192, v53, v53
	v_mul_f32_e32 v201, v36, v36
	v_mul_f32_e32 v202, v37, v37
	v_pk_mov_b32 v[154:155], v[182:183], v[180:181] op_sel:[1,0]
	v_mov_b32_e32 v183, v181
	v_pk_fma_f32 v[166:167], v[38:39], v[38:39], v[184:185] op_sel_hi:[1,1,0]
	v_pk_fma_f32 v[170:171], v[40:41], v[40:41], v[186:187] op_sel_hi:[1,1,0]
	v_pk_add_f32 v[194:195], v[148:149], v[148:149] op_sel:[0,1] op_sel_hi:[1,0]
	v_pk_add_f32 v[196:197], v[150:151], v[150:151] op_sel:[0,1] op_sel_hi:[1,0]
	v_pk_add_f32 v[152:153], v[152:153], v[178:179]
	v_pk_add_f32 v[178:179], v[188:189], v[190:191]
	v_mov_b32_e32 v169, v185
	v_mov_b32_e32 v173, v192
	v_pk_mul_f32 v[174:175], v[32:33], v[32:33]
	v_pk_mul_f32 v[176:177], v[30:31], v[30:31]
	v_pk_mul_f32 v[180:181], v[28:29], v[28:29]
	v_pk_mul_f32 v[184:185], v[26:27], v[26:27]
	v_pk_add_f32 v[154:155], v[154:155], v[182:183]
	v_mov_b32_e32 v167, v201
	v_mov_b32_e32 v171, v202
	v_mov_b32_e32 v195, v193
	v_mov_b32_e32 v197, v198
	v_pk_add_f32 v[164:165], v[178:179], v[164:165]
	v_mul_f32_e32 v199, v34, v34
	v_mul_f32_e32 v200, v35, v35
	v_pk_add_f32 v[168:169], v[168:169], v[172:173]
	v_pk_mov_b32 v[172:173], v[176:177], v[174:175] op_sel:[1,0]
	v_mov_b32_e32 v177, v175
	v_pk_mov_b32 v[174:175], v[184:185], v[180:181] op_sel:[1,0]
	v_mov_b32_e32 v185, v181
	v_pk_add_f32 v[180:181], v[152:153], v[152:153] op_sel:[0,1] op_sel_hi:[1,0]
	v_pk_add_f32 v[182:183], v[154:155], v[154:155] op_sel:[0,1] op_sel_hi:[1,0]
	v_pk_add_f32 v[166:167], v[166:167], v[170:171]
	v_pk_add_f32 v[170:171], v[194:195], v[196:197]
	v_add_f32_e32 v163, v164, v165
	v_mov_b32_e32 v181, v199
	v_mov_b32_e32 v183, v200
	v_pk_add_f32 v[164:165], v[170:171], v[168:169]
	ds_bpermute_b32 v171, v133, v163
	v_pk_add_f32 v[168:169], v[180:181], v[182:183]
	v_add_f32_e32 v170, v164, v165
	v_pk_add_f32 v[164:165], v[168:169], v[166:167]
	v_add_f32_e32 v164, v164, v165
	s_waitcnt lgkmcnt(0)
	v_add_f32_e32 v163, v163, v171
	s_waitcnt lgkmcnt(0)
	s_nop 1
	v_add_f32_dpp v166, v170, v170 quad_perm:[1,0,3,2] row_mask:0xf bank_mask:0xf
	s_waitcnt lgkmcnt(0)
	s_nop 1
	v_add_f32_dpp v164, v164, v164 quad_perm:[1,0,3,2] row_mask:0xf bank_mask:0xf
	s_waitcnt lgkmcnt(0)
	s_nop 1
	v_add_f32_dpp v163, v163, v163 quad_perm:[2,3,0,1] row_mask:0xf bank_mask:0xf
	ds_bpermute_b32 v167, v157, v163
	s_waitcnt lgkmcnt(2)
	s_nop 1
	v_add_f32_dpp v166, v166, v166 quad_perm:[2,3,0,1] row_mask:0xf bank_mask:0xf
	s_waitcnt lgkmcnt(0)
	s_nop 1
	v_add_f32_dpp v164, v164, v164 quad_perm:[2,3,0,1] row_mask:0xf bank_mask:0xf
	s_waitcnt lgkmcnt(0)
	v_add_f32_e32 v163, v163, v167
	ds_bpermute_b32 v167, v158, v163
	s_waitcnt lgkmcnt(2)
	s_nop 1
	v_add_f32_dpp v166, v166, v166 row_half_mirror row_mask:0xf bank_mask:0xf
	s_waitcnt lgkmcnt(0)
	s_nop 1
	v_add_f32_dpp v164, v164, v164 row_half_mirror row_mask:0xf bank_mask:0xf
	s_waitcnt lgkmcnt(0)
	v_add_f32_e32 v163, v163, v167
	s_waitcnt lgkmcnt(0)
	s_nop 1
	v_add_f32_dpp v166, v166, v166 row_mirror row_mask:0xf bank_mask:0xf
	s_waitcnt lgkmcnt(0)
	s_nop 1
	v_add_f32_dpp v164, v164, v164 row_mirror row_mask:0xf bank_mask:0xf
	s_waitcnt lgkmcnt(0)
	v_mov_b32_e32 v167, v163
	s_nop 1
	v_permlane16_swap_b32_e32 v163, v167
	v_add_f32_e32 v163, v163, v167
	s_waitcnt lgkmcnt(0)
	v_mov_b32_e32 v168, v166
	s_nop 1
	v_permlane16_swap_b32_e32 v166, v168
	v_add_f32_e32 v166, v166, v168
	s_waitcnt lgkmcnt(0)
	v_mov_b32_e32 v165, v164
	s_nop 1
	v_permlane16_swap_b32_e32 v164, v165
	v_add_f32_e32 v164, v164, v165
	s_waitcnt lgkmcnt(0)
	v_mov_b32_e32 v167, v163
	s_nop 1
	v_permlane32_swap_b32_e32 v163, v167
	v_add_f32_e32 v163, v163, v167
	v_fmamk_f32 v163, v163, 0x3a800000, v161
	s_waitcnt lgkmcnt(1)
	v_mov_b32_e32 v168, v166
	s_nop 1
	v_permlane32_swap_b32_e32 v166, v168
	v_add_f32_e32 v166, v166, v168
	v_mul_f32_e32 v167, 0x4f800000, v163
	v_cmp_gt_f32_e32 vcc, s19, v163
	v_fmamk_f32 v166, v166, 0x3a800000, v161
	s_waitcnt lgkmcnt(0)
	v_mov_b32_e32 v165, v164
	s_nop 1
	v_permlane32_swap_b32_e32 v164, v165
	v_add_f32_e32 v164, v164, v165
	v_cndmask_b32_e32 v163, v163, v167, vcc
	v_mul_f32_e32 v165, 0x4f800000, v166
	v_cmp_gt_f32_e64 s[6:7], s19, v166
	v_sqrt_f32_e32 v167, v163
	v_fmamk_f32 v164, v164, 0x3a800000, v161
	v_cndmask_b32_e64 v165, v166, v165, s[6:7]
	v_mul_f32_e32 v166, 0x4f800000, v164
	v_cmp_gt_f32_e64 s[8:9], s19, v164
	v_sqrt_f32_e32 v168, v165
	v_add_u32_e32 v169, -1, v167
	v_cndmask_b32_e64 v164, v164, v166, s[8:9]
	v_sqrt_f32_e32 v166, v164
	v_add_u32_e32 v170, 1, v167
	v_fma_f32 v171, -v169, v167, v163
	v_pk_add_f32 v[152:153], v[172:173], v[176:177]
	v_fma_f32 v172, -v170, v167, v163
	v_add_u32_e32 v173, -1, v168
	v_cmp_ge_f32_e64 s[10:11], 0, v171
	v_pk_add_f32 v[154:155], v[174:175], v[184:185]
	v_add_u32_e32 v174, 1, v168
	v_cndmask_b32_e64 v167, v167, v169, s[10:11]
	v_fma_f32 v169, -v173, v168, v165
	v_cmp_lt_f32_e64 s[10:11], 0, v172
	v_fma_f32 v171, -v174, v168, v165
	v_add_u32_e32 v175, -1, v166
	v_cndmask_b32_e64 v167, v167, v170, s[10:11]
	v_cmp_ge_f32_e64 s[10:11], 0, v169
	v_add_u32_e32 v176, 1, v166
	v_fma_f32 v169, -v175, v166, v164
	v_cndmask_b32_e64 v168, v168, v173, s[10:11]
	v_cmp_lt_f32_e64 s[10:11], 0, v171
	v_fma_f32 v170, -v176, v166, v164
	v_mul_f32_e32 v171, 0x37800000, v167
	v_cndmask_b32_e64 v168, v168, v174, s[10:11]
	v_cmp_ge_f32_e64 s[10:11], 0, v169
	v_cndmask_b32_e32 v167, v167, v171, vcc
	v_cmp_class_f32_e32 vcc, v163, v162
	v_cndmask_b32_e64 v166, v166, v175, s[10:11]
	v_cmp_lt_f32_e64 s[10:11], 0, v170
	v_mul_f32_e32 v169, 0x37800000, v168
	v_cndmask_b32_e32 v163, v167, v163, vcc
	v_cndmask_b32_e64 v166, v166, v176, s[10:11]
	v_cndmask_b32_e64 v167, v168, v169, s[6:7]
	v_cmp_class_f32_e32 vcc, v165, v162
	v_mul_f32_e32 v168, 0x37800000, v166
	v_div_scale_f32 v169, s[6:7], v163, v163, 1.0
	v_cndmask_b32_e32 v165, v167, v165, vcc
	v_cndmask_b32_e64 v166, v166, v168, s[8:9]
	v_cmp_class_f32_e32 vcc, v164, v162
	v_rcp_f32_e32 v167, v169
	v_div_scale_f32 v168, s[8:9], v165, v165, 1.0
	v_cndmask_b32_e32 v166, v166, v164, vcc
	v_rcp_f32_e32 v172, v168
	v_div_scale_f32 v173, s[10:11], v166, v166, 1.0
	v_rcp_f32_e32 v175, v173
	v_fma_f32 v164, -v169, v167, 1.0
	v_div_scale_f32 v170, s[6:7], 1.0, v163, 1.0
	v_fmac_f32_e32 v167, v164, v167
	v_fma_f32 v164, -v168, v172, 1.0
	v_mul_f32_e32 v176, v170, v167
	v_div_scale_f32 v171, s[8:9], 1.0, v165, 1.0
	v_fmac_f32_e32 v172, v164, v172
	v_fma_f32 v164, -v173, v175, 1.0
	v_fma_f32 v177, -v169, v176, v170
	v_div_scale_f32 v174, s[10:11], 1.0, v166, 1.0
	v_mul_f32_e32 v178, v171, v172
	v_fmac_f32_e32 v175, v164, v175
	v_fmac_f32_e32 v176, v177, v167
	v_fma_f32 v164, -v168, v178, v171
	v_mul_f32_e32 v177, v174, v175
	v_fma_f32 v169, -v169, v176, v170
	s_mov_b64 vcc, s[6:7]
	v_fmac_f32_e32 v178, v164, v172
	v_fma_f32 v164, -v173, v177, v174
	v_div_fmas_f32 v167, v169, v167, v176
	v_fma_f32 v168, -v168, v178, v171
	v_fmac_f32_e32 v177, v164, v175
	v_div_fixup_f32 v164, v167, v163, 1.0
	s_mov_b64 vcc, s[8:9]
	v_div_fmas_f32 v163, v168, v172, v178
	v_fma_f32 v167, -v173, v177, v174
	v_pk_mul_f32 v[80:81], v[80:81], v[164:165] op_sel_hi:[1,0]
	v_pk_mul_f32 v[78:79], v[78:79], v[164:165] op_sel_hi:[1,0]
	s_mov_b64 vcc, s[10:11]
	v_pk_add_f32 v[88:89], v[88:89], 1.0 op_sel_hi:[1,0]
	v_pk_add_f32 v[86:87], v[86:87], 1.0 op_sel_hi:[1,0]
	v_pk_mul_f32 v[76:77], v[76:77], v[164:165] op_sel_hi:[1,0]
	v_pk_mul_f32 v[74:75], v[74:75], v[164:165] op_sel_hi:[1,0]
	v_pk_mul_f32 v[72:73], v[72:73], v[164:165] op_sel_hi:[1,0]
	v_pk_mul_f32 v[70:71], v[70:71], v[164:165] op_sel_hi:[1,0]
	v_pk_mul_f32 v[68:69], v[68:69], v[164:165] op_sel_hi:[1,0]
	v_pk_mul_f32 v[66:67], v[66:67], v[164:165] op_sel_hi:[1,0]
	v_div_fixup_f32 v164, v163, v165, 1.0
	v_div_fmas_f32 v163, v167, v175, v177
	v_pk_mul_f32 v[78:79], v[78:79], v[2:3]
	v_pk_mul_f32 v[80:81], v[80:81], v[4:5]
	v_pk_mul_f32 v[64:65], v[64:65], v[164:165] op_sel_hi:[1,0]
	v_pk_mul_f32 v[62:63], v[62:63], v[164:165] op_sel_hi:[1,0]
	v_pk_mul_f32 v[60:61], v[60:61], v[164:165] op_sel_hi:[1,0]
	v_pk_mul_f32 v[58:59], v[58:59], v[164:165] op_sel_hi:[1,0]
	v_pk_mul_f32 v[56:57], v[56:57], v[164:165] op_sel_hi:[1,0]
	v_pk_mul_f32 v[54:55], v[54:55], v[164:165] op_sel_hi:[1,0]
	v_pk_mul_f32 v[52:53], v[52:53], v[164:165] op_sel_hi:[1,0]
	v_pk_mul_f32 v[50:51], v[50:51], v[164:165] op_sel_hi:[1,0]
	v_div_fixup_f32 v164, v163, v166, 1.0
	v_pk_fma_f32 v[80:81], v[80:81], v[88:89], v[84:85]
	v_pk_fma_f32 v[78:79], v[78:79], v[86:87], v[82:83]
	v_pk_mul_f32 v[82:83], v[50:51], v[14:15]
	v_pk_mul_f32 v[84:85], v[52:53], v[16:17]
	v_pk_mul_f32 v[48:49], v[48:49], v[164:165] op_sel_hi:[1,0]
	v_pk_mul_f32 v[46:47], v[46:47], v[164:165] op_sel_hi:[1,0]
	v_pk_mul_f32 v[86:87], v[46:47], v[2:3]
	v_pk_mul_f32 v[88:89], v[48:49], v[4:5]
	v_cvt_pk_bf16_f32 v46, v78, v79
	v_cvt_pk_bf16_f32 v47, v80, v81
	global_store_dwordx2 v[102:103], v[46:47], off
	global_load_dwordx4 v[46:49], v[142:143], off
	s_nop 0
	global_load_dwordx4 v[50:53], v[122:123], off offset:1024
	v_pk_mul_f32 v[74:75], v[74:75], v[6:7]
	v_pk_mul_f32 v[76:77], v[76:77], v[8:9]
	v_pk_mul_f32 v[70:71], v[70:71], v[10:11]
	v_pk_mul_f32 v[72:73], v[72:73], v[12:13]
	v_pk_mul_f32 v[66:67], v[66:67], v[14:15]
	v_pk_mul_f32 v[68:69], v[68:69], v[16:17]
	v_pk_mul_f32 v[62:63], v[62:63], v[2:3]
	v_pk_mul_f32 v[64:65], v[64:65], v[4:5]
	v_pk_mul_f32 v[58:59], v[58:59], v[6:7]
	v_pk_mul_f32 v[60:61], v[60:61], v[8:9]
	v_pk_mul_f32 v[54:55], v[54:55], v[10:11]
	v_pk_mul_f32 v[56:57], v[56:57], v[12:13]
	v_pk_mul_f32 v[44:45], v[44:45], v[164:165] op_sel_hi:[1,0]
	v_pk_mul_f32 v[42:43], v[42:43], v[164:165] op_sel_hi:[1,0]
	v_pk_mul_f32 v[44:45], v[44:45], v[8:9]
	v_pk_mul_f32 v[42:43], v[42:43], v[6:7]
	v_pk_mul_f32 v[40:41], v[40:41], v[164:165] op_sel_hi:[1,0]
	v_pk_mul_f32 v[38:39], v[38:39], v[164:165] op_sel_hi:[1,0]
	v_pk_mul_f32 v[40:41], v[40:41], v[12:13]
	v_pk_mul_f32 v[38:39], v[38:39], v[10:11]
	v_pk_mul_f32 v[36:37], v[36:37], v[164:165] op_sel_hi:[1,0]
	v_pk_mul_f32 v[34:35], v[34:35], v[164:165] op_sel_hi:[1,0]
	v_pk_mul_f32 v[36:37], v[36:37], v[16:17]
	v_pk_mul_f32 v[34:35], v[34:35], v[14:15]
	v_mul_f32_e32 v186, v23, v23
	v_mul_f32_e32 v192, v25, v25
	v_mul_f32_e32 v203, v18, v18
	v_mul_f32_e32 v204, v19, v19
	v_mul_f32_e32 v205, v20, v20
	v_mul_f32_e32 v206, v21, v21
	v_pk_fma_f32 v[148:149], v[22:23], v[22:23], v[186:187] op_sel_hi:[1,1,0]
	v_pk_fma_f32 v[150:151], v[24:25], v[24:25], v[192:193] op_sel_hi:[1,1,0]
	v_mov_b32_e32 v149, v205
	v_mov_b32_e32 v151, v206
	s_waitcnt vmcnt(0) lgkmcnt(0)
	v_pk_add_f32 v[48:49], v[48:49], 1.0 op_sel_hi:[1,0]
	v_pk_add_f32 v[46:47], v[46:47], 1.0 op_sel_hi:[1,0]
	v_pk_fma_f32 v[48:49], v[76:77], v[48:49], v[52:53]
	v_pk_fma_f32 v[46:47], v[74:75], v[46:47], v[50:51]
	v_cvt_pk_bf16_f32 v46, v46, v47
	v_cvt_pk_bf16_f32 v47, v48, v49
	global_store_dwordx2 v[102:103], v[46:47], off offset:512
	global_load_dwordx4 v[46:49], v[138:139], off
	s_nop 0
	global_load_dwordx4 v[50:53], v[122:123], off offset:2048
	s_waitcnt vmcnt(0) lgkmcnt(0)
	v_pk_add_f32 v[48:49], v[48:49], 1.0 op_sel_hi:[1,0]
	v_pk_add_f32 v[46:47], v[46:47], 1.0 op_sel_hi:[1,0]
	v_pk_fma_f32 v[48:49], v[72:73], v[48:49], v[52:53]
	v_pk_fma_f32 v[46:47], v[70:71], v[46:47], v[50:51]
	v_cvt_pk_bf16_f32 v46, v46, v47
	v_cvt_pk_bf16_f32 v47, v48, v49
	global_store_dwordx2 v[102:103], v[46:47], off offset:1024
	global_load_dwordx4 v[46:49], v[128:129], off
	s_nop 0
	global_load_dwordx4 v[50:53], v[122:123], off offset:3072
	s_waitcnt vmcnt(0) lgkmcnt(0)
	v_pk_add_f32 v[48:49], v[48:49], 1.0 op_sel_hi:[1,0]
	v_pk_add_f32 v[46:47], v[46:47], 1.0 op_sel_hi:[1,0]
	v_pk_fma_f32 v[48:49], v[68:69], v[48:49], v[52:53]
	v_pk_fma_f32 v[46:47], v[66:67], v[46:47], v[50:51]
	v_cvt_pk_bf16_f32 v46, v46, v47
	v_cvt_pk_bf16_f32 v47, v48, v49
	global_store_dwordx2 v[102:103], v[46:47], off offset:1536
	global_load_dwordx4 v[46:49], v[124:125], off
	s_nop 0
	global_load_dwordx4 v[50:53], v[110:111], off
	s_waitcnt vmcnt(0) lgkmcnt(0)
	v_pk_add_f32 v[48:49], v[48:49], 1.0 op_sel_hi:[1,0]
	v_pk_add_f32 v[46:47], v[46:47], 1.0 op_sel_hi:[1,0]
	v_pk_fma_f32 v[48:49], v[64:65], v[48:49], v[52:53]
	v_pk_fma_f32 v[46:47], v[62:63], v[46:47], v[50:51]
	v_cvt_pk_bf16_f32 v46, v46, v47
	v_cvt_pk_bf16_f32 v47, v48, v49
	global_store_dwordx2 v[102:103], v[46:47], off offset:2048
	global_load_dwordx4 v[46:49], v[118:119], off
	s_nop 0
	global_load_dwordx4 v[50:53], v[110:111], off offset:1024
	s_waitcnt vmcnt(0) lgkmcnt(0)
	v_pk_add_f32 v[48:49], v[48:49], 1.0 op_sel_hi:[1,0]
	v_pk_add_f32 v[46:47], v[46:47], 1.0 op_sel_hi:[1,0]
	v_pk_fma_f32 v[48:49], v[60:61], v[48:49], v[52:53]
	v_pk_fma_f32 v[46:47], v[58:59], v[46:47], v[50:51]
	v_cvt_pk_bf16_f32 v46, v46, v47
	v_cvt_pk_bf16_f32 v47, v48, v49
	global_store_dwordx2 v[102:103], v[46:47], off offset:2560
	global_load_dwordx4 v[46:49], v[114:115], off
	s_nop 0
	global_load_dwordx4 v[50:53], v[110:111], off offset:2048
	v_pk_add_f32 v[58:59], v[148:149], v[150:151]
	s_waitcnt vmcnt(0) lgkmcnt(0)
	v_pk_add_f32 v[48:49], v[48:49], 1.0 op_sel_hi:[1,0]
	v_pk_add_f32 v[46:47], v[46:47], 1.0 op_sel_hi:[1,0]
	v_pk_fma_f32 v[48:49], v[56:57], v[48:49], v[52:53]
	v_pk_fma_f32 v[46:47], v[54:55], v[46:47], v[50:51]
	v_cvt_pk_bf16_f32 v46, v46, v47
	v_cvt_pk_bf16_f32 v47, v48, v49
	global_store_dwordx2 v[102:103], v[46:47], off offset:3072
	global_load_dwordx4 v[46:49], v[112:113], off
	s_nop 0
	global_load_dwordx4 v[50:53], v[110:111], off offset:3072
	v_pk_add_f32 v[54:55], v[152:153], v[152:153] op_sel:[0,1] op_sel_hi:[1,0]
	v_pk_add_f32 v[56:57], v[154:155], v[154:155] op_sel:[0,1] op_sel_hi:[1,0]
	v_mov_b32_e32 v55, v203
	v_mov_b32_e32 v57, v204
	s_waitcnt vmcnt(0) lgkmcnt(0)
	v_pk_add_f32 v[48:49], v[48:49], 1.0 op_sel_hi:[1,0]
	v_pk_add_f32 v[46:47], v[46:47], 1.0 op_sel_hi:[1,0]
	v_pk_fma_f32 v[48:49], v[84:85], v[48:49], v[52:53]
	v_pk_fma_f32 v[46:47], v[82:83], v[46:47], v[50:51]
	v_cvt_pk_bf16_f32 v46, v46, v47
	v_cvt_pk_bf16_f32 v47, v48, v49
	global_store_dwordx2 v[102:103], v[46:47], off offset:3584
	global_load_dwordx4 v[46:49], v[146:147], off
	s_nop 0
	global_load_dwordx4 v[50:53], v[108:109], off
	s_waitcnt vmcnt(0) lgkmcnt(0)
	v_pk_add_f32 v[48:49], v[48:49], 1.0 op_sel_hi:[1,0]
	v_pk_add_f32 v[46:47], v[46:47], 1.0 op_sel_hi:[1,0]
	v_pk_fma_f32 v[48:49], v[88:89], v[48:49], v[52:53]
	v_pk_fma_f32 v[46:47], v[86:87], v[46:47], v[50:51]
	v_cvt_pk_bf16_f32 v46, v46, v47
	v_cvt_pk_bf16_f32 v47, v48, v49
	global_store_dwordx2 v[104:105], v[46:47], off
	global_load_dwordx4 v[46:49], v[144:145], off
	s_nop 0
	global_load_dwordx4 v[50:53], v[108:109], off offset:1024
	s_waitcnt vmcnt(0) lgkmcnt(0)
	v_pk_add_f32 v[48:49], v[48:49], 1.0 op_sel_hi:[1,0]
	v_pk_add_f32 v[46:47], v[46:47], 1.0 op_sel_hi:[1,0]
	v_pk_fma_f32 v[44:45], v[44:45], v[48:49], v[52:53]
	v_pk_fma_f32 v[42:43], v[42:43], v[46:47], v[50:51]
	v_cvt_pk_bf16_f32 v42, v42, v43
	v_cvt_pk_bf16_f32 v43, v44, v45
	global_store_dwordx2 v[104:105], v[42:43], off offset:512
	global_load_dwordx4 v[42:45], v[140:141], off
	s_nop 0
	global_load_dwordx4 v[46:49], v[108:109], off offset:2048
	v_pk_add_f32 v[50:51], v[54:55], v[56:57]
	s_waitcnt vmcnt(0) lgkmcnt(0)
	v_pk_add_f32 v[44:45], v[44:45], 1.0 op_sel_hi:[1,0]
	v_pk_add_f32 v[42:43], v[42:43], 1.0 op_sel_hi:[1,0]
	v_pk_fma_f32 v[40:41], v[40:41], v[44:45], v[48:49]
	v_pk_fma_f32 v[38:39], v[38:39], v[42:43], v[46:47]
	v_cvt_pk_bf16_f32 v38, v38, v39
	v_cvt_pk_bf16_f32 v39, v40, v41
	global_store_dwordx2 v[104:105], v[38:39], off offset:1024
	global_load_dwordx4 v[38:41], v[126:127], off
	s_nop 0
	global_load_dwordx4 v[42:45], v[108:109], off offset:3072
	v_pk_add_f32 v[50:51], v[50:51], v[58:59]
	s_waitcnt vmcnt(0) lgkmcnt(0)
	v_pk_add_f32 v[40:41], v[40:41], 1.0 op_sel_hi:[1,0]
	v_pk_add_f32 v[38:39], v[38:39], 1.0 op_sel_hi:[1,0]
	v_pk_fma_f32 v[36:37], v[36:37], v[40:41], v[44:45]
	v_pk_fma_f32 v[34:35], v[34:35], v[38:39], v[42:43]
	v_cvt_pk_bf16_f32 v34, v34, v35
	v_cvt_pk_bf16_f32 v35, v36, v37
	global_store_dwordx2 v[104:105], v[34:35], off offset:1536
	global_load_dwordx4 v[34:37], v[120:121], off
	s_nop 0
	global_load_dwordx4 v[38:41], v[106:107], off
	v_add_f32_e32 v50, v50, v51
	s_waitcnt lgkmcnt(0)
	s_nop 1
	v_add_f32_dpp v50, v50, v50 quad_perm:[1,0,3,2] row_mask:0xf bank_mask:0xf
	ds_bpermute_b32 v51, v156, v50
	s_waitcnt lgkmcnt(0)
	v_add_f32_e32 v50, v50, v51
	ds_bpermute_b32 v46, v157, v50
	s_waitcnt lgkmcnt(0)
	v_add_f32_e32 v46, v50, v46
	ds_bpermute_b32 v47, v158, v46
	s_waitcnt lgkmcnt(0)
	v_add_f32_e32 v46, v46, v47
	s_waitcnt lgkmcnt(0)
	v_mov_b32_e32 v47, v46
	s_nop 1
	v_permlane16_swap_b32_e32 v46, v47
	v_add_f32_e32 v46, v46, v47
	s_waitcnt lgkmcnt(0)
	v_mov_b32_e32 v47, v46
	s_nop 1
	v_permlane32_swap_b32_e32 v46, v47
	v_add_f32_e32 v46, v46, v47
	v_fmamk_f32 v46, v46, 0x3a800000, v161
	v_mul_f32_e32 v47, 0x4f800000, v46
	v_cmp_gt_f32_e32 vcc, s19, v46
	s_waitcnt vmcnt(0)
	v_pk_add_f32 v[36:37], v[36:37], 1.0 op_sel_hi:[1,0]
	v_cndmask_b32_e32 v42, v46, v47, vcc
	v_sqrt_f32_e32 v43, v42
	v_pk_add_f32 v[34:35], v[34:35], 1.0 op_sel_hi:[1,0]
	v_add_u32_e32 v44, -1, v43
	v_add_u32_e32 v45, 1, v43
	v_fma_f32 v46, -v44, v43, v42
	v_fma_f32 v47, -v45, v43, v42
	v_cmp_ge_f32_e64 s[6:7], 0, v46
	s_nop 1
	v_cndmask_b32_e64 v43, v43, v44, s[6:7]
	v_cmp_lt_f32_e64 s[6:7], 0, v47
	s_nop 1
	v_cndmask_b32_e64 v43, v43, v45, s[6:7]
	v_mul_f32_e32 v44, 0x37800000, v43
	v_cndmask_b32_e32 v43, v43, v44, vcc
	v_cmp_class_f32_e32 vcc, v42, v162
	s_nop 1
	v_cndmask_b32_e32 v42, v43, v42, vcc
	v_div_scale_f32 v43, s[6:7], v42, v42, 1.0
	v_rcp_f32_e32 v45, v43
	v_div_scale_f32 v44, vcc, 1.0, v42, 1.0
	v_fma_f32 v46, -v43, v45, 1.0
	v_fmac_f32_e32 v45, v46, v45
	v_mul_f32_e32 v46, v44, v45
	v_fma_f32 v47, -v43, v46, v44
	v_fmac_f32_e32 v46, v47, v45
	v_fma_f32 v43, -v43, v46, v44
	v_div_fmas_f32 v43, v43, v45, v46
	v_div_fixup_f32 v42, v43, v42, 1.0
	v_pk_mul_f32 v[32:33], v[32:33], v[42:43] op_sel_hi:[1,0]
	v_pk_mul_f32 v[30:31], v[30:31], v[42:43] op_sel_hi:[1,0]
	v_pk_mul_f32 v[32:33], v[32:33], v[4:5]
	v_pk_mul_f32 v[30:31], v[30:31], v[2:3]
	v_pk_fma_f32 v[32:33], v[32:33], v[36:37], v[40:41]
	v_pk_fma_f32 v[30:31], v[30:31], v[34:35], v[38:39]
	v_cvt_pk_bf16_f32 v30, v30, v31
	v_cvt_pk_bf16_f32 v31, v32, v33
	global_store_dwordx2 v[104:105], v[30:31], off offset:2048
	global_load_dwordx4 v[30:33], v[116:117], off
	s_nop 0
	global_load_dwordx4 v[34:37], v[106:107], off offset:1024
	v_pk_mul_f32 v[28:29], v[28:29], v[42:43] op_sel_hi:[1,0]
	v_pk_mul_f32 v[26:27], v[26:27], v[42:43] op_sel_hi:[1,0]
	v_pk_mul_f32 v[28:29], v[28:29], v[8:9]
	v_pk_mul_f32 v[26:27], v[26:27], v[6:7]
	v_lshl_add_u64 v[38:39], s[24:25], 0, v[98:99]
	v_pk_mul_f32 v[24:25], v[24:25], v[42:43] op_sel_hi:[1,0]
	v_pk_mul_f32 v[22:23], v[22:23], v[42:43] op_sel_hi:[1,0]
	v_pk_mul_f32 v[24:25], v[24:25], v[12:13]
	v_pk_mul_f32 v[22:23], v[22:23], v[10:11]
	v_pk_mul_f32 v[20:21], v[20:21], v[42:43] op_sel_hi:[1,0]
	v_pk_mul_f32 v[18:19], v[18:19], v[42:43] op_sel_hi:[1,0]
	v_pk_mul_f32 v[20:21], v[20:21], v[16:17]
	v_pk_mul_f32 v[18:19], v[18:19], v[14:15]
	s_waitcnt vmcnt(0) lgkmcnt(0)
	v_pk_add_f32 v[32:33], v[32:33], 1.0 op_sel_hi:[1,0]
	v_pk_add_f32 v[30:31], v[30:31], 1.0 op_sel_hi:[1,0]
	v_pk_fma_f32 v[28:29], v[28:29], v[32:33], v[36:37]
	v_pk_fma_f32 v[26:27], v[26:27], v[30:31], v[34:35]
	v_cvt_pk_bf16_f32 v26, v26, v27
	v_cvt_pk_bf16_f32 v27, v28, v29
	global_store_dwordx2 v[104:105], v[26:27], off offset:2560
	global_load_dwordx4 v[26:29], v[38:39], off
	s_nop 0
	global_load_dwordx4 v[30:33], v[106:107], off offset:2048
	v_lshl_add_u64 v[34:35], s[24:25], 0, v[100:101]
	s_waitcnt vmcnt(0) lgkmcnt(0)
	v_pk_add_f32 v[28:29], v[28:29], 1.0 op_sel_hi:[1,0]
	v_pk_add_f32 v[26:27], v[26:27], 1.0 op_sel_hi:[1,0]
	v_pk_fma_f32 v[24:25], v[24:25], v[28:29], v[32:33]
	v_pk_fma_f32 v[22:23], v[22:23], v[26:27], v[30:31]
	v_cvt_pk_bf16_f32 v22, v22, v23
	v_cvt_pk_bf16_f32 v23, v24, v25
	global_store_dwordx2 v[104:105], v[22:23], off offset:3072
	global_load_dwordx4 v[22:25], v[34:35], off
	s_nop 0
	global_load_dwordx4 v[26:29], v[106:107], off offset:3072
	s_waitcnt vmcnt(0) lgkmcnt(0)
	v_pk_add_f32 v[24:25], v[24:25], 1.0 op_sel_hi:[1,0]
	v_pk_add_f32 v[22:23], v[22:23], 1.0 op_sel_hi:[1,0]
	v_pk_fma_f32 v[20:21], v[20:21], v[24:25], v[28:29]
	v_pk_fma_f32 v[18:19], v[18:19], v[22:23], v[26:27]
	v_cvt_pk_bf16_f32 v18, v18, v19
	v_cvt_pk_bf16_f32 v19, v20, v21
	global_store_dwordx2 v[104:105], v[18:19], off offset:3584
	s_cbranch_scc1 .LBB0_842

.LBB0_1004:
	v_lshl_add_u64 v[18:19], s[38:39], 0, v[94:95]
	v_lshl_add_u64 v[22:23], s[38:39], 0, v[92:93]
	v_add_co_u32_e32 v20, vcc, 0x7800000, v18
	v_add_co_u32_e64 v102, s[6:7], s24, v22
	s_nop 0
	v_addc_co_u32_e32 v21, vcc, 0, v19, vcc
	v_addc_co_u32_e64 v103, s[6:7], 0, v23, s[6:7]
	v_add_co_u32_e64 v104, s[6:7], s25, v22
	v_add_co_u32_e32 v22, vcc, 0x7801000, v18
	s_nop 0
	v_addc_co_u32_e64 v105, s[6:7], 0, v23, s[6:7]
	global_load_dwordx4 v[78:81], v[20:21], off
	global_load_dwordx4 v[74:77], v[20:21], off offset:1024
	global_load_dwordx4 v[70:73], v[20:21], off offset:2048
	global_load_dwordx4 v[66:69], v[20:21], off offset:3072
	v_addc_co_u32_e32 v23, vcc, 0, v19, vcc
	v_add_co_u32_e32 v20, vcc, 0x7802000, v18
	global_load_dwordx4 v[62:65], v[22:23], off
	global_load_dwordx4 v[58:61], v[22:23], off offset:1024
	global_load_dwordx4 v[54:57], v[22:23], off offset:2048
	global_load_dwordx4 v[50:53], v[22:23], off offset:3072
	v_addc_co_u32_e32 v21, vcc, 0, v19, vcc
	global_load_dwordx4 v[46:49], v[20:21], off
	global_load_dwordx4 v[42:45], v[20:21], off offset:1024
	global_load_dwordx4 v[38:41], v[20:21], off offset:2048
	global_load_dwordx4 v[34:37], v[20:21], off offset:3072
	v_add_co_u32_e32 v82, vcc, 0x7803000, v18
	s_add_i32 s26, s8, 32
	s_nop 0
	v_addc_co_u32_e32 v83, vcc, 0, v19, vcc
	global_load_dwordx4 v[30:33], v[82:83], off
	global_load_dwordx4 v[26:29], v[82:83], off offset:1024
	global_load_dwordx4 v[22:25], v[82:83], off offset:2048
	global_load_dwordx4 v[18:21], v[82:83], off offset:3072
	s_add_i32 s10, s8, 0xffffc022
	s_ashr_i32 s9, s26, 13
	s_cmpk_lt_i32 s26, 0x4000
	s_cselect_b32 s6, s9, s10
	s_mul_hi_i32 s7, s6, 0x9000
	s_mul_i32 s6, s6, 0x9000
	s_add_u32 s6, s2, s6
	s_addc_u32 s7, s13, s7
	s_add_u32 s10, s6, 0x1000
	s_addc_u32 s11, s7, 0
	v_lshl_add_u64 v[124:125], s[6:7], 0, v[90:91]
	v_lshl_add_u64 v[86:87], s[10:11], 0, v[90:91]
	global_load_dwordx4 v[82:85], v[124:125], off
	s_add_i32 s6, s8, 0xffffc023
	global_load_dwordx4 v[86:89], v[86:87], off
	s_cmpk_lt_i32 s26, 0x3fff
	s_cselect_b32 s6, s9, s6
	s_mul_hi_i32 s7, s6, 0x9000
	s_mul_i32 s6, s6, 0x9000
	s_add_u32 s6, s2, s6
	s_addc_u32 s7, s13, s7
	v_lshl_add_u64 v[138:139], s[10:11], 0, v[96:97]
	v_lshl_add_u64 v[134:135], s[10:11], 0, v[98:99]
	v_lshl_add_u64 v[128:129], s[10:11], 0, v[100:101]
	s_add_u32 s10, s6, 0x1000
	v_lshl_add_u64 v[110:111], s[6:7], 0, v[90:91]
	s_addc_u32 s11, s7, 0
	s_add_i32 s6, s8, 0xffffc024
	s_cmpk_lt_i32 s26, 0x3ffe
	s_cselect_b32 s6, s9, s6
	s_mul_hi_i32 s7, s6, 0x9000
	s_mul_i32 s6, s6, 0x9000
	v_lshl_add_u64 v[126:127], s[10:11], 0, v[90:91]
	v_lshl_add_u64 v[120:121], s[10:11], 0, v[96:97]
	v_lshl_add_u64 v[116:117], s[10:11], 0, v[98:99]
	v_lshl_add_u64 v[112:113], s[10:11], 0, v[100:101]
	s_add_u32 s10, s2, s6
	s_addc_u32 s11, s13, s7
	s_add_u32 s6, s10, 0x1000
	s_addc_u32 s7, s11, 0
	s_addk_i32 s8, 0xc025
	s_cmpk_lt_i32 s26, 0x3ffd
	v_lshl_add_u64 v[142:143], s[6:7], 0, v[90:91]
	v_lshl_add_u64 v[140:141], s[6:7], 0, v[96:97]
	v_lshl_add_u64 v[136:137], s[6:7], 0, v[98:99]
	v_lshl_add_u64 v[122:123], s[6:7], 0, v[100:101]
	s_cselect_b32 s6, s9, s8
	s_mul_hi_i32 s7, s6, 0x9000
	s_mul_i32 s6, s6, 0x9000
	s_add_u32 s6, s2, s6
	s_addc_u32 s7, s13, s7
	s_add_u32 s20, s6, 0x1000
	v_lshl_add_u64 v[106:107], s[6:7], 0, v[90:91]
	s_addc_u32 s21, s7, 0
	v_lshl_add_u64 v[108:109], s[10:11], 0, v[90:91]
	v_lshl_add_u64 v[118:119], s[20:21], 0, v[90:91]
	v_lshl_add_u64 v[114:115], s[20:21], 0, v[96:97]
	v_lshl_add_u64 v[92:93], v[92:93], 0, s[16:17]
	v_lshl_add_u64 v[94:95], v[94:95], 0, s[18:19]
	s_cmp_lt_i32 s26, s22
	s_waitcnt vmcnt(0) lgkmcnt(0)
	v_pk_mul_f32 v[144:145], v[80:81], v[80:81]
	v_pk_mul_f32 v[146:147], v[78:79], v[78:79]
	v_pk_mul_f32 v[148:149], v[76:77], v[76:77]
	v_pk_mul_f32 v[150:151], v[74:75], v[74:75]
	v_mul_f32_e32 v158, v71, v71
	v_mul_f32_e32 v160, v73, v73
	v_pk_mov_b32 v[162:163], v[146:147], v[144:145] op_sel:[1,0]
	v_mov_b32_e32 v147, v145
	v_pk_mov_b32 v[144:145], v[150:151], v[148:149] op_sel:[1,0]
	v_mov_b32_e32 v151, v149
	v_mul_f32_e32 v171, v68, v68
	v_mul_f32_e32 v173, v69, v69
	v_pk_fma_f32 v[148:149], v[70:71], v[70:71], v[158:159] op_sel_hi:[1,1,0]
	v_pk_fma_f32 v[158:159], v[72:73], v[72:73], v[160:161] op_sel_hi:[1,1,0]
	v_pk_mul_f32 v[160:161], v[64:65], v[64:65]
	v_pk_mul_f32 v[164:165], v[62:63], v[62:63]
	v_pk_mul_f32 v[166:167], v[60:61], v[60:61]
	v_pk_mul_f32 v[168:169], v[58:59], v[58:59]
	v_mul_f32_e32 v170, v55, v55
	v_mul_f32_e32 v172, v57, v57
	v_pk_add_f32 v[146:147], v[162:163], v[146:147]
	v_pk_add_f32 v[144:145], v[144:145], v[150:151]
	v_mul_f32_e32 v157, v66, v66
	v_mul_f32_e32 v181, v67, v67
	v_mov_b32_e32 v149, v171
	v_mov_b32_e32 v159, v173
	v_pk_mov_b32 v[150:151], v[164:165], v[160:161] op_sel:[1,0]
	v_mov_b32_e32 v165, v161
	v_pk_mov_b32 v[160:161], v[168:169], v[166:167] op_sel:[1,0]
	v_mov_b32_e32 v169, v167
	v_pk_fma_f32 v[162:163], v[54:55], v[54:55], v[170:171] op_sel_hi:[1,1,0]
	v_pk_fma_f32 v[166:167], v[56:57], v[56:57], v[172:173] op_sel_hi:[1,1,0]
	v_pk_mul_f32 v[170:171], v[48:49], v[48:49]
	v_pk_mul_f32 v[172:173], v[46:47], v[46:47]
	v_pk_add_f32 v[182:183], v[146:147], v[146:147] op_sel:[0,1] op_sel_hi:[1,0]
	v_pk_add_f32 v[184:185], v[144:145], v[144:145] op_sel:[0,1] op_sel_hi:[1,0]
	v_mul_f32_e32 v179, v52, v52
	v_pk_mul_f32 v[174:175], v[44:45], v[44:45]
	v_pk_mul_f32 v[176:177], v[42:43], v[42:43]
	v_mul_f32_e32 v178, v39, v39
	v_mul_f32_e32 v180, v41, v41
	v_pk_add_f32 v[158:159], v[148:149], v[158:159]
	v_pk_add_f32 v[144:145], v[150:151], v[164:165]
	v_pk_add_f32 v[146:147], v[160:161], v[168:169]
	v_pk_mov_b32 v[148:149], v[172:173], v[170:171] op_sel:[1,0]
	v_mov_b32_e32 v173, v171
	v_mov_b32_e32 v183, v157
	v_mov_b32_e32 v185, v181
	v_mul_f32_e32 v187, v50, v50
	v_mul_f32_e32 v192, v51, v51
	v_mul_f32_e32 v186, v53, v53
	v_mul_f32_e32 v195, v36, v36
	v_mul_f32_e32 v196, v37, v37
	v_pk_mov_b32 v[150:151], v[176:177], v[174:175] op_sel:[1,0]
	v_mov_b32_e32 v177, v175
	v_pk_fma_f32 v[160:161], v[38:39], v[38:39], v[178:179] op_sel_hi:[1,1,0]
	v_pk_fma_f32 v[164:165], v[40:41], v[40:41], v[180:181] op_sel_hi:[1,1,0]
	v_pk_add_f32 v[188:189], v[144:145], v[144:145] op_sel:[0,1] op_sel_hi:[1,0]
	v_pk_add_f32 v[190:191], v[146:147], v[146:147] op_sel:[0,1] op_sel_hi:[1,0]
	v_pk_add_f32 v[148:149], v[148:149], v[172:173]
	v_pk_add_f32 v[172:173], v[182:183], v[184:185]
	v_mov_b32_e32 v163, v179
	v_mov_b32_e32 v167, v186
	v_pk_mul_f32 v[168:169], v[32:33], v[32:33]
	v_pk_mul_f32 v[170:171], v[30:31], v[30:31]
	v_pk_mul_f32 v[174:175], v[28:29], v[28:29]
	v_pk_mul_f32 v[178:179], v[26:27], v[26:27]
	v_pk_add_f32 v[150:151], v[150:151], v[176:177]
	v_mov_b32_e32 v161, v195
	v_mov_b32_e32 v165, v196
	v_mov_b32_e32 v189, v187
	v_mov_b32_e32 v191, v192
	v_pk_add_f32 v[158:159], v[172:173], v[158:159]
	v_mul_f32_e32 v193, v34, v34
	v_mul_f32_e32 v194, v35, v35
	v_pk_add_f32 v[162:163], v[162:163], v[166:167]
	v_pk_mov_b32 v[166:167], v[170:171], v[168:169] op_sel:[1,0]
	v_mov_b32_e32 v171, v169
	v_pk_mov_b32 v[168:169], v[178:179], v[174:175] op_sel:[1,0]
	v_mov_b32_e32 v179, v175
	v_pk_add_f32 v[174:175], v[148:149], v[148:149] op_sel:[0,1] op_sel_hi:[1,0]
	v_pk_add_f32 v[176:177], v[150:151], v[150:151] op_sel:[0,1] op_sel_hi:[1,0]
	v_pk_add_f32 v[160:161], v[160:161], v[164:165]
	v_pk_add_f32 v[164:165], v[188:189], v[190:191]
	v_add_f32_e32 v157, v158, v159
	v_mov_b32_e32 v175, v193
	v_mov_b32_e32 v177, v194
	v_pk_add_f32 v[158:159], v[164:165], v[162:163]
	ds_bpermute_b32 v165, v1, v157
	v_pk_add_f32 v[162:163], v[174:175], v[176:177]
	v_add_f32_e32 v164, v158, v159
	v_pk_add_f32 v[158:159], v[162:163], v[160:161]
	v_add_f32_e32 v158, v158, v159
	s_waitcnt lgkmcnt(0)
	v_add_f32_e32 v157, v157, v165
	s_waitcnt lgkmcnt(0)
	s_nop 1
	v_add_f32_dpp v160, v164, v164 quad_perm:[1,0,3,2] row_mask:0xf bank_mask:0xf
	s_waitcnt lgkmcnt(0)
	s_nop 1
	v_add_f32_dpp v158, v158, v158 quad_perm:[1,0,3,2] row_mask:0xf bank_mask:0xf
	s_waitcnt lgkmcnt(0)
	s_nop 1
	v_add_f32_dpp v157, v157, v157 quad_perm:[2,3,0,1] row_mask:0xf bank_mask:0xf
	ds_bpermute_b32 v161, v133, v157
	s_waitcnt lgkmcnt(2)
	s_nop 1
	v_add_f32_dpp v160, v160, v160 quad_perm:[2,3,0,1] row_mask:0xf bank_mask:0xf
	s_waitcnt lgkmcnt(0)
	s_nop 1
	v_add_f32_dpp v158, v158, v158 quad_perm:[2,3,0,1] row_mask:0xf bank_mask:0xf
	s_waitcnt lgkmcnt(0)
	v_add_f32_e32 v157, v157, v161
	ds_bpermute_b32 v161, v152, v157
	s_waitcnt lgkmcnt(2)
	s_nop 1
	v_add_f32_dpp v160, v160, v160 row_half_mirror row_mask:0xf bank_mask:0xf
	s_waitcnt lgkmcnt(0)
	s_nop 1
	v_add_f32_dpp v158, v158, v158 row_half_mirror row_mask:0xf bank_mask:0xf
	s_waitcnt lgkmcnt(0)
	v_add_f32_e32 v157, v157, v161
	s_waitcnt lgkmcnt(0)
	s_nop 1
	v_add_f32_dpp v160, v160, v160 row_mirror row_mask:0xf bank_mask:0xf
	s_waitcnt lgkmcnt(0)
	s_nop 1
	v_add_f32_dpp v158, v158, v158 row_mirror row_mask:0xf bank_mask:0xf
	s_waitcnt lgkmcnt(0)
	v_mov_b32_e32 v161, v157
	s_nop 1
	v_permlane16_swap_b32_e32 v157, v161
	v_add_f32_e32 v157, v157, v161
	s_waitcnt lgkmcnt(0)
	v_mov_b32_e32 v162, v160
	s_nop 1
	v_permlane16_swap_b32_e32 v160, v162
	v_add_f32_e32 v160, v160, v162
	s_waitcnt lgkmcnt(0)
	v_mov_b32_e32 v159, v158
	s_nop 1
	v_permlane16_swap_b32_e32 v158, v159
	v_add_f32_e32 v158, v158, v159
	s_waitcnt lgkmcnt(0)
	v_mov_b32_e32 v161, v157
	s_nop 1
	v_permlane32_swap_b32_e32 v157, v161
	v_add_f32_e32 v157, v157, v161
	v_fmamk_f32 v157, v157, 0x3a800000, v155
	s_waitcnt lgkmcnt(1)
	v_mov_b32_e32 v162, v160
	s_nop 1
	v_permlane32_swap_b32_e32 v160, v162
	v_add_f32_e32 v160, v160, v162
	v_mul_f32_e32 v161, 0x4f800000, v157
	v_cmp_gt_f32_e32 vcc, s4, v157
	v_fmamk_f32 v160, v160, 0x3a800000, v155
	s_waitcnt lgkmcnt(0)
	v_mov_b32_e32 v159, v158
	s_nop 1
	v_permlane32_swap_b32_e32 v158, v159
	v_add_f32_e32 v158, v158, v159
	v_cndmask_b32_e32 v157, v157, v161, vcc
	v_mul_f32_e32 v159, 0x4f800000, v160
	v_cmp_gt_f32_e64 s[6:7], s4, v160
	v_sqrt_f32_e32 v161, v157
	v_fmamk_f32 v158, v158, 0x3a800000, v155
	v_cndmask_b32_e64 v159, v160, v159, s[6:7]
	v_mul_f32_e32 v160, 0x4f800000, v158
	v_cmp_gt_f32_e64 s[8:9], s4, v158
	v_sqrt_f32_e32 v162, v159
	v_add_u32_e32 v163, -1, v161
	v_cndmask_b32_e64 v158, v158, v160, s[8:9]
	v_sqrt_f32_e32 v160, v158
	v_add_u32_e32 v164, 1, v161
	v_fma_f32 v165, -v163, v161, v157
	v_pk_add_f32 v[148:149], v[166:167], v[170:171]
	v_fma_f32 v166, -v164, v161, v157
	v_add_u32_e32 v167, -1, v162
	v_cmp_ge_f32_e64 s[10:11], 0, v165
	v_pk_add_f32 v[150:151], v[168:169], v[178:179]
	v_add_u32_e32 v168, 1, v162
	v_cndmask_b32_e64 v161, v161, v163, s[10:11]
	v_fma_f32 v163, -v167, v162, v159
	v_cmp_lt_f32_e64 s[10:11], 0, v166
	v_fma_f32 v165, -v168, v162, v159
	v_add_u32_e32 v169, -1, v160
	v_cndmask_b32_e64 v161, v161, v164, s[10:11]
	v_cmp_ge_f32_e64 s[10:11], 0, v163
	v_add_u32_e32 v170, 1, v160
	v_fma_f32 v163, -v169, v160, v158
	v_cndmask_b32_e64 v162, v162, v167, s[10:11]
	v_cmp_lt_f32_e64 s[10:11], 0, v165
	v_fma_f32 v164, -v170, v160, v158
	v_mul_f32_e32 v165, 0x37800000, v161
	v_cndmask_b32_e64 v162, v162, v168, s[10:11]
	v_cmp_ge_f32_e64 s[10:11], 0, v163
	v_cndmask_b32_e32 v161, v161, v165, vcc
	v_cmp_class_f32_e32 vcc, v157, v156
	v_cndmask_b32_e64 v160, v160, v169, s[10:11]
	v_cmp_lt_f32_e64 s[10:11], 0, v164
	v_mul_f32_e32 v163, 0x37800000, v162
	v_cndmask_b32_e32 v157, v161, v157, vcc
	v_cndmask_b32_e64 v160, v160, v170, s[10:11]
	v_cndmask_b32_e64 v161, v162, v163, s[6:7]
	v_cmp_class_f32_e32 vcc, v159, v156
	v_mul_f32_e32 v162, 0x37800000, v160
	v_div_scale_f32 v163, s[6:7], v157, v157, 1.0
	v_cndmask_b32_e32 v159, v161, v159, vcc
	v_cndmask_b32_e64 v160, v160, v162, s[8:9]
	v_cmp_class_f32_e32 vcc, v158, v156
	v_rcp_f32_e32 v161, v163
	v_div_scale_f32 v162, s[8:9], v159, v159, 1.0
	v_cndmask_b32_e32 v160, v160, v158, vcc
	v_rcp_f32_e32 v166, v162
	v_div_scale_f32 v167, s[10:11], v160, v160, 1.0
	v_rcp_f32_e32 v169, v167
	v_fma_f32 v158, -v163, v161, 1.0
	v_div_scale_f32 v164, s[6:7], 1.0, v157, 1.0
	v_fmac_f32_e32 v161, v158, v161
	v_fma_f32 v158, -v162, v166, 1.0
	v_mul_f32_e32 v170, v164, v161
	v_div_scale_f32 v165, s[8:9], 1.0, v159, 1.0
	v_fmac_f32_e32 v166, v158, v166
	v_fma_f32 v158, -v167, v169, 1.0
	v_fma_f32 v171, -v163, v170, v164
	v_div_scale_f32 v168, s[10:11], 1.0, v160, 1.0
	v_mul_f32_e32 v172, v165, v166
	v_fmac_f32_e32 v169, v158, v169
	v_fmac_f32_e32 v170, v171, v161
	v_fma_f32 v158, -v162, v172, v165
	v_mul_f32_e32 v171, v168, v169
	v_fma_f32 v163, -v163, v170, v164
	s_mov_b64 vcc, s[6:7]
	v_fmac_f32_e32 v172, v158, v166
	v_fma_f32 v158, -v167, v171, v168
	v_div_fmas_f32 v161, v163, v161, v170
	v_fma_f32 v162, -v162, v172, v165
	v_fmac_f32_e32 v171, v158, v169
	v_div_fixup_f32 v158, v161, v157, 1.0
	s_mov_b64 vcc, s[8:9]
	v_div_fmas_f32 v157, v162, v166, v172
	v_fma_f32 v161, -v167, v171, v168
	v_pk_mul_f32 v[80:81], v[80:81], v[158:159] op_sel_hi:[1,0]
	v_pk_mul_f32 v[78:79], v[78:79], v[158:159] op_sel_hi:[1,0]
	s_mov_b64 vcc, s[10:11]
	v_pk_add_f32 v[88:89], v[88:89], 1.0 op_sel_hi:[1,0]
	v_pk_add_f32 v[86:87], v[86:87], 1.0 op_sel_hi:[1,0]
	v_pk_mul_f32 v[76:77], v[76:77], v[158:159] op_sel_hi:[1,0]
	v_pk_mul_f32 v[74:75], v[74:75], v[158:159] op_sel_hi:[1,0]
	v_pk_mul_f32 v[72:73], v[72:73], v[158:159] op_sel_hi:[1,0]
	v_pk_mul_f32 v[70:71], v[70:71], v[158:159] op_sel_hi:[1,0]
	v_pk_mul_f32 v[68:69], v[68:69], v[158:159] op_sel_hi:[1,0]
	v_pk_mul_f32 v[66:67], v[66:67], v[158:159] op_sel_hi:[1,0]
	v_div_fixup_f32 v158, v157, v159, 1.0
	v_div_fmas_f32 v157, v161, v169, v171
	v_pk_mul_f32 v[78:79], v[78:79], v[2:3]
	v_pk_mul_f32 v[80:81], v[80:81], v[4:5]
	v_pk_mul_f32 v[64:65], v[64:65], v[158:159] op_sel_hi:[1,0]
	v_pk_mul_f32 v[62:63], v[62:63], v[158:159] op_sel_hi:[1,0]
	v_pk_mul_f32 v[60:61], v[60:61], v[158:159] op_sel_hi:[1,0]
	v_pk_mul_f32 v[58:59], v[58:59], v[158:159] op_sel_hi:[1,0]
	v_pk_mul_f32 v[56:57], v[56:57], v[158:159] op_sel_hi:[1,0]
	v_pk_mul_f32 v[54:55], v[54:55], v[158:159] op_sel_hi:[1,0]
	v_pk_mul_f32 v[52:53], v[52:53], v[158:159] op_sel_hi:[1,0]
	v_pk_mul_f32 v[158:159], v[50:51], v[158:159] op_sel_hi:[1,0]
	v_div_fixup_f32 v50, v157, v160, 1.0
	v_pk_fma_f32 v[80:81], v[80:81], v[88:89], v[84:85]
	v_pk_fma_f32 v[78:79], v[78:79], v[86:87], v[82:83]
	v_pk_mul_f32 v[86:87], v[52:53], v[16:17]
	v_pk_mul_f32 v[48:49], v[48:49], v[50:51] op_sel_hi:[1,0]
	v_pk_mul_f32 v[46:47], v[46:47], v[50:51] op_sel_hi:[1,0]
	v_pk_mul_f32 v[82:83], v[54:55], v[10:11]
	v_pk_mul_f32 v[84:85], v[158:159], v[14:15]
	v_pk_mul_f32 v[88:89], v[46:47], v[2:3]
	v_pk_mul_f32 v[158:159], v[48:49], v[4:5]
	v_cvt_pk_bf16_f32 v46, v78, v79
	v_cvt_pk_bf16_f32 v47, v80, v81
	global_store_dwordx2 v[102:103], v[46:47], off
	global_load_dwordx4 v[46:49], v[138:139], off
	s_nop 0
	global_load_dwordx4 v[52:55], v[124:125], off offset:1024
	v_pk_mul_f32 v[74:75], v[74:75], v[6:7]
	v_pk_mul_f32 v[76:77], v[76:77], v[8:9]
	v_pk_mul_f32 v[70:71], v[70:71], v[10:11]
	v_pk_mul_f32 v[72:73], v[72:73], v[12:13]
	v_pk_mul_f32 v[66:67], v[66:67], v[14:15]
	v_pk_mul_f32 v[68:69], v[68:69], v[16:17]
	v_pk_mul_f32 v[62:63], v[62:63], v[2:3]
	v_pk_mul_f32 v[64:65], v[64:65], v[4:5]
	v_pk_mul_f32 v[58:59], v[58:59], v[6:7]
	v_pk_mul_f32 v[60:61], v[60:61], v[8:9]
	v_pk_mul_f32 v[56:57], v[56:57], v[12:13]
	v_mul_f32_e32 v180, v23, v23
	v_mul_f32_e32 v186, v25, v25
	v_mul_f32_e32 v197, v18, v18
	v_mul_f32_e32 v198, v19, v19
	v_mul_f32_e32 v199, v20, v20
	v_mul_f32_e32 v200, v21, v21
	v_pk_fma_f32 v[144:145], v[22:23], v[22:23], v[180:181] op_sel_hi:[1,1,0]
	v_pk_fma_f32 v[146:147], v[24:25], v[24:25], v[186:187] op_sel_hi:[1,1,0]
	v_mov_b32_e32 v145, v199
	v_mov_b32_e32 v147, v200
	s_mov_b32 s8, s26
	s_waitcnt vmcnt(0) lgkmcnt(0)
	v_pk_add_f32 v[48:49], v[48:49], 1.0 op_sel_hi:[1,0]
	v_pk_add_f32 v[46:47], v[46:47], 1.0 op_sel_hi:[1,0]
	v_pk_fma_f32 v[48:49], v[76:77], v[48:49], v[54:55]
	v_pk_fma_f32 v[46:47], v[74:75], v[46:47], v[52:53]
	v_cvt_pk_bf16_f32 v46, v46, v47
	v_cvt_pk_bf16_f32 v47, v48, v49
	global_store_dwordx2 v[102:103], v[46:47], off offset:512
	global_load_dwordx4 v[46:49], v[134:135], off
	s_nop 0
	global_load_dwordx4 v[52:55], v[124:125], off offset:2048
	s_waitcnt vmcnt(0) lgkmcnt(0)
	v_pk_add_f32 v[48:49], v[48:49], 1.0 op_sel_hi:[1,0]
	v_pk_add_f32 v[46:47], v[46:47], 1.0 op_sel_hi:[1,0]
	v_pk_fma_f32 v[48:49], v[72:73], v[48:49], v[54:55]
	v_pk_fma_f32 v[46:47], v[70:71], v[46:47], v[52:53]
	v_cvt_pk_bf16_f32 v46, v46, v47
	v_cvt_pk_bf16_f32 v47, v48, v49
	global_store_dwordx2 v[102:103], v[46:47], off offset:1024
	global_load_dwordx4 v[46:49], v[128:129], off
	s_nop 0
	global_load_dwordx4 v[52:55], v[124:125], off offset:3072
	s_waitcnt vmcnt(0) lgkmcnt(0)
	v_pk_add_f32 v[48:49], v[48:49], 1.0 op_sel_hi:[1,0]
	v_pk_add_f32 v[46:47], v[46:47], 1.0 op_sel_hi:[1,0]
	v_pk_fma_f32 v[48:49], v[68:69], v[48:49], v[54:55]
	v_pk_fma_f32 v[46:47], v[66:67], v[46:47], v[52:53]
	v_cvt_pk_bf16_f32 v46, v46, v47
	v_cvt_pk_bf16_f32 v47, v48, v49
	global_store_dwordx2 v[102:103], v[46:47], off offset:1536
	global_load_dwordx4 v[46:49], v[126:127], off
	s_nop 0
	global_load_dwordx4 v[52:55], v[110:111], off
	s_waitcnt vmcnt(0) lgkmcnt(0)
	v_pk_add_f32 v[48:49], v[48:49], 1.0 op_sel_hi:[1,0]
	v_pk_add_f32 v[46:47], v[46:47], 1.0 op_sel_hi:[1,0]
	v_pk_fma_f32 v[48:49], v[64:65], v[48:49], v[54:55]
	v_pk_fma_f32 v[46:47], v[62:63], v[46:47], v[52:53]
	v_cvt_pk_bf16_f32 v46, v46, v47
	v_cvt_pk_bf16_f32 v47, v48, v49
	global_store_dwordx2 v[102:103], v[46:47], off offset:2048
	global_load_dwordx4 v[46:49], v[120:121], off
	s_nop 0
	global_load_dwordx4 v[52:55], v[110:111], off offset:1024
	s_waitcnt vmcnt(0) lgkmcnt(0)
	v_pk_add_f32 v[48:49], v[48:49], 1.0 op_sel_hi:[1,0]
	v_pk_add_f32 v[46:47], v[46:47], 1.0 op_sel_hi:[1,0]
	v_pk_fma_f32 v[48:49], v[60:61], v[48:49], v[54:55]
	v_pk_fma_f32 v[46:47], v[58:59], v[46:47], v[52:53]
	v_cvt_pk_bf16_f32 v46, v46, v47
	v_cvt_pk_bf16_f32 v47, v48, v49
	global_store_dwordx2 v[102:103], v[46:47], off offset:2560
	global_load_dwordx4 v[46:49], v[116:117], off
	s_nop 0
	global_load_dwordx4 v[52:55], v[110:111], off offset:2048
	v_pk_add_f32 v[58:59], v[150:151], v[150:151] op_sel:[0,1] op_sel_hi:[1,0]
	v_pk_add_f32 v[60:61], v[144:145], v[146:147]
	v_mov_b32_e32 v59, v198
	s_waitcnt vmcnt(0) lgkmcnt(0)
	v_pk_add_f32 v[48:49], v[48:49], 1.0 op_sel_hi:[1,0]
	v_pk_add_f32 v[46:47], v[46:47], 1.0 op_sel_hi:[1,0]
	v_pk_fma_f32 v[48:49], v[56:57], v[48:49], v[54:55]
	v_pk_fma_f32 v[46:47], v[82:83], v[46:47], v[52:53]
	v_cvt_pk_bf16_f32 v46, v46, v47
	v_cvt_pk_bf16_f32 v47, v48, v49
	global_store_dwordx2 v[102:103], v[46:47], off offset:3072
	global_load_dwordx4 v[46:49], v[112:113], off
	s_nop 0
	global_load_dwordx4 v[52:55], v[110:111], off offset:3072
	v_pk_add_f32 v[56:57], v[148:149], v[148:149] op_sel:[0,1] op_sel_hi:[1,0]
	s_waitcnt vmcnt(0) lgkmcnt(0)
	v_pk_add_f32 v[48:49], v[48:49], 1.0 op_sel_hi:[1,0]
	v_pk_add_f32 v[46:47], v[46:47], 1.0 op_sel_hi:[1,0]
	v_pk_fma_f32 v[48:49], v[86:87], v[48:49], v[54:55]
	v_pk_fma_f32 v[46:47], v[84:85], v[46:47], v[52:53]
	v_cvt_pk_bf16_f32 v46, v46, v47
	v_cvt_pk_bf16_f32 v47, v48, v49
	global_store_dwordx2 v[102:103], v[46:47], off offset:3584
	global_load_dwordx4 v[46:49], v[142:143], off
	s_nop 0
	global_load_dwordx4 v[52:55], v[108:109], off
	v_mov_b32_e32 v57, v197
	s_waitcnt vmcnt(0) lgkmcnt(0)
	v_pk_add_f32 v[48:49], v[48:49], 1.0 op_sel_hi:[1,0]
	v_pk_add_f32 v[46:47], v[46:47], 1.0 op_sel_hi:[1,0]
	v_pk_fma_f32 v[48:49], v[158:159], v[48:49], v[54:55]
	v_pk_fma_f32 v[46:47], v[88:89], v[46:47], v[52:53]
	v_bfe_u32 v51, v46, 16, 1
	v_bfe_u32 v52, v47, 16, 1
	v_add3_u32 v46, v46, v51, s5
	v_add3_u32 v47, v47, v52, s5
	v_lshrrev_b32_e32 v46, 16, v46
	v_and_or_b32 v46, v47, s23, v46
	v_cvt_pk_bf16_f32 v47, v48, v49
	global_store_dwordx2 v[104:105], v[46:47], off
	global_load_dwordx4 v[46:49], v[140:141], off
	s_nop 0
	global_load_dwordx4 v[52:55], v[108:109], off offset:1024
	v_pk_mul_f32 v[44:45], v[44:45], v[50:51] op_sel_hi:[1,0]
	v_pk_mul_f32 v[42:43], v[42:43], v[50:51] op_sel_hi:[1,0]
	v_pk_mul_f32 v[44:45], v[44:45], v[8:9]
	v_pk_mul_f32 v[42:43], v[42:43], v[6:7]
	s_waitcnt vmcnt(0) lgkmcnt(0)
	v_pk_add_f32 v[48:49], v[48:49], 1.0 op_sel_hi:[1,0]
	v_pk_add_f32 v[46:47], v[46:47], 1.0 op_sel_hi:[1,0]
	v_pk_fma_f32 v[44:45], v[44:45], v[48:49], v[54:55]
	v_pk_fma_f32 v[42:43], v[42:43], v[46:47], v[52:53]
	v_cvt_pk_bf16_f32 v42, v42, v43
	v_cvt_pk_bf16_f32 v43, v44, v45
	global_store_dwordx2 v[104:105], v[42:43], off offset:512
	global_load_dwordx4 v[42:45], v[136:137], off
	s_nop 0
	global_load_dwordx4 v[46:49], v[108:109], off offset:2048
	v_pk_add_f32 v[52:53], v[56:57], v[58:59]
	s_waitcnt vmcnt(0) lgkmcnt(0)
	v_pk_add_f32 v[44:45], v[44:45], 1.0 op_sel_hi:[1,0]
	v_pk_add_f32 v[52:53], v[52:53], v[60:61]
	v_pk_add_f32 v[42:43], v[42:43], 1.0 op_sel_hi:[1,0]
	v_add_f32_e32 v51, v52, v53
	s_waitcnt lgkmcnt(0)
	s_nop 1
	v_add_f32_dpp v51, v51, v51 quad_perm:[1,0,3,2] row_mask:0xf bank_mask:0xf
	ds_bpermute_b32 v52, v131, v51
	s_waitcnt lgkmcnt(0)
	v_add_f32_e32 v51, v51, v52
	v_pk_mul_f32 v[40:41], v[40:41], v[50:51] op_sel_hi:[1,0]
	v_pk_mul_f32 v[38:39], v[38:39], v[50:51] op_sel_hi:[1,0]
	v_pk_mul_f32 v[40:41], v[40:41], v[12:13]
	v_pk_mul_f32 v[38:39], v[38:39], v[10:11]
	v_pk_fma_f32 v[40:41], v[40:41], v[44:45], v[48:49]
	v_pk_fma_f32 v[38:39], v[38:39], v[42:43], v[46:47]
	v_cvt_pk_bf16_f32 v38, v38, v39
	v_cvt_pk_bf16_f32 v39, v40, v41
	global_store_dwordx2 v[104:105], v[38:39], off offset:1024
	global_load_dwordx4 v[38:41], v[122:123], off
	s_nop 0
	global_load_dwordx4 v[42:45], v[108:109], off offset:3072
	v_pk_mul_f32 v[36:37], v[36:37], v[50:51] op_sel_hi:[1,0]
	v_pk_mul_f32 v[34:35], v[34:35], v[50:51] op_sel_hi:[1,0]
	v_pk_mul_f32 v[36:37], v[36:37], v[16:17]
	v_pk_mul_f32 v[34:35], v[34:35], v[14:15]
	ds_bpermute_b32 v46, v133, v51
	s_waitcnt lgkmcnt(0)
	v_add_f32_e32 v46, v51, v46
	ds_bpermute_b32 v47, v152, v46
	s_waitcnt lgkmcnt(0)
	v_add_f32_e32 v46, v46, v47
	s_waitcnt lgkmcnt(0)
	v_mov_b32_e32 v47, v46
	s_nop 1
	v_permlane16_swap_b32_e32 v46, v47
	v_add_f32_e32 v46, v46, v47
	s_waitcnt lgkmcnt(0)
	v_mov_b32_e32 v47, v46
	s_nop 1
	v_permlane32_swap_b32_e32 v46, v47
	v_add_f32_e32 v46, v46, v47
	v_fmamk_f32 v46, v46, 0x3a800000, v155
	v_mul_f32_e32 v47, 0x4f800000, v46
	v_cmp_gt_f32_e32 vcc, s4, v46
	s_waitcnt vmcnt(0)
	v_pk_add_f32 v[40:41], v[40:41], 1.0 op_sel_hi:[1,0]
	v_pk_add_f32 v[38:39], v[38:39], 1.0 op_sel_hi:[1,0]
	v_pk_fma_f32 v[36:37], v[36:37], v[40:41], v[44:45]
	v_pk_fma_f32 v[34:35], v[34:35], v[38:39], v[42:43]
	v_cvt_pk_bf16_f32 v34, v34, v35
	v_cvt_pk_bf16_f32 v35, v36, v37
	global_store_dwordx2 v[104:105], v[34:35], off offset:1536
	global_load_dwordx4 v[34:37], v[118:119], off
	s_nop 0
	global_load_dwordx4 v[38:41], v[106:107], off
	v_cndmask_b32_e32 v42, v46, v47, vcc
	v_sqrt_f32_e32 v43, v42
	s_waitcnt vmcnt(0) lgkmcnt(0)
	v_pk_add_f32 v[36:37], v[36:37], 1.0 op_sel_hi:[1,0]
	v_add_u32_e32 v44, -1, v43
	v_add_u32_e32 v45, 1, v43
	v_fma_f32 v46, -v44, v43, v42
	v_fma_f32 v47, -v45, v43, v42
	v_cmp_ge_f32_e64 s[6:7], 0, v46
	v_pk_add_f32 v[34:35], v[34:35], 1.0 op_sel_hi:[1,0]
	s_nop 0
	v_cndmask_b32_e64 v43, v43, v44, s[6:7]
	v_cmp_lt_f32_e64 s[6:7], 0, v47
	s_nop 1
	v_cndmask_b32_e64 v43, v43, v45, s[6:7]
	v_mul_f32_e32 v44, 0x37800000, v43
	v_cndmask_b32_e32 v43, v43, v44, vcc
	v_cmp_class_f32_e32 vcc, v42, v156
	s_nop 1
	v_cndmask_b32_e32 v42, v43, v42, vcc
	v_div_scale_f32 v43, s[6:7], v42, v42, 1.0
	v_rcp_f32_e32 v45, v43
	v_div_scale_f32 v44, vcc, 1.0, v42, 1.0
	v_fma_f32 v46, -v43, v45, 1.0
	v_fmac_f32_e32 v45, v46, v45
	v_mul_f32_e32 v46, v44, v45
	v_fma_f32 v47, -v43, v46, v44
	v_fmac_f32_e32 v46, v47, v45
	v_fma_f32 v43, -v43, v46, v44
	v_div_fmas_f32 v43, v43, v45, v46
	v_div_fixup_f32 v42, v43, v42, 1.0
	v_pk_mul_f32 v[32:33], v[32:33], v[42:43] op_sel_hi:[1,0]
	v_pk_mul_f32 v[30:31], v[30:31], v[42:43] op_sel_hi:[1,0]
	v_pk_mul_f32 v[32:33], v[32:33], v[4:5]
	v_pk_mul_f32 v[30:31], v[30:31], v[2:3]
	v_pk_fma_f32 v[32:33], v[32:33], v[36:37], v[40:41]
	v_pk_fma_f32 v[30:31], v[30:31], v[34:35], v[38:39]
	v_cvt_pk_bf16_f32 v30, v30, v31
	v_cvt_pk_bf16_f32 v31, v32, v33
	global_store_dwordx2 v[104:105], v[30:31], off offset:2048
	global_load_dwordx4 v[30:33], v[114:115], off
	s_nop 0
	global_load_dwordx4 v[34:37], v[106:107], off offset:1024
	v_pk_mul_f32 v[28:29], v[28:29], v[42:43] op_sel_hi:[1,0]
	v_pk_mul_f32 v[26:27], v[26:27], v[42:43] op_sel_hi:[1,0]
	v_pk_mul_f32 v[28:29], v[28:29], v[8:9]
	v_pk_mul_f32 v[26:27], v[26:27], v[6:7]
	v_lshl_add_u64 v[38:39], s[20:21], 0, v[98:99]
	v_pk_mul_f32 v[24:25], v[24:25], v[42:43] op_sel_hi:[1,0]
	v_pk_mul_f32 v[22:23], v[22:23], v[42:43] op_sel_hi:[1,0]
	v_pk_mul_f32 v[24:25], v[24:25], v[12:13]
	v_pk_mul_f32 v[22:23], v[22:23], v[10:11]
	v_pk_mul_f32 v[20:21], v[20:21], v[42:43] op_sel_hi:[1,0]
	v_pk_mul_f32 v[18:19], v[18:19], v[42:43] op_sel_hi:[1,0]
	v_pk_mul_f32 v[20:21], v[20:21], v[16:17]
	v_pk_mul_f32 v[18:19], v[18:19], v[14:15]
	s_waitcnt vmcnt(0) lgkmcnt(0)
	v_pk_add_f32 v[32:33], v[32:33], 1.0 op_sel_hi:[1,0]
	v_pk_add_f32 v[30:31], v[30:31], 1.0 op_sel_hi:[1,0]
	v_pk_fma_f32 v[28:29], v[28:29], v[32:33], v[36:37]
	v_pk_fma_f32 v[26:27], v[26:27], v[30:31], v[34:35]
	v_cvt_pk_bf16_f32 v26, v26, v27
	v_cvt_pk_bf16_f32 v27, v28, v29
	global_store_dwordx2 v[104:105], v[26:27], off offset:2560
	global_load_dwordx4 v[26:29], v[38:39], off
	s_nop 0
	global_load_dwordx4 v[30:33], v[106:107], off offset:2048
	v_lshl_add_u64 v[34:35], s[20:21], 0, v[100:101]
	s_waitcnt vmcnt(0) lgkmcnt(0)
	v_pk_add_f32 v[28:29], v[28:29], 1.0 op_sel_hi:[1,0]
	v_pk_add_f32 v[26:27], v[26:27], 1.0 op_sel_hi:[1,0]
	v_pk_fma_f32 v[24:25], v[24:25], v[28:29], v[32:33]
	v_pk_fma_f32 v[22:23], v[22:23], v[26:27], v[30:31]
	v_cvt_pk_bf16_f32 v22, v22, v23
	v_cvt_pk_bf16_f32 v23, v24, v25
	global_store_dwordx2 v[104:105], v[22:23], off offset:3072
	global_load_dwordx4 v[22:25], v[34:35], off
	s_nop 0
	global_load_dwordx4 v[26:29], v[106:107], off offset:3072
	s_waitcnt vmcnt(0) lgkmcnt(0)
	v_pk_add_f32 v[24:25], v[24:25], 1.0 op_sel_hi:[1,0]
	v_pk_add_f32 v[22:23], v[22:23], 1.0 op_sel_hi:[1,0]
	v_pk_fma_f32 v[20:21], v[20:21], v[24:25], v[28:29]
	v_pk_fma_f32 v[18:19], v[18:19], v[22:23], v[26:27]
	v_cvt_pk_bf16_f32 v18, v18, v19
	v_cvt_pk_bf16_f32 v19, v20, v21
	global_store_dwordx2 v[104:105], v[18:19], off offset:3584
	s_cbranch_scc1 .LBB0_1004

.LBB0_1644:
	s_andn2_saveexec_b64 s[24:25], s[16:17]
	s_cbranch_execz .LBB0_1648
	v_mov_b32_e32 v41, s22
	s_mov_b32 s21, s19
	v_mov_b32_e32 v46, s23
	v_add_co_u32_e32 v54, vcc, 0x2000, v41
	v_lshl_add_u64 v[42:43], v[10:11], 2, s[22:23]
	v_lshl_add_u64 v[44:45], v[12:13], 2, s[22:23]
	v_addc_co_u32_e32 v55, vcc, 0, v46, vcc
	global_load_dword v41, v[42:43], off
	global_load_dword v66, v[44:45], off
	s_nop 0
	global_load_dwordx4 v[42:45], v[54:55], off offset:1120
	global_load_dwordx4 v[46:49], v[54:55], off offset:1136
	global_load_dwordx4 v[50:53], v[54:55], off offset:1152
	s_nop 0
	global_load_dwordx4 v[54:57], v[54:55], off offset:1168
	v_xor_b32_e32 v80, 32, v1
	s_waitcnt lgkmcnt(0)
	v_lshl_add_u64 v[58:59], v[232:233], 0, s[20:21]
	v_lshl_add_u64 v[60:61], v[8:9], 2, v[250:251]
	v_lshl_add_u64 v[58:59], v[130:131], 2, v[58:59]
	global_load_dword v67, v[60:61], off
	global_load_dword v68, v[58:59], off
	global_load_dword v69, v[58:59], off offset:1024
	global_load_dword v70, v[58:59], off offset:2048
	global_load_dword v71, v[58:59], off offset:3072
	v_add_co_u32_e64 v62, s[16:17], s30, v58
	v_add_co_u32_e32 v60, vcc, s31, v58
	s_nop 0
	v_addc_co_u32_e64 v63, s[16:17], 0, v59, s[16:17]
	v_add_co_u32_e64 v64, s[16:17], s29, v58
	v_addc_co_u32_e32 v61, vcc, 0, v59, vcc
	s_nop 0
	v_addc_co_u32_e64 v65, s[16:17], 0, v59, s[16:17]
	global_load_dword v58, v[62:63], off offset:-4096
	global_load_dword v59, v[60:61], off offset:1024
	global_load_dword v72, v[60:61], off offset:2048
	s_nop 0
	global_load_dword v60, v[60:61], off offset:3072
	s_nop 0
	global_load_dword v61, v[62:63], off
	global_load_dword v73, v[62:63], off offset:1024
	global_load_dword v74, v[62:63], off offset:2048
	s_nop 0
	global_load_dword v62, v[62:63], off offset:3072
	s_nop 0
	global_load_dword v63, v[64:65], off
	global_load_dword v75, v[64:65], off offset:1024
	global_load_dword v76, v[64:65], off offset:2048
	s_nop 0
	global_load_dword v64, v[64:65], off offset:3072
	global_load_dwordx4 v[234:237], v[234:235], off
	global_load_dwordx4 v[238:241], v[238:239], off
	global_load_dwordx4 v[242:245], v[242:243], off
	global_load_dwordx4 v[246:249], v[246:247], off
	v_cmp_lt_i32_e32 vcc, v36, v35
	s_waitcnt vmcnt(4)
	v_mul_f32_e32 v77, 0x3e000000, v41
	v_mul_f32_e32 v41, v77, v66
	v_cndmask_b32_e32 v65, v1, v36, vcc
	v_lshlrev_b32_e32 v65, 2, v65
	ds_bpermute_b32 v41, v65, v41
	v_cmp_lt_i32_e32 vcc, v37, v35
	s_waitcnt lgkmcnt(0)
	v_fmac_f32_e32 v41, v77, v66
	v_cndmask_b32_e32 v65, v1, v37, vcc
	v_lshlrev_b32_e32 v65, 2, v65
	ds_bpermute_b32 v65, v65, v41
	v_cmp_lt_i32_e32 vcc, v38, v35
	s_waitcnt lgkmcnt(0)
	v_add_f32_e32 v41, v41, v65
	v_cndmask_b32_e32 v78, v1, v38, vcc
	v_cmp_lt_i32_e32 vcc, v39, v35
	v_lshlrev_b32_e32 v78, 2, v78
	ds_bpermute_b32 v65, v78, v41
	v_cndmask_b32_e32 v79, v1, v39, vcc
	v_cmp_lt_i32_e32 vcc, v40, v35
	v_lshlrev_b32_e32 v79, 2, v79
	s_waitcnt lgkmcnt(0)
	v_add_f32_e32 v41, v41, v65
	v_cndmask_b32_e32 v78, v1, v40, vcc
	v_cmp_lt_i32_e32 vcc, v80, v35
	ds_bpermute_b32 v65, v79, v41
	v_lshlrev_b32_e32 v78, 2, v78
	s_waitcnt lgkmcnt(0)
	v_add_f32_e32 v41, v41, v65
	v_fmac_f32_e32 v67, v42, v68
	v_fmac_f32_e32 v67, v43, v69
	v_fmac_f32_e32 v67, v44, v70
	v_fmac_f32_e32 v67, v45, v71
	v_cndmask_b32_e32 v43, v1, v80, vcc
	v_fmac_f32_e32 v67, v46, v58
	v_fmac_f32_e32 v67, v47, v59
	v_fmac_f32_e32 v67, v48, v72
	v_fmac_f32_e32 v67, v49, v60
	v_fmac_f32_e32 v67, v50, v61
	v_fmac_f32_e32 v67, v51, v73
	v_fmac_f32_e32 v67, v52, v74
	v_fmac_f32_e32 v67, v53, v62
	v_fmac_f32_e32 v67, v54, v63
	v_fmac_f32_e32 v67, v55, v75
	v_fmac_f32_e32 v67, v56, v76
	v_fmac_f32_e32 v67, v57, v64
	v_mul_f32_e64 v42, |v67|, s33
	v_exp_f32_e32 v42, v42
	v_min_f32_e32 v45, 0, v67
	v_lshlrev_b32_e32 v43, 2, v43
	v_add_f32_e32 v42, 1.0, v42
	v_cmp_gt_f32_e32 vcc, s34, v42
	s_nop 1
	v_cndmask_b32_e64 v44, 0, 32, vcc
	v_ldexp_f32 v42, v42, v44
	v_log_f32_e32 v42, v42
	v_cndmask_b32_e32 v46, 0, v34, vcc
	v_mul_f32_e32 v47, 0x3f317217, v42
	v_fma_f32 v47, v42, s35, -v47
	v_fmac_f32_e32 v47, 0x3377d1cf, v42
	v_fmac_f32_e32 v47, 0x3f317217, v42
	v_cmp_lt_f32_e64 vcc, |v42|, s36
	s_waitcnt lgkmcnt(0)
	v_mov_b32_e32 v44, v41
	s_nop 1
	v_permlane16_swap_b32_e32 v41, v44
	v_add_f32_e32 v41, v41, v44
	v_cndmask_b32_e32 v42, v42, v47, vcc
	v_sub_f32_e32 v42, v42, v46
	v_sub_f32_e32 v42, v45, v42
	v_mul_f32_e32 v42, 0x3d800000, v42
	v_mul_f32_e32 v42, 0x3fb8aa3b, v42
	v_exp_f32_e32 v45, v42
	ds_bpermute_b32 v42, v43, v41
	v_mul_f32_e32 v43, v77, v45
	ds_write2st64_b32 v6, v43, v66 offset0:128 offset1:129
	ds_write_b32 v6, v45 offset:33280
	s_and_saveexec_b64 s[16:17], s[12:13]
	s_cbranch_execz .LBB0_1647
	s_waitcnt lgkmcnt(2)
	v_add_f32_e32 v41, v41, v42
	v_mov_b32_e32 v42, s96
	ds_write_b32 v42, v41 offset:34048

.LBB0_1650:
	v_mov_b32_e32 v70, s24
	v_add_u32_e32 v72, s21, v6
	ds_read2st64_b32 v[42:43], v72 offset1:2
	ds_read2st64_b32 v[44:45], v72 offset0:4 offset1:6
	ds_read2st64_b32 v[46:47], v72 offset0:8 offset1:10
	ds_read2_b32 v[48:49], v70 offset1:1
	ds_read2_b32 v[50:51], v70 offset0:2 offset1:3
	ds_read2_b32 v[52:53], v70 offset0:4 offset1:5
	ds_read2_b32 v[54:55], v70 offset0:6 offset1:7
	ds_read2st64_b32 v[56:57], v72 offset0:12 offset1:14
	ds_read2st64_b32 v[58:59], v72 offset0:16 offset1:18
	ds_read2st64_b32 v[60:61], v72 offset0:20 offset1:22
	ds_read2st64_b32 v[62:63], v72 offset0:24 offset1:26
	ds_read2_b32 v[64:65], v70 offset0:8 offset1:9
	ds_read2_b32 v[66:67], v70 offset0:10 offset1:11
	ds_read2_b32 v[68:69], v70 offset0:12 offset1:13
	ds_read2_b32 v[70:71], v70 offset0:14 offset1:15
	ds_read2st64_b32 v[72:73], v72 offset0:28 offset1:30
	s_waitcnt lgkmcnt(0)
	v_fmac_f32_e32 v41, v48, v42
	v_fmac_f32_e32 v41, v49, v43
	v_fmac_f32_e32 v41, v50, v44
	v_fmac_f32_e32 v41, v51, v45
	v_fmac_f32_e32 v41, v52, v46
	v_fmac_f32_e32 v41, v53, v47
	v_fmac_f32_e32 v41, v54, v56
	v_fmac_f32_e32 v41, v55, v57
	v_fmac_f32_e32 v41, v64, v58
	v_fmac_f32_e32 v41, v65, v59
	v_fmac_f32_e32 v41, v66, v60
	v_fmac_f32_e32 v41, v67, v61
	v_fmac_f32_e32 v41, v68, v62
	v_fmac_f32_e32 v41, v69, v63
	s_add_i32 s24, s24, 64
	s_addk_i32 s21, 0x2000
	v_fmac_f32_e32 v41, v70, v72
	s_cmpk_eq_u32 s21, 0x8000
	v_fmac_f32_e32 v41, v71, v73
	s_cbranch_scc0 .LBB0_1650
	v_mov_b32_e32 v42, s96
	ds_read_b32 v43, v6 offset:33536
	ds_read_b32 v42, v42 offset:34048
	v_cmp_lt_i32_e32 vcc, v36, v35
	s_waitcnt lgkmcnt(0)
	v_fmac_f32_e32 v41, v42, v43
	v_cndmask_b32_e32 v44, v1, v36, vcc
	v_lshlrev_b32_e32 v44, 2, v44
	v_mul_f32_e32 v42, v41, v41
	ds_bpermute_b32 v42, v44, v42
	v_cmp_lt_i32_e32 vcc, v37, v35
	s_waitcnt lgkmcnt(0)
	v_fmac_f32_e32 v42, v41, v41
	v_cndmask_b32_e32 v43, v1, v37, vcc
	v_lshlrev_b32_e32 v43, 2, v43
	ds_bpermute_b32 v43, v43, v42
	v_cmp_lt_i32_e32 vcc, v38, v35
	s_waitcnt lgkmcnt(0)
	v_add_f32_e32 v42, v42, v43
	v_cndmask_b32_e32 v44, v1, v38, vcc
	v_lshlrev_b32_e32 v44, 2, v44
	ds_bpermute_b32 v43, v44, v42
	v_cmp_lt_i32_e32 vcc, v39, v35
	s_waitcnt lgkmcnt(0)
	v_add_f32_e32 v42, v42, v43
	v_cndmask_b32_e32 v44, v1, v39, vcc
	v_lshlrev_b32_e32 v44, 2, v44
	ds_bpermute_b32 v43, v44, v42
	v_cmp_lt_i32_e32 vcc, v40, v35
	s_waitcnt lgkmcnt(0)
	v_add_f32_e32 v42, v42, v43
	v_cndmask_b32_e32 v44, v1, v40, vcc
	v_lshlrev_b32_e32 v44, 2, v44
	v_xor_b32_e32 v44, 32, v1
	v_cmp_lt_i32_e32 vcc, v44, v35
	s_waitcnt lgkmcnt(0)
	v_mov_b32_e32 v43, v42
	s_nop 1
	v_permlane16_swap_b32_e32 v42, v43
	v_add_f32_e32 v42, v42, v43
	v_cndmask_b32_e32 v44, v1, v44, vcc
	v_lshlrev_b32_e32 v43, 2, v44
	ds_bpermute_b32 v43, v43, v42
	s_and_saveexec_b64 s[24:25], s[14:15]
	s_cbranch_execz .LBB0_1653
	s_waitcnt lgkmcnt(0)
	v_add_f32_e32 v42, v42, v43
	v_mov_b32_e32 v43, s27
	ds_write_b32 v43, v42 offset:34052

.LBB0_2291:
	s_cmp_lt_i32 s5, 4
	s_cselect_b64 s[20:21], -1, 0
	s_cmp_gt_i32 s5, 3
	s_waitcnt lgkmcnt(0)
	s_barrier
	s_cbranch_scc1 .LBB0_2293
	s_lshl_b32 s6, s5, 9
	s_add_i32 s6, s36, s6
	v_lshl_add_u32 v4, v1, 2, s6
	ds_read2st64_b32 v[2:3], v4 offset0:4 offset1:5
	v_and_b32_e32 v5, 64, v166
	v_xor_b32_e32 v6, 1, v166
	v_add_u32_e32 v5, 64, v5
	v_cmp_lt_i32_e32 vcc, v6, v5
	s_waitcnt lgkmcnt(0)
	v_max_f32_e32 v7, v3, v3
	v_max_f32_e32 v8, v2, v2
	v_cndmask_b32_e32 v6, v166, v6, vcc
	v_max_f32_e32 v7, v8, v7
	v_lshlrev_b32_e32 v6, 2, v6
	ds_bpermute_b32 v8, v6, v7
	v_xor_b32_e32 v9, 2, v166
	v_cmp_lt_i32_e32 vcc, v9, v5
	v_xor_b32_e32 v10, 4, v166
	v_xor_b32_e32 v11, 8, v166
	s_waitcnt lgkmcnt(0)
	v_max_f32_e32 v8, v8, v8
	v_max_f32_e32 v7, v7, v8
	v_cndmask_b32_e32 v8, v166, v9, vcc
	v_lshlrev_b32_e32 v8, 2, v8
	ds_bpermute_b32 v9, v8, v7
	v_cmp_lt_i32_e32 vcc, v10, v5
	v_xor_b32_e32 v12, 16, v166
	v_xor_b32_e32 v13, 32, v166
	s_waitcnt lgkmcnt(0)
	v_max_f32_e32 v9, v9, v9
	v_max_f32_e32 v7, v7, v9
	v_cndmask_b32_e32 v9, v166, v10, vcc
	v_lshlrev_b32_e32 v9, 2, v9
	ds_bpermute_b32 v10, v9, v7
	v_cmp_lt_i32_e32 vcc, v11, v5
	s_waitcnt lgkmcnt(0)
	v_max_f32_e32 v10, v10, v10
	v_max_f32_e32 v7, v7, v10
	v_cndmask_b32_e32 v10, v166, v11, vcc
	v_lshlrev_b32_e32 v10, 2, v10
	ds_bpermute_b32 v11, v10, v7
	v_cmp_lt_i32_e32 vcc, v12, v5
	s_waitcnt lgkmcnt(0)
	v_max_f32_e32 v11, v11, v11
	v_max_f32_e32 v7, v7, v11
	v_cndmask_b32_e32 v11, v166, v12, vcc
	v_lshlrev_b32_e32 v11, 2, v11
	ds_bpermute_b32 v12, v11, v7
	v_cmp_lt_i32_e32 vcc, v13, v5
	s_waitcnt lgkmcnt(0)
	v_max_f32_e32 v12, v12, v12
	v_cndmask_b32_e32 v5, v166, v13, vcc
	v_max_f32_e32 v7, v7, v12
	v_lshlrev_b32_e32 v5, 2, v5
	ds_bpermute_b32 v12, v5, v7
	s_waitcnt lgkmcnt(0)
	v_max_f32_e32 v12, v12, v12
	v_max_f32_e32 v7, v7, v12
	v_sub_f32_e32 v2, v2, v7
	v_sub_f32_e32 v3, v3, v7
	v_mul_f32_e32 v2, 0x3fb8aa3b, v2
	v_mul_f32_e32 v3, 0x3fb8aa3b, v3
	v_exp_f32_e32 v2, v2
	v_exp_f32_e32 v3, v3
	s_nop 0
	v_add_f32_e32 v7, v2, v3
	ds_bpermute_b32 v6, v6, v7
	s_waitcnt lgkmcnt(0)
	v_add_f32_e32 v6, v7, v6
	s_waitcnt lgkmcnt(0)
	s_nop 1
	v_add_f32_dpp v6, v6, v6 quad_perm:[2,3,0,1] row_mask:0xf bank_mask:0xf
	ds_bpermute_b32 v7, v9, v6
	s_waitcnt lgkmcnt(0)
	v_add_f32_e32 v6, v6, v7
	ds_bpermute_b32 v7, v10, v6
	s_waitcnt lgkmcnt(0)
	v_add_f32_e32 v6, v6, v7
	s_waitcnt lgkmcnt(0)
	v_mov_b32_e32 v7, v6
	s_nop 1
	v_permlane16_swap_b32_e32 v6, v7
	v_add_f32_e32 v6, v6, v7
	ds_bpermute_b32 v5, v5, v6
	s_waitcnt lgkmcnt(0)
	v_add_f32_e32 v5, v6, v5
	v_max_f32_e32 v5, 0xda24260, v5
	v_div_scale_f32 v6, s[6:7], v5, v5, 1.0
	v_rcp_f32_e32 v7, v6
	v_div_scale_f32 v8, vcc, 1.0, v5, 1.0
	v_fma_f32 v9, -v6, v7, 1.0
	v_fmac_f32_e32 v7, v9, v7
	v_mul_f32_e32 v9, v8, v7
	v_fma_f32 v10, -v6, v9, v8
	v_fmac_f32_e32 v9, v10, v7
	v_fma_f32 v6, -v6, v9, v8
	v_div_fmas_f32 v6, v6, v7, v9
	v_div_fixup_f32 v5, v6, v5, 1.0
	v_mul_f32_e32 v2, v2, v5
	v_mul_f32_e32 v3, v3, v5
	ds_write2st64_b32 v4, v2, v3 offset0:4 offset1:5

.LBB0_2752:
	s_lshr_b32 s10, s52, 2
	s_cmp_lt_u32 s52, 4
	s_cselect_b64 vcc, -1, 0
	s_cmp_eq_u32 s10, 2
	s_cselect_b32 s12, s31, s29
	s_cselect_b32 s13, s48, s30
	s_cmp_eq_u32 s10, 1
	s_cselect_b64 s[10:11], -1, 0
	v_cndmask_b32_e64 v66, v106, v108, s[10:11]
	v_cndmask_b32_e64 v67, v107, v109, s[10:11]
	s_and_b64 s[10:11], s[10:11], exec
	s_cselect_b32 s14, s27, s28
	s_and_b64 s[10:11], vcc, exec
	s_cselect_b32 s14, s26, s14
	s_sub_i32 s10, s49, 32
	s_and_b32 s15, s10, 32
	s_or_b32 s10, s15, s14
	v_add_u32_e32 v80, s10, v100
	v_add_u32_e32 v144, 16, v80
	v_cndmask_b32_e32 v78, v66, v104, vcc
	v_subrev_u32_e32 v66, s14, v144
	v_cndmask_b32_e32 v79, v67, v105, vcc
	v_ashrrev_i32_e32 v67, 31, v66
	v_lshlrev_b64 v[66:67], 10, v[66:67]
	v_lshl_add_u64 v[66:67], v[78:79], 0, v[66:67]
	v_mov_b32_e32 v82, s13
	v_cmp_gt_i32_e64 s[10:11], s44, v144
	v_mov_b32_e32 v83, s12
	v_add_u32_e32 v147, 20, v80
	v_cndmask_b32_e64 v67, v82, v67, s[10:11]
	v_cndmask_b32_e64 v66, v83, v66, s[10:11]
	v_lshl_add_u64 v[66:67], v[66:67], 0, v[98:99]
	v_add_u32_e32 v146, 24, v80
	v_add_u32_e32 v145, 28, v80
	global_load_dwordx4 v[94:97], v[66:67], off
	global_load_dwordx4 v[74:77], v[66:67], off offset:512
	v_subrev_u32_e32 v66, s14, v147
	v_subrev_u32_e32 v70, s14, v146
	v_subrev_u32_e32 v80, s14, v145
	v_ashrrev_i32_e32 v67, 31, v66
	v_ashrrev_i32_e32 v71, 31, v70
	v_ashrrev_i32_e32 v81, 31, v80
	v_lshlrev_b64 v[66:67], 10, v[66:67]
	v_lshlrev_b64 v[70:71], 10, v[70:71]
	v_lshlrev_b64 v[80:81], 10, v[80:81]
	v_lshl_add_u64 v[66:67], v[78:79], 0, v[66:67]
	v_lshl_add_u64 v[70:71], v[78:79], 0, v[70:71]
	v_lshl_add_u64 v[78:79], v[78:79], 0, v[80:81]
	s_waitcnt vmcnt(0) lgkmcnt(0)
	v_mul_f32_e32 v80, v11, v3
	v_fmac_f32_e32 v80, v10, v2
	v_fmac_f32_e32 v80, v12, v4
	v_fmac_f32_e32 v80, v13, v5
	v_cmp_gt_i32_e64 s[10:11], s44, v147
	v_mul_f32_e32 v148, v11, v27
	v_fmac_f32_e32 v148, v10, v26
	v_cndmask_b32_e64 v67, v82, v67, s[10:11]
	s_waitcnt lgkmcnt(0)
	v_add_f32_dpp v80, v80, v80 quad_perm:[1,0,3,2] row_mask:0xf bank_mask:0xf
	v_cndmask_b32_e64 v66, v83, v66, s[10:11]
	v_cmp_gt_i32_e64 s[10:11], s44, v146
	v_mul_f32_e32 v125, v23, v3
	v_cndmask_b32_e64 v71, v82, v71, s[10:11]
	v_cndmask_b32_e64 v70, v83, v70, s[10:11]
	v_cmp_gt_i32_e64 s[10:11], s44, v145
	s_waitcnt lgkmcnt(0)
	v_add_f32_dpp v80, v80, v80 quad_perm:[2,3,0,1] row_mask:0xf bank_mask:0xf
	v_cndmask_b32_e64 v79, v82, v79, s[10:11]
	v_mul_f32_e32 v82, v15, v3
	v_fmac_f32_e32 v82, v14, v2
	v_fmac_f32_e32 v82, v16, v4
	v_fmac_f32_e32 v82, v17, v5
	v_cndmask_b32_e64 v78, v83, v78, s[10:11]
	s_and_b32 s10, s52, 12
	s_waitcnt lgkmcnt(0)
	v_add_f32_dpp v118, v80, v80 row_half_mirror row_mask:0xf bank_mask:0xf
	s_cmp_eq_u32 s10, 4
	s_waitcnt lgkmcnt(0)
	v_add_f32_dpp v120, v82, v82 quad_perm:[1,0,3,2] row_mask:0xf bank_mask:0xf
	s_cselect_b32 s12, s27, s28
	s_and_b64 s[10:11], vcc, exec
	s_cselect_b32 s10, s26, s12
	s_or_b32 s10, s10, s15
	v_add_u32_e32 v156, s10, v100
	v_sub_u32_e32 v84, 0x800, v156
	s_waitcnt lgkmcnt(0)
	v_add_f32_dpp v118, v118, v118 row_mirror row_mask:0xf bank_mask:0xf
	s_waitcnt lgkmcnt(0)
	v_add_f32_dpp v119, v120, v120 quad_perm:[2,3,0,1] row_mask:0xf bank_mask:0xf
	v_cvt_f32_u32_e32 v124, v84
	v_cmp_gt_i32_e32 vcc, s45, v156
	v_fmac_f32_e32 v125, v22, v2
	v_fma_f32 v118, -v127, v124, v118
	v_cndmask_b32_e32 v169, v135, v118, vcc
	s_waitcnt lgkmcnt(0)
	v_add_f32_dpp v120, v119, v119 row_half_mirror row_mask:0xf bank_mask:0xf
	v_pk_mul_f32 v[118:119], v[12:13], v[28:29]
	v_fmac_f32_e32 v125, v24, v4
	v_add_f32_e32 v118, v118, v148
	v_add_f32_e32 v118, v119, v118
	v_fmac_f32_e32 v125, v25, v5
	v_mul_f32_e32 v150, v15, v27
	v_fmac_f32_e32 v150, v14, v26
	s_waitcnt lgkmcnt(0)
	v_add_f32_dpp v118, v118, v118 quad_perm:[1,0,3,2] row_mask:0xf bank_mask:0xf
	v_fmac_f32_e32 v150, v16, v28
	s_waitcnt lgkmcnt(0)
	v_add_f32_dpp v125, v125, v125 quad_perm:[1,0,3,2] row_mask:0xf bank_mask:0xf
	v_fmac_f32_e32 v150, v17, v29
	s_waitcnt lgkmcnt(0)
	v_add_f32_dpp v118, v118, v118 quad_perm:[2,3,0,1] row_mask:0xf bank_mask:0xf
	s_movk_i32 s10, 0x7fd
	s_waitcnt lgkmcnt(0)
	s_nop 1
	v_add_f32_dpp v148, v125, v125 quad_perm:[2,3,0,1] row_mask:0xf bank_mask:0xf
	v_sub_u32_e32 v125, 0x7fc, v156
	s_waitcnt lgkmcnt(0)
	v_add_f32_dpp v118, v118, v118 row_half_mirror row_mask:0xf bank_mask:0xf
	v_cvt_f32_u32_e32 v125, v125
	v_cmp_gt_i32_e64 s[10:11], s10, v156
	v_mul_f32_e32 v154, v11, v35
	v_fmac_f32_e32 v154, v10, v34
	s_waitcnt lgkmcnt(0)
	v_add_f32_dpp v118, v118, v118 row_mirror row_mask:0xf bank_mask:0xf
	v_add_f32_dpp v119, v150, v150 quad_perm:[1,0,3,2] row_mask:0xf bank_mask:0xf
	v_mul_f32_e32 v151, v19, v27
	v_fma_f32 v118, -v127, v125, v118
	v_fmac_f32_e32 v151, v18, v26
	v_fmac_f32_e32 v151, v20, v28
	v_cndmask_b32_e64 v172, v135, v118, s[10:11]
	s_waitcnt lgkmcnt(0)
	v_add_f32_dpp v118, v119, v119 quad_perm:[2,3,0,1] row_mask:0xf bank_mask:0xf
	v_fmac_f32_e32 v151, v21, v29
	v_lshl_add_u64 v[66:67], v[66:67], 0, v[98:99]
	v_lshl_add_u64 v[70:71], v[70:71], 0, v[98:99]
	v_lshl_add_u64 v[78:79], v[78:79], 0, v[98:99]
	s_waitcnt lgkmcnt(0)
	v_add_f32_dpp v164, v118, v118 row_half_mirror row_mask:0xf bank_mask:0xf
	v_pk_mul_f32 v[118:119], v[12:13], v[36:37]
	s_waitcnt lgkmcnt(0)
	v_add_f32_dpp v150, v151, v151 quad_perm:[1,0,3,2] row_mask:0xf bank_mask:0xf
	v_mul_f32_e32 v152, v23, v27
	v_add_f32_e32 v118, v118, v154
	v_fmac_f32_e32 v152, v22, v26
	v_add_f32_e32 v118, v119, v118
	v_fmac_f32_e32 v152, v24, v28
	v_fmac_f32_e32 v152, v25, v29
	global_load_dwordx4 v[90:93], v[66:67], off
	s_nop 0
	global_load_dwordx4 v[66:69], v[66:67], off offset:512
	s_waitcnt lgkmcnt(0)
	v_add_f32_dpp v118, v118, v118 quad_perm:[1,0,3,2] row_mask:0xf bank_mask:0xf
	v_add_f32_dpp v152, v152, v152 quad_perm:[1,0,3,2] row_mask:0xf bank_mask:0xf
	global_load_dwordx4 v[86:89], v[70:71], off
	s_nop 0
	global_load_dwordx4 v[70:73], v[70:71], off offset:512
	s_nop 0
	global_load_dwordx4 v[82:85], v[78:79], off
	s_nop 0
	global_load_dwordx4 v[78:81], v[78:79], off offset:512
	v_mul_f32_e32 v154, v15, v35
	s_waitcnt lgkmcnt(0)
	v_add_f32_dpp v118, v118, v118 quad_perm:[2,3,0,1] row_mask:0xf bank_mask:0xf
	v_fmac_f32_e32 v154, v14, v34
	v_fmac_f32_e32 v154, v16, v36
	v_add_f32_dpp v150, v150, v150 quad_perm:[2,3,0,1] row_mask:0xf bank_mask:0xf
	v_add_f32_dpp v152, v152, v152 quad_perm:[2,3,0,1] row_mask:0xf bank_mask:0xf
	v_fmac_f32_e32 v154, v17, v37
	s_waitcnt lgkmcnt(0)
	v_add_f32_dpp v118, v118, v118 row_half_mirror row_mask:0xf bank_mask:0xf
	v_add_f32_dpp v158, v150, v150 row_half_mirror row_mask:0xf bank_mask:0xf
	v_add_f32_dpp v150, v152, v152 row_half_mirror row_mask:0xf bank_mask:0xf
	v_sub_u32_e32 v152, 0x7f8, v156
	v_add_f32_dpp v154, v154, v154 quad_perm:[1,0,3,2] row_mask:0xf bank_mask:0xf
	v_cvt_f32_u32_e32 v152, v152
	v_or_b32_e32 v153, 8, v156
	s_waitcnt lgkmcnt(0)
	v_add_f32_dpp v118, v118, v118 row_mirror row_mask:0xf bank_mask:0xf
	v_fma_f32 v118, -v127, v152, v118
	v_cmp_gt_i32_e64 s[12:13], s45, v153
	v_mul_f32_e32 v153, v19, v35
	v_fmac_f32_e32 v153, v18, v34
	v_cndmask_b32_e64 v173, v135, v118, s[12:13]
	v_add_f32_dpp v118, v154, v154 quad_perm:[2,3,0,1] row_mask:0xf bank_mask:0xf
	v_mul_f32_e32 v155, v23, v35
	v_fmac_f32_e32 v155, v22, v34
	v_fmac_f32_e32 v153, v20, v36
	v_fmac_f32_e32 v155, v24, v36
	v_fmac_f32_e32 v153, v21, v37
	v_fmac_f32_e32 v155, v25, v37
	s_movk_i32 s14, 0x7f5
	v_cmp_gt_i32_e64 s[14:15], s14, v156
	s_waitcnt lgkmcnt(0)
	v_add_f32_dpp v153, v153, v153 quad_perm:[1,0,3,2] row_mask:0xf bank_mask:0xf
	s_nop 1
	v_add_f32_dpp v160, v155, v155 quad_perm:[1,0,3,2] row_mask:0xf bank_mask:0xf
	v_pk_mul_f32 v[154:155], v[10:11], v[46:47]
	v_add_f32_dpp v167, v118, v118 row_half_mirror row_mask:0xf bank_mask:0xf
	v_pk_mul_f32 v[118:119], v[12:13], v[48:49]
	v_add_f32_e32 v154, v154, v155
	v_add_f32_e32 v118, v118, v154
	v_add_f32_e32 v118, v119, v118
	v_mul_f32_e32 v122, v19, v3
	s_waitcnt lgkmcnt(0)
	v_add_f32_dpp v153, v153, v153 quad_perm:[2,3,0,1] row_mask:0xf bank_mask:0xf
	v_add_f32_dpp v155, v160, v160 quad_perm:[2,3,0,1] row_mask:0xf bank_mask:0xf
	v_add_f32_dpp v118, v118, v118 quad_perm:[1,0,3,2] row_mask:0xf bank_mask:0xf
	v_fmac_f32_e32 v122, v18, v2
	s_waitcnt lgkmcnt(0)
	v_add_f32_dpp v160, v153, v153 row_half_mirror row_mask:0xf bank_mask:0xf
	v_add_f32_dpp v153, v155, v155 row_half_mirror row_mask:0xf bank_mask:0xf
	v_mul_f32_e32 v162, v15, v47
	v_add_f32_dpp v118, v118, v118 quad_perm:[2,3,0,1] row_mask:0xf bank_mask:0xf
	v_fmac_f32_e32 v162, v14, v46
	v_fmac_f32_e32 v162, v16, v48
	v_fmac_f32_e32 v162, v17, v49
	v_sub_u32_e32 v155, 0x7f4, v156
	s_waitcnt lgkmcnt(0)
	v_add_f32_dpp v118, v118, v118 row_half_mirror row_mask:0xf bank_mask:0xf
	v_cvt_f32_u32_e32 v155, v155
	v_add_f32_dpp v162, v162, v162 quad_perm:[1,0,3,2] row_mask:0xf bank_mask:0xf
	v_mul_f32_e32 v156, v19, v47
	s_waitcnt lgkmcnt(0)
	v_add_f32_dpp v118, v118, v118 row_mirror row_mask:0xf bank_mask:0xf
	v_fma_f32 v118, -v127, v155, v118
	v_cndmask_b32_e64 v174, v135, v118, s[14:15]
	v_add_f32_dpp v118, v162, v162 quad_perm:[2,3,0,1] row_mask:0xf bank_mask:0xf
	v_mul_f32_e32 v163, v23, v47
	v_fmac_f32_e32 v156, v18, v46
	v_fmac_f32_e32 v163, v22, v46
	v_fmac_f32_e32 v122, v20, v4
	v_fmac_f32_e32 v156, v20, v48
	v_fmac_f32_e32 v163, v24, v48
	v_fmac_f32_e32 v122, v21, v5
	v_fmac_f32_e32 v156, v21, v49
	v_fmac_f32_e32 v163, v25, v49
	v_max3_f32 v157, v169, s35, v172
	s_waitcnt lgkmcnt(0)
	v_add_f32_dpp v122, v122, v122 quad_perm:[1,0,3,2] row_mask:0xf bank_mask:0xf
	v_add_f32_dpp v170, v118, v118 row_half_mirror row_mask:0xf bank_mask:0xf
	v_add_f32_dpp v118, v156, v156 quad_perm:[1,0,3,2] row_mask:0xf bank_mask:0xf
	v_add_f32_dpp v156, v163, v163 quad_perm:[1,0,3,2] row_mask:0xf bank_mask:0xf
	v_max3_f32 v157, v157, v173, v174
	ds_bpermute_b32 v163, v142, v157
	s_waitcnt lgkmcnt(0)
	v_add_f32_dpp v122, v122, v122 quad_perm:[2,3,0,1] row_mask:0xf bank_mask:0xf
	v_add_f32_dpp v118, v118, v118 quad_perm:[2,3,0,1] row_mask:0xf bank_mask:0xf
	v_add_f32_dpp v156, v156, v156 quad_perm:[2,3,0,1] row_mask:0xf bank_mask:0xf
	v_max_f32_e32 v162, v163, v163
	v_max_f32_e32 v176, v157, v162
	ds_bpermute_b32 v177, v143, v176
	s_waitcnt lgkmcnt(0)
	v_add_f32_dpp v122, v122, v122 row_half_mirror row_mask:0xf bank_mask:0xf
	v_add_f32_dpp v148, v148, v148 row_half_mirror row_mask:0xf bank_mask:0xf
	v_add_f32_dpp v162, v118, v118 row_half_mirror row_mask:0xf bank_mask:0xf
	v_add_f32_dpp v156, v156, v156 row_half_mirror row_mask:0xf bank_mask:0xf
	ds_bpermute_b32 v121, v141, v120
	ds_bpermute_b32 v123, v141, v122
	ds_bpermute_b32 v149, v141, v148
	ds_bpermute_b32 v165, v141, v164
	ds_bpermute_b32 v159, v141, v158
	ds_bpermute_b32 v151, v141, v150
	ds_bpermute_b32 v168, v141, v167
	ds_bpermute_b32 v161, v141, v160
	ds_bpermute_b32 v154, v141, v153
	ds_bpermute_b32 v171, v141, v170
	ds_bpermute_b32 v163, v141, v162
	ds_bpermute_b32 v157, v141, v156
	v_max_f32_e32 v118, v177, v177
	v_max_f32_e32 v175, v176, v118
	v_cmp_neq_f32_e64 s[16:17], s35, v175
	v_mov_b64_e32 v[118:119], v[112:113]
	s_and_saveexec_b64 s[22:23], s[16:17]
	s_cbranch_execz .LBB0_2754
	v_max_f32_e32 v118, v175, v175
	v_max_f32_e32 v119, v113, v113
	v_max_f32_e32 v119, v119, v118
	v_sub_f32_e32 v118, v169, v119
	v_mul_f32_e32 v118, 0x3fb8aa3b, v118
	v_exp_f32_e32 v118, v118
	v_sub_f32_e32 v113, v113, v119
	v_mul_f32_e32 v113, 0x3fb8aa3b, v113
	v_add_f32_e32 v169, 0, v118
	v_pk_fma_f32 v[176:177], v[8:9], v[118:119], 0 op_sel_hi:[1,0,0]
	v_pk_fma_f32 v[178:179], v[6:7], v[118:119], 0 op_sel_hi:[1,0,0]
	v_sub_f32_e32 v118, v172, v119
	v_mul_f32_e32 v118, 0x3fb8aa3b, v118
	v_exp_f32_e32 v118, v118
	s_nop 0
	v_add_f32_e32 v169, v118, v169
	v_pk_fma_f32 v[176:177], v[32:33], v[118:119], v[176:177] op_sel_hi:[1,0,1]
	v_pk_fma_f32 v[178:179], v[30:31], v[118:119], v[178:179] op_sel_hi:[1,0,1]
	v_sub_f32_e32 v118, v173, v119
	v_mul_f32_e32 v118, 0x3fb8aa3b, v118
	v_exp_f32_e32 v118, v118
	s_nop 0
	v_add_f32_e32 v169, v118, v169
	v_pk_fma_f32 v[172:173], v[38:39], v[118:119], v[178:179] op_sel_hi:[1,0,1]
	v_pk_fma_f32 v[176:177], v[40:41], v[118:119], v[176:177] op_sel_hi:[1,0,1]
	v_sub_f32_e32 v118, v174, v119
	v_mul_f32_e32 v118, 0x3fb8aa3b, v118
	v_exp_f32_e32 v118, v118
	s_nop 0
	v_add_f32_e32 v169, v118, v169
	v_pk_fma_f32 v[174:175], v[56:57], v[118:119], v[176:177] op_sel_hi:[1,0,1]
	v_exp_f32_e32 v176, v113
	ds_bpermute_b32 v113, v142, v169
	v_pk_fma_f32 v[172:173], v[54:55], v[118:119], v[172:173] op_sel_hi:[1,0,1]
	ds_bpermute_b32 v178, v142, v174
	ds_bpermute_b32 v179, v142, v175
	s_waitcnt lgkmcnt(0)
	v_add_f32_e32 v113, v169, v113
	v_pk_add_f32 v[174:175], v[174:175], v[178:179]
	ds_bpermute_b32 v178, v143, v174
	ds_bpermute_b32 v179, v143, v175
	s_waitcnt lgkmcnt(0)
	v_mov_b32_e32 v118, v113
	s_nop 1
	v_permlane32_swap_b32_e32 v113, v118
	v_add_f32_e32 v118, v113, v118
	v_fmac_f32_e32 v118, v112, v176
	ds_bpermute_b32 v112, v142, v172
	ds_bpermute_b32 v113, v142, v173
	s_waitcnt lgkmcnt(0)
	v_pk_add_f32 v[112:113], v[172:173], v[112:113]
	ds_bpermute_b32 v172, v143, v112
	ds_bpermute_b32 v173, v143, v113
	s_waitcnt lgkmcnt(0)
	v_pk_add_f32 v[112:113], v[112:113], v[172:173]
	v_pk_add_f32 v[172:173], v[174:175], v[178:179]
	v_pk_fma_f32 v[62:63], v[62:63], v[176:177], v[112:113] op_sel_hi:[1,0,1]
	v_pk_fma_f32 v[64:65], v[64:65], v[176:177], v[172:173] op_sel_hi:[1,0,1]
	v_mov_b32_e32 v112, v118
	v_mov_b32_e32 v113, v119
.LBB0_2754:
	s_or_b64 exec, exec, s[22:23]
	s_waitcnt lgkmcnt(0)
	v_add_f32_e32 v120, v120, v121
	v_fma_f32 v120, -v128, v124, v120
	v_add_f32_e32 v121, v167, v168
	v_cndmask_b32_e32 v172, v135, v120, vcc
	v_add_f32_e32 v120, v164, v165
	v_fma_f32 v121, -v128, v152, v121
	v_fma_f32 v120, -v128, v125, v120
	v_cndmask_b32_e64 v165, v135, v121, s[12:13]
	v_add_f32_e32 v121, v170, v171
	v_cndmask_b32_e64 v169, v135, v120, s[10:11]
	v_fma_f32 v121, -v128, v155, v121
	v_max3_f32 v120, v172, s35, v169
	v_cndmask_b32_e64 v164, v135, v121, s[14:15]
	v_max3_f32 v120, v120, v165, v164
	ds_bpermute_b32 v121, v142, v120
	s_waitcnt lgkmcnt(0)
	v_max_f32_e32 v121, v121, v121
	v_max_f32_e32 v120, v120, v121
	ds_bpermute_b32 v121, v143, v120
	s_waitcnt lgkmcnt(0)
	v_max_f32_e32 v121, v121, v121
	v_max_f32_e32 v167, v120, v121
	v_cmp_neq_f32_e64 s[16:17], s35, v167
	v_mov_b64_e32 v[120:121], v[116:117]
	s_and_saveexec_b64 s[22:23], s[16:17]
	s_cbranch_execz .LBB0_2756
	v_max_f32_e32 v120, v167, v167
	v_max_f32_e32 v121, v117, v117
	v_max_f32_e32 v121, v121, v120
	v_sub_f32_e32 v120, v172, v121
	v_mul_f32_e32 v120, 0x3fb8aa3b, v120
	v_exp_f32_e32 v120, v120
	v_sub_f32_e32 v117, v117, v121
	v_mul_f32_e32 v117, 0x3fb8aa3b, v117
	v_add_f32_e32 v167, 0, v120
	v_pk_fma_f32 v[170:171], v[8:9], v[120:121], 0 op_sel_hi:[1,0,0]
	v_pk_fma_f32 v[172:173], v[6:7], v[120:121], 0 op_sel_hi:[1,0,0]
	v_sub_f32_e32 v120, v169, v121
	v_mul_f32_e32 v120, 0x3fb8aa3b, v120
	v_exp_f32_e32 v120, v120
	s_nop 0
	v_add_f32_e32 v167, v120, v167
	v_pk_fma_f32 v[168:169], v[32:33], v[120:121], v[170:171] op_sel_hi:[1,0,1]
	v_pk_fma_f32 v[170:171], v[30:31], v[120:121], v[172:173] op_sel_hi:[1,0,1]
	v_sub_f32_e32 v120, v165, v121
	v_mul_f32_e32 v120, 0x3fb8aa3b, v120
	v_exp_f32_e32 v120, v120
	s_nop 0
	v_add_f32_e32 v165, v120, v167
	v_pk_fma_f32 v[170:171], v[38:39], v[120:121], v[170:171] op_sel_hi:[1,0,1]
	v_pk_fma_f32 v[168:169], v[40:41], v[120:121], v[168:169] op_sel_hi:[1,0,1]
	v_sub_f32_e32 v120, v164, v121
	v_mul_f32_e32 v120, 0x3fb8aa3b, v120
	v_exp_f32_e32 v120, v120
	s_nop 0
	v_add_f32_e32 v167, v120, v165
	v_pk_fma_f32 v[164:165], v[56:57], v[120:121], v[168:169] op_sel_hi:[1,0,1]
	v_pk_fma_f32 v[168:169], v[54:55], v[120:121], v[170:171] op_sel_hi:[1,0,1]
	v_exp_f32_e32 v170, v117
	ds_bpermute_b32 v117, v142, v167
	ds_bpermute_b32 v172, v142, v164
	ds_bpermute_b32 v173, v142, v165
	s_waitcnt lgkmcnt(0)
	v_add_f32_e32 v117, v167, v117
	v_pk_add_f32 v[164:165], v[164:165], v[172:173]
	ds_bpermute_b32 v172, v143, v164
	ds_bpermute_b32 v173, v143, v165
	s_waitcnt lgkmcnt(0)
	v_mov_b32_e32 v120, v117
	s_nop 1
	v_permlane32_swap_b32_e32 v117, v120
	v_add_f32_e32 v120, v117, v120
	v_fmac_f32_e32 v120, v116, v170
	ds_bpermute_b32 v116, v142, v168
	ds_bpermute_b32 v117, v142, v169
	v_pk_add_f32 v[164:165], v[164:165], v[172:173]
	s_waitcnt lgkmcnt(0)
	v_pk_add_f32 v[116:117], v[168:169], v[116:117]
	ds_bpermute_b32 v168, v143, v116
	ds_bpermute_b32 v169, v143, v117
	v_pk_fma_f32 v[60:61], v[60:61], v[170:171], v[164:165] op_sel_hi:[1,0,1]
	s_waitcnt lgkmcnt(0)
	v_pk_add_f32 v[116:117], v[116:117], v[168:169]
	s_nop 0
	v_pk_fma_f32 v[58:59], v[58:59], v[170:171], v[116:117] op_sel_hi:[1,0,1]
	v_mov_b32_e32 v116, v120
	v_mov_b32_e32 v117, v121
.LBB0_2756:
	s_or_b64 exec, exec, s[22:23]
	v_add_f32_e32 v122, v122, v123
	v_fma_f32 v122, -v129, v124, v122
	v_add_f32_e32 v123, v160, v161
	v_cndmask_b32_e32 v165, v135, v122, vcc
	v_add_f32_e32 v122, v158, v159
	v_fma_f32 v123, -v129, v152, v123
	v_fma_f32 v122, -v129, v125, v122
	v_cndmask_b32_e64 v159, v135, v123, s[12:13]
	v_add_f32_e32 v123, v162, v163
	v_cndmask_b32_e64 v164, v135, v122, s[10:11]
	v_fma_f32 v123, -v129, v155, v123
	v_max3_f32 v122, v165, s35, v164
	v_cndmask_b32_e64 v158, v135, v123, s[14:15]
	v_max3_f32 v122, v122, v159, v158
	ds_bpermute_b32 v123, v142, v122
	s_waitcnt lgkmcnt(0)
	v_max_f32_e32 v123, v123, v123
	v_max_f32_e32 v122, v122, v123
	ds_bpermute_b32 v123, v143, v122
	s_waitcnt lgkmcnt(0)
	v_max_f32_e32 v123, v123, v123
	v_max_f32_e32 v160, v122, v123
	v_cmp_neq_f32_e64 s[16:17], s35, v160
	v_mov_b64_e32 v[122:123], v[114:115]
	s_and_saveexec_b64 s[22:23], s[16:17]
	s_cbranch_execz .LBB0_2758
	v_max_f32_e32 v122, v160, v160
	v_max_f32_e32 v123, v115, v115
	v_max_f32_e32 v123, v123, v122
	v_sub_f32_e32 v122, v165, v123
	v_mul_f32_e32 v122, 0x3fb8aa3b, v122
	v_exp_f32_e32 v122, v122
	v_sub_f32_e32 v115, v115, v123
	v_mul_f32_e32 v115, 0x3fb8aa3b, v115
	v_add_f32_e32 v165, 0, v122
	v_pk_fma_f32 v[160:161], v[8:9], v[122:123], 0 op_sel_hi:[1,0,0]
	v_pk_fma_f32 v[162:163], v[6:7], v[122:123], 0 op_sel_hi:[1,0,0]
	v_sub_f32_e32 v122, v164, v123
	v_mul_f32_e32 v122, 0x3fb8aa3b, v122
	v_exp_f32_e32 v122, v122
	s_nop 0
	v_add_f32_e32 v164, v122, v165
	v_pk_fma_f32 v[160:161], v[32:33], v[122:123], v[160:161] op_sel_hi:[1,0,1]
	v_pk_fma_f32 v[162:163], v[30:31], v[122:123], v[162:163] op_sel_hi:[1,0,1]
	v_sub_f32_e32 v122, v159, v123
	v_mul_f32_e32 v122, 0x3fb8aa3b, v122
	v_exp_f32_e32 v122, v122
	s_nop 0
	v_add_f32_e32 v159, v122, v164
	v_pk_fma_f32 v[162:163], v[38:39], v[122:123], v[162:163] op_sel_hi:[1,0,1]
	v_pk_fma_f32 v[160:161], v[40:41], v[122:123], v[160:161] op_sel_hi:[1,0,1]
	v_sub_f32_e32 v122, v158, v123
	v_mul_f32_e32 v122, 0x3fb8aa3b, v122
	v_exp_f32_e32 v122, v122
	s_nop 0
	v_add_f32_e32 v164, v122, v159
	v_pk_fma_f32 v[158:159], v[56:57], v[122:123], v[160:161] op_sel_hi:[1,0,1]
	v_pk_fma_f32 v[160:161], v[54:55], v[122:123], v[162:163] op_sel_hi:[1,0,1]
	v_exp_f32_e32 v162, v115
	ds_bpermute_b32 v165, v142, v159
	s_waitcnt lgkmcnt(0)
	v_mov_b32_e32 v115, v164
	s_nop 1
	v_permlane16_swap_b32_e32 v164, v115
	v_add_f32_e32 v115, v164, v115
	ds_bpermute_b32 v164, v142, v158
	s_waitcnt lgkmcnt(0)
	v_mov_b32_e32 v122, v115
	s_nop 1
	v_permlane32_swap_b32_e32 v115, v122
	v_add_f32_e32 v122, v115, v122
	v_fmac_f32_e32 v122, v114, v162
	ds_bpermute_b32 v114, v142, v160
	ds_bpermute_b32 v115, v142, v161
	v_pk_add_f32 v[158:159], v[158:159], v[164:165]
	ds_bpermute_b32 v164, v143, v158
	ds_bpermute_b32 v165, v143, v159
	s_waitcnt lgkmcnt(0)
	v_pk_add_f32 v[114:115], v[160:161], v[114:115]
	ds_bpermute_b32 v160, v143, v114
	ds_bpermute_b32 v161, v143, v115
	v_pk_add_f32 v[158:159], v[158:159], v[164:165]
	s_waitcnt lgkmcnt(0)
	v_pk_add_f32 v[114:115], v[114:115], v[160:161]
	v_pk_fma_f32 v[52:53], v[52:53], v[162:163], v[158:159] op_sel_hi:[1,0,1]
	v_pk_fma_f32 v[50:51], v[50:51], v[162:163], v[114:115] op_sel_hi:[1,0,1]
	v_mov_b32_e32 v114, v122
	v_mov_b32_e32 v115, v123
.LBB0_2758:
	s_or_b64 exec, exec, s[22:23]
	v_add_f32_e32 v148, v148, v149
	v_fma_f32 v124, -v130, v124, v148
	v_cndmask_b32_e32 v158, v135, v124, vcc
	v_add_f32_e32 v124, v150, v151
	v_fma_f32 v124, -v130, v125, v124
	v_add_f32_e32 v125, v153, v154
	v_fma_f32 v125, -v130, v152, v125
	v_cndmask_b32_e64 v149, v135, v125, s[12:13]
	v_add_f32_e32 v125, v156, v157
	v_cndmask_b32_e64 v150, v135, v124, s[10:11]
	v_fma_f32 v125, -v130, v155, v125
	v_max3_f32 v124, v158, s35, v150
	v_cndmask_b32_e64 v148, v135, v125, s[14:15]
	v_max3_f32 v124, v124, v149, v148
	ds_bpermute_b32 v125, v142, v124
	s_waitcnt lgkmcnt(0)
	v_max_f32_e32 v125, v125, v125
	v_max_f32_e32 v124, v124, v125
	ds_bpermute_b32 v125, v143, v124
	s_waitcnt lgkmcnt(0)
	v_max_f32_e32 v125, v125, v125
	v_max_f32_e32 v151, v124, v125
	v_cmp_neq_f32_e32 vcc, s35, v151
	v_mov_b64_e32 v[124:125], v[110:111]
	s_and_saveexec_b64 s[10:11], vcc
	s_cbranch_execz .LBB0_2760
	v_max_f32_e32 v124, v151, v151
	v_max_f32_e32 v125, v111, v111
	v_max_f32_e32 v125, v125, v124
	v_sub_f32_e32 v124, v158, v125
	v_mul_f32_e32 v124, 0x3fb8aa3b, v124
	v_exp_f32_e32 v124, v124
	v_sub_f32_e32 v111, v111, v125
	v_mul_f32_e32 v111, 0x3fb8aa3b, v111
	v_add_f32_e32 v151, 0, v124
	v_pk_fma_f32 v[152:153], v[8:9], v[124:125], 0 op_sel_hi:[1,0,0]
	v_pk_fma_f32 v[154:155], v[6:7], v[124:125], 0 op_sel_hi:[1,0,0]
	v_sub_f32_e32 v124, v150, v125
	v_mul_f32_e32 v124, 0x3fb8aa3b, v124
	v_exp_f32_e32 v124, v124
	s_nop 0
	v_add_f32_e32 v156, v124, v151
	v_pk_fma_f32 v[150:151], v[32:33], v[124:125], v[152:153] op_sel_hi:[1,0,1]
	v_pk_fma_f32 v[152:153], v[30:31], v[124:125], v[154:155] op_sel_hi:[1,0,1]
	v_sub_f32_e32 v124, v149, v125
	v_mul_f32_e32 v124, 0x3fb8aa3b, v124
	v_exp_f32_e32 v124, v124
	s_nop 0
	v_add_f32_e32 v149, v124, v156
	v_pk_fma_f32 v[152:153], v[38:39], v[124:125], v[152:153] op_sel_hi:[1,0,1]
	v_pk_fma_f32 v[150:151], v[40:41], v[124:125], v[150:151] op_sel_hi:[1,0,1]
	v_sub_f32_e32 v124, v148, v125
	v_mul_f32_e32 v124, 0x3fb8aa3b, v124
	v_exp_f32_e32 v124, v124
	s_nop 0
	v_add_f32_e32 v154, v124, v149
	v_pk_fma_f32 v[148:149], v[56:57], v[124:125], v[150:151] op_sel_hi:[1,0,1]
	v_pk_fma_f32 v[150:151], v[54:55], v[124:125], v[152:153] op_sel_hi:[1,0,1]
	v_exp_f32_e32 v152, v111
	ds_bpermute_b32 v155, v142, v149
	s_waitcnt lgkmcnt(0)
	v_mov_b32_e32 v111, v154
	s_nop 1
	v_permlane16_swap_b32_e32 v154, v111
	v_add_f32_e32 v111, v154, v111
	ds_bpermute_b32 v154, v142, v148
	s_waitcnt lgkmcnt(0)
	v_mov_b32_e32 v124, v111
	s_nop 1
	v_permlane32_swap_b32_e32 v111, v124
	v_add_f32_e32 v124, v111, v124
	v_fmac_f32_e32 v124, v110, v152
	ds_bpermute_b32 v110, v142, v150
	ds_bpermute_b32 v111, v142, v151
	v_pk_add_f32 v[148:149], v[148:149], v[154:155]
	ds_bpermute_b32 v154, v143, v148
	ds_bpermute_b32 v155, v143, v149
	s_waitcnt lgkmcnt(0)
	v_pk_add_f32 v[110:111], v[150:151], v[110:111]
	ds_bpermute_b32 v150, v143, v110
	ds_bpermute_b32 v151, v143, v111
	v_pk_add_f32 v[148:149], v[148:149], v[154:155]
	s_waitcnt lgkmcnt(0)
	v_pk_add_f32 v[110:111], v[110:111], v[150:151]
	v_pk_fma_f32 v[44:45], v[44:45], v[152:153], v[148:149] op_sel_hi:[1,0,1]
	v_pk_fma_f32 v[42:43], v[42:43], v[152:153], v[110:111] op_sel_hi:[1,0,1]
	v_mov_b32_e32 v110, v124
	v_mov_b32_e32 v111, v125

.LBB0_2762:
	v_mul_f32_e32 v149, v11, v95
	v_fmac_f32_e32 v149, v10, v94
	v_fmac_f32_e32 v149, v12, v96
	v_fmac_f32_e32 v149, v13, v97
	v_sub_u32_e32 v148, 0x800, v144
	v_cvt_f32_u32_e32 v148, v148
	v_cmp_gt_i32_e32 vcc, s45, v144
	s_waitcnt vmcnt(0)
	v_pk_mul_f32 v[154:155], v[12:13], v[92:93]
	s_waitcnt lgkmcnt(0)
	v_add_f32_dpp v149, v149, v149 quad_perm:[1,0,3,2] row_mask:0xf bank_mask:0xf
	v_cmp_gt_i32_e64 s[10:11], s45, v147
	v_pk_mul_f32 v[158:159], v[12:13], v[88:89]
	v_cmp_gt_i32_e64 s[12:13], s45, v146
	v_pk_mul_f32 v[160:161], v[10:11], v[82:83]
	s_waitcnt lgkmcnt(0)
	v_add_f32_dpp v149, v149, v149 quad_perm:[2,3,0,1] row_mask:0xf bank_mask:0xf
	v_cmp_gt_i32_e64 s[14:15], s45, v145
	s_waitcnt lgkmcnt(0)
	v_add_f32_dpp v149, v149, v149 row_half_mirror row_mask:0xf bank_mask:0xf
	s_waitcnt lgkmcnt(0)
	s_nop 0
	v_add_f32_dpp v149, v149, v149 row_mirror row_mask:0xf bank_mask:0xf
	v_fma_f32 v149, -v127, v148, v149
	v_cndmask_b32_e32 v153, v135, v149, vcc
	v_mul_f32_e32 v149, v15, v95
	v_fmac_f32_e32 v149, v14, v94
	v_fmac_f32_e32 v149, v16, v96
	v_fmac_f32_e32 v149, v17, v97
	s_waitcnt lgkmcnt(0)
	s_nop 0
	v_add_f32_dpp v149, v149, v149 quad_perm:[1,0,3,2] row_mask:0xf bank_mask:0xf
	s_waitcnt lgkmcnt(0)
	s_nop 0
	v_add_f32_dpp v149, v149, v149 quad_perm:[2,3,0,1] row_mask:0xf bank_mask:0xf
	s_waitcnt lgkmcnt(0)
	s_nop 0
	v_add_f32_dpp v151, v149, v149 row_half_mirror row_mask:0xf bank_mask:0xf
	v_mul_f32_e32 v149, v19, v95
	v_mul_f32_e32 v95, v23, v95
	v_fmac_f32_e32 v149, v18, v94
	v_fmac_f32_e32 v95, v22, v94
	v_fmac_f32_e32 v149, v20, v96
	v_fmac_f32_e32 v95, v24, v96
	v_fmac_f32_e32 v149, v21, v97
	v_fmac_f32_e32 v95, v25, v97
	v_mul_f32_e32 v97, v11, v91
	v_fmac_f32_e32 v97, v10, v90
	v_add_f32_e32 v97, v154, v97
	v_add_f32_e32 v97, v155, v97
	ds_bpermute_b32 v152, v141, v151
	s_waitcnt lgkmcnt(0)
	v_add_f32_dpp v97, v97, v97 quad_perm:[1,0,3,2] row_mask:0xf bank_mask:0xf
	s_waitcnt lgkmcnt(0)
	s_nop 1
	v_add_f32_dpp v94, v95, v95 quad_perm:[1,0,3,2] row_mask:0xf bank_mask:0xf
	s_waitcnt lgkmcnt(0)
	v_add_f32_dpp v149, v149, v149 quad_perm:[1,0,3,2] row_mask:0xf bank_mask:0xf
	s_waitcnt lgkmcnt(0)
	v_add_f32_dpp v97, v97, v97 quad_perm:[2,3,0,1] row_mask:0xf bank_mask:0xf
	s_waitcnt lgkmcnt(0)
	v_add_f32_dpp v94, v94, v94 quad_perm:[2,3,0,1] row_mask:0xf bank_mask:0xf
	s_waitcnt lgkmcnt(0)
	v_add_f32_dpp v149, v149, v149 quad_perm:[2,3,0,1] row_mask:0xf bank_mask:0xf
	s_waitcnt lgkmcnt(0)
	v_add_f32_dpp v97, v97, v97 row_half_mirror row_mask:0xf bank_mask:0xf
	s_waitcnt lgkmcnt(0)
	v_add_f32_dpp v94, v94, v94 row_half_mirror row_mask:0xf bank_mask:0xf
	v_sub_u32_e32 v95, 0x7fc, v144
	v_cvt_f32_u32_e32 v95, v95
	s_waitcnt lgkmcnt(0)
	v_add_f32_dpp v149, v149, v149 row_half_mirror row_mask:0xf bank_mask:0xf
	s_waitcnt lgkmcnt(0)
	v_add_f32_dpp v97, v97, v97 row_mirror row_mask:0xf bank_mask:0xf
	ds_bpermute_b32 v150, v141, v149
	v_fma_f32 v97, -v127, v95, v97
	v_cndmask_b32_e64 v156, v135, v97, s[10:11]
	v_mul_f32_e32 v97, v15, v91
	v_fmac_f32_e32 v97, v14, v90
	v_fmac_f32_e32 v97, v16, v92
	v_fmac_f32_e32 v97, v17, v93
	v_max3_f32 v162, v153, s35, v156
	ds_bpermute_b32 v96, v141, v94
	s_waitcnt lgkmcnt(0)
	v_add_f32_dpp v97, v97, v97 quad_perm:[1,0,3,2] row_mask:0xf bank_mask:0xf
	s_waitcnt lgkmcnt(0)
	s_nop 0
	v_add_f32_dpp v97, v97, v97 quad_perm:[2,3,0,1] row_mask:0xf bank_mask:0xf
	s_waitcnt lgkmcnt(0)
	s_nop 0
	v_add_f32_dpp v154, v97, v97 row_half_mirror row_mask:0xf bank_mask:0xf
	v_mul_f32_e32 v97, v19, v91
	v_mul_f32_e32 v91, v23, v91
	v_fmac_f32_e32 v97, v18, v90
	v_fmac_f32_e32 v91, v22, v90
	v_fmac_f32_e32 v97, v20, v92
	v_fmac_f32_e32 v91, v24, v92
	v_fmac_f32_e32 v97, v21, v93
	v_fmac_f32_e32 v91, v25, v93
	v_mul_f32_e32 v93, v11, v87
	v_fmac_f32_e32 v93, v10, v86
	v_add_f32_e32 v93, v158, v93
	v_add_f32_e32 v93, v159, v93
	ds_bpermute_b32 v155, v141, v154
	s_waitcnt lgkmcnt(0)
	v_add_f32_dpp v93, v93, v93 quad_perm:[1,0,3,2] row_mask:0xf bank_mask:0xf
	s_waitcnt lgkmcnt(0)
	s_nop 1
	v_add_f32_dpp v90, v91, v91 quad_perm:[1,0,3,2] row_mask:0xf bank_mask:0xf
	s_waitcnt lgkmcnt(0)
	v_add_f32_dpp v97, v97, v97 quad_perm:[1,0,3,2] row_mask:0xf bank_mask:0xf
	s_waitcnt lgkmcnt(0)
	v_add_f32_dpp v93, v93, v93 quad_perm:[2,3,0,1] row_mask:0xf bank_mask:0xf
	s_waitcnt lgkmcnt(0)
	v_add_f32_dpp v90, v90, v90 quad_perm:[2,3,0,1] row_mask:0xf bank_mask:0xf
	ds_bpermute_b32 v91, v140, v90
	s_waitcnt lgkmcnt(0)
	v_add_f32_dpp v97, v97, v97 quad_perm:[2,3,0,1] row_mask:0xf bank_mask:0xf
	s_waitcnt lgkmcnt(0)
	v_add_f32_dpp v93, v93, v93 row_half_mirror row_mask:0xf bank_mask:0xf
	s_waitcnt lgkmcnt(0)
	v_add_f32_e32 v91, v90, v91
	v_sub_u32_e32 v90, 0x7f8, v144
	v_cvt_f32_u32_e32 v90, v90
	s_waitcnt lgkmcnt(0)
	v_add_f32_dpp v97, v97, v97 row_half_mirror row_mask:0xf bank_mask:0xf
	s_waitcnt lgkmcnt(0)
	v_add_f32_dpp v93, v93, v93 row_mirror row_mask:0xf bank_mask:0xf
	ds_bpermute_b32 v147, v141, v97
	v_fma_f32 v93, -v127, v90, v93
	v_cndmask_b32_e64 v159, v135, v93, s[12:13]
	v_mul_f32_e32 v93, v15, v87
	v_fmac_f32_e32 v93, v14, v86
	v_fmac_f32_e32 v93, v16, v88
	v_fmac_f32_e32 v93, v17, v89
	ds_bpermute_b32 v92, v141, v91
	s_waitcnt lgkmcnt(0)
	v_add_f32_dpp v93, v93, v93 quad_perm:[1,0,3,2] row_mask:0xf bank_mask:0xf
	s_waitcnt lgkmcnt(0)
	s_nop 0
	v_add_f32_dpp v93, v93, v93 quad_perm:[2,3,0,1] row_mask:0xf bank_mask:0xf
	s_waitcnt lgkmcnt(0)
	s_nop 0
	v_add_f32_dpp v157, v93, v93 row_half_mirror row_mask:0xf bank_mask:0xf
	v_mul_f32_e32 v93, v19, v87
	v_mul_f32_e32 v87, v23, v87
	v_fmac_f32_e32 v87, v22, v86
	v_fmac_f32_e32 v87, v24, v88
	v_fmac_f32_e32 v87, v25, v89
	v_fmac_f32_e32 v93, v18, v86
	v_fmac_f32_e32 v93, v20, v88
	v_fmac_f32_e32 v93, v21, v89
	v_add_f32_e32 v89, v160, v161
	s_waitcnt lgkmcnt(0)
	s_nop 1
	v_add_f32_dpp v86, v87, v87 quad_perm:[1,0,3,2] row_mask:0xf bank_mask:0xf
	ds_bpermute_b32 v158, v141, v157
	s_waitcnt lgkmcnt(0)
	v_add_f32_dpp v93, v93, v93 quad_perm:[1,0,3,2] row_mask:0xf bank_mask:0xf
	s_waitcnt lgkmcnt(0)
	v_add_f32_dpp v86, v86, v86 quad_perm:[2,3,0,1] row_mask:0xf bank_mask:0xf
	s_waitcnt lgkmcnt(0)
	v_add_f32_dpp v93, v93, v93 quad_perm:[2,3,0,1] row_mask:0xf bank_mask:0xf
	s_waitcnt lgkmcnt(0)
	v_add_f32_dpp v86, v86, v86 row_half_mirror row_mask:0xf bank_mask:0xf
	v_sub_u32_e32 v87, 0x7f4, v144
	v_pk_mul_f32 v[144:145], v[12:13], v[84:85]
	v_cvt_f32_u32_e32 v87, v87
	v_add_f32_e32 v89, v144, v89
	v_add_f32_e32 v89, v145, v89
	s_waitcnt lgkmcnt(0)
	v_add_f32_dpp v93, v93, v93 row_half_mirror row_mask:0xf bank_mask:0xf
	ds_bpermute_b32 v146, v141, v93
	ds_bpermute_b32 v88, v141, v86
	s_waitcnt lgkmcnt(0)
	v_add_f32_dpp v89, v89, v89 quad_perm:[1,0,3,2] row_mask:0xf bank_mask:0xf
	s_waitcnt lgkmcnt(0)
	s_nop 0
	v_add_f32_dpp v89, v89, v89 quad_perm:[2,3,0,1] row_mask:0xf bank_mask:0xf
	s_waitcnt lgkmcnt(0)
	s_nop 0
	v_add_f32_dpp v89, v89, v89 row_half_mirror row_mask:0xf bank_mask:0xf
	s_waitcnt lgkmcnt(0)
	s_nop 0
	v_add_f32_dpp v89, v89, v89 row_mirror row_mask:0xf bank_mask:0xf
	v_fma_f32 v89, -v127, v87, v89
	v_cndmask_b32_e64 v161, v135, v89, s[14:15]
	v_mul_f32_e32 v89, v15, v83
	v_fmac_f32_e32 v89, v14, v82
	v_fmac_f32_e32 v89, v16, v84
	v_fmac_f32_e32 v89, v17, v85
	v_max3_f32 v162, v162, v159, v161
	s_waitcnt lgkmcnt(0)
	v_add_f32_dpp v89, v89, v89 quad_perm:[1,0,3,2] row_mask:0xf bank_mask:0xf
	s_waitcnt lgkmcnt(0)
	s_nop 0
	v_add_f32_dpp v89, v89, v89 quad_perm:[2,3,0,1] row_mask:0xf bank_mask:0xf
	s_waitcnt lgkmcnt(0)
	s_nop 0
	v_add_f32_dpp v145, v89, v89 row_half_mirror row_mask:0xf bank_mask:0xf
	v_mul_f32_e32 v89, v19, v83
	v_mul_f32_e32 v83, v23, v83
	v_fmac_f32_e32 v89, v18, v82
	v_fmac_f32_e32 v83, v22, v82
	v_fmac_f32_e32 v89, v20, v84
	v_fmac_f32_e32 v83, v24, v84
	v_fmac_f32_e32 v89, v21, v85
	v_fmac_f32_e32 v83, v25, v85
	ds_bpermute_b32 v84, v142, v162
	ds_bpermute_b32 v160, v141, v145
	s_waitcnt lgkmcnt(0)
	v_add_f32_dpp v89, v89, v89 quad_perm:[1,0,3,2] row_mask:0xf bank_mask:0xf
	s_waitcnt lgkmcnt(0)
	s_nop 1
	v_add_f32_dpp v82, v83, v83 quad_perm:[1,0,3,2] row_mask:0xf bank_mask:0xf
	s_waitcnt lgkmcnt(0)
	v_max_f32_e32 v84, v84, v84
	v_max_f32_e32 v84, v162, v84
	ds_bpermute_b32 v85, v143, v84
	s_waitcnt lgkmcnt(0)
	v_add_f32_dpp v89, v89, v89 quad_perm:[2,3,0,1] row_mask:0xf bank_mask:0xf
	s_waitcnt lgkmcnt(0)
	v_add_f32_dpp v82, v82, v82 quad_perm:[2,3,0,1] row_mask:0xf bank_mask:0xf
	s_waitcnt lgkmcnt(0)
	v_max_f32_e32 v85, v85, v85
	v_max_f32_e32 v84, v84, v85
	v_cmp_neq_f32_e64 s[16:17], s35, v84
	s_waitcnt lgkmcnt(0)
	v_add_f32_dpp v89, v89, v89 row_half_mirror row_mask:0xf bank_mask:0xf
	s_waitcnt lgkmcnt(0)
	v_add_f32_dpp v82, v82, v82 row_half_mirror row_mask:0xf bank_mask:0xf
	ds_bpermute_b32 v144, v141, v89
	ds_bpermute_b32 v83, v141, v82
	s_and_saveexec_b64 s[24:25], s[16:17]
	s_cbranch_execz .LBB0_2764
	v_max_f32_e32 v84, v84, v84
	v_max_f32_e32 v85, v113, v113
	v_max_f32_e32 v119, v85, v84
	v_sub_f32_e32 v84, v113, v119
	v_mul_f32_e32 v113, 0x3fb8aa3b, v84
	v_sub_f32_e32 v84, v153, v119
	v_mul_f32_e32 v84, 0x3fb8aa3b, v84
	v_sub_f32_e32 v118, v156, v119
	v_exp_f32_e32 v84, v84
	v_mul_f32_e32 v118, 0x3fb8aa3b, v118
	v_exp_f32_e32 v118, v118
	v_exp_f32_e32 v156, v113
	v_add_f32_e32 v153, 0, v84
	v_pk_fma_f32 v[162:163], v[76:77], v[84:85], 0 op_sel_hi:[1,0,0]
	v_pk_fma_f32 v[84:85], v[74:75], v[84:85], 0 op_sel_hi:[1,0,0]
	v_add_f32_e32 v153, v118, v153
	v_pk_fma_f32 v[162:163], v[68:69], v[118:119], v[162:163] op_sel_hi:[1,0,1]
	v_pk_fma_f32 v[84:85], v[66:67], v[118:119], v[84:85] op_sel_hi:[1,0,1]
	v_sub_f32_e32 v118, v159, v119
	v_mul_f32_e32 v118, 0x3fb8aa3b, v118
	v_exp_f32_e32 v118, v118
	s_nop 0
	v_add_f32_e32 v153, v118, v153
	v_pk_fma_f32 v[84:85], v[70:71], v[118:119], v[84:85] op_sel_hi:[1,0,1]
	v_pk_fma_f32 v[162:163], v[72:73], v[118:119], v[162:163] op_sel_hi:[1,0,1]
	v_sub_f32_e32 v118, v161, v119
	v_mul_f32_e32 v118, 0x3fb8aa3b, v118
	v_exp_f32_e32 v118, v118
	s_nop 0
	v_add_f32_e32 v153, v118, v153
	ds_bpermute_b32 v113, v142, v153
	v_pk_fma_f32 v[162:163], v[80:81], v[118:119], v[162:163] op_sel_hi:[1,0,1]
	v_pk_fma_f32 v[84:85], v[78:79], v[118:119], v[84:85] op_sel_hi:[1,0,1]
	ds_bpermute_b32 v164, v142, v162
	ds_bpermute_b32 v165, v142, v163
	s_waitcnt lgkmcnt(0)
	v_add_f32_e32 v113, v153, v113
	s_waitcnt lgkmcnt(0)
	v_pk_add_f32 v[162:163], v[162:163], v[164:165]
	ds_bpermute_b32 v164, v143, v162
	s_waitcnt lgkmcnt(0)
	v_mov_b32_e32 v118, v113
	s_nop 1
	v_permlane32_swap_b32_e32 v113, v118
	v_add_f32_e32 v118, v113, v118
	v_fmac_f32_e32 v118, v112, v156
	ds_bpermute_b32 v112, v142, v84
	ds_bpermute_b32 v113, v142, v85
	ds_bpermute_b32 v165, v143, v163
	s_waitcnt lgkmcnt(0)
	v_pk_add_f32 v[84:85], v[84:85], v[112:113]
	ds_bpermute_b32 v112, v143, v84
	ds_bpermute_b32 v113, v143, v85
	s_waitcnt lgkmcnt(0)
	v_pk_add_f32 v[84:85], v[84:85], v[112:113]
	v_pk_add_f32 v[112:113], v[162:163], v[164:165]
	v_pk_fma_f32 v[62:63], v[62:63], v[156:157], v[84:85] op_sel_hi:[1,0,1]
	v_pk_fma_f32 v[64:65], v[64:65], v[156:157], v[112:113] op_sel_hi:[1,0,1]
	v_mov_b32_e32 v112, v118
	v_mov_b32_e32 v113, v119
.LBB0_2764:
	s_or_b64 exec, exec, s[24:25]
	v_add_f32_e32 v84, v151, v152
	v_fma_f32 v84, -v128, v148, v84
	v_cndmask_b32_e32 v152, v135, v84, vcc
	v_add_f32_e32 v84, v154, v155
	v_fma_f32 v84, -v128, v95, v84
	v_cndmask_b32_e64 v151, v135, v84, s[10:11]
	v_add_f32_e32 v84, v157, v158
	v_fma_f32 v84, -v128, v90, v84
	v_cndmask_b32_e64 v85, v135, v84, s[12:13]
	v_add_f32_e32 v84, v145, v160
	v_fma_f32 v84, -v128, v87, v84
	v_max3_f32 v153, v152, s35, v151
	v_cndmask_b32_e64 v84, v135, v84, s[14:15]
	v_max3_f32 v145, v153, v85, v84
	ds_bpermute_b32 v153, v142, v145
	s_waitcnt lgkmcnt(0)
	v_max_f32_e32 v153, v153, v153
	v_max_f32_e32 v145, v145, v153
	ds_bpermute_b32 v153, v143, v145
	s_waitcnt lgkmcnt(0)
	v_max_f32_e32 v153, v153, v153
	v_max_f32_e32 v145, v145, v153
	v_cmp_neq_f32_e64 s[16:17], s35, v145
	s_and_saveexec_b64 s[24:25], s[16:17]
	s_cbranch_execz .LBB0_2766
	v_max_f32_e32 v120, v145, v145
	v_max_f32_e32 v121, v117, v117
	v_max_f32_e32 v121, v121, v120
	v_sub_f32_e32 v120, v152, v121
	v_mul_f32_e32 v120, 0x3fb8aa3b, v120
	v_exp_f32_e32 v120, v120
	v_sub_f32_e32 v85, v85, v121
	v_mul_f32_e32 v85, 0x3fb8aa3b, v85
	v_sub_f32_e32 v84, v84, v121
	v_add_f32_e32 v145, 0, v120
	v_pk_fma_f32 v[152:153], v[76:77], v[120:121], 0 op_sel_hi:[1,0,0]
	v_pk_fma_f32 v[154:155], v[74:75], v[120:121], 0 op_sel_hi:[1,0,0]
	v_sub_f32_e32 v120, v151, v121
	v_mul_f32_e32 v120, 0x3fb8aa3b, v120
	v_exp_f32_e32 v120, v120
	v_mul_f32_e32 v84, 0x3fb8aa3b, v84
	v_exp_f32_e32 v84, v84
	v_sub_f32_e32 v117, v117, v121
	v_add_f32_e32 v145, v120, v145
	v_pk_fma_f32 v[152:153], v[68:69], v[120:121], v[152:153] op_sel_hi:[1,0,1]
	v_pk_fma_f32 v[154:155], v[66:67], v[120:121], v[154:155] op_sel_hi:[1,0,1]
	v_exp_f32_e32 v120, v85
	v_mul_f32_e32 v117, 0x3fb8aa3b, v117
	v_add_f32_e32 v85, v120, v145
	v_pk_fma_f32 v[154:155], v[70:71], v[120:121], v[154:155] op_sel_hi:[1,0,1]
	v_pk_fma_f32 v[152:153], v[72:73], v[120:121], v[152:153] op_sel_hi:[1,0,1]
	v_add_f32_e32 v120, v84, v85
	v_pk_fma_f32 v[152:153], v[80:81], v[84:85], v[152:153] op_sel_hi:[1,0,1]
	v_pk_fma_f32 v[84:85], v[78:79], v[84:85], v[154:155] op_sel_hi:[1,0,1]
	v_exp_f32_e32 v154, v117
	ds_bpermute_b32 v156, v142, v152
	ds_bpermute_b32 v157, v142, v153
	s_waitcnt lgkmcnt(0)
	v_mov_b32_e32 v117, v120
	s_nop 1
	v_permlane16_swap_b32_e32 v120, v117
	v_add_f32_e32 v117, v120, v117
	s_waitcnt lgkmcnt(0)
	v_pk_add_f32 v[152:153], v[152:153], v[156:157]
	ds_bpermute_b32 v156, v143, v152
	ds_bpermute_b32 v157, v143, v153
	s_waitcnt lgkmcnt(0)
	v_mov_b32_e32 v120, v117
	s_nop 1
	v_permlane32_swap_b32_e32 v117, v120
	v_add_f32_e32 v120, v117, v120
	v_fmac_f32_e32 v120, v116, v154
	ds_bpermute_b32 v116, v142, v84
	ds_bpermute_b32 v117, v142, v85
	s_waitcnt lgkmcnt(0)
	v_pk_add_f32 v[84:85], v[84:85], v[116:117]
	ds_bpermute_b32 v116, v143, v84
	ds_bpermute_b32 v117, v143, v85
	s_waitcnt lgkmcnt(0)
	v_pk_add_f32 v[84:85], v[84:85], v[116:117]
	v_pk_add_f32 v[116:117], v[152:153], v[156:157]
	v_pk_fma_f32 v[58:59], v[58:59], v[154:155], v[84:85] op_sel_hi:[1,0,1]
	v_pk_fma_f32 v[60:61], v[60:61], v[154:155], v[116:117] op_sel_hi:[1,0,1]
	v_mov_b32_e32 v116, v120
	v_mov_b32_e32 v117, v121
.LBB0_2766:
	s_or_b64 exec, exec, s[24:25]
	v_add_f32_e32 v84, v149, v150
	v_fma_f32 v84, -v129, v148, v84
	v_cndmask_b32_e32 v145, v135, v84, vcc
	v_add_f32_e32 v84, v97, v147
	v_fma_f32 v84, -v129, v95, v84
	v_cndmask_b32_e64 v97, v135, v84, s[10:11]
	v_add_f32_e32 v84, v93, v146
	v_fma_f32 v84, -v129, v90, v84
	v_cndmask_b32_e64 v85, v135, v84, s[12:13]
	v_add_f32_e32 v84, v89, v144
	v_fma_f32 v84, -v129, v87, v84
	v_max3_f32 v147, v145, s35, v97
	v_cndmask_b32_e64 v84, v135, v84, s[14:15]
	v_max3_f32 v89, v147, v85, v84
	ds_bpermute_b32 v93, v142, v89
	s_waitcnt lgkmcnt(0)
	v_max_f32_e32 v93, v93, v93
	v_max_f32_e32 v89, v89, v93
	ds_bpermute_b32 v93, v143, v89
	s_waitcnt lgkmcnt(0)
	v_max_f32_e32 v93, v93, v93
	v_max_f32_e32 v89, v89, v93
	v_cmp_neq_f32_e64 s[16:17], s35, v89
	s_and_saveexec_b64 s[24:25], s[16:17]
	s_cbranch_execz .LBB0_2768
	v_max_f32_e32 v89, v89, v89
	v_max_f32_e32 v93, v115, v115
	v_max_f32_e32 v123, v93, v89
	v_sub_f32_e32 v93, v145, v123
	v_mul_f32_e32 v93, 0x3fb8aa3b, v93
	v_exp_f32_e32 v122, v93
	v_sub_f32_e32 v97, v97, v123
	v_mul_f32_e32 v97, 0x3fb8aa3b, v97
	v_sub_f32_e32 v85, v85, v123
	v_add_f32_e32 v93, 0, v122
	v_pk_fma_f32 v[144:145], v[76:77], v[122:123], 0 op_sel_hi:[1,0,0]
	v_pk_fma_f32 v[146:147], v[74:75], v[122:123], 0 op_sel_hi:[1,0,0]
	v_exp_f32_e32 v122, v97
	v_mul_f32_e32 v85, 0x3fb8aa3b, v85
	v_sub_f32_e32 v84, v84, v123
	v_mul_f32_e32 v84, 0x3fb8aa3b, v84
	v_add_f32_e32 v93, v122, v93
	v_pk_fma_f32 v[144:145], v[68:69], v[122:123], v[144:145] op_sel_hi:[1,0,1]
	v_pk_fma_f32 v[146:147], v[66:67], v[122:123], v[146:147] op_sel_hi:[1,0,1]
	v_exp_f32_e32 v122, v85
	v_exp_f32_e32 v84, v84
	v_sub_f32_e32 v89, v115, v123
	v_mul_f32_e32 v89, 0x3fb8aa3b, v89
	v_add_f32_e32 v85, v122, v93
	v_pk_fma_f32 v[146:147], v[70:71], v[122:123], v[146:147] op_sel_hi:[1,0,1]
	v_pk_fma_f32 v[144:145], v[72:73], v[122:123], v[144:145] op_sel_hi:[1,0,1]
	v_add_f32_e32 v93, v84, v85
	v_pk_fma_f32 v[144:145], v[80:81], v[84:85], v[144:145] op_sel_hi:[1,0,1]
	v_pk_fma_f32 v[84:85], v[78:79], v[84:85], v[146:147] op_sel_hi:[1,0,1]
	v_exp_f32_e32 v146, v89
	ds_bpermute_b32 v115, v142, v85
	ds_bpermute_b32 v150, v142, v144
	ds_bpermute_b32 v151, v142, v145
	s_waitcnt lgkmcnt(0)
	v_mov_b32_e32 v89, v93
	s_nop 1
	v_permlane16_swap_b32_e32 v93, v89
	v_add_f32_e32 v89, v93, v89
	ds_bpermute_b32 v93, v143, v89
	s_waitcnt lgkmcnt(0)
	v_pk_add_f32 v[144:145], v[144:145], v[150:151]
	ds_bpermute_b32 v150, v143, v144
	ds_bpermute_b32 v151, v143, v145
	s_waitcnt lgkmcnt(0)
	v_add_f32_e32 v122, v89, v93
	v_fmac_f32_e32 v122, v114, v146
	ds_bpermute_b32 v114, v142, v84
	s_waitcnt lgkmcnt(0)
	v_pk_add_f32 v[84:85], v[84:85], v[114:115]
	ds_bpermute_b32 v114, v143, v84
	ds_bpermute_b32 v115, v143, v85
	s_waitcnt lgkmcnt(0)
	v_pk_add_f32 v[84:85], v[84:85], v[114:115]
	v_pk_add_f32 v[114:115], v[144:145], v[150:151]
	v_pk_fma_f32 v[50:51], v[50:51], v[146:147], v[84:85] op_sel_hi:[1,0,1]
	v_pk_fma_f32 v[52:53], v[52:53], v[146:147], v[114:115] op_sel_hi:[1,0,1]
	v_mov_b32_e32 v114, v122
	v_mov_b32_e32 v115, v123
.LBB0_2768:
	s_or_b64 exec, exec, s[24:25]
	v_add_f32_e32 v84, v94, v96
	v_fma_f32 v84, -v130, v148, v84
	v_cndmask_b32_e32 v89, v135, v84, vcc
	v_add_f32_e32 v84, v91, v92
	v_fma_f32 v84, -v130, v95, v84
	v_cndmask_b32_e64 v85, v135, v84, s[10:11]
	v_add_f32_e32 v84, v86, v88
	v_add_f32_e32 v82, v82, v83
	v_fma_f32 v84, -v130, v90, v84
	v_fma_f32 v82, -v130, v87, v82
	v_max3_f32 v91, v89, s35, v85
	v_cndmask_b32_e64 v84, v135, v84, s[12:13]
	v_cndmask_b32_e64 v82, v135, v82, s[14:15]
	v_max3_f32 v83, v91, v84, v82
	ds_bpermute_b32 v86, v142, v83
	s_waitcnt lgkmcnt(0)
	v_max_f32_e32 v86, v86, v86
	v_max_f32_e32 v83, v83, v86
	ds_bpermute_b32 v86, v143, v83
	s_waitcnt lgkmcnt(0)
	v_max_f32_e32 v86, v86, v86
	v_max_f32_e32 v83, v83, v86
	v_cmp_neq_f32_e32 vcc, s35, v83
	s_and_saveexec_b64 s[10:11], vcc
	s_cbranch_execz .LBB0_2770
	v_max_f32_e32 v83, v83, v83
	v_max_f32_e32 v86, v111, v111
	v_max_f32_e32 v125, v86, v83
	v_sub_f32_e32 v86, v89, v125
	v_mul_f32_e32 v86, 0x3fb8aa3b, v86
	v_exp_f32_e32 v86, v86
	v_sub_f32_e32 v85, v85, v125
	v_mul_f32_e32 v85, 0x3fb8aa3b, v85
	v_sub_f32_e32 v83, v111, v125
	v_add_f32_e32 v87, 0, v86
	v_pk_fma_f32 v[76:77], v[76:77], v[86:87], 0 op_sel_hi:[1,0,0]
	v_pk_fma_f32 v[74:75], v[74:75], v[86:87], 0 op_sel_hi:[1,0,0]
	v_exp_f32_e32 v86, v85
	v_mul_f32_e32 v83, 0x3fb8aa3b, v83
	v_mov_b32_e32 v111, v125
	v_pk_fma_f32 v[66:67], v[66:67], v[86:87], v[74:75] op_sel_hi:[1,0,1]
	v_sub_f32_e32 v74, v84, v125
	v_mul_f32_e32 v74, 0x3fb8aa3b, v74
	v_exp_f32_e32 v74, v74
	v_add_f32_e32 v85, v86, v87
	v_pk_fma_f32 v[68:69], v[68:69], v[86:87], v[76:77] op_sel_hi:[1,0,1]
	v_add_f32_e32 v75, v74, v85
	v_pk_fma_f32 v[66:67], v[70:71], v[74:75], v[66:67] op_sel_hi:[1,0,1]
	v_sub_f32_e32 v70, v82, v125
	v_mul_f32_e32 v70, 0x3fb8aa3b, v70
	v_exp_f32_e32 v70, v70
	v_pk_fma_f32 v[68:69], v[72:73], v[74:75], v[68:69] op_sel_hi:[1,0,1]
	v_add_f32_e32 v71, v70, v75
	v_pk_fma_f32 v[68:69], v[80:81], v[70:71], v[68:69] op_sel_hi:[1,0,1]
	v_pk_fma_f32 v[66:67], v[78:79], v[70:71], v[66:67] op_sel_hi:[1,0,1]
	ds_bpermute_b32 v73, v142, v67
	ds_bpermute_b32 v74, v142, v68
	s_waitcnt lgkmcnt(0)
	v_mov_b32_e32 v72, v71
	s_nop 1
	v_permlane16_swap_b32_e32 v71, v72
	v_add_f32_e32 v71, v71, v72
	ds_bpermute_b32 v72, v143, v71
	ds_bpermute_b32 v75, v142, v69
	v_exp_f32_e32 v70, v83
	s_waitcnt lgkmcnt(0)
	v_add_f32_e32 v124, v71, v72
	ds_bpermute_b32 v72, v142, v66
	s_waitcnt lgkmcnt(0)
	v_pk_add_f32 v[68:69], v[68:69], v[74:75]
	ds_bpermute_b32 v74, v143, v68
	ds_bpermute_b32 v75, v143, v69
	v_fmac_f32_e32 v124, v110, v70
	s_waitcnt lgkmcnt(0)
	v_pk_add_f32 v[66:67], v[66:67], v[72:73]
	ds_bpermute_b32 v72, v143, v66
	ds_bpermute_b32 v73, v143, v67
	s_waitcnt lgkmcnt(0)
	v_pk_add_f32 v[68:69], v[68:69], v[74:75]
	v_mov_b32_e32 v110, v124
	v_pk_fma_f32 v[44:45], v[44:45], v[70:71], v[68:69] op_sel_hi:[1,0,1]
	s_waitcnt lgkmcnt(0)
	v_pk_add_f32 v[66:67], v[66:67], v[72:73]
	s_nop 0
	v_pk_fma_f32 v[42:43], v[42:43], v[70:71], v[66:67] op_sel_hi:[1,0,1]

.LBB0_2937:
	v_lshl_add_u64 v[18:19], s[68:69], 0, v[94:95]
	v_lshl_add_u64 v[22:23], s[68:69], 0, v[92:93]
	v_add_co_u32_e32 v20, vcc, 0x7800000, v18
	v_add_co_u32_e64 v102, s[6:7], s24, v22
	s_nop 0
	v_addc_co_u32_e32 v21, vcc, 0, v19, vcc
	v_addc_co_u32_e64 v103, s[6:7], 0, v23, s[6:7]
	v_add_co_u32_e64 v104, s[6:7], s25, v22
	v_add_co_u32_e32 v22, vcc, 0x7801000, v18
	s_nop 0
	v_addc_co_u32_e64 v105, s[6:7], 0, v23, s[6:7]
	global_load_dwordx4 v[78:81], v[20:21], off
	global_load_dwordx4 v[74:77], v[20:21], off offset:1024
	global_load_dwordx4 v[70:73], v[20:21], off offset:2048
	global_load_dwordx4 v[66:69], v[20:21], off offset:3072
	v_addc_co_u32_e32 v23, vcc, 0, v19, vcc
	v_add_co_u32_e32 v20, vcc, 0x7802000, v18
	global_load_dwordx4 v[62:65], v[22:23], off
	global_load_dwordx4 v[58:61], v[22:23], off offset:1024
	global_load_dwordx4 v[54:57], v[22:23], off offset:2048
	global_load_dwordx4 v[50:53], v[22:23], off offset:3072
	v_addc_co_u32_e32 v21, vcc, 0, v19, vcc
	v_add_co_u32_e32 v82, vcc, 0x7803000, v18
	global_load_dwordx4 v[46:49], v[20:21], off
	global_load_dwordx4 v[42:45], v[20:21], off offset:1024
	global_load_dwordx4 v[38:41], v[20:21], off offset:2048
	global_load_dwordx4 v[34:37], v[20:21], off offset:3072
	v_addc_co_u32_e32 v83, vcc, 0, v19, vcc
	global_load_dwordx4 v[30:33], v[82:83], off
	global_load_dwordx4 v[26:29], v[82:83], off offset:1024
	global_load_dwordx4 v[22:25], v[82:83], off offset:2048
	global_load_dwordx4 v[18:21], v[82:83], off offset:3072
	s_ashr_i32 s8, s12, 13
	s_add_i32 s9, s12, 0xffffc002
	s_cmpk_lt_i32 s12, 0x4000
	s_cselect_b32 s6, s8, s9
	s_mul_hi_i32 s7, s6, 0x9000
	s_mul_i32 s6, s6, 0x9000
	s_add_u32 s9, s3, s6
	s_addc_u32 s11, s4, s7
	s_add_u32 s6, s9, 0x6000
	s_addc_u32 s7, s11, 0
	s_add_u32 s10, s9, 0x7000
	s_addc_u32 s11, s11, 0
	v_lshl_add_u64 v[82:83], s[6:7], 0, v[90:91]
	v_lshl_add_u64 v[86:87], s[10:11], 0, v[90:91]
	global_load_dwordx4 v[82:85], v[82:83], off
	v_lshl_add_u64 v[148:149], s[6:7], 0, v[96:97]
	global_load_dwordx4 v[86:89], v[86:87], off
	v_lshl_add_u64 v[142:143], s[6:7], 0, v[98:99]
	v_lshl_add_u64 v[134:135], s[6:7], 0, v[100:101]
	s_add_i32 s6, s12, 0xffffc003
	s_cmpk_lt_i32 s12, 0x3fff
	s_cselect_b32 s6, s8, s6
	s_mul_hi_i32 s7, s6, 0x9000
	s_mul_i32 s6, s6, 0x9000
	s_add_u32 s9, s3, s6
	v_lshl_add_u64 v[152:153], s[10:11], 0, v[96:97]
	v_lshl_add_u64 v[146:147], s[10:11], 0, v[98:99]
	v_lshl_add_u64 v[140:141], s[10:11], 0, v[100:101]
	s_addc_u32 s11, s4, s7
	s_add_u32 s6, s9, 0x6000
	s_addc_u32 s7, s11, 0
	s_add_u32 s10, s9, 0x7000
	v_lshl_add_u64 v[132:133], s[6:7], 0, v[90:91]
	v_lshl_add_u64 v[126:127], s[6:7], 0, v[96:97]
	v_lshl_add_u64 v[118:119], s[6:7], 0, v[98:99]
	v_lshl_add_u64 v[114:115], s[6:7], 0, v[100:101]
	s_addc_u32 s11, s11, 0
	s_add_i32 s6, s12, 0xffffc004
	s_cmpk_lt_i32 s12, 0x3ffe
	s_cselect_b32 s6, s8, s6
	s_mul_hi_i32 s7, s6, 0x9000
	s_mul_i32 s6, s6, 0x9000
	s_add_u32 s6, s3, s6
	s_addc_u32 s7, s4, s7
	v_lshl_add_u64 v[138:139], s[10:11], 0, v[90:91]
	v_lshl_add_u64 v[130:131], s[10:11], 0, v[96:97]
	v_lshl_add_u64 v[122:123], s[10:11], 0, v[98:99]
	v_lshl_add_u64 v[116:117], s[10:11], 0, v[100:101]
	s_add_u32 s10, s6, 0x6000
	s_addc_u32 s11, s7, 0
	s_add_u32 s6, s6, 0x7000
	s_addc_u32 s7, s7, 0
	s_add_i32 s9, s12, 0xffffc005
	s_cmpk_lt_i32 s12, 0x3ffd
	v_lshl_add_u64 v[156:157], s[6:7], 0, v[90:91]
	v_lshl_add_u64 v[154:155], s[6:7], 0, v[96:97]
	v_lshl_add_u64 v[150:151], s[6:7], 0, v[98:99]
	v_lshl_add_u64 v[136:137], s[6:7], 0, v[100:101]
	s_cselect_b32 s6, s8, s9
	s_mul_hi_i32 s7, s6, 0x9000
	s_mul_i32 s6, s6, 0x9000
	s_add_u32 s6, s3, s6
	s_addc_u32 s7, s4, s7
	s_waitcnt vmcnt(0) lgkmcnt(0)
	v_pk_mul_f32 v[158:159], v[80:81], v[80:81]
	v_pk_mul_f32 v[160:161], v[78:79], v[78:79]
	v_pk_mul_f32 v[162:163], v[76:77], v[76:77]
	v_pk_mul_f32 v[164:165], v[74:75], v[74:75]
	v_mul_f32_e32 v174, v71, v71
	v_mul_f32_e32 v176, v73, v73
	v_mul_f32_e32 v187, v68, v68
	v_mul_f32_e32 v189, v69, v69
	v_pk_mov_b32 v[178:179], v[160:161], v[158:159] op_sel:[1,0]
	v_mov_b32_e32 v161, v159
	v_pk_mov_b32 v[158:159], v[164:165], v[162:163] op_sel:[1,0]
	v_mov_b32_e32 v165, v163
	v_pk_fma_f32 v[162:163], v[70:71], v[70:71], v[174:175] op_sel_hi:[1,1,0]
	v_pk_fma_f32 v[174:175], v[72:73], v[72:73], v[176:177] op_sel_hi:[1,1,0]
	v_pk_mul_f32 v[176:177], v[64:65], v[64:65]
	v_pk_mul_f32 v[180:181], v[62:63], v[62:63]
	v_pk_mul_f32 v[182:183], v[60:61], v[60:61]
	v_pk_mul_f32 v[184:185], v[58:59], v[58:59]
	v_mul_f32_e32 v186, v55, v55
	v_mul_f32_e32 v188, v57, v57
	v_pk_add_f32 v[160:161], v[178:179], v[160:161]
	v_pk_add_f32 v[158:159], v[158:159], v[164:165]
	v_mov_b32_e32 v163, v187
	v_mov_b32_e32 v175, v189
	v_pk_mov_b32 v[164:165], v[180:181], v[176:177] op_sel:[1,0]
	v_mov_b32_e32 v181, v177
	v_pk_mov_b32 v[176:177], v[184:185], v[182:183] op_sel:[1,0]
	v_mov_b32_e32 v185, v183
	v_pk_fma_f32 v[178:179], v[54:55], v[54:55], v[186:187] op_sel_hi:[1,1,0]
	v_pk_fma_f32 v[182:183], v[56:57], v[56:57], v[188:189] op_sel_hi:[1,1,0]
	v_pk_mul_f32 v[186:187], v[48:49], v[48:49]
	v_pk_mul_f32 v[188:189], v[46:47], v[46:47]
	v_pk_mul_f32 v[190:191], v[44:45], v[44:45]
	v_pk_mul_f32 v[192:193], v[42:43], v[42:43]
	v_mul_f32_e32 v197, v66, v66
	v_mul_f32_e32 v203, v67, v67
	v_mul_f32_e32 v195, v52, v52
	v_mul_f32_e32 v202, v53, v53
	v_mul_f32_e32 v194, v39, v39
	v_mul_f32_e32 v196, v41, v41
	v_pk_add_f32 v[198:199], v[160:161], v[160:161] op_sel:[0,1] op_sel_hi:[1,0]
	v_pk_add_f32 v[200:201], v[158:159], v[158:159] op_sel:[0,1] op_sel_hi:[1,0]
	v_pk_add_f32 v[174:175], v[162:163], v[174:175]
	v_pk_add_f32 v[158:159], v[164:165], v[180:181]
	v_pk_add_f32 v[160:161], v[176:177], v[184:185]
	v_pk_mov_b32 v[162:163], v[188:189], v[186:187] op_sel:[1,0]
	v_mov_b32_e32 v189, v187
	v_pk_mov_b32 v[164:165], v[192:193], v[190:191] op_sel:[1,0]
	v_mov_b32_e32 v193, v191
	v_mul_f32_e32 v208, v50, v50
	v_mul_f32_e32 v209, v51, v51
	v_mul_f32_e32 v212, v36, v36
	v_mul_f32_e32 v213, v37, v37
	v_mov_b32_e32 v179, v195
	v_mov_b32_e32 v183, v202
	v_pk_fma_f32 v[176:177], v[38:39], v[38:39], v[194:195] op_sel_hi:[1,1,0]
	v_pk_fma_f32 v[180:181], v[40:41], v[40:41], v[196:197] op_sel_hi:[1,1,0]
	v_pk_mul_f32 v[184:185], v[32:33], v[32:33]
	v_pk_mul_f32 v[186:187], v[30:31], v[30:31]
	v_pk_mul_f32 v[190:191], v[28:29], v[28:29]
	v_pk_mul_f32 v[194:195], v[26:27], v[26:27]
	v_mov_b32_e32 v199, v197
	v_mov_b32_e32 v201, v203
	v_pk_add_f32 v[204:205], v[158:159], v[158:159] op_sel:[0,1] op_sel_hi:[1,0]
	v_pk_add_f32 v[206:207], v[160:161], v[160:161] op_sel:[0,1] op_sel_hi:[1,0]
	v_pk_add_f32 v[162:163], v[162:163], v[188:189]
	v_pk_add_f32 v[164:165], v[164:165], v[192:193]
	v_mul_f32_e32 v210, v34, v34
	v_mul_f32_e32 v211, v35, v35
	v_pk_add_f32 v[178:179], v[178:179], v[182:183]
	v_mov_b32_e32 v177, v212
	v_mov_b32_e32 v181, v213
	v_pk_mov_b32 v[182:183], v[186:187], v[184:185] op_sel:[1,0]
	v_mov_b32_e32 v187, v185
	v_pk_mov_b32 v[184:185], v[194:195], v[190:191] op_sel:[1,0]
	v_mov_b32_e32 v195, v191
	v_pk_add_f32 v[188:189], v[198:199], v[200:201]
	v_mov_b32_e32 v205, v208
	v_mov_b32_e32 v207, v209
	v_pk_add_f32 v[190:191], v[162:163], v[162:163] op_sel:[0,1] op_sel_hi:[1,0]
	v_pk_add_f32 v[192:193], v[164:165], v[164:165] op_sel:[0,1] op_sel_hi:[1,0]
	v_pk_add_f32 v[176:177], v[176:177], v[180:181]
	v_pk_add_f32 v[174:175], v[188:189], v[174:175]
	v_pk_add_f32 v[180:181], v[204:205], v[206:207]
	v_mov_b32_e32 v191, v210
	v_mov_b32_e32 v193, v211
	v_pk_add_f32 v[162:163], v[182:183], v[186:187]
	v_add_f32_e32 v182, v174, v175
	v_pk_add_f32 v[174:175], v[180:181], v[178:179]
	v_pk_add_f32 v[178:179], v[190:191], v[192:193]
	v_add_f32_e32 v180, v174, v175
	v_pk_add_f32 v[174:175], v[178:179], v[176:177]
	v_add_f32_e32 v174, v174, v175
	s_add_u32 s18, s6, 0x6000
	s_waitcnt lgkmcnt(0)
	s_nop 1
	v_add_f32_dpp v176, v182, v182 quad_perm:[1,0,3,2] row_mask:0xf bank_mask:0xf
	s_waitcnt lgkmcnt(0)
	s_nop 1
	v_add_f32_dpp v177, v180, v180 quad_perm:[1,0,3,2] row_mask:0xf bank_mask:0xf
	s_waitcnt lgkmcnt(0)
	s_nop 1
	v_add_f32_dpp v174, v174, v174 quad_perm:[1,0,3,2] row_mask:0xf bank_mask:0xf
	s_waitcnt lgkmcnt(0)
	s_nop 1
	v_add_f32_dpp v176, v176, v176 quad_perm:[2,3,0,1] row_mask:0xf bank_mask:0xf
	s_waitcnt lgkmcnt(0)
	s_nop 1
	v_add_f32_dpp v177, v177, v177 quad_perm:[2,3,0,1] row_mask:0xf bank_mask:0xf
	s_waitcnt lgkmcnt(0)
	s_nop 1
	v_add_f32_dpp v174, v174, v174 quad_perm:[2,3,0,1] row_mask:0xf bank_mask:0xf
	s_waitcnt lgkmcnt(0)
	s_nop 1
	v_add_f32_dpp v176, v176, v176 row_half_mirror row_mask:0xf bank_mask:0xf
	s_waitcnt lgkmcnt(0)
	s_nop 1
	v_add_f32_dpp v177, v177, v177 row_half_mirror row_mask:0xf bank_mask:0xf
	s_waitcnt lgkmcnt(0)
	s_nop 1
	v_add_f32_dpp v174, v174, v174 row_half_mirror row_mask:0xf bank_mask:0xf
	s_waitcnt lgkmcnt(0)
	s_nop 1
	v_add_f32_dpp v176, v176, v176 row_mirror row_mask:0xf bank_mask:0xf
	s_waitcnt lgkmcnt(0)
	s_nop 1
	v_add_f32_dpp v177, v177, v177 row_mirror row_mask:0xf bank_mask:0xf
	s_waitcnt lgkmcnt(0)
	s_nop 1
	v_add_f32_dpp v174, v174, v174 row_mirror row_mask:0xf bank_mask:0xf
	s_waitcnt lgkmcnt(0)
	v_mov_b32_e32 v178, v176
	s_nop 1
	v_permlane16_swap_b32_e32 v176, v178
	v_add_f32_e32 v176, v176, v178
	s_waitcnt lgkmcnt(0)
	v_mov_b32_e32 v179, v177
	s_nop 1
	v_permlane16_swap_b32_e32 v177, v179
	v_add_f32_e32 v177, v177, v179
	s_waitcnt lgkmcnt(0)
	v_mov_b32_e32 v175, v174
	s_nop 1
	v_permlane16_swap_b32_e32 v174, v175
	v_add_f32_e32 v174, v174, v175
	ds_bpermute_b32 v175, v171, v174
	s_waitcnt lgkmcnt(2)
	v_mov_b32_e32 v178, v176
	s_nop 1
	v_permlane32_swap_b32_e32 v176, v178
	v_add_f32_e32 v176, v176, v178
	v_fmamk_f32 v176, v176, 0x3a800000, v172
	s_addc_u32 s19, s7, 0
	s_waitcnt lgkmcnt(1)
	v_mov_b32_e32 v179, v177
	s_nop 1
	v_permlane32_swap_b32_e32 v177, v179
	v_add_f32_e32 v177, v177, v179
	v_mul_f32_e32 v178, 0x4f800000, v176
	v_cmp_gt_f32_e32 vcc, s13, v176
	s_add_u32 s20, s6, 0x7000
	v_fmamk_f32 v177, v177, 0x3a800000, v172
	s_waitcnt lgkmcnt(0)
	v_add_f32_e32 v174, v174, v175
	v_cndmask_b32_e32 v175, v176, v178, vcc
	s_addc_u32 s21, s7, 0
	v_mul_f32_e32 v176, 0x4f800000, v177
	v_cmp_gt_f32_e64 s[6:7], s13, v177
	v_sqrt_f32_e32 v178, v175
	v_fmamk_f32 v174, v174, 0x3a800000, v172
	v_cndmask_b32_e64 v176, v177, v176, s[6:7]
	v_mul_f32_e32 v177, 0x4f800000, v174
	v_cmp_gt_f32_e64 s[8:9], s13, v174
	v_sqrt_f32_e32 v179, v176
	v_add_u32_e32 v180, -1, v178
	v_cndmask_b32_e64 v174, v174, v177, s[8:9]
	v_sqrt_f32_e32 v177, v174
	v_add_u32_e32 v181, 1, v178
	v_fma_f32 v182, -v180, v178, v175
	v_lshl_add_u64 v[112:113], s[10:11], 0, v[90:91]
	v_lshl_add_u64 v[106:107], s[10:11], 0, v[96:97]
	v_lshl_add_u64 v[110:111], s[10:11], 0, v[98:99]
	v_lshl_add_u64 v[108:109], s[10:11], 0, v[100:101]
	v_pk_add_f32 v[164:165], v[184:185], v[194:195]
	v_fma_f32 v183, -v181, v178, v175
	v_add_u32_e32 v184, -1, v179
	v_cmp_ge_f32_e64 s[10:11], 0, v182
	v_add_u32_e32 v185, 1, v179
	v_fma_f32 v182, -v185, v179, v176
	v_cndmask_b32_e64 v178, v178, v180, s[10:11]
	v_fma_f32 v180, -v184, v179, v176
	v_cmp_lt_f32_e64 s[10:11], 0, v183
	v_add_u32_e32 v186, -1, v177
	v_add_u32_e32 v187, 1, v177
	v_cndmask_b32_e64 v178, v178, v181, s[10:11]
	v_cmp_ge_f32_e64 s[10:11], 0, v180
	v_fma_f32 v180, -v186, v177, v174
	v_fma_f32 v181, -v187, v177, v174
	v_cndmask_b32_e64 v179, v179, v184, s[10:11]
	v_cmp_lt_f32_e64 s[10:11], 0, v182
	v_mul_f32_e32 v182, 0x37800000, v178
	v_cndmask_b32_e32 v178, v178, v182, vcc
	v_cndmask_b32_e64 v179, v179, v185, s[10:11]
	v_cmp_ge_f32_e64 s[10:11], 0, v180
	v_mul_f32_e32 v180, 0x37800000, v179
	v_cmp_class_f32_e32 vcc, v175, v173
	v_cndmask_b32_e64 v177, v177, v186, s[10:11]
	v_cmp_lt_f32_e64 s[10:11], 0, v181
	v_cndmask_b32_e32 v175, v178, v175, vcc
	v_cndmask_b32_e64 v178, v179, v180, s[6:7]
	v_cndmask_b32_e64 v177, v177, v187, s[10:11]
	v_cmp_class_f32_e32 vcc, v176, v173
	v_mul_f32_e32 v179, 0x37800000, v177
	v_div_scale_f32 v180, s[6:7], v175, v175, 1.0
	v_cndmask_b32_e32 v176, v178, v176, vcc
	v_cndmask_b32_e64 v177, v177, v179, s[8:9]
	v_cmp_class_f32_e32 vcc, v174, v173
	v_rcp_f32_e32 v178, v180
	v_div_scale_f32 v179, s[8:9], v176, v176, 1.0
	v_cndmask_b32_e32 v177, v177, v174, vcc
	v_rcp_f32_e32 v183, v179
	v_div_scale_f32 v184, s[10:11], v177, v177, 1.0
	v_rcp_f32_e32 v186, v184
	v_fma_f32 v174, -v180, v178, 1.0
	v_div_scale_f32 v181, s[6:7], 1.0, v175, 1.0
	v_fmac_f32_e32 v178, v174, v178
	v_fma_f32 v174, -v179, v183, 1.0
	v_div_scale_f32 v182, s[8:9], 1.0, v176, 1.0
	v_mul_f32_e32 v187, v181, v178
	v_fmac_f32_e32 v183, v174, v183
	v_fma_f32 v174, -v184, v186, 1.0
	v_fma_f32 v188, -v180, v187, v181
	v_mul_f32_e32 v189, v182, v183
	v_div_scale_f32 v185, s[10:11], 1.0, v177, 1.0
	v_fmac_f32_e32 v186, v174, v186
	v_fmac_f32_e32 v187, v188, v178
	v_fma_f32 v174, -v179, v189, v182
	v_mul_f32_e32 v188, v185, v186
	v_fma_f32 v180, -v180, v187, v181
	v_fmac_f32_e32 v189, v174, v183
	s_mov_b64 vcc, s[6:7]
	v_fma_f32 v174, -v184, v188, v185
	v_div_fmas_f32 v178, v180, v178, v187
	v_fma_f32 v179, -v179, v189, v182
	s_mov_b64 vcc, s[8:9]
	v_fmac_f32_e32 v188, v174, v186
	v_div_fixup_f32 v174, v178, v175, 1.0
	v_div_fmas_f32 v175, v179, v183, v189
	v_fma_f32 v178, -v184, v188, v185
	v_pk_mul_f32 v[80:81], v[80:81], v[174:175] op_sel_hi:[1,0]
	v_pk_mul_f32 v[78:79], v[78:79], v[174:175] op_sel_hi:[1,0]
	s_mov_b64 vcc, s[10:11]
	v_pk_add_f32 v[88:89], v[88:89], 1.0 op_sel_hi:[1,0]
	v_pk_add_f32 v[86:87], v[86:87], 1.0 op_sel_hi:[1,0]
	v_pk_mul_f32 v[76:77], v[76:77], v[174:175] op_sel_hi:[1,0]
	v_pk_mul_f32 v[74:75], v[74:75], v[174:175] op_sel_hi:[1,0]
	v_pk_mul_f32 v[72:73], v[72:73], v[174:175] op_sel_hi:[1,0]
	v_pk_mul_f32 v[70:71], v[70:71], v[174:175] op_sel_hi:[1,0]
	v_pk_mul_f32 v[68:69], v[68:69], v[174:175] op_sel_hi:[1,0]
	v_pk_mul_f32 v[66:67], v[66:67], v[174:175] op_sel_hi:[1,0]
	v_div_fixup_f32 v174, v175, v176, 1.0
	v_div_fmas_f32 v176, v178, v186, v188
	v_pk_mul_f32 v[78:79], v[2:3], v[78:79]
	v_pk_mul_f32 v[80:81], v[4:5], v[80:81]
	v_pk_mul_f32 v[64:65], v[64:65], v[174:175] op_sel_hi:[1,0]
	v_pk_mul_f32 v[62:63], v[62:63], v[174:175] op_sel_hi:[1,0]
	v_pk_mul_f32 v[60:61], v[60:61], v[174:175] op_sel_hi:[1,0]
	v_pk_mul_f32 v[58:59], v[58:59], v[174:175] op_sel_hi:[1,0]
	v_pk_mul_f32 v[56:57], v[56:57], v[174:175] op_sel_hi:[1,0]
	v_pk_mul_f32 v[54:55], v[54:55], v[174:175] op_sel_hi:[1,0]
	v_pk_mul_f32 v[52:53], v[52:53], v[174:175] op_sel_hi:[1,0]
	v_pk_mul_f32 v[174:175], v[50:51], v[174:175] op_sel_hi:[1,0]
	v_div_fixup_f32 v50, v176, v177, 1.0
	v_pk_fma_f32 v[80:81], v[88:89], v[80:81], v[84:85]
	v_pk_fma_f32 v[78:79], v[86:87], v[78:79], v[82:83]
	v_pk_mul_f32 v[86:87], v[16:17], v[52:53]
	v_pk_mul_f32 v[48:49], v[48:49], v[50:51] op_sel_hi:[1,0]
	v_pk_mul_f32 v[46:47], v[46:47], v[50:51] op_sel_hi:[1,0]
	v_pk_mul_f32 v[82:83], v[10:11], v[54:55]
	v_pk_mul_f32 v[84:85], v[14:15], v[174:175]
	v_pk_mul_f32 v[88:89], v[2:3], v[46:47]
	v_pk_mul_f32 v[174:175], v[4:5], v[48:49]
	v_cvt_pk_bf16_f32 v46, v78, v79
	v_cvt_pk_bf16_f32 v47, v80, v81
	global_store_dwordx2 v[102:103], v[46:47], off
	global_load_dwordx4 v[46:49], v[152:153], off
	s_nop 0
	global_load_dwordx4 v[52:55], v[148:149], off
	v_pk_mul_f32 v[74:75], v[6:7], v[74:75]
	v_pk_mul_f32 v[76:77], v[8:9], v[76:77]
	v_pk_mul_f32 v[70:71], v[10:11], v[70:71]
	v_pk_mul_f32 v[72:73], v[12:13], v[72:73]
	v_pk_mul_f32 v[66:67], v[66:67], v[14:15]
	v_pk_mul_f32 v[68:69], v[68:69], v[16:17]
	v_pk_mul_f32 v[62:63], v[2:3], v[62:63]
	v_pk_mul_f32 v[64:65], v[4:5], v[64:65]
	v_pk_mul_f32 v[58:59], v[6:7], v[58:59]
	v_pk_mul_f32 v[60:61], v[8:9], v[60:61]
	v_pk_mul_f32 v[56:57], v[12:13], v[56:57]
	v_mul_f32_e32 v196, v23, v23
	v_mul_f32_e32 v202, v25, v25
	v_mul_f32_e32 v214, v18, v18
	v_mul_f32_e32 v215, v19, v19
	v_mul_f32_e32 v216, v20, v20
	v_mul_f32_e32 v217, v21, v21
	v_pk_fma_f32 v[158:159], v[22:23], v[22:23], v[196:197] op_sel_hi:[1,1,0]
	v_pk_fma_f32 v[160:161], v[24:25], v[24:25], v[202:203] op_sel_hi:[1,1,0]
	v_mov_b32_e32 v159, v216
	v_mov_b32_e32 v161, v217
	v_lshl_add_u64 v[144:145], s[20:21], 0, v[90:91]
	v_lshl_add_u64 v[128:129], s[18:19], 0, v[90:91]
	v_lshl_add_u64 v[124:125], s[20:21], 0, v[96:97]
	v_lshl_add_u64 v[120:121], s[18:19], 0, v[96:97]
	s_add_i32 s12, s12, 32
	v_lshl_add_u64 v[92:93], v[92:93], 0, s[14:15]
	v_lshl_add_u64 v[94:95], v[94:95], 0, s[16:17]
	s_cmp_lt_i32 s12, s2
	s_waitcnt vmcnt(0) lgkmcnt(0)
	v_pk_add_f32 v[48:49], v[48:49], 1.0 op_sel_hi:[1,0]
	v_pk_add_f32 v[46:47], v[46:47], 1.0 op_sel_hi:[1,0]
	v_pk_fma_f32 v[48:49], v[48:49], v[76:77], v[54:55]
	v_pk_fma_f32 v[46:47], v[46:47], v[74:75], v[52:53]
	v_cvt_pk_bf16_f32 v46, v46, v47
	v_cvt_pk_bf16_f32 v47, v48, v49
	global_store_dwordx2 v[102:103], v[46:47], off offset:512
	global_load_dwordx4 v[46:49], v[146:147], off
	s_nop 0
	global_load_dwordx4 v[52:55], v[142:143], off
	s_waitcnt vmcnt(0) lgkmcnt(0)
	v_pk_add_f32 v[48:49], v[48:49], 1.0 op_sel_hi:[1,0]
	v_pk_add_f32 v[46:47], v[46:47], 1.0 op_sel_hi:[1,0]
	v_pk_fma_f32 v[48:49], v[72:73], v[48:49], v[54:55]
	v_pk_fma_f32 v[46:47], v[70:71], v[46:47], v[52:53]
	v_cvt_pk_bf16_f32 v46, v46, v47
	v_cvt_pk_bf16_f32 v47, v48, v49
	global_store_dwordx2 v[102:103], v[46:47], off offset:1024
	global_load_dwordx4 v[46:49], v[140:141], off
	s_nop 0
	global_load_dwordx4 v[52:55], v[134:135], off
	s_waitcnt vmcnt(0) lgkmcnt(0)
	v_pk_add_f32 v[48:49], v[48:49], 1.0 op_sel_hi:[1,0]
	v_pk_add_f32 v[46:47], v[46:47], 1.0 op_sel_hi:[1,0]
	v_pk_fma_f32 v[48:49], v[68:69], v[48:49], v[54:55]
	v_pk_fma_f32 v[46:47], v[66:67], v[46:47], v[52:53]
	v_cvt_pk_bf16_f32 v46, v46, v47
	v_cvt_pk_bf16_f32 v47, v48, v49
	global_store_dwordx2 v[102:103], v[46:47], off offset:1536
	global_load_dwordx4 v[46:49], v[138:139], off
	s_nop 0
	global_load_dwordx4 v[52:55], v[132:133], off
	s_waitcnt vmcnt(0) lgkmcnt(0)
	v_pk_add_f32 v[48:49], v[48:49], 1.0 op_sel_hi:[1,0]
	v_pk_add_f32 v[46:47], v[46:47], 1.0 op_sel_hi:[1,0]
	v_pk_fma_f32 v[48:49], v[48:49], v[64:65], v[54:55]
	v_pk_fma_f32 v[46:47], v[46:47], v[62:63], v[52:53]
	v_cvt_pk_bf16_f32 v46, v46, v47
	v_cvt_pk_bf16_f32 v47, v48, v49
	global_store_dwordx2 v[102:103], v[46:47], off offset:2048
	global_load_dwordx4 v[46:49], v[130:131], off
	s_nop 0
	global_load_dwordx4 v[52:55], v[126:127], off
	s_waitcnt vmcnt(0) lgkmcnt(0)
	v_pk_add_f32 v[48:49], v[48:49], 1.0 op_sel_hi:[1,0]
	v_pk_add_f32 v[46:47], v[46:47], 1.0 op_sel_hi:[1,0]
	v_pk_fma_f32 v[48:49], v[48:49], v[60:61], v[54:55]
	v_pk_fma_f32 v[46:47], v[46:47], v[58:59], v[52:53]
	v_cvt_pk_bf16_f32 v46, v46, v47
	v_cvt_pk_bf16_f32 v47, v48, v49
	global_store_dwordx2 v[102:103], v[46:47], off offset:2560
	global_load_dwordx4 v[46:49], v[122:123], off
	s_nop 0
	global_load_dwordx4 v[52:55], v[118:119], off
	v_pk_add_f32 v[58:59], v[164:165], v[164:165] op_sel:[0,1] op_sel_hi:[1,0]
	v_pk_add_f32 v[60:61], v[158:159], v[160:161]
	v_mov_b32_e32 v59, v215
	s_waitcnt vmcnt(0) lgkmcnt(0)
	v_pk_add_f32 v[48:49], v[48:49], 1.0 op_sel_hi:[1,0]
	v_pk_add_f32 v[46:47], v[46:47], 1.0 op_sel_hi:[1,0]
	v_pk_fma_f32 v[48:49], v[48:49], v[56:57], v[54:55]
	v_pk_fma_f32 v[46:47], v[46:47], v[82:83], v[52:53]
	v_cvt_pk_bf16_f32 v46, v46, v47
	v_cvt_pk_bf16_f32 v47, v48, v49
	global_store_dwordx2 v[102:103], v[46:47], off offset:3072
	global_load_dwordx4 v[46:49], v[116:117], off
	s_nop 0
	global_load_dwordx4 v[52:55], v[114:115], off
	v_pk_add_f32 v[56:57], v[162:163], v[162:163] op_sel:[0,1] op_sel_hi:[1,0]
	s_waitcnt vmcnt(0) lgkmcnt(0)
	v_pk_add_f32 v[48:49], v[48:49], 1.0 op_sel_hi:[1,0]
	v_pk_add_f32 v[46:47], v[46:47], 1.0 op_sel_hi:[1,0]
	v_pk_fma_f32 v[48:49], v[86:87], v[48:49], v[54:55]
	v_pk_fma_f32 v[46:47], v[84:85], v[46:47], v[52:53]
	v_cvt_pk_bf16_f32 v46, v46, v47
	v_cvt_pk_bf16_f32 v47, v48, v49
	global_store_dwordx2 v[102:103], v[46:47], off offset:3584
	global_load_dwordx4 v[46:49], v[156:157], off
	s_nop 0
	global_load_dwordx4 v[52:55], v[112:113], off
	v_mov_b32_e32 v57, v214
	s_waitcnt vmcnt(0) lgkmcnt(0)
	v_pk_add_f32 v[48:49], v[48:49], 1.0 op_sel_hi:[1,0]
	v_pk_add_f32 v[46:47], v[46:47], 1.0 op_sel_hi:[1,0]
	v_pk_fma_f32 v[48:49], v[48:49], v[174:175], v[54:55]
	v_pk_fma_f32 v[46:47], v[46:47], v[88:89], v[52:53]
	v_bfe_u32 v51, v46, 16, 1
	v_bfe_u32 v52, v47, 16, 1
	v_add3_u32 v46, v46, v51, s22
	v_add3_u32 v47, v47, v52, s22
	v_lshrrev_b32_e32 v46, 16, v46
	v_and_or_b32 v46, v47, s23, v46
	v_cvt_pk_bf16_f32 v47, v48, v49
	global_store_dwordx2 v[104:105], v[46:47], off
	global_load_dwordx4 v[46:49], v[154:155], off
	s_nop 0
	global_load_dwordx4 v[52:55], v[106:107], off
	v_pk_mul_f32 v[44:45], v[44:45], v[50:51] op_sel_hi:[1,0]
	v_pk_mul_f32 v[42:43], v[42:43], v[50:51] op_sel_hi:[1,0]
	v_pk_mul_f32 v[44:45], v[8:9], v[44:45]
	v_pk_mul_f32 v[42:43], v[6:7], v[42:43]
	s_waitcnt vmcnt(0) lgkmcnt(0)
	v_pk_add_f32 v[48:49], v[48:49], 1.0 op_sel_hi:[1,0]
	v_pk_add_f32 v[46:47], v[46:47], 1.0 op_sel_hi:[1,0]
	v_pk_fma_f32 v[44:45], v[48:49], v[44:45], v[54:55]
	v_pk_fma_f32 v[42:43], v[46:47], v[42:43], v[52:53]
	v_cvt_pk_bf16_f32 v42, v42, v43
	v_cvt_pk_bf16_f32 v43, v44, v45
	global_store_dwordx2 v[104:105], v[42:43], off offset:512
	global_load_dwordx4 v[42:45], v[150:151], off
	s_nop 0
	global_load_dwordx4 v[46:49], v[110:111], off
	v_pk_add_f32 v[52:53], v[56:57], v[58:59]
	s_waitcnt vmcnt(0) lgkmcnt(0)
	v_pk_add_f32 v[44:45], v[44:45], 1.0 op_sel_hi:[1,0]
	v_pk_add_f32 v[52:53], v[52:53], v[60:61]
	v_pk_add_f32 v[42:43], v[42:43], 1.0 op_sel_hi:[1,0]
	v_add_f32_e32 v51, v52, v53
	s_waitcnt lgkmcnt(0)
	s_nop 1
	v_add_f32_dpp v51, v51, v51 quad_perm:[1,0,3,2] row_mask:0xf bank_mask:0xf
	ds_bpermute_b32 v52, v167, v51
	s_waitcnt lgkmcnt(0)
	v_add_f32_e32 v51, v51, v52
	v_pk_mul_f32 v[40:41], v[40:41], v[50:51] op_sel_hi:[1,0]
	v_pk_mul_f32 v[38:39], v[38:39], v[50:51] op_sel_hi:[1,0]
	v_pk_mul_f32 v[40:41], v[12:13], v[40:41]
	v_pk_mul_f32 v[38:39], v[10:11], v[38:39]
	v_pk_fma_f32 v[40:41], v[44:45], v[40:41], v[48:49]
	v_pk_fma_f32 v[38:39], v[42:43], v[38:39], v[46:47]
	v_cvt_pk_bf16_f32 v38, v38, v39
	v_cvt_pk_bf16_f32 v39, v40, v41
	global_store_dwordx2 v[104:105], v[38:39], off offset:1024
	global_load_dwordx4 v[38:41], v[136:137], off
	s_nop 0
	global_load_dwordx4 v[42:45], v[108:109], off
	v_pk_mul_f32 v[36:37], v[36:37], v[50:51] op_sel_hi:[1,0]
	v_pk_mul_f32 v[34:35], v[34:35], v[50:51] op_sel_hi:[1,0]
	v_pk_mul_f32 v[36:37], v[16:17], v[36:37]
	v_pk_mul_f32 v[34:35], v[14:15], v[34:35]
	ds_bpermute_b32 v46, v168, v51
	s_waitcnt lgkmcnt(0)
	v_add_f32_e32 v46, v51, v46
	ds_bpermute_b32 v47, v169, v46
	s_waitcnt lgkmcnt(0)
	v_add_f32_e32 v46, v46, v47
	s_waitcnt lgkmcnt(0)
	v_mov_b32_e32 v47, v46
	s_nop 1
	v_permlane16_swap_b32_e32 v46, v47
	v_add_f32_e32 v46, v46, v47
	s_waitcnt lgkmcnt(0)
	v_mov_b32_e32 v47, v46
	s_nop 1
	v_permlane32_swap_b32_e32 v46, v47
	v_add_f32_e32 v46, v46, v47
	v_fmamk_f32 v46, v46, 0x3a800000, v172
	v_mul_f32_e32 v47, 0x4f800000, v46
	v_cmp_gt_f32_e32 vcc, s13, v46
	s_waitcnt vmcnt(0)
	v_pk_add_f32 v[40:41], v[40:41], 1.0 op_sel_hi:[1,0]
	v_pk_add_f32 v[38:39], v[38:39], 1.0 op_sel_hi:[1,0]
	v_pk_fma_f32 v[36:37], v[36:37], v[40:41], v[44:45]
	v_pk_fma_f32 v[34:35], v[34:35], v[38:39], v[42:43]
	v_cvt_pk_bf16_f32 v34, v34, v35
	v_cvt_pk_bf16_f32 v35, v36, v37
	global_store_dwordx2 v[104:105], v[34:35], off offset:1536
	global_load_dwordx4 v[34:37], v[144:145], off
	s_nop 0
	global_load_dwordx4 v[38:41], v[128:129], off
	v_cndmask_b32_e32 v42, v46, v47, vcc
	v_sqrt_f32_e32 v43, v42
	s_waitcnt vmcnt(0) lgkmcnt(0)
	v_pk_add_f32 v[36:37], v[36:37], 1.0 op_sel_hi:[1,0]
	v_add_u32_e32 v44, -1, v43
	v_add_u32_e32 v45, 1, v43
	v_fma_f32 v46, -v44, v43, v42
	v_fma_f32 v47, -v45, v43, v42
	v_cmp_ge_f32_e64 s[6:7], 0, v46
	v_pk_add_f32 v[34:35], v[34:35], 1.0 op_sel_hi:[1,0]
	s_nop 0
	v_cndmask_b32_e64 v43, v43, v44, s[6:7]
	v_cmp_lt_f32_e64 s[6:7], 0, v47
	s_nop 1
	v_cndmask_b32_e64 v43, v43, v45, s[6:7]
	v_mul_f32_e32 v44, 0x37800000, v43
	v_cndmask_b32_e32 v43, v43, v44, vcc
	v_cmp_class_f32_e32 vcc, v42, v173
	s_nop 1
	v_cndmask_b32_e32 v42, v43, v42, vcc
	v_div_scale_f32 v43, s[6:7], v42, v42, 1.0
	v_rcp_f32_e32 v45, v43
	v_div_scale_f32 v44, vcc, 1.0, v42, 1.0
	v_fma_f32 v46, -v43, v45, 1.0
	v_fmac_f32_e32 v45, v46, v45
	v_mul_f32_e32 v46, v44, v45
	v_fma_f32 v47, -v43, v46, v44
	v_fmac_f32_e32 v46, v47, v45
	v_fma_f32 v43, -v43, v46, v44
	v_div_fmas_f32 v43, v43, v45, v46
	v_div_fixup_f32 v42, v43, v42, 1.0
	v_pk_mul_f32 v[32:33], v[32:33], v[42:43] op_sel_hi:[1,0]
	v_pk_mul_f32 v[30:31], v[30:31], v[42:43] op_sel_hi:[1,0]
	v_pk_mul_f32 v[32:33], v[4:5], v[32:33]
	v_pk_mul_f32 v[30:31], v[2:3], v[30:31]
	v_pk_fma_f32 v[32:33], v[36:37], v[32:33], v[40:41]
	v_pk_fma_f32 v[30:31], v[34:35], v[30:31], v[38:39]
	v_cvt_pk_bf16_f32 v30, v30, v31
	v_cvt_pk_bf16_f32 v31, v32, v33
	global_store_dwordx2 v[104:105], v[30:31], off offset:2048
	global_load_dwordx4 v[30:33], v[124:125], off
	s_nop 0
	global_load_dwordx4 v[34:37], v[120:121], off
	v_pk_mul_f32 v[28:29], v[28:29], v[42:43] op_sel_hi:[1,0]
	v_pk_mul_f32 v[26:27], v[26:27], v[42:43] op_sel_hi:[1,0]
	v_pk_mul_f32 v[28:29], v[8:9], v[28:29]
	v_pk_mul_f32 v[26:27], v[6:7], v[26:27]
	v_lshl_add_u64 v[40:41], s[20:21], 0, v[98:99]
	v_lshl_add_u64 v[38:39], s[18:19], 0, v[98:99]
	v_pk_mul_f32 v[24:25], v[24:25], v[42:43] op_sel_hi:[1,0]
	v_pk_mul_f32 v[22:23], v[22:23], v[42:43] op_sel_hi:[1,0]
	v_pk_mul_f32 v[24:25], v[12:13], v[24:25]
	v_pk_mul_f32 v[22:23], v[10:11], v[22:23]
	v_pk_mul_f32 v[20:21], v[20:21], v[42:43] op_sel_hi:[1,0]
	v_pk_mul_f32 v[18:19], v[18:19], v[42:43] op_sel_hi:[1,0]
	v_pk_mul_f32 v[20:21], v[16:17], v[20:21]
	v_pk_mul_f32 v[18:19], v[14:15], v[18:19]
	s_waitcnt vmcnt(0) lgkmcnt(0)
	v_pk_add_f32 v[32:33], v[32:33], 1.0 op_sel_hi:[1,0]
	v_pk_add_f32 v[30:31], v[30:31], 1.0 op_sel_hi:[1,0]
	v_pk_fma_f32 v[28:29], v[32:33], v[28:29], v[36:37]
	v_pk_fma_f32 v[26:27], v[30:31], v[26:27], v[34:35]
	v_cvt_pk_bf16_f32 v26, v26, v27
	v_cvt_pk_bf16_f32 v27, v28, v29
	global_store_dwordx2 v[104:105], v[26:27], off offset:2560
	global_load_dwordx4 v[26:29], v[40:41], off
	s_nop 0
	global_load_dwordx4 v[30:33], v[38:39], off
	v_lshl_add_u64 v[36:37], s[20:21], 0, v[100:101]
	v_lshl_add_u64 v[34:35], s[18:19], 0, v[100:101]
	s_waitcnt vmcnt(0) lgkmcnt(0)
	v_pk_add_f32 v[28:29], v[28:29], 1.0 op_sel_hi:[1,0]
	v_pk_add_f32 v[26:27], v[26:27], 1.0 op_sel_hi:[1,0]
	v_pk_fma_f32 v[24:25], v[28:29], v[24:25], v[32:33]
	v_pk_fma_f32 v[22:23], v[26:27], v[22:23], v[30:31]
	v_cvt_pk_bf16_f32 v22, v22, v23
	v_cvt_pk_bf16_f32 v23, v24, v25
	global_store_dwordx2 v[104:105], v[22:23], off offset:3072
	global_load_dwordx4 v[22:25], v[36:37], off
	s_nop 0
	global_load_dwordx4 v[26:29], v[34:35], off
	s_waitcnt vmcnt(0) lgkmcnt(0)
	v_pk_add_f32 v[24:25], v[24:25], 1.0 op_sel_hi:[1,0]
	v_pk_add_f32 v[22:23], v[22:23], 1.0 op_sel_hi:[1,0]
	v_pk_fma_f32 v[20:21], v[20:21], v[24:25], v[28:29]
	v_pk_fma_f32 v[18:19], v[18:19], v[22:23], v[26:27]
	v_cvt_pk_bf16_f32 v18, v18, v19
	v_cvt_pk_bf16_f32 v19, v20, v21
	global_store_dwordx2 v[104:105], v[18:19], off offset:3584
	s_cbranch_scc1 .LBB0_2937

.LBB0_3086:
	v_lshl_add_u64 v[18:19], s[68:69], 0, v[94:95]
	v_lshl_add_u64 v[22:23], s[68:69], 0, v[92:93]
	v_add_co_u32_e32 v20, vcc, 0x7800000, v18
	v_add_co_u32_e64 v102, s[6:7], s22, v22
	s_nop 0
	v_addc_co_u32_e32 v21, vcc, 0, v19, vcc
	v_addc_co_u32_e64 v103, s[6:7], 0, v23, s[6:7]
	v_add_co_u32_e64 v104, s[6:7], s23, v22
	v_add_co_u32_e32 v22, vcc, 0x7801000, v18
	s_nop 0
	v_addc_co_u32_e64 v105, s[6:7], 0, v23, s[6:7]
	global_load_dwordx4 v[78:81], v[20:21], off
	global_load_dwordx4 v[74:77], v[20:21], off offset:1024
	global_load_dwordx4 v[70:73], v[20:21], off offset:2048
	global_load_dwordx4 v[66:69], v[20:21], off offset:3072
	v_addc_co_u32_e32 v23, vcc, 0, v19, vcc
	v_add_co_u32_e32 v20, vcc, 0x7802000, v18
	global_load_dwordx4 v[62:65], v[22:23], off
	global_load_dwordx4 v[58:61], v[22:23], off offset:1024
	global_load_dwordx4 v[54:57], v[22:23], off offset:2048
	global_load_dwordx4 v[50:53], v[22:23], off offset:3072
	v_addc_co_u32_e32 v21, vcc, 0, v19, vcc
	v_add_co_u32_e32 v82, vcc, 0x7803000, v18
	global_load_dwordx4 v[46:49], v[20:21], off
	global_load_dwordx4 v[42:45], v[20:21], off offset:1024
	global_load_dwordx4 v[38:41], v[20:21], off offset:2048
	global_load_dwordx4 v[34:37], v[20:21], off offset:3072
	v_addc_co_u32_e32 v83, vcc, 0, v19, vcc
	global_load_dwordx4 v[30:33], v[82:83], off
	global_load_dwordx4 v[26:29], v[82:83], off offset:1024
	global_load_dwordx4 v[22:25], v[82:83], off offset:2048
	global_load_dwordx4 v[18:21], v[82:83], off offset:3072
	s_add_i32 s24, s8, 32
	s_add_i32 s10, s8, 0xffffc022
	s_ashr_i32 s9, s24, 13
	s_cmpk_lt_i32 s24, 0x4000
	s_cselect_b32 s6, s9, s10
	s_mul_hi_i32 s7, s6, 0x9000
	s_mul_i32 s6, s6, 0x9000
	s_add_u32 s10, s4, s6
	s_addc_u32 s11, s5, s7
	s_add_u32 s6, s10, 0x6000
	s_addc_u32 s7, s11, 0
	s_add_u32 s10, s10, 0x7000
	s_addc_u32 s11, s11, 0
	v_lshl_add_u64 v[82:83], s[6:7], 0, v[90:91]
	v_lshl_add_u64 v[86:87], s[10:11], 0, v[90:91]
	global_load_dwordx4 v[82:85], v[82:83], off
	v_lshl_add_u64 v[148:149], s[6:7], 0, v[96:97]
	global_load_dwordx4 v[86:89], v[86:87], off
	v_lshl_add_u64 v[142:143], s[6:7], 0, v[98:99]
	v_lshl_add_u64 v[134:135], s[6:7], 0, v[100:101]
	s_add_i32 s6, s8, 0xffffc023
	s_cmpk_lt_i32 s24, 0x3fff
	s_cselect_b32 s6, s9, s6
	s_mul_hi_i32 s7, s6, 0x9000
	s_mul_i32 s6, s6, 0x9000
	v_lshl_add_u64 v[152:153], s[10:11], 0, v[96:97]
	v_lshl_add_u64 v[146:147], s[10:11], 0, v[98:99]
	v_lshl_add_u64 v[140:141], s[10:11], 0, v[100:101]
	s_add_u32 s10, s4, s6
	s_addc_u32 s11, s5, s7
	s_add_u32 s6, s10, 0x6000
	s_addc_u32 s7, s11, 0
	s_add_u32 s10, s10, 0x7000
	v_lshl_add_u64 v[132:133], s[6:7], 0, v[90:91]
	v_lshl_add_u64 v[126:127], s[6:7], 0, v[96:97]
	v_lshl_add_u64 v[118:119], s[6:7], 0, v[98:99]
	v_lshl_add_u64 v[114:115], s[6:7], 0, v[100:101]
	s_addc_u32 s11, s11, 0
	s_add_i32 s6, s8, 0xffffc024
	s_cmpk_lt_i32 s24, 0x3ffe
	s_cselect_b32 s6, s9, s6
	s_mul_hi_i32 s7, s6, 0x9000
	s_mul_i32 s6, s6, 0x9000
	s_add_u32 s6, s4, s6
	s_addc_u32 s7, s5, s7
	v_lshl_add_u64 v[138:139], s[10:11], 0, v[90:91]
	v_lshl_add_u64 v[130:131], s[10:11], 0, v[96:97]
	v_lshl_add_u64 v[124:125], s[10:11], 0, v[98:99]
	v_lshl_add_u64 v[116:117], s[10:11], 0, v[100:101]
	s_add_u32 s10, s6, 0x6000
	s_addc_u32 s11, s7, 0
	s_add_u32 s6, s6, 0x7000
	s_addc_u32 s7, s7, 0
	s_addk_i32 s8, 0xc025
	s_cmpk_lt_i32 s24, 0x3ffd
	v_lshl_add_u64 v[156:157], s[6:7], 0, v[90:91]
	v_lshl_add_u64 v[154:155], s[6:7], 0, v[96:97]
	v_lshl_add_u64 v[150:151], s[6:7], 0, v[98:99]
	v_lshl_add_u64 v[136:137], s[6:7], 0, v[100:101]
	s_cselect_b32 s6, s9, s8
	s_mul_hi_i32 s7, s6, 0x9000
	s_mul_i32 s6, s6, 0x9000
	s_add_u32 s6, s4, s6
	s_waitcnt vmcnt(0) lgkmcnt(0)
	v_pk_mul_f32 v[158:159], v[80:81], v[80:81]
	v_pk_mul_f32 v[160:161], v[78:79], v[78:79]
	v_pk_mul_f32 v[162:163], v[76:77], v[76:77]
	v_pk_mul_f32 v[164:165], v[74:75], v[74:75]
	v_mul_f32_e32 v174, v71, v71
	v_mul_f32_e32 v176, v73, v73
	v_mul_f32_e32 v187, v68, v68
	v_mul_f32_e32 v189, v69, v69
	v_pk_mov_b32 v[178:179], v[160:161], v[158:159] op_sel:[1,0]
	v_mov_b32_e32 v161, v159
	v_pk_mov_b32 v[158:159], v[164:165], v[162:163] op_sel:[1,0]
	v_mov_b32_e32 v165, v163
	v_pk_fma_f32 v[162:163], v[70:71], v[70:71], v[174:175] op_sel_hi:[1,1,0]
	v_pk_fma_f32 v[174:175], v[72:73], v[72:73], v[176:177] op_sel_hi:[1,1,0]
	v_pk_mul_f32 v[176:177], v[64:65], v[64:65]
	v_pk_mul_f32 v[180:181], v[62:63], v[62:63]
	v_pk_mul_f32 v[182:183], v[60:61], v[60:61]
	v_pk_mul_f32 v[184:185], v[58:59], v[58:59]
	v_mul_f32_e32 v186, v55, v55
	v_mul_f32_e32 v188, v57, v57
	v_pk_add_f32 v[160:161], v[178:179], v[160:161]
	v_pk_add_f32 v[158:159], v[158:159], v[164:165]
	v_mov_b32_e32 v163, v187
	v_mov_b32_e32 v175, v189
	v_pk_mov_b32 v[164:165], v[180:181], v[176:177] op_sel:[1,0]
	v_mov_b32_e32 v181, v177
	v_pk_mov_b32 v[176:177], v[184:185], v[182:183] op_sel:[1,0]
	v_mov_b32_e32 v185, v183
	v_pk_fma_f32 v[178:179], v[54:55], v[54:55], v[186:187] op_sel_hi:[1,1,0]
	v_pk_fma_f32 v[182:183], v[56:57], v[56:57], v[188:189] op_sel_hi:[1,1,0]
	v_pk_mul_f32 v[186:187], v[48:49], v[48:49]
	v_pk_mul_f32 v[188:189], v[46:47], v[46:47]
	v_pk_mul_f32 v[190:191], v[44:45], v[44:45]
	v_pk_mul_f32 v[192:193], v[42:43], v[42:43]
	v_mul_f32_e32 v173, v66, v66
	v_mul_f32_e32 v197, v67, v67
	v_mul_f32_e32 v195, v52, v52
	v_mul_f32_e32 v202, v53, v53
	v_mul_f32_e32 v194, v39, v39
	v_mul_f32_e32 v196, v41, v41
	v_pk_add_f32 v[198:199], v[160:161], v[160:161] op_sel:[0,1] op_sel_hi:[1,0]
	v_pk_add_f32 v[200:201], v[158:159], v[158:159] op_sel:[0,1] op_sel_hi:[1,0]
	v_pk_add_f32 v[174:175], v[162:163], v[174:175]
	v_pk_add_f32 v[158:159], v[164:165], v[180:181]
	v_pk_add_f32 v[160:161], v[176:177], v[184:185]
	v_pk_mov_b32 v[162:163], v[188:189], v[186:187] op_sel:[1,0]
	v_mov_b32_e32 v189, v187
	v_pk_mov_b32 v[164:165], v[192:193], v[190:191] op_sel:[1,0]
	v_mov_b32_e32 v193, v191
	v_mul_f32_e32 v203, v50, v50
	v_mul_f32_e32 v208, v51, v51
	v_mul_f32_e32 v211, v36, v36
	v_mul_f32_e32 v212, v37, v37
	v_mov_b32_e32 v179, v195
	v_mov_b32_e32 v183, v202
	v_pk_fma_f32 v[176:177], v[38:39], v[38:39], v[194:195] op_sel_hi:[1,1,0]
	v_pk_fma_f32 v[180:181], v[40:41], v[40:41], v[196:197] op_sel_hi:[1,1,0]
	v_pk_mul_f32 v[184:185], v[32:33], v[32:33]
	v_pk_mul_f32 v[186:187], v[30:31], v[30:31]
	v_pk_mul_f32 v[190:191], v[28:29], v[28:29]
	v_pk_mul_f32 v[194:195], v[26:27], v[26:27]
	v_mov_b32_e32 v199, v173
	v_mov_b32_e32 v201, v197
	v_pk_add_f32 v[204:205], v[158:159], v[158:159] op_sel:[0,1] op_sel_hi:[1,0]
	v_pk_add_f32 v[206:207], v[160:161], v[160:161] op_sel:[0,1] op_sel_hi:[1,0]
	v_pk_add_f32 v[162:163], v[162:163], v[188:189]
	v_pk_add_f32 v[164:165], v[164:165], v[192:193]
	v_mul_f32_e32 v209, v34, v34
	v_mul_f32_e32 v210, v35, v35
	v_pk_add_f32 v[178:179], v[178:179], v[182:183]
	v_mov_b32_e32 v177, v211
	v_mov_b32_e32 v181, v212
	v_pk_mov_b32 v[182:183], v[186:187], v[184:185] op_sel:[1,0]
	v_mov_b32_e32 v187, v185
	v_pk_mov_b32 v[184:185], v[194:195], v[190:191] op_sel:[1,0]
	v_mov_b32_e32 v195, v191
	v_pk_add_f32 v[188:189], v[198:199], v[200:201]
	v_mov_b32_e32 v205, v203
	v_mov_b32_e32 v207, v208
	v_pk_add_f32 v[190:191], v[162:163], v[162:163] op_sel:[0,1] op_sel_hi:[1,0]
	v_pk_add_f32 v[192:193], v[164:165], v[164:165] op_sel:[0,1] op_sel_hi:[1,0]
	v_pk_add_f32 v[176:177], v[176:177], v[180:181]
	v_pk_add_f32 v[174:175], v[188:189], v[174:175]
	v_pk_add_f32 v[180:181], v[204:205], v[206:207]
	v_mov_b32_e32 v191, v209
	v_mov_b32_e32 v193, v210
	v_add_f32_e32 v173, v174, v175
	v_pk_add_f32 v[174:175], v[180:181], v[178:179]
	v_pk_add_f32 v[178:179], v[190:191], v[192:193]
	v_add_f32_e32 v180, v174, v175
	v_pk_add_f32 v[174:175], v[178:179], v[176:177]
	v_add_f32_e32 v174, v174, v175
	s_addc_u32 s7, s5, s7
	s_waitcnt lgkmcnt(0)
	s_nop 1
	v_add_f32_dpp v173, v173, v173 quad_perm:[1,0,3,2] row_mask:0xf bank_mask:0xf
	s_waitcnt lgkmcnt(0)
	s_nop 1
	v_add_f32_dpp v175, v180, v180 quad_perm:[1,0,3,2] row_mask:0xf bank_mask:0xf
	s_waitcnt lgkmcnt(0)
	s_nop 1
	v_add_f32_dpp v174, v174, v174 quad_perm:[1,0,3,2] row_mask:0xf bank_mask:0xf
	s_waitcnt lgkmcnt(0)
	s_nop 1
	v_add_f32_dpp v173, v173, v173 quad_perm:[2,3,0,1] row_mask:0xf bank_mask:0xf
	s_waitcnt lgkmcnt(0)
	s_nop 1
	v_add_f32_dpp v175, v175, v175 quad_perm:[2,3,0,1] row_mask:0xf bank_mask:0xf
	s_waitcnt lgkmcnt(0)
	s_nop 1
	v_add_f32_dpp v174, v174, v174 quad_perm:[2,3,0,1] row_mask:0xf bank_mask:0xf
	s_waitcnt lgkmcnt(0)
	s_nop 1
	v_add_f32_dpp v173, v173, v173 row_half_mirror row_mask:0xf bank_mask:0xf
	s_waitcnt lgkmcnt(0)
	s_nop 1
	v_add_f32_dpp v175, v175, v175 row_half_mirror row_mask:0xf bank_mask:0xf
	s_waitcnt lgkmcnt(0)
	s_nop 1
	v_add_f32_dpp v174, v174, v174 row_half_mirror row_mask:0xf bank_mask:0xf
	s_waitcnt lgkmcnt(0)
	s_nop 1
	v_add_f32_dpp v173, v173, v173 row_mirror row_mask:0xf bank_mask:0xf
	s_waitcnt lgkmcnt(0)
	s_nop 1
	v_add_f32_dpp v175, v175, v175 row_mirror row_mask:0xf bank_mask:0xf
	s_waitcnt lgkmcnt(0)
	s_nop 1
	v_add_f32_dpp v174, v174, v174 row_mirror row_mask:0xf bank_mask:0xf
	s_waitcnt lgkmcnt(0)
	v_mov_b32_e32 v176, v173
	s_nop 1
	v_permlane16_swap_b32_e32 v173, v176
	v_add_f32_e32 v173, v173, v176
	s_waitcnt lgkmcnt(0)
	v_mov_b32_e32 v178, v175
	s_nop 1
	v_permlane16_swap_b32_e32 v175, v178
	v_add_f32_e32 v175, v175, v178
	s_waitcnt lgkmcnt(0)
	v_mov_b32_e32 v177, v174
	s_nop 1
	v_permlane16_swap_b32_e32 v174, v177
	v_add_f32_e32 v174, v174, v177
	ds_bpermute_b32 v177, v170, v174
	s_waitcnt lgkmcnt(2)
	v_mov_b32_e32 v176, v173
	s_nop 1
	v_permlane32_swap_b32_e32 v173, v176
	v_add_f32_e32 v173, v173, v176
	s_add_u32 s16, s6, 0x6000
	v_fmamk_f32 v173, v173, 0x3a800000, v171
	s_addc_u32 s17, s7, 0
	s_waitcnt lgkmcnt(1)
	v_mov_b32_e32 v178, v175
	s_nop 1
	v_permlane32_swap_b32_e32 v175, v178
	v_add_f32_e32 v175, v175, v178
	v_mul_f32_e32 v176, 0x4f800000, v173
	v_cmp_gt_f32_e32 vcc, s2, v173
	s_add_u32 s18, s6, 0x7000
	v_fmamk_f32 v175, v175, 0x3a800000, v171
	v_cndmask_b32_e32 v173, v173, v176, vcc
	s_addc_u32 s19, s7, 0
	s_waitcnt lgkmcnt(0)
	v_add_f32_e32 v174, v174, v177
	v_mul_f32_e32 v176, 0x4f800000, v175
	v_cmp_gt_f32_e64 s[6:7], s2, v175
	v_sqrt_f32_e32 v177, v173
	v_fmamk_f32 v174, v174, 0x3a800000, v171
	v_cndmask_b32_e64 v175, v175, v176, s[6:7]
	v_mul_f32_e32 v176, 0x4f800000, v174
	v_cmp_gt_f32_e64 s[8:9], s2, v174
	v_sqrt_f32_e32 v178, v175
	v_add_u32_e32 v179, -1, v177
	v_cndmask_b32_e64 v174, v174, v176, s[8:9]
	v_sqrt_f32_e32 v176, v174
	v_add_u32_e32 v180, 1, v177
	v_fma_f32 v181, -v179, v177, v173
	v_lshl_add_u64 v[112:113], s[10:11], 0, v[90:91]
	v_lshl_add_u64 v[106:107], s[10:11], 0, v[96:97]
	v_lshl_add_u64 v[108:109], s[10:11], 0, v[98:99]
	v_lshl_add_u64 v[110:111], s[10:11], 0, v[100:101]
	v_pk_add_f32 v[162:163], v[182:183], v[186:187]
	v_fma_f32 v182, -v180, v177, v173
	v_add_u32_e32 v183, -1, v178
	v_cmp_ge_f32_e64 s[10:11], 0, v181
	v_pk_add_f32 v[164:165], v[184:185], v[194:195]
	v_add_u32_e32 v184, 1, v178
	v_cndmask_b32_e64 v177, v177, v179, s[10:11]
	v_fma_f32 v179, -v183, v178, v175
	v_cmp_lt_f32_e64 s[10:11], 0, v182
	v_fma_f32 v181, -v184, v178, v175
	v_add_u32_e32 v185, -1, v176
	v_cndmask_b32_e64 v177, v177, v180, s[10:11]
	v_cmp_ge_f32_e64 s[10:11], 0, v179
	v_add_u32_e32 v186, 1, v176
	v_fma_f32 v179, -v185, v176, v174
	v_cndmask_b32_e64 v178, v178, v183, s[10:11]
	v_cmp_lt_f32_e64 s[10:11], 0, v181
	v_fma_f32 v180, -v186, v176, v174
	v_mul_f32_e32 v181, 0x37800000, v177
	v_cndmask_b32_e64 v178, v178, v184, s[10:11]
	v_cmp_ge_f32_e64 s[10:11], 0, v179
	v_cndmask_b32_e32 v177, v177, v181, vcc
	v_cmp_class_f32_e32 vcc, v173, v172
	v_cndmask_b32_e64 v176, v176, v185, s[10:11]
	v_cmp_lt_f32_e64 s[10:11], 0, v180
	v_mul_f32_e32 v179, 0x37800000, v178
	v_cndmask_b32_e32 v173, v177, v173, vcc
	v_cndmask_b32_e64 v176, v176, v186, s[10:11]
	v_cndmask_b32_e64 v177, v178, v179, s[6:7]
	v_cmp_class_f32_e32 vcc, v175, v172
	v_mul_f32_e32 v178, 0x37800000, v176
	v_div_scale_f32 v179, s[6:7], v173, v173, 1.0
	v_cndmask_b32_e32 v175, v177, v175, vcc
	v_cndmask_b32_e64 v176, v176, v178, s[8:9]
	v_cmp_class_f32_e32 vcc, v174, v172
	v_rcp_f32_e32 v177, v179
	v_div_scale_f32 v178, s[8:9], v175, v175, 1.0
	v_cndmask_b32_e32 v176, v176, v174, vcc
	v_rcp_f32_e32 v182, v178
	v_div_scale_f32 v183, s[10:11], v176, v176, 1.0
	v_rcp_f32_e32 v185, v183
	v_fma_f32 v174, -v179, v177, 1.0
	v_div_scale_f32 v180, s[6:7], 1.0, v173, 1.0
	v_fmac_f32_e32 v177, v174, v177
	v_fma_f32 v174, -v178, v182, 1.0
	v_mul_f32_e32 v186, v180, v177
	v_div_scale_f32 v181, s[8:9], 1.0, v175, 1.0
	v_fmac_f32_e32 v182, v174, v182
	v_fma_f32 v174, -v183, v185, 1.0
	v_fma_f32 v187, -v179, v186, v180
	v_div_scale_f32 v184, s[10:11], 1.0, v176, 1.0
	v_mul_f32_e32 v188, v181, v182
	v_fmac_f32_e32 v185, v174, v185
	v_fmac_f32_e32 v186, v187, v177
	v_fma_f32 v174, -v178, v188, v181
	v_mul_f32_e32 v187, v184, v185
	v_fma_f32 v179, -v179, v186, v180
	s_mov_b64 vcc, s[6:7]
	v_fmac_f32_e32 v188, v174, v182
	v_fma_f32 v174, -v183, v187, v184
	v_div_fmas_f32 v177, v179, v177, v186
	v_fma_f32 v178, -v178, v188, v181
	v_fmac_f32_e32 v187, v174, v185
	v_div_fixup_f32 v174, v177, v173, 1.0
	s_mov_b64 vcc, s[8:9]
	v_div_fmas_f32 v173, v178, v182, v188
	v_fma_f32 v177, -v183, v187, v184
	v_pk_mul_f32 v[80:81], v[80:81], v[174:175] op_sel_hi:[1,0]
	v_pk_mul_f32 v[78:79], v[78:79], v[174:175] op_sel_hi:[1,0]
	s_mov_b64 vcc, s[10:11]
	v_pk_add_f32 v[88:89], v[88:89], 1.0 op_sel_hi:[1,0]
	v_pk_add_f32 v[86:87], v[86:87], 1.0 op_sel_hi:[1,0]
	v_pk_mul_f32 v[76:77], v[76:77], v[174:175] op_sel_hi:[1,0]
	v_pk_mul_f32 v[74:75], v[74:75], v[174:175] op_sel_hi:[1,0]
	v_pk_mul_f32 v[72:73], v[72:73], v[174:175] op_sel_hi:[1,0]
	v_pk_mul_f32 v[70:71], v[70:71], v[174:175] op_sel_hi:[1,0]
	v_pk_mul_f32 v[68:69], v[68:69], v[174:175] op_sel_hi:[1,0]
	v_pk_mul_f32 v[66:67], v[66:67], v[174:175] op_sel_hi:[1,0]
	v_div_fixup_f32 v174, v173, v175, 1.0
	v_div_fmas_f32 v173, v177, v185, v187
	v_pk_mul_f32 v[78:79], v[2:3], v[78:79]
	v_pk_mul_f32 v[80:81], v[4:5], v[80:81]
	v_pk_mul_f32 v[64:65], v[64:65], v[174:175] op_sel_hi:[1,0]
	v_pk_mul_f32 v[62:63], v[62:63], v[174:175] op_sel_hi:[1,0]
	v_pk_mul_f32 v[60:61], v[60:61], v[174:175] op_sel_hi:[1,0]
	v_pk_mul_f32 v[58:59], v[58:59], v[174:175] op_sel_hi:[1,0]
	v_pk_mul_f32 v[56:57], v[56:57], v[174:175] op_sel_hi:[1,0]
	v_pk_mul_f32 v[54:55], v[54:55], v[174:175] op_sel_hi:[1,0]
	v_pk_mul_f32 v[52:53], v[52:53], v[174:175] op_sel_hi:[1,0]
	v_pk_mul_f32 v[174:175], v[50:51], v[174:175] op_sel_hi:[1,0]
	v_div_fixup_f32 v50, v173, v176, 1.0
	v_pk_fma_f32 v[80:81], v[88:89], v[80:81], v[84:85]
	v_pk_fma_f32 v[78:79], v[86:87], v[78:79], v[82:83]
	v_pk_mul_f32 v[86:87], v[16:17], v[52:53]
	v_pk_mul_f32 v[48:49], v[48:49], v[50:51] op_sel_hi:[1,0]
	v_pk_mul_f32 v[46:47], v[46:47], v[50:51] op_sel_hi:[1,0]
	v_pk_mul_f32 v[82:83], v[10:11], v[54:55]
	v_pk_mul_f32 v[84:85], v[14:15], v[174:175]
	v_pk_mul_f32 v[88:89], v[2:3], v[46:47]
	v_pk_mul_f32 v[174:175], v[4:5], v[48:49]
	v_cvt_pk_bf16_f32 v46, v78, v79
	v_cvt_pk_bf16_f32 v47, v80, v81
	global_store_dwordx2 v[102:103], v[46:47], off
	global_load_dwordx4 v[46:49], v[152:153], off
	s_nop 0
	global_load_dwordx4 v[52:55], v[148:149], off
	v_pk_mul_f32 v[74:75], v[6:7], v[74:75]
	v_pk_mul_f32 v[76:77], v[8:9], v[76:77]
	v_pk_mul_f32 v[70:71], v[10:11], v[70:71]
	v_pk_mul_f32 v[72:73], v[12:13], v[72:73]
	v_pk_mul_f32 v[66:67], v[66:67], v[14:15]
	v_pk_mul_f32 v[68:69], v[68:69], v[16:17]
	v_pk_mul_f32 v[62:63], v[2:3], v[62:63]
	v_pk_mul_f32 v[64:65], v[4:5], v[64:65]
	v_pk_mul_f32 v[58:59], v[6:7], v[58:59]
	v_pk_mul_f32 v[60:61], v[8:9], v[60:61]
	v_pk_mul_f32 v[56:57], v[12:13], v[56:57]
	v_mul_f32_e32 v196, v23, v23
	v_mul_f32_e32 v202, v25, v25
	v_mul_f32_e32 v213, v18, v18
	v_mul_f32_e32 v214, v19, v19
	v_mul_f32_e32 v215, v20, v20
	v_mul_f32_e32 v216, v21, v21
	v_pk_fma_f32 v[158:159], v[22:23], v[22:23], v[196:197] op_sel_hi:[1,1,0]
	v_pk_fma_f32 v[160:161], v[24:25], v[24:25], v[202:203] op_sel_hi:[1,1,0]
	v_mov_b32_e32 v159, v215
	v_mov_b32_e32 v161, v216
	v_lshl_add_u64 v[144:145], s[18:19], 0, v[90:91]
	v_lshl_add_u64 v[128:129], s[16:17], 0, v[90:91]
	v_lshl_add_u64 v[122:123], s[18:19], 0, v[96:97]
	v_lshl_add_u64 v[120:121], s[16:17], 0, v[96:97]
	v_lshl_add_u64 v[92:93], v[92:93], 0, s[12:13]
	v_lshl_add_u64 v[94:95], v[94:95], 0, s[14:15]
	s_mov_b32 s8, s24
	s_cmp_lt_i32 s24, s20
	s_waitcnt vmcnt(0) lgkmcnt(0)
	v_pk_add_f32 v[48:49], v[48:49], 1.0 op_sel_hi:[1,0]
	v_pk_add_f32 v[46:47], v[46:47], 1.0 op_sel_hi:[1,0]
	v_pk_fma_f32 v[48:49], v[48:49], v[76:77], v[54:55]
	v_pk_fma_f32 v[46:47], v[46:47], v[74:75], v[52:53]
	v_cvt_pk_bf16_f32 v46, v46, v47
	v_cvt_pk_bf16_f32 v47, v48, v49
	global_store_dwordx2 v[102:103], v[46:47], off offset:512
	global_load_dwordx4 v[46:49], v[146:147], off
	s_nop 0
	global_load_dwordx4 v[52:55], v[142:143], off
	s_waitcnt vmcnt(0) lgkmcnt(0)
	v_pk_add_f32 v[48:49], v[48:49], 1.0 op_sel_hi:[1,0]
	v_pk_add_f32 v[46:47], v[46:47], 1.0 op_sel_hi:[1,0]
	v_pk_fma_f32 v[48:49], v[72:73], v[48:49], v[54:55]
	v_pk_fma_f32 v[46:47], v[70:71], v[46:47], v[52:53]
	v_cvt_pk_bf16_f32 v46, v46, v47
	v_cvt_pk_bf16_f32 v47, v48, v49
	global_store_dwordx2 v[102:103], v[46:47], off offset:1024
	global_load_dwordx4 v[46:49], v[140:141], off
	s_nop 0
	global_load_dwordx4 v[52:55], v[134:135], off
	s_waitcnt vmcnt(0) lgkmcnt(0)
	v_pk_add_f32 v[48:49], v[48:49], 1.0 op_sel_hi:[1,0]
	v_pk_add_f32 v[46:47], v[46:47], 1.0 op_sel_hi:[1,0]
	v_pk_fma_f32 v[48:49], v[68:69], v[48:49], v[54:55]
	v_pk_fma_f32 v[46:47], v[66:67], v[46:47], v[52:53]
	v_cvt_pk_bf16_f32 v46, v46, v47
	v_cvt_pk_bf16_f32 v47, v48, v49
	global_store_dwordx2 v[102:103], v[46:47], off offset:1536
	global_load_dwordx4 v[46:49], v[138:139], off
	s_nop 0
	global_load_dwordx4 v[52:55], v[132:133], off
	s_waitcnt vmcnt(0) lgkmcnt(0)
	v_pk_add_f32 v[48:49], v[48:49], 1.0 op_sel_hi:[1,0]
	v_pk_add_f32 v[46:47], v[46:47], 1.0 op_sel_hi:[1,0]
	v_pk_fma_f32 v[48:49], v[48:49], v[64:65], v[54:55]
	v_pk_fma_f32 v[46:47], v[46:47], v[62:63], v[52:53]
	v_cvt_pk_bf16_f32 v46, v46, v47
	v_cvt_pk_bf16_f32 v47, v48, v49
	global_store_dwordx2 v[102:103], v[46:47], off offset:2048
	global_load_dwordx4 v[46:49], v[130:131], off
	s_nop 0
	global_load_dwordx4 v[52:55], v[126:127], off
	s_waitcnt vmcnt(0) lgkmcnt(0)
	v_pk_add_f32 v[48:49], v[48:49], 1.0 op_sel_hi:[1,0]
	v_pk_add_f32 v[46:47], v[46:47], 1.0 op_sel_hi:[1,0]
	v_pk_fma_f32 v[48:49], v[48:49], v[60:61], v[54:55]
	v_pk_fma_f32 v[46:47], v[46:47], v[58:59], v[52:53]
	v_cvt_pk_bf16_f32 v46, v46, v47
	v_cvt_pk_bf16_f32 v47, v48, v49
	global_store_dwordx2 v[102:103], v[46:47], off offset:2560
	global_load_dwordx4 v[46:49], v[124:125], off
	s_nop 0
	global_load_dwordx4 v[52:55], v[118:119], off
	v_pk_add_f32 v[58:59], v[164:165], v[164:165] op_sel:[0,1] op_sel_hi:[1,0]
	v_pk_add_f32 v[60:61], v[158:159], v[160:161]
	v_mov_b32_e32 v59, v214
	s_waitcnt vmcnt(0) lgkmcnt(0)
	v_pk_add_f32 v[48:49], v[48:49], 1.0 op_sel_hi:[1,0]
	v_pk_add_f32 v[46:47], v[46:47], 1.0 op_sel_hi:[1,0]
	v_pk_fma_f32 v[48:49], v[48:49], v[56:57], v[54:55]
	v_pk_fma_f32 v[46:47], v[46:47], v[82:83], v[52:53]
	v_cvt_pk_bf16_f32 v46, v46, v47
	v_cvt_pk_bf16_f32 v47, v48, v49
	global_store_dwordx2 v[102:103], v[46:47], off offset:3072
	global_load_dwordx4 v[46:49], v[116:117], off
	s_nop 0
	global_load_dwordx4 v[52:55], v[114:115], off
	v_pk_add_f32 v[56:57], v[162:163], v[162:163] op_sel:[0,1] op_sel_hi:[1,0]
	s_waitcnt vmcnt(0) lgkmcnt(0)
	v_pk_add_f32 v[48:49], v[48:49], 1.0 op_sel_hi:[1,0]
	v_pk_add_f32 v[46:47], v[46:47], 1.0 op_sel_hi:[1,0]
	v_pk_fma_f32 v[48:49], v[86:87], v[48:49], v[54:55]
	v_pk_fma_f32 v[46:47], v[84:85], v[46:47], v[52:53]
	v_cvt_pk_bf16_f32 v46, v46, v47
	v_cvt_pk_bf16_f32 v47, v48, v49
	global_store_dwordx2 v[102:103], v[46:47], off offset:3584
	global_load_dwordx4 v[46:49], v[156:157], off
	s_nop 0
	global_load_dwordx4 v[52:55], v[112:113], off
	v_mov_b32_e32 v57, v213
	s_waitcnt vmcnt(0) lgkmcnt(0)
	v_pk_add_f32 v[48:49], v[48:49], 1.0 op_sel_hi:[1,0]
	v_pk_add_f32 v[46:47], v[46:47], 1.0 op_sel_hi:[1,0]
	v_pk_fma_f32 v[48:49], v[48:49], v[174:175], v[54:55]
	v_pk_fma_f32 v[46:47], v[46:47], v[88:89], v[52:53]
	v_bfe_u32 v51, v46, 16, 1
	v_bfe_u32 v52, v47, 16, 1
	v_add3_u32 v46, v46, v51, s3
	v_add3_u32 v47, v47, v52, s3
	v_lshrrev_b32_e32 v46, 16, v46
	v_and_or_b32 v46, v47, s21, v46
	v_cvt_pk_bf16_f32 v47, v48, v49
	global_store_dwordx2 v[104:105], v[46:47], off
	global_load_dwordx4 v[46:49], v[154:155], off
	s_nop 0
	global_load_dwordx4 v[52:55], v[106:107], off
	v_pk_mul_f32 v[44:45], v[44:45], v[50:51] op_sel_hi:[1,0]
	v_pk_mul_f32 v[42:43], v[42:43], v[50:51] op_sel_hi:[1,0]
	v_pk_mul_f32 v[44:45], v[8:9], v[44:45]
	v_pk_mul_f32 v[42:43], v[6:7], v[42:43]
	s_waitcnt vmcnt(0) lgkmcnt(0)
	v_pk_add_f32 v[48:49], v[48:49], 1.0 op_sel_hi:[1,0]
	v_pk_add_f32 v[46:47], v[46:47], 1.0 op_sel_hi:[1,0]
	v_pk_fma_f32 v[44:45], v[48:49], v[44:45], v[54:55]
	v_pk_fma_f32 v[42:43], v[46:47], v[42:43], v[52:53]
	v_cvt_pk_bf16_f32 v42, v42, v43
	v_cvt_pk_bf16_f32 v43, v44, v45
	global_store_dwordx2 v[104:105], v[42:43], off offset:512
	global_load_dwordx4 v[42:45], v[150:151], off
	s_nop 0
	global_load_dwordx4 v[46:49], v[108:109], off
	v_pk_add_f32 v[52:53], v[56:57], v[58:59]
	s_waitcnt vmcnt(0) lgkmcnt(0)
	v_pk_add_f32 v[44:45], v[44:45], 1.0 op_sel_hi:[1,0]
	v_pk_add_f32 v[52:53], v[52:53], v[60:61]
	v_pk_add_f32 v[42:43], v[42:43], 1.0 op_sel_hi:[1,0]
	v_add_f32_e32 v51, v52, v53
	s_waitcnt lgkmcnt(0)
	s_nop 1
	v_add_f32_dpp v51, v51, v51 quad_perm:[1,0,3,2] row_mask:0xf bank_mask:0xf
	ds_bpermute_b32 v52, v166, v51
	s_waitcnt lgkmcnt(0)
	v_add_f32_e32 v51, v51, v52
	v_pk_mul_f32 v[40:41], v[40:41], v[50:51] op_sel_hi:[1,0]
	v_pk_mul_f32 v[38:39], v[38:39], v[50:51] op_sel_hi:[1,0]
	v_pk_mul_f32 v[40:41], v[12:13], v[40:41]
	v_pk_mul_f32 v[38:39], v[10:11], v[38:39]
	v_pk_fma_f32 v[40:41], v[44:45], v[40:41], v[48:49]
	v_pk_fma_f32 v[38:39], v[42:43], v[38:39], v[46:47]
	v_cvt_pk_bf16_f32 v38, v38, v39
	v_cvt_pk_bf16_f32 v39, v40, v41
	global_store_dwordx2 v[104:105], v[38:39], off offset:1024
	global_load_dwordx4 v[38:41], v[136:137], off
	s_nop 0
	global_load_dwordx4 v[42:45], v[110:111], off
	v_pk_mul_f32 v[36:37], v[36:37], v[50:51] op_sel_hi:[1,0]
	v_pk_mul_f32 v[34:35], v[34:35], v[50:51] op_sel_hi:[1,0]
	v_pk_mul_f32 v[36:37], v[16:17], v[36:37]
	v_pk_mul_f32 v[34:35], v[14:15], v[34:35]
	ds_bpermute_b32 v46, v167, v51
	s_waitcnt lgkmcnt(0)
	v_add_f32_e32 v46, v51, v46
	ds_bpermute_b32 v47, v168, v46
	s_waitcnt lgkmcnt(0)
	v_add_f32_e32 v46, v46, v47
	s_waitcnt lgkmcnt(0)
	v_mov_b32_e32 v47, v46
	s_nop 1
	v_permlane16_swap_b32_e32 v46, v47
	v_add_f32_e32 v46, v46, v47
	s_waitcnt lgkmcnt(0)
	v_mov_b32_e32 v47, v46
	s_nop 1
	v_permlane32_swap_b32_e32 v46, v47
	v_add_f32_e32 v46, v46, v47
	v_fmamk_f32 v46, v46, 0x3a800000, v171
	v_mul_f32_e32 v47, 0x4f800000, v46
	v_cmp_gt_f32_e32 vcc, s2, v46
	s_waitcnt vmcnt(0)
	v_pk_add_f32 v[40:41], v[40:41], 1.0 op_sel_hi:[1,0]
	v_pk_add_f32 v[38:39], v[38:39], 1.0 op_sel_hi:[1,0]
	v_pk_fma_f32 v[36:37], v[36:37], v[40:41], v[44:45]
	v_pk_fma_f32 v[34:35], v[34:35], v[38:39], v[42:43]
	v_cvt_pk_bf16_f32 v34, v34, v35
	v_cvt_pk_bf16_f32 v35, v36, v37
	global_store_dwordx2 v[104:105], v[34:35], off offset:1536
	global_load_dwordx4 v[34:37], v[144:145], off
	s_nop 0
	global_load_dwordx4 v[38:41], v[128:129], off
	v_cndmask_b32_e32 v42, v46, v47, vcc
	v_sqrt_f32_e32 v43, v42
	s_waitcnt vmcnt(0) lgkmcnt(0)
	v_pk_add_f32 v[36:37], v[36:37], 1.0 op_sel_hi:[1,0]
	v_add_u32_e32 v44, -1, v43
	v_add_u32_e32 v45, 1, v43
	v_fma_f32 v46, -v44, v43, v42
	v_fma_f32 v47, -v45, v43, v42
	v_cmp_ge_f32_e64 s[6:7], 0, v46
	v_pk_add_f32 v[34:35], v[34:35], 1.0 op_sel_hi:[1,0]
	s_nop 0
	v_cndmask_b32_e64 v43, v43, v44, s[6:7]
	v_cmp_lt_f32_e64 s[6:7], 0, v47
	s_nop 1
	v_cndmask_b32_e64 v43, v43, v45, s[6:7]
	v_mul_f32_e32 v44, 0x37800000, v43
	v_cndmask_b32_e32 v43, v43, v44, vcc
	v_cmp_class_f32_e32 vcc, v42, v172
	s_nop 1
	v_cndmask_b32_e32 v42, v43, v42, vcc
	v_div_scale_f32 v43, s[6:7], v42, v42, 1.0
	v_rcp_f32_e32 v45, v43
	v_div_scale_f32 v44, vcc, 1.0, v42, 1.0
	v_fma_f32 v46, -v43, v45, 1.0
	v_fmac_f32_e32 v45, v46, v45
	v_mul_f32_e32 v46, v44, v45
	v_fma_f32 v47, -v43, v46, v44
	v_fmac_f32_e32 v46, v47, v45
	v_fma_f32 v43, -v43, v46, v44
	v_div_fmas_f32 v43, v43, v45, v46
	v_div_fixup_f32 v42, v43, v42, 1.0
	v_pk_mul_f32 v[32:33], v[32:33], v[42:43] op_sel_hi:[1,0]
	v_pk_mul_f32 v[30:31], v[30:31], v[42:43] op_sel_hi:[1,0]
	v_pk_mul_f32 v[32:33], v[4:5], v[32:33]
	v_pk_mul_f32 v[30:31], v[2:3], v[30:31]
	v_pk_fma_f32 v[32:33], v[36:37], v[32:33], v[40:41]
	v_pk_fma_f32 v[30:31], v[34:35], v[30:31], v[38:39]
	v_cvt_pk_bf16_f32 v30, v30, v31
	v_cvt_pk_bf16_f32 v31, v32, v33
	global_store_dwordx2 v[104:105], v[30:31], off offset:2048
	global_load_dwordx4 v[30:33], v[122:123], off
	s_nop 0
	global_load_dwordx4 v[34:37], v[120:121], off
	v_pk_mul_f32 v[28:29], v[28:29], v[42:43] op_sel_hi:[1,0]
	v_pk_mul_f32 v[26:27], v[26:27], v[42:43] op_sel_hi:[1,0]
	v_pk_mul_f32 v[28:29], v[8:9], v[28:29]
	v_pk_mul_f32 v[26:27], v[6:7], v[26:27]
	v_lshl_add_u64 v[40:41], s[18:19], 0, v[98:99]
	v_lshl_add_u64 v[38:39], s[16:17], 0, v[98:99]
	v_pk_mul_f32 v[24:25], v[24:25], v[42:43] op_sel_hi:[1,0]
	v_pk_mul_f32 v[22:23], v[22:23], v[42:43] op_sel_hi:[1,0]
	v_pk_mul_f32 v[24:25], v[12:13], v[24:25]
	v_pk_mul_f32 v[22:23], v[10:11], v[22:23]
	v_pk_mul_f32 v[20:21], v[20:21], v[42:43] op_sel_hi:[1,0]
	v_pk_mul_f32 v[18:19], v[18:19], v[42:43] op_sel_hi:[1,0]
	v_pk_mul_f32 v[20:21], v[16:17], v[20:21]
	v_pk_mul_f32 v[18:19], v[14:15], v[18:19]
	s_waitcnt vmcnt(0) lgkmcnt(0)
	v_pk_add_f32 v[32:33], v[32:33], 1.0 op_sel_hi:[1,0]
	v_pk_add_f32 v[30:31], v[30:31], 1.0 op_sel_hi:[1,0]
	v_pk_fma_f32 v[28:29], v[32:33], v[28:29], v[36:37]
	v_pk_fma_f32 v[26:27], v[30:31], v[26:27], v[34:35]
	v_cvt_pk_bf16_f32 v26, v26, v27
	v_cvt_pk_bf16_f32 v27, v28, v29
	global_store_dwordx2 v[104:105], v[26:27], off offset:2560
	global_load_dwordx4 v[26:29], v[40:41], off
	s_nop 0
	global_load_dwordx4 v[30:33], v[38:39], off
	v_lshl_add_u64 v[36:37], s[18:19], 0, v[100:101]
	v_lshl_add_u64 v[34:35], s[16:17], 0, v[100:101]
	s_waitcnt vmcnt(0) lgkmcnt(0)
	v_pk_add_f32 v[28:29], v[28:29], 1.0 op_sel_hi:[1,0]
	v_pk_add_f32 v[26:27], v[26:27], 1.0 op_sel_hi:[1,0]
	v_pk_fma_f32 v[24:25], v[28:29], v[24:25], v[32:33]
	v_pk_fma_f32 v[22:23], v[26:27], v[22:23], v[30:31]
	v_cvt_pk_bf16_f32 v22, v22, v23
	v_cvt_pk_bf16_f32 v23, v24, v25
	global_store_dwordx2 v[104:105], v[22:23], off offset:3072
	global_load_dwordx4 v[22:25], v[36:37], off
	s_nop 0
	global_load_dwordx4 v[26:29], v[34:35], off
	s_waitcnt vmcnt(0) lgkmcnt(0)
	v_pk_add_f32 v[24:25], v[24:25], 1.0 op_sel_hi:[1,0]
	v_pk_add_f32 v[22:23], v[22:23], 1.0 op_sel_hi:[1,0]
	v_pk_fma_f32 v[20:21], v[20:21], v[24:25], v[28:29]
	v_pk_fma_f32 v[18:19], v[18:19], v[22:23], v[26:27]
	v_cvt_pk_bf16_f32 v18, v18, v19
	v_cvt_pk_bf16_f32 v19, v20, v21
	global_store_dwordx2 v[104:105], v[18:19], off offset:3584
	s_cbranch_scc1 .LBB0_3086

.LBB0_3194:
	v_lshl_add_u64 v[18:19], s[12:13], 0, v[94:95]
	v_lshl_add_u64 v[22:23], s[12:13], 0, v[92:93]
	v_add_co_u32_e32 v20, vcc, 0x7800000, v18
	v_add_co_u32_e64 v102, s[6:7], s29, v22
	s_nop 0
	v_addc_co_u32_e32 v21, vcc, 0, v19, vcc
	v_addc_co_u32_e64 v103, s[6:7], 0, v23, s[6:7]
	v_add_co_u32_e64 v104, s[6:7], s30, v22
	v_add_co_u32_e32 v22, vcc, 0x7801000, v18
	s_nop 0
	v_addc_co_u32_e64 v105, s[6:7], 0, v23, s[6:7]
	global_load_dwordx4 v[78:81], v[20:21], off
	global_load_dwordx4 v[74:77], v[20:21], off offset:1024
	global_load_dwordx4 v[70:73], v[20:21], off offset:2048
	global_load_dwordx4 v[66:69], v[20:21], off offset:3072
	v_addc_co_u32_e32 v23, vcc, 0, v19, vcc
	v_add_co_u32_e32 v20, vcc, 0x7802000, v18
	global_load_dwordx4 v[62:65], v[22:23], off
	global_load_dwordx4 v[58:61], v[22:23], off offset:1024
	global_load_dwordx4 v[54:57], v[22:23], off offset:2048
	global_load_dwordx4 v[50:53], v[22:23], off offset:3072
	v_addc_co_u32_e32 v21, vcc, 0, v19, vcc
	global_load_dwordx4 v[46:49], v[20:21], off
	global_load_dwordx4 v[42:45], v[20:21], off offset:1024
	global_load_dwordx4 v[38:41], v[20:21], off offset:2048
	global_load_dwordx4 v[34:37], v[20:21], off offset:3072
	v_add_co_u32_e32 v82, vcc, 0x7803000, v18
	s_ashr_i32 s8, s24, 13
	s_nop 0
	v_addc_co_u32_e32 v83, vcc, 0, v19, vcc
	global_load_dwordx4 v[30:33], v[82:83], off
	global_load_dwordx4 v[26:29], v[82:83], off offset:1024
	global_load_dwordx4 v[22:25], v[82:83], off offset:2048
	global_load_dwordx4 v[18:21], v[82:83], off offset:3072
	s_add_i32 s9, s24, 0xffffc002
	s_cmpk_lt_i32 s24, 0x4000
	s_cselect_b32 s6, s8, s9
	s_addk_i32 s6, 0x82
	s_mul_hi_i32 s7, s6, 0x9000
	s_mul_i32 s6, s6, 0x9000
	s_add_u32 s6, s14, s6
	s_addc_u32 s7, s15, s7
	s_add_u32 s10, s6, 0x1000
	s_addc_u32 s11, s7, 0
	v_lshl_add_u64 v[124:125], s[6:7], 0, v[90:91]
	v_lshl_add_u64 v[86:87], s[10:11], 0, v[90:91]
	global_load_dwordx4 v[82:85], v[124:125], off
	s_add_i32 s6, s24, 0xffffc003
	global_load_dwordx4 v[86:89], v[86:87], off
	s_cmpk_lt_i32 s24, 0x3fff
	s_cselect_b32 s6, s8, s6
	s_addk_i32 s6, 0x82
	s_mul_hi_i32 s7, s6, 0x9000
	s_mul_i32 s6, s6, 0x9000
	s_add_u32 s6, s14, s6
	s_addc_u32 s7, s15, s7
	v_lshl_add_u64 v[134:135], s[10:11], 0, v[96:97]
	v_lshl_add_u64 v[130:131], s[10:11], 0, v[98:99]
	v_lshl_add_u64 v[128:129], s[10:11], 0, v[100:101]
	s_add_u32 s10, s6, 0x1000
	v_lshl_add_u64 v[110:111], s[6:7], 0, v[90:91]
	s_addc_u32 s11, s7, 0
	s_add_i32 s6, s24, 0xffffc004
	s_cmpk_lt_i32 s24, 0x3ffe
	s_cselect_b32 s6, s8, s6
	s_addk_i32 s6, 0x82
	s_mul_hi_i32 s7, s6, 0x9000
	s_mul_i32 s6, s6, 0x9000
	v_lshl_add_u64 v[126:127], s[10:11], 0, v[90:91]
	v_lshl_add_u64 v[120:121], s[10:11], 0, v[96:97]
	v_lshl_add_u64 v[116:117], s[10:11], 0, v[98:99]
	v_lshl_add_u64 v[112:113], s[10:11], 0, v[100:101]
	s_add_u32 s10, s14, s6
	s_addc_u32 s11, s15, s7
	s_add_u32 s6, s10, 0x1000
	s_addc_u32 s7, s11, 0
	s_add_i32 s9, s24, 0xffffc005
	s_cmpk_lt_i32 s24, 0x3ffd
	v_lshl_add_u64 v[138:139], s[6:7], 0, v[90:91]
	v_lshl_add_u64 v[136:137], s[6:7], 0, v[96:97]
	v_lshl_add_u64 v[132:133], s[6:7], 0, v[98:99]
	v_lshl_add_u64 v[122:123], s[6:7], 0, v[100:101]
	s_cselect_b32 s6, s8, s9
	s_addk_i32 s6, 0x82
	s_mul_hi_i32 s7, s6, 0x9000
	s_mul_i32 s6, s6, 0x9000
	s_add_u32 s6, s14, s6
	s_addc_u32 s7, s15, s7
	s_add_u32 s40, s6, 0x1000
	v_lshl_add_u64 v[106:107], s[6:7], 0, v[90:91]
	s_addc_u32 s41, s7, 0
	v_lshl_add_u64 v[108:109], s[10:11], 0, v[90:91]
	v_lshl_add_u64 v[118:119], s[40:41], 0, v[90:91]
	v_lshl_add_u64 v[114:115], s[40:41], 0, v[96:97]
	s_add_i32 s24, s24, 32
	v_lshl_add_u64 v[92:93], v[92:93], 0, s[26:27]
	s_waitcnt vmcnt(0) lgkmcnt(0)
	v_pk_mul_f32 v[140:141], v[80:81], v[80:81]
	v_pk_mul_f32 v[142:143], v[78:79], v[78:79]
	v_pk_mul_f32 v[144:145], v[76:77], v[76:77]
	v_pk_mul_f32 v[146:147], v[74:75], v[74:75]
	v_mul_f32_e32 v156, v71, v71
	v_mul_f32_e32 v158, v73, v73
	v_pk_mov_b32 v[160:161], v[142:143], v[140:141] op_sel:[1,0]
	v_mov_b32_e32 v143, v141
	v_pk_mov_b32 v[140:141], v[146:147], v[144:145] op_sel:[1,0]
	v_mov_b32_e32 v147, v145
	v_mul_f32_e32 v169, v68, v68
	v_mul_f32_e32 v171, v69, v69
	v_pk_fma_f32 v[144:145], v[70:71], v[70:71], v[156:157] op_sel_hi:[1,1,0]
	v_pk_fma_f32 v[156:157], v[72:73], v[72:73], v[158:159] op_sel_hi:[1,1,0]
	v_pk_mul_f32 v[158:159], v[64:65], v[64:65]
	v_pk_mul_f32 v[162:163], v[62:63], v[62:63]
	v_pk_mul_f32 v[164:165], v[60:61], v[60:61]
	v_pk_mul_f32 v[166:167], v[58:59], v[58:59]
	v_mul_f32_e32 v168, v55, v55
	v_mul_f32_e32 v170, v57, v57
	v_pk_add_f32 v[142:143], v[160:161], v[142:143]
	v_pk_add_f32 v[140:141], v[140:141], v[146:147]
	v_mul_f32_e32 v155, v66, v66
	v_mul_f32_e32 v179, v67, v67
	v_mov_b32_e32 v145, v169
	v_mov_b32_e32 v157, v171
	v_pk_mov_b32 v[146:147], v[162:163], v[158:159] op_sel:[1,0]
	v_mov_b32_e32 v163, v159
	v_pk_mov_b32 v[158:159], v[166:167], v[164:165] op_sel:[1,0]
	v_mov_b32_e32 v167, v165
	v_pk_fma_f32 v[160:161], v[54:55], v[54:55], v[168:169] op_sel_hi:[1,1,0]
	v_pk_fma_f32 v[164:165], v[56:57], v[56:57], v[170:171] op_sel_hi:[1,1,0]
	v_pk_mul_f32 v[168:169], v[48:49], v[48:49]
	v_pk_mul_f32 v[170:171], v[46:47], v[46:47]
	v_pk_add_f32 v[180:181], v[142:143], v[142:143] op_sel:[0,1] op_sel_hi:[1,0]
	v_pk_add_f32 v[182:183], v[140:141], v[140:141] op_sel:[0,1] op_sel_hi:[1,0]
	v_mul_f32_e32 v177, v52, v52
	v_pk_mul_f32 v[172:173], v[44:45], v[44:45]
	v_pk_mul_f32 v[174:175], v[42:43], v[42:43]
	v_mul_f32_e32 v176, v39, v39
	v_mul_f32_e32 v178, v41, v41
	v_pk_add_f32 v[156:157], v[144:145], v[156:157]
	v_pk_add_f32 v[140:141], v[146:147], v[162:163]
	v_pk_add_f32 v[142:143], v[158:159], v[166:167]
	v_pk_mov_b32 v[144:145], v[170:171], v[168:169] op_sel:[1,0]
	v_mov_b32_e32 v171, v169
	v_mov_b32_e32 v181, v155
	v_mov_b32_e32 v183, v179
	v_mul_f32_e32 v185, v50, v50
	v_mul_f32_e32 v190, v51, v51
	v_mul_f32_e32 v184, v53, v53
	v_mul_f32_e32 v193, v36, v36
	v_mul_f32_e32 v194, v37, v37
	v_pk_mov_b32 v[146:147], v[174:175], v[172:173] op_sel:[1,0]
	v_mov_b32_e32 v175, v173
	v_pk_fma_f32 v[158:159], v[38:39], v[38:39], v[176:177] op_sel_hi:[1,1,0]
	v_pk_fma_f32 v[162:163], v[40:41], v[40:41], v[178:179] op_sel_hi:[1,1,0]
	v_pk_add_f32 v[186:187], v[140:141], v[140:141] op_sel:[0,1] op_sel_hi:[1,0]
	v_pk_add_f32 v[188:189], v[142:143], v[142:143] op_sel:[0,1] op_sel_hi:[1,0]
	v_pk_add_f32 v[144:145], v[144:145], v[170:171]
	v_pk_add_f32 v[170:171], v[180:181], v[182:183]
	v_mov_b32_e32 v161, v177
	v_mov_b32_e32 v165, v184
	v_pk_mul_f32 v[166:167], v[32:33], v[32:33]
	v_pk_mul_f32 v[168:169], v[30:31], v[30:31]
	v_pk_mul_f32 v[172:173], v[28:29], v[28:29]
	v_pk_mul_f32 v[176:177], v[26:27], v[26:27]
	v_pk_add_f32 v[146:147], v[146:147], v[174:175]
	v_mov_b32_e32 v159, v193
	v_mov_b32_e32 v163, v194
	v_mov_b32_e32 v187, v185
	v_mov_b32_e32 v189, v190
	v_pk_add_f32 v[156:157], v[170:171], v[156:157]
	v_mul_f32_e32 v191, v34, v34
	v_mul_f32_e32 v192, v35, v35
	v_pk_add_f32 v[160:161], v[160:161], v[164:165]
	v_pk_mov_b32 v[164:165], v[168:169], v[166:167] op_sel:[1,0]
	v_mov_b32_e32 v169, v167
	v_pk_mov_b32 v[166:167], v[176:177], v[172:173] op_sel:[1,0]
	v_mov_b32_e32 v177, v173
	v_pk_add_f32 v[172:173], v[144:145], v[144:145] op_sel:[0,1] op_sel_hi:[1,0]
	v_pk_add_f32 v[174:175], v[146:147], v[146:147] op_sel:[0,1] op_sel_hi:[1,0]
	v_pk_add_f32 v[158:159], v[158:159], v[162:163]
	v_pk_add_f32 v[162:163], v[186:187], v[188:189]
	v_add_f32_e32 v155, v156, v157
	v_mov_b32_e32 v173, v191
	v_mov_b32_e32 v175, v192
	v_pk_add_f32 v[156:157], v[162:163], v[160:161]
	ds_bpermute_b32 v163, v1, v155
	v_pk_add_f32 v[160:161], v[172:173], v[174:175]
	v_add_f32_e32 v162, v156, v157
	v_pk_add_f32 v[156:157], v[160:161], v[158:159]
	v_add_f32_e32 v156, v156, v157
	s_waitcnt lgkmcnt(0)
	v_add_f32_e32 v155, v155, v163
	s_waitcnt lgkmcnt(0)
	s_nop 1
	v_add_f32_dpp v158, v162, v162 quad_perm:[1,0,3,2] row_mask:0xf bank_mask:0xf
	s_waitcnt lgkmcnt(0)
	s_nop 1
	v_add_f32_dpp v156, v156, v156 quad_perm:[1,0,3,2] row_mask:0xf bank_mask:0xf
	s_waitcnt lgkmcnt(0)
	s_nop 1
	v_add_f32_dpp v155, v155, v155 quad_perm:[2,3,0,1] row_mask:0xf bank_mask:0xf
	ds_bpermute_b32 v159, v149, v155
	s_waitcnt lgkmcnt(2)
	s_nop 1
	v_add_f32_dpp v158, v158, v158 quad_perm:[2,3,0,1] row_mask:0xf bank_mask:0xf
	s_waitcnt lgkmcnt(0)
	s_nop 1
	v_add_f32_dpp v156, v156, v156 quad_perm:[2,3,0,1] row_mask:0xf bank_mask:0xf
	s_waitcnt lgkmcnt(0)
	v_add_f32_e32 v155, v155, v159
	ds_bpermute_b32 v159, v150, v155
	s_waitcnt lgkmcnt(2)
	s_nop 1
	v_add_f32_dpp v158, v158, v158 row_half_mirror row_mask:0xf bank_mask:0xf
	s_waitcnt lgkmcnt(0)
	s_nop 1
	v_add_f32_dpp v156, v156, v156 row_half_mirror row_mask:0xf bank_mask:0xf
	s_waitcnt lgkmcnt(0)
	v_add_f32_e32 v155, v155, v159
	s_waitcnt lgkmcnt(0)
	s_nop 1
	v_add_f32_dpp v158, v158, v158 row_mirror row_mask:0xf bank_mask:0xf
	s_waitcnt lgkmcnt(0)
	s_nop 1
	v_add_f32_dpp v156, v156, v156 row_mirror row_mask:0xf bank_mask:0xf
	s_waitcnt lgkmcnt(0)
	v_mov_b32_e32 v159, v155
	s_nop 1
	v_permlane16_swap_b32_e32 v155, v159
	v_add_f32_e32 v155, v155, v159
	s_waitcnt lgkmcnt(0)
	v_mov_b32_e32 v160, v158
	s_nop 1
	v_permlane16_swap_b32_e32 v158, v160
	v_add_f32_e32 v158, v158, v160
	s_waitcnt lgkmcnt(0)
	v_mov_b32_e32 v157, v156
	s_nop 1
	v_permlane16_swap_b32_e32 v156, v157
	v_add_f32_e32 v156, v156, v157
	s_waitcnt lgkmcnt(0)
	v_mov_b32_e32 v159, v155
	s_nop 1
	v_permlane32_swap_b32_e32 v155, v159
	v_add_f32_e32 v155, v155, v159
	v_fmamk_f32 v155, v155, 0x3a800000, v153
	s_waitcnt lgkmcnt(1)
	v_mov_b32_e32 v160, v158
	s_nop 1
	v_permlane32_swap_b32_e32 v158, v160
	v_add_f32_e32 v158, v158, v160
	v_mul_f32_e32 v159, 0x4f800000, v155
	v_cmp_gt_f32_e32 vcc, s17, v155
	v_fmamk_f32 v158, v158, 0x3a800000, v153
	s_waitcnt lgkmcnt(0)
	v_mov_b32_e32 v157, v156
	s_nop 1
	v_permlane32_swap_b32_e32 v156, v157
	v_add_f32_e32 v156, v156, v157
	v_cndmask_b32_e32 v155, v155, v159, vcc
	v_mul_f32_e32 v157, 0x4f800000, v158
	v_cmp_gt_f32_e64 s[6:7], s17, v158
	v_sqrt_f32_e32 v159, v155
	v_fmamk_f32 v156, v156, 0x3a800000, v153
	v_cndmask_b32_e64 v157, v158, v157, s[6:7]
	v_mul_f32_e32 v158, 0x4f800000, v156
	v_cmp_gt_f32_e64 s[8:9], s17, v156
	v_sqrt_f32_e32 v160, v157
	v_add_u32_e32 v161, -1, v159
	v_cndmask_b32_e64 v156, v156, v158, s[8:9]
	v_sqrt_f32_e32 v158, v156
	v_add_u32_e32 v162, 1, v159
	v_fma_f32 v163, -v161, v159, v155
	v_pk_add_f32 v[144:145], v[164:165], v[168:169]
	v_fma_f32 v164, -v162, v159, v155
	v_add_u32_e32 v165, -1, v160
	v_cmp_ge_f32_e64 s[10:11], 0, v163
	v_pk_add_f32 v[146:147], v[166:167], v[176:177]
	v_add_u32_e32 v166, 1, v160
	v_cndmask_b32_e64 v159, v159, v161, s[10:11]
	v_fma_f32 v161, -v165, v160, v157
	v_cmp_lt_f32_e64 s[10:11], 0, v164
	v_fma_f32 v163, -v166, v160, v157
	v_add_u32_e32 v167, -1, v158
	v_cndmask_b32_e64 v159, v159, v162, s[10:11]
	v_cmp_ge_f32_e64 s[10:11], 0, v161
	v_add_u32_e32 v168, 1, v158
	v_fma_f32 v161, -v167, v158, v156
	v_cndmask_b32_e64 v160, v160, v165, s[10:11]
	v_cmp_lt_f32_e64 s[10:11], 0, v163
	v_fma_f32 v162, -v168, v158, v156
	v_mul_f32_e32 v163, 0x37800000, v159
	v_cndmask_b32_e64 v160, v160, v166, s[10:11]
	v_cmp_ge_f32_e64 s[10:11], 0, v161
	v_cndmask_b32_e32 v159, v159, v163, vcc
	v_cmp_class_f32_e32 vcc, v155, v154
	v_cndmask_b32_e64 v158, v158, v167, s[10:11]
	v_cmp_lt_f32_e64 s[10:11], 0, v162
	v_mul_f32_e32 v161, 0x37800000, v160
	v_cndmask_b32_e32 v155, v159, v155, vcc
	v_cndmask_b32_e64 v158, v158, v168, s[10:11]
	v_cndmask_b32_e64 v159, v160, v161, s[6:7]
	v_cmp_class_f32_e32 vcc, v157, v154
	v_mul_f32_e32 v160, 0x37800000, v158
	v_div_scale_f32 v161, s[6:7], v155, v155, 1.0
	v_cndmask_b32_e32 v157, v159, v157, vcc
	v_cndmask_b32_e64 v158, v158, v160, s[8:9]
	v_cmp_class_f32_e32 vcc, v156, v154
	v_rcp_f32_e32 v159, v161
	v_div_scale_f32 v160, s[8:9], v157, v157, 1.0
	v_cndmask_b32_e32 v158, v158, v156, vcc
	v_rcp_f32_e32 v164, v160
	v_div_scale_f32 v165, s[10:11], v158, v158, 1.0
	v_rcp_f32_e32 v167, v165
	v_fma_f32 v156, -v161, v159, 1.0
	v_div_scale_f32 v162, s[6:7], 1.0, v155, 1.0
	v_fmac_f32_e32 v159, v156, v159
	v_fma_f32 v156, -v160, v164, 1.0
	v_mul_f32_e32 v168, v162, v159
	v_div_scale_f32 v163, s[8:9], 1.0, v157, 1.0
	v_fmac_f32_e32 v164, v156, v164
	v_fma_f32 v156, -v165, v167, 1.0
	v_fma_f32 v169, -v161, v168, v162
	v_div_scale_f32 v166, s[10:11], 1.0, v158, 1.0
	v_mul_f32_e32 v170, v163, v164
	v_fmac_f32_e32 v167, v156, v167
	v_fmac_f32_e32 v168, v169, v159
	v_fma_f32 v156, -v160, v170, v163
	v_mul_f32_e32 v169, v166, v167
	v_fma_f32 v161, -v161, v168, v162
	s_mov_b64 vcc, s[6:7]
	v_fmac_f32_e32 v170, v156, v164
	v_fma_f32 v156, -v165, v169, v166
	v_div_fmas_f32 v159, v161, v159, v168
	v_fma_f32 v160, -v160, v170, v163
	v_fmac_f32_e32 v169, v156, v167
	v_div_fixup_f32 v156, v159, v155, 1.0
	s_mov_b64 vcc, s[8:9]
	v_div_fmas_f32 v155, v160, v164, v170
	v_fma_f32 v159, -v165, v169, v166
	v_pk_mul_f32 v[80:81], v[80:81], v[156:157] op_sel_hi:[1,0]
	v_pk_mul_f32 v[78:79], v[78:79], v[156:157] op_sel_hi:[1,0]
	s_mov_b64 vcc, s[10:11]
	v_pk_add_f32 v[88:89], v[88:89], 1.0 op_sel_hi:[1,0]
	v_pk_add_f32 v[86:87], v[86:87], 1.0 op_sel_hi:[1,0]
	v_pk_mul_f32 v[76:77], v[76:77], v[156:157] op_sel_hi:[1,0]
	v_pk_mul_f32 v[74:75], v[74:75], v[156:157] op_sel_hi:[1,0]
	v_pk_mul_f32 v[72:73], v[72:73], v[156:157] op_sel_hi:[1,0]
	v_pk_mul_f32 v[70:71], v[70:71], v[156:157] op_sel_hi:[1,0]
	v_pk_mul_f32 v[68:69], v[68:69], v[156:157] op_sel_hi:[1,0]
	v_pk_mul_f32 v[66:67], v[66:67], v[156:157] op_sel_hi:[1,0]
	v_div_fixup_f32 v156, v155, v157, 1.0
	v_div_fmas_f32 v155, v159, v167, v169
	v_pk_mul_f32 v[78:79], v[78:79], v[2:3]
	v_pk_mul_f32 v[80:81], v[80:81], v[4:5]
	v_pk_mul_f32 v[64:65], v[64:65], v[156:157] op_sel_hi:[1,0]
	v_pk_mul_f32 v[62:63], v[62:63], v[156:157] op_sel_hi:[1,0]
	v_pk_mul_f32 v[60:61], v[60:61], v[156:157] op_sel_hi:[1,0]
	v_pk_mul_f32 v[58:59], v[58:59], v[156:157] op_sel_hi:[1,0]
	v_pk_mul_f32 v[56:57], v[56:57], v[156:157] op_sel_hi:[1,0]
	v_pk_mul_f32 v[54:55], v[54:55], v[156:157] op_sel_hi:[1,0]
	v_pk_mul_f32 v[52:53], v[52:53], v[156:157] op_sel_hi:[1,0]
	v_pk_mul_f32 v[156:157], v[50:51], v[156:157] op_sel_hi:[1,0]
	v_div_fixup_f32 v50, v155, v158, 1.0
	v_pk_fma_f32 v[80:81], v[80:81], v[88:89], v[84:85]
	v_pk_fma_f32 v[78:79], v[78:79], v[86:87], v[82:83]
	v_pk_mul_f32 v[86:87], v[52:53], v[16:17]
	v_pk_mul_f32 v[48:49], v[48:49], v[50:51] op_sel_hi:[1,0]
	v_pk_mul_f32 v[46:47], v[46:47], v[50:51] op_sel_hi:[1,0]
	v_pk_mul_f32 v[82:83], v[54:55], v[10:11]
	v_pk_mul_f32 v[84:85], v[156:157], v[14:15]
	v_pk_mul_f32 v[88:89], v[46:47], v[2:3]
	v_pk_mul_f32 v[156:157], v[48:49], v[4:5]
	v_cvt_pk_bf16_f32 v46, v78, v79
	v_cvt_pk_bf16_f32 v47, v80, v81
	global_store_dwordx2 v[102:103], v[46:47], off
	global_load_dwordx4 v[46:49], v[134:135], off
	s_nop 0
	global_load_dwordx4 v[52:55], v[124:125], off offset:1024
	v_pk_mul_f32 v[74:75], v[74:75], v[6:7]
	v_pk_mul_f32 v[76:77], v[76:77], v[8:9]
	v_pk_mul_f32 v[70:71], v[70:71], v[10:11]
	v_pk_mul_f32 v[72:73], v[72:73], v[12:13]
	v_pk_mul_f32 v[66:67], v[66:67], v[14:15]
	v_pk_mul_f32 v[68:69], v[68:69], v[16:17]
	v_pk_mul_f32 v[62:63], v[62:63], v[2:3]
	v_pk_mul_f32 v[64:65], v[64:65], v[4:5]
	v_pk_mul_f32 v[58:59], v[58:59], v[6:7]
	v_pk_mul_f32 v[60:61], v[60:61], v[8:9]
	v_pk_mul_f32 v[56:57], v[56:57], v[12:13]
	v_mul_f32_e32 v178, v23, v23
	v_mul_f32_e32 v184, v25, v25
	v_mul_f32_e32 v195, v18, v18
	v_mul_f32_e32 v196, v19, v19
	v_mul_f32_e32 v197, v20, v20
	v_mul_f32_e32 v198, v21, v21
	v_pk_fma_f32 v[140:141], v[22:23], v[22:23], v[178:179] op_sel_hi:[1,1,0]
	v_pk_fma_f32 v[142:143], v[24:25], v[24:25], v[184:185] op_sel_hi:[1,1,0]
	v_mov_b32_e32 v141, v197
	v_mov_b32_e32 v143, v198
	v_lshl_add_u64 v[94:95], v[94:95], 0, s[38:39]
	s_cmp_lt_i32 s24, s5
	s_waitcnt vmcnt(0) lgkmcnt(0)
	v_pk_add_f32 v[48:49], v[48:49], 1.0 op_sel_hi:[1,0]
	v_pk_add_f32 v[46:47], v[46:47], 1.0 op_sel_hi:[1,0]
	v_pk_fma_f32 v[48:49], v[76:77], v[48:49], v[54:55]
	v_pk_fma_f32 v[46:47], v[74:75], v[46:47], v[52:53]
	v_cvt_pk_bf16_f32 v46, v46, v47
	v_cvt_pk_bf16_f32 v47, v48, v49
	global_store_dwordx2 v[102:103], v[46:47], off offset:512
	global_load_dwordx4 v[46:49], v[130:131], off
	s_nop 0
	global_load_dwordx4 v[52:55], v[124:125], off offset:2048
	s_waitcnt vmcnt(0) lgkmcnt(0)
	v_pk_add_f32 v[48:49], v[48:49], 1.0 op_sel_hi:[1,0]
	v_pk_add_f32 v[46:47], v[46:47], 1.0 op_sel_hi:[1,0]
	v_pk_fma_f32 v[48:49], v[72:73], v[48:49], v[54:55]
	v_pk_fma_f32 v[46:47], v[70:71], v[46:47], v[52:53]
	v_cvt_pk_bf16_f32 v46, v46, v47
	v_cvt_pk_bf16_f32 v47, v48, v49
	global_store_dwordx2 v[102:103], v[46:47], off offset:1024
	global_load_dwordx4 v[46:49], v[128:129], off
	s_nop 0
	global_load_dwordx4 v[52:55], v[124:125], off offset:3072
	s_waitcnt vmcnt(0) lgkmcnt(0)
	v_pk_add_f32 v[48:49], v[48:49], 1.0 op_sel_hi:[1,0]
	v_pk_add_f32 v[46:47], v[46:47], 1.0 op_sel_hi:[1,0]
	v_pk_fma_f32 v[48:49], v[68:69], v[48:49], v[54:55]
	v_pk_fma_f32 v[46:47], v[66:67], v[46:47], v[52:53]
	v_cvt_pk_bf16_f32 v46, v46, v47
	v_cvt_pk_bf16_f32 v47, v48, v49
	global_store_dwordx2 v[102:103], v[46:47], off offset:1536
	global_load_dwordx4 v[46:49], v[126:127], off
	s_nop 0
	global_load_dwordx4 v[52:55], v[110:111], off
	s_waitcnt vmcnt(0) lgkmcnt(0)
	v_pk_add_f32 v[48:49], v[48:49], 1.0 op_sel_hi:[1,0]
	v_pk_add_f32 v[46:47], v[46:47], 1.0 op_sel_hi:[1,0]
	v_pk_fma_f32 v[48:49], v[64:65], v[48:49], v[54:55]
	v_pk_fma_f32 v[46:47], v[62:63], v[46:47], v[52:53]
	v_cvt_pk_bf16_f32 v46, v46, v47
	v_cvt_pk_bf16_f32 v47, v48, v49
	global_store_dwordx2 v[102:103], v[46:47], off offset:2048
	global_load_dwordx4 v[46:49], v[120:121], off
	s_nop 0
	global_load_dwordx4 v[52:55], v[110:111], off offset:1024
	s_waitcnt vmcnt(0) lgkmcnt(0)
	v_pk_add_f32 v[48:49], v[48:49], 1.0 op_sel_hi:[1,0]
	v_pk_add_f32 v[46:47], v[46:47], 1.0 op_sel_hi:[1,0]
	v_pk_fma_f32 v[48:49], v[60:61], v[48:49], v[54:55]
	v_pk_fma_f32 v[46:47], v[58:59], v[46:47], v[52:53]
	v_cvt_pk_bf16_f32 v46, v46, v47
	v_cvt_pk_bf16_f32 v47, v48, v49
	global_store_dwordx2 v[102:103], v[46:47], off offset:2560
	global_load_dwordx4 v[46:49], v[116:117], off
	s_nop 0
	global_load_dwordx4 v[52:55], v[110:111], off offset:2048
	v_pk_add_f32 v[58:59], v[146:147], v[146:147] op_sel:[0,1] op_sel_hi:[1,0]
	v_pk_add_f32 v[60:61], v[140:141], v[142:143]
	v_mov_b32_e32 v59, v196
	s_waitcnt vmcnt(0) lgkmcnt(0)
	v_pk_add_f32 v[48:49], v[48:49], 1.0 op_sel_hi:[1,0]
	v_pk_add_f32 v[46:47], v[46:47], 1.0 op_sel_hi:[1,0]
	v_pk_fma_f32 v[48:49], v[56:57], v[48:49], v[54:55]
	v_pk_fma_f32 v[46:47], v[82:83], v[46:47], v[52:53]
	v_cvt_pk_bf16_f32 v46, v46, v47
	v_cvt_pk_bf16_f32 v47, v48, v49
	global_store_dwordx2 v[102:103], v[46:47], off offset:3072
	global_load_dwordx4 v[46:49], v[112:113], off
	s_nop 0
	global_load_dwordx4 v[52:55], v[110:111], off offset:3072
	v_pk_add_f32 v[56:57], v[144:145], v[144:145] op_sel:[0,1] op_sel_hi:[1,0]
	s_waitcnt vmcnt(0) lgkmcnt(0)
	v_pk_add_f32 v[48:49], v[48:49], 1.0 op_sel_hi:[1,0]
	v_pk_add_f32 v[46:47], v[46:47], 1.0 op_sel_hi:[1,0]
	v_pk_fma_f32 v[48:49], v[86:87], v[48:49], v[54:55]
	v_pk_fma_f32 v[46:47], v[84:85], v[46:47], v[52:53]
	v_cvt_pk_bf16_f32 v46, v46, v47
	v_cvt_pk_bf16_f32 v47, v48, v49
	global_store_dwordx2 v[102:103], v[46:47], off offset:3584
	global_load_dwordx4 v[46:49], v[138:139], off
	s_nop 0
	global_load_dwordx4 v[52:55], v[108:109], off
	v_mov_b32_e32 v57, v195
	s_waitcnt vmcnt(0) lgkmcnt(0)
	v_pk_add_f32 v[48:49], v[48:49], 1.0 op_sel_hi:[1,0]
	v_pk_add_f32 v[46:47], v[46:47], 1.0 op_sel_hi:[1,0]
	v_pk_fma_f32 v[48:49], v[156:157], v[48:49], v[54:55]
	v_pk_fma_f32 v[46:47], v[88:89], v[46:47], v[52:53]
	v_bfe_u32 v51, v46, 16, 1
	v_bfe_u32 v52, v47, 16, 1
	v_add3_u32 v46, v46, v51, s25
	v_add3_u32 v47, v47, v52, s25
	v_lshrrev_b32_e32 v46, 16, v46
	v_and_or_b32 v46, v47, s28, v46
	v_cvt_pk_bf16_f32 v47, v48, v49
	global_store_dwordx2 v[104:105], v[46:47], off
	global_load_dwordx4 v[46:49], v[136:137], off
	s_nop 0
	global_load_dwordx4 v[52:55], v[108:109], off offset:1024
	v_pk_mul_f32 v[44:45], v[44:45], v[50:51] op_sel_hi:[1,0]
	v_pk_mul_f32 v[42:43], v[42:43], v[50:51] op_sel_hi:[1,0]
	v_pk_mul_f32 v[44:45], v[44:45], v[8:9]
	v_pk_mul_f32 v[42:43], v[42:43], v[6:7]
	s_waitcnt vmcnt(0) lgkmcnt(0)
	v_pk_add_f32 v[48:49], v[48:49], 1.0 op_sel_hi:[1,0]
	v_pk_add_f32 v[46:47], v[46:47], 1.0 op_sel_hi:[1,0]
	v_pk_fma_f32 v[44:45], v[44:45], v[48:49], v[54:55]
	v_pk_fma_f32 v[42:43], v[42:43], v[46:47], v[52:53]
	v_cvt_pk_bf16_f32 v42, v42, v43
	v_cvt_pk_bf16_f32 v43, v44, v45
	global_store_dwordx2 v[104:105], v[42:43], off offset:512
	global_load_dwordx4 v[42:45], v[132:133], off
	s_nop 0
	global_load_dwordx4 v[46:49], v[108:109], off offset:2048
	v_pk_add_f32 v[52:53], v[56:57], v[58:59]
	s_waitcnt vmcnt(0) lgkmcnt(0)
	v_pk_add_f32 v[44:45], v[44:45], 1.0 op_sel_hi:[1,0]
	v_pk_add_f32 v[52:53], v[52:53], v[60:61]
	v_pk_add_f32 v[42:43], v[42:43], 1.0 op_sel_hi:[1,0]
	v_add_f32_e32 v51, v52, v53
	s_waitcnt lgkmcnt(0)
	s_nop 1
	v_add_f32_dpp v51, v51, v51 quad_perm:[1,0,3,2] row_mask:0xf bank_mask:0xf
	ds_bpermute_b32 v52, v148, v51
	s_waitcnt lgkmcnt(0)
	v_add_f32_e32 v51, v51, v52
	v_pk_mul_f32 v[40:41], v[40:41], v[50:51] op_sel_hi:[1,0]
	v_pk_mul_f32 v[38:39], v[38:39], v[50:51] op_sel_hi:[1,0]
	v_pk_mul_f32 v[40:41], v[40:41], v[12:13]
	v_pk_mul_f32 v[38:39], v[38:39], v[10:11]
	v_pk_fma_f32 v[40:41], v[40:41], v[44:45], v[48:49]
	v_pk_fma_f32 v[38:39], v[38:39], v[42:43], v[46:47]
	v_cvt_pk_bf16_f32 v38, v38, v39
	v_cvt_pk_bf16_f32 v39, v40, v41
	global_store_dwordx2 v[104:105], v[38:39], off offset:1024
	global_load_dwordx4 v[38:41], v[122:123], off
	s_nop 0
	global_load_dwordx4 v[42:45], v[108:109], off offset:3072
	v_pk_mul_f32 v[36:37], v[36:37], v[50:51] op_sel_hi:[1,0]
	v_pk_mul_f32 v[34:35], v[34:35], v[50:51] op_sel_hi:[1,0]
	v_pk_mul_f32 v[36:37], v[36:37], v[16:17]
	v_pk_mul_f32 v[34:35], v[34:35], v[14:15]
	ds_bpermute_b32 v46, v149, v51
	s_waitcnt lgkmcnt(0)
	v_add_f32_e32 v46, v51, v46
	ds_bpermute_b32 v47, v150, v46
	s_waitcnt lgkmcnt(0)
	v_add_f32_e32 v46, v46, v47
	s_waitcnt lgkmcnt(0)
	v_mov_b32_e32 v47, v46
	s_nop 1
	v_permlane16_swap_b32_e32 v46, v47
	v_add_f32_e32 v46, v46, v47
	s_waitcnt lgkmcnt(0)
	v_mov_b32_e32 v47, v46
	s_nop 1
	v_permlane32_swap_b32_e32 v46, v47
	v_add_f32_e32 v46, v46, v47
	v_fmamk_f32 v46, v46, 0x3a800000, v153
	v_mul_f32_e32 v47, 0x4f800000, v46
	v_cmp_gt_f32_e32 vcc, s17, v46
	s_waitcnt vmcnt(0)
	v_pk_add_f32 v[40:41], v[40:41], 1.0 op_sel_hi:[1,0]
	v_pk_add_f32 v[38:39], v[38:39], 1.0 op_sel_hi:[1,0]
	v_pk_fma_f32 v[36:37], v[36:37], v[40:41], v[44:45]
	v_pk_fma_f32 v[34:35], v[34:35], v[38:39], v[42:43]
	v_cvt_pk_bf16_f32 v34, v34, v35
	v_cvt_pk_bf16_f32 v35, v36, v37
	global_store_dwordx2 v[104:105], v[34:35], off offset:1536
	global_load_dwordx4 v[34:37], v[118:119], off
	s_nop 0
	global_load_dwordx4 v[38:41], v[106:107], off
	v_cndmask_b32_e32 v42, v46, v47, vcc
	v_sqrt_f32_e32 v43, v42
	s_waitcnt vmcnt(0) lgkmcnt(0)
	v_pk_add_f32 v[36:37], v[36:37], 1.0 op_sel_hi:[1,0]
	v_add_u32_e32 v44, -1, v43
	v_add_u32_e32 v45, 1, v43
	v_fma_f32 v46, -v44, v43, v42
	v_fma_f32 v47, -v45, v43, v42
	v_cmp_ge_f32_e64 s[6:7], 0, v46
	v_pk_add_f32 v[34:35], v[34:35], 1.0 op_sel_hi:[1,0]
	s_nop 0
	v_cndmask_b32_e64 v43, v43, v44, s[6:7]
	v_cmp_lt_f32_e64 s[6:7], 0, v47
	s_nop 1
	v_cndmask_b32_e64 v43, v43, v45, s[6:7]
	v_mul_f32_e32 v44, 0x37800000, v43
	v_cndmask_b32_e32 v43, v43, v44, vcc
	v_cmp_class_f32_e32 vcc, v42, v154
	s_nop 1
	v_cndmask_b32_e32 v42, v43, v42, vcc
	v_div_scale_f32 v43, s[6:7], v42, v42, 1.0
	v_rcp_f32_e32 v45, v43
	v_div_scale_f32 v44, vcc, 1.0, v42, 1.0
	v_fma_f32 v46, -v43, v45, 1.0
	v_fmac_f32_e32 v45, v46, v45
	v_mul_f32_e32 v46, v44, v45
	v_fma_f32 v47, -v43, v46, v44
	v_fmac_f32_e32 v46, v47, v45
	v_fma_f32 v43, -v43, v46, v44
	v_div_fmas_f32 v43, v43, v45, v46
	v_div_fixup_f32 v42, v43, v42, 1.0
	v_pk_mul_f32 v[32:33], v[32:33], v[42:43] op_sel_hi:[1,0]
	v_pk_mul_f32 v[30:31], v[30:31], v[42:43] op_sel_hi:[1,0]
	v_pk_mul_f32 v[32:33], v[32:33], v[4:5]
	v_pk_mul_f32 v[30:31], v[30:31], v[2:3]
	v_pk_fma_f32 v[32:33], v[32:33], v[36:37], v[40:41]
	v_pk_fma_f32 v[30:31], v[30:31], v[34:35], v[38:39]
	v_cvt_pk_bf16_f32 v30, v30, v31
	v_cvt_pk_bf16_f32 v31, v32, v33
	global_store_dwordx2 v[104:105], v[30:31], off offset:2048
	global_load_dwordx4 v[30:33], v[114:115], off
	s_nop 0
	global_load_dwordx4 v[34:37], v[106:107], off offset:1024
	v_pk_mul_f32 v[28:29], v[28:29], v[42:43] op_sel_hi:[1,0]
	v_pk_mul_f32 v[26:27], v[26:27], v[42:43] op_sel_hi:[1,0]
	v_pk_mul_f32 v[28:29], v[28:29], v[8:9]
	v_pk_mul_f32 v[26:27], v[26:27], v[6:7]
	v_lshl_add_u64 v[38:39], s[40:41], 0, v[98:99]
	v_pk_mul_f32 v[24:25], v[24:25], v[42:43] op_sel_hi:[1,0]
	v_pk_mul_f32 v[22:23], v[22:23], v[42:43] op_sel_hi:[1,0]
	v_pk_mul_f32 v[24:25], v[24:25], v[12:13]
	v_pk_mul_f32 v[22:23], v[22:23], v[10:11]
	v_pk_mul_f32 v[20:21], v[20:21], v[42:43] op_sel_hi:[1,0]
	v_pk_mul_f32 v[18:19], v[18:19], v[42:43] op_sel_hi:[1,0]
	v_pk_mul_f32 v[20:21], v[20:21], v[16:17]
	v_pk_mul_f32 v[18:19], v[18:19], v[14:15]
	s_waitcnt vmcnt(0) lgkmcnt(0)
	v_pk_add_f32 v[32:33], v[32:33], 1.0 op_sel_hi:[1,0]
	v_pk_add_f32 v[30:31], v[30:31], 1.0 op_sel_hi:[1,0]
	v_pk_fma_f32 v[28:29], v[28:29], v[32:33], v[36:37]
	v_pk_fma_f32 v[26:27], v[26:27], v[30:31], v[34:35]
	v_cvt_pk_bf16_f32 v26, v26, v27
	v_cvt_pk_bf16_f32 v27, v28, v29
	global_store_dwordx2 v[104:105], v[26:27], off offset:2560
	global_load_dwordx4 v[26:29], v[38:39], off
	s_nop 0
	global_load_dwordx4 v[30:33], v[106:107], off offset:2048
	v_lshl_add_u64 v[34:35], s[40:41], 0, v[100:101]
	s_waitcnt vmcnt(0) lgkmcnt(0)
	v_pk_add_f32 v[28:29], v[28:29], 1.0 op_sel_hi:[1,0]
	v_pk_add_f32 v[26:27], v[26:27], 1.0 op_sel_hi:[1,0]
	v_pk_fma_f32 v[24:25], v[24:25], v[28:29], v[32:33]
	v_pk_fma_f32 v[22:23], v[22:23], v[26:27], v[30:31]
	v_cvt_pk_bf16_f32 v22, v22, v23
	v_cvt_pk_bf16_f32 v23, v24, v25
	global_store_dwordx2 v[104:105], v[22:23], off offset:3072
	global_load_dwordx4 v[22:25], v[34:35], off
	s_nop 0
	global_load_dwordx4 v[26:29], v[106:107], off offset:3072
	s_waitcnt vmcnt(0) lgkmcnt(0)
	v_pk_add_f32 v[24:25], v[24:25], 1.0 op_sel_hi:[1,0]
	v_pk_add_f32 v[22:23], v[22:23], 1.0 op_sel_hi:[1,0]
	v_pk_fma_f32 v[20:21], v[20:21], v[24:25], v[28:29]
	v_pk_fma_f32 v[18:19], v[18:19], v[22:23], v[26:27]
	v_cvt_pk_bf16_f32 v18, v18, v19
	v_cvt_pk_bf16_f32 v19, v20, v21
	global_store_dwordx2 v[104:105], v[18:19], off offset:3584
	s_cbranch_scc1 .LBB0_3194

.LBB0_3341:
	v_lshl_add_u64 v[18:19], s[12:13], 0, v[94:95]
	v_lshl_add_u64 v[22:23], s[12:13], 0, v[92:93]
	v_add_co_u32_e32 v20, vcc, 0x7800000, v18
	v_add_co_u32_e64 v102, s[6:7], s28, v22
	s_nop 0
	v_addc_co_u32_e32 v21, vcc, 0, v19, vcc
	v_addc_co_u32_e64 v103, s[6:7], 0, v23, s[6:7]
	v_add_co_u32_e64 v104, s[6:7], s29, v22
	v_add_co_u32_e32 v22, vcc, 0x7801000, v18
	s_nop 0
	v_addc_co_u32_e64 v105, s[6:7], 0, v23, s[6:7]
	global_load_dwordx4 v[78:81], v[20:21], off
	global_load_dwordx4 v[74:77], v[20:21], off offset:1024
	global_load_dwordx4 v[70:73], v[20:21], off offset:2048
	global_load_dwordx4 v[66:69], v[20:21], off offset:3072
	v_addc_co_u32_e32 v23, vcc, 0, v19, vcc
	v_add_co_u32_e32 v20, vcc, 0x7802000, v18
	global_load_dwordx4 v[62:65], v[22:23], off
	global_load_dwordx4 v[58:61], v[22:23], off offset:1024
	global_load_dwordx4 v[54:57], v[22:23], off offset:2048
	global_load_dwordx4 v[50:53], v[22:23], off offset:3072
	v_addc_co_u32_e32 v21, vcc, 0, v19, vcc
	v_add_co_u32_e32 v82, vcc, 0x7803000, v18
	global_load_dwordx4 v[46:49], v[20:21], off
	global_load_dwordx4 v[42:45], v[20:21], off offset:1024
	global_load_dwordx4 v[38:41], v[20:21], off offset:2048
	global_load_dwordx4 v[34:37], v[20:21], off offset:3072
	v_addc_co_u32_e32 v83, vcc, 0, v19, vcc
	global_load_dwordx4 v[30:33], v[82:83], off
	global_load_dwordx4 v[26:29], v[82:83], off offset:1024
	global_load_dwordx4 v[22:25], v[82:83], off offset:2048
	global_load_dwordx4 v[18:21], v[82:83], off offset:3072
	s_add_i32 s30, s8, 32
	s_add_i32 s10, s8, 0xffffc022
	s_ashr_i32 s9, s30, 13
	s_cmpk_lt_i32 s30, 0x4000
	s_cselect_b32 s6, s9, s10
	s_addk_i32 s6, 0x82
	s_mul_hi_i32 s7, s6, 0x9000
	s_mul_i32 s6, s6, 0x9000
	s_add_u32 s6, s14, s6
	s_addc_u32 s7, s15, s7
	s_add_u32 s10, s6, 0x1000
	s_addc_u32 s11, s7, 0
	v_lshl_add_u64 v[124:125], s[6:7], 0, v[90:91]
	v_lshl_add_u64 v[86:87], s[10:11], 0, v[90:91]
	global_load_dwordx4 v[82:85], v[124:125], off
	s_add_i32 s6, s8, 0xffffc023
	global_load_dwordx4 v[86:89], v[86:87], off
	s_cmpk_lt_i32 s30, 0x3fff
	s_cselect_b32 s6, s9, s6
	s_addk_i32 s6, 0x82
	s_mul_hi_i32 s7, s6, 0x9000
	s_mul_i32 s6, s6, 0x9000
	s_add_u32 s6, s14, s6
	s_addc_u32 s7, s15, s7
	v_lshl_add_u64 v[134:135], s[10:11], 0, v[96:97]
	v_lshl_add_u64 v[130:131], s[10:11], 0, v[98:99]
	v_lshl_add_u64 v[128:129], s[10:11], 0, v[100:101]
	s_add_u32 s10, s6, 0x1000
	v_lshl_add_u64 v[110:111], s[6:7], 0, v[90:91]
	s_addc_u32 s11, s7, 0
	s_add_i32 s6, s8, 0xffffc024
	s_cmpk_lt_i32 s30, 0x3ffe
	s_cselect_b32 s6, s9, s6
	s_addk_i32 s6, 0x82
	s_mul_hi_i32 s7, s6, 0x9000
	s_mul_i32 s6, s6, 0x9000
	v_lshl_add_u64 v[126:127], s[10:11], 0, v[90:91]
	v_lshl_add_u64 v[120:121], s[10:11], 0, v[96:97]
	v_lshl_add_u64 v[116:117], s[10:11], 0, v[98:99]
	v_lshl_add_u64 v[112:113], s[10:11], 0, v[100:101]
	s_add_u32 s10, s14, s6
	s_addc_u32 s11, s15, s7
	s_add_u32 s6, s10, 0x1000
	s_addc_u32 s7, s11, 0
	s_addk_i32 s8, 0xc025
	s_cmpk_lt_i32 s30, 0x3ffd
	v_lshl_add_u64 v[138:139], s[6:7], 0, v[90:91]
	v_lshl_add_u64 v[136:137], s[6:7], 0, v[96:97]
	v_lshl_add_u64 v[132:133], s[6:7], 0, v[98:99]
	v_lshl_add_u64 v[122:123], s[6:7], 0, v[100:101]
	s_cselect_b32 s6, s9, s8
	s_addk_i32 s6, 0x82
	s_mul_hi_i32 s7, s6, 0x9000
	s_mul_i32 s6, s6, 0x9000
	s_add_u32 s6, s14, s6
	s_addc_u32 s7, s15, s7
	s_add_u32 s22, s6, 0x1000
	v_lshl_add_u64 v[106:107], s[6:7], 0, v[90:91]
	s_addc_u32 s23, s7, 0
	v_lshl_add_u64 v[108:109], s[10:11], 0, v[90:91]
	v_lshl_add_u64 v[118:119], s[22:23], 0, v[90:91]
	v_lshl_add_u64 v[114:115], s[22:23], 0, v[96:97]
	v_lshl_add_u64 v[92:93], v[92:93], 0, s[16:17]
	s_waitcnt vmcnt(0) lgkmcnt(0)
	v_pk_mul_f32 v[140:141], v[80:81], v[80:81]
	v_pk_mul_f32 v[142:143], v[78:79], v[78:79]
	v_pk_mul_f32 v[144:145], v[76:77], v[76:77]
	v_pk_mul_f32 v[146:147], v[74:75], v[74:75]
	v_mul_f32_e32 v156, v71, v71
	v_mul_f32_e32 v158, v73, v73
	v_mul_f32_e32 v169, v68, v68
	v_mul_f32_e32 v171, v69, v69
	v_pk_mov_b32 v[160:161], v[142:143], v[140:141] op_sel:[1,0]
	v_mov_b32_e32 v143, v141
	v_pk_mov_b32 v[140:141], v[146:147], v[144:145] op_sel:[1,0]
	v_mov_b32_e32 v147, v145
	v_pk_fma_f32 v[144:145], v[70:71], v[70:71], v[156:157] op_sel_hi:[1,1,0]
	v_pk_fma_f32 v[156:157], v[72:73], v[72:73], v[158:159] op_sel_hi:[1,1,0]
	v_pk_mul_f32 v[158:159], v[64:65], v[64:65]
	v_pk_mul_f32 v[162:163], v[62:63], v[62:63]
	v_pk_mul_f32 v[164:165], v[60:61], v[60:61]
	v_pk_mul_f32 v[166:167], v[58:59], v[58:59]
	v_mul_f32_e32 v168, v55, v55
	v_mul_f32_e32 v170, v57, v57
	v_pk_add_f32 v[142:143], v[160:161], v[142:143]
	v_pk_add_f32 v[140:141], v[140:141], v[146:147]
	v_mov_b32_e32 v145, v169
	v_mov_b32_e32 v157, v171
	v_pk_mov_b32 v[146:147], v[162:163], v[158:159] op_sel:[1,0]
	v_mov_b32_e32 v163, v159
	v_pk_mov_b32 v[158:159], v[166:167], v[164:165] op_sel:[1,0]
	v_mov_b32_e32 v167, v165
	v_pk_fma_f32 v[160:161], v[54:55], v[54:55], v[168:169] op_sel_hi:[1,1,0]
	v_pk_fma_f32 v[164:165], v[56:57], v[56:57], v[170:171] op_sel_hi:[1,1,0]
	v_pk_mul_f32 v[168:169], v[48:49], v[48:49]
	v_pk_mul_f32 v[170:171], v[46:47], v[46:47]
	v_pk_mul_f32 v[172:173], v[44:45], v[44:45]
	v_pk_mul_f32 v[174:175], v[42:43], v[42:43]
	v_mul_f32_e32 v155, v66, v66
	v_mul_f32_e32 v179, v67, v67
	v_mul_f32_e32 v177, v52, v52
	v_mul_f32_e32 v184, v53, v53
	v_mul_f32_e32 v176, v39, v39
	v_mul_f32_e32 v178, v41, v41
	v_pk_add_f32 v[180:181], v[142:143], v[142:143] op_sel:[0,1] op_sel_hi:[1,0]
	v_pk_add_f32 v[182:183], v[140:141], v[140:141] op_sel:[0,1] op_sel_hi:[1,0]
	v_pk_add_f32 v[156:157], v[144:145], v[156:157]
	v_pk_add_f32 v[140:141], v[146:147], v[162:163]
	v_pk_add_f32 v[142:143], v[158:159], v[166:167]
	v_pk_mov_b32 v[144:145], v[170:171], v[168:169] op_sel:[1,0]
	v_mov_b32_e32 v171, v169
	v_pk_mov_b32 v[146:147], v[174:175], v[172:173] op_sel:[1,0]
	v_mov_b32_e32 v175, v173
	v_mul_f32_e32 v185, v50, v50
	v_mul_f32_e32 v190, v51, v51
	v_mul_f32_e32 v193, v36, v36
	v_mul_f32_e32 v194, v37, v37
	v_mov_b32_e32 v161, v177
	v_mov_b32_e32 v165, v184
	v_pk_fma_f32 v[158:159], v[38:39], v[38:39], v[176:177] op_sel_hi:[1,1,0]
	v_pk_fma_f32 v[162:163], v[40:41], v[40:41], v[178:179] op_sel_hi:[1,1,0]
	v_pk_mul_f32 v[166:167], v[32:33], v[32:33]
	v_pk_mul_f32 v[168:169], v[30:31], v[30:31]
	v_pk_mul_f32 v[172:173], v[28:29], v[28:29]
	v_pk_mul_f32 v[176:177], v[26:27], v[26:27]
	v_mov_b32_e32 v181, v155
	v_mov_b32_e32 v183, v179
	v_pk_add_f32 v[186:187], v[140:141], v[140:141] op_sel:[0,1] op_sel_hi:[1,0]
	v_pk_add_f32 v[188:189], v[142:143], v[142:143] op_sel:[0,1] op_sel_hi:[1,0]
	v_pk_add_f32 v[144:145], v[144:145], v[170:171]
	v_pk_add_f32 v[146:147], v[146:147], v[174:175]
	v_mul_f32_e32 v191, v34, v34
	v_mul_f32_e32 v192, v35, v35
	v_pk_add_f32 v[160:161], v[160:161], v[164:165]
	v_mov_b32_e32 v159, v193
	v_mov_b32_e32 v163, v194
	v_pk_mov_b32 v[164:165], v[168:169], v[166:167] op_sel:[1,0]
	v_mov_b32_e32 v169, v167
	v_pk_mov_b32 v[166:167], v[176:177], v[172:173] op_sel:[1,0]
	v_mov_b32_e32 v177, v173
	v_pk_add_f32 v[170:171], v[180:181], v[182:183]
	v_mov_b32_e32 v187, v185
	v_mov_b32_e32 v189, v190
	v_pk_add_f32 v[172:173], v[144:145], v[144:145] op_sel:[0,1] op_sel_hi:[1,0]
	v_pk_add_f32 v[174:175], v[146:147], v[146:147] op_sel:[0,1] op_sel_hi:[1,0]
	v_pk_add_f32 v[158:159], v[158:159], v[162:163]
	v_pk_add_f32 v[156:157], v[170:171], v[156:157]
	v_pk_add_f32 v[162:163], v[186:187], v[188:189]
	v_mov_b32_e32 v173, v191
	v_mov_b32_e32 v175, v192
	v_add_f32_e32 v155, v156, v157
	v_pk_add_f32 v[156:157], v[162:163], v[160:161]
	v_pk_add_f32 v[160:161], v[172:173], v[174:175]
	v_add_f32_e32 v162, v156, v157
	v_pk_add_f32 v[156:157], v[160:161], v[158:159]
	v_add_f32_e32 v156, v156, v157
	v_pk_add_f32 v[144:145], v[164:165], v[168:169]
	s_waitcnt lgkmcnt(0)
	s_nop 1
	v_add_f32_dpp v155, v155, v155 quad_perm:[1,0,3,2] row_mask:0xf bank_mask:0xf
	s_waitcnt lgkmcnt(0)
	s_nop 1
	v_add_f32_dpp v159, v162, v162 quad_perm:[1,0,3,2] row_mask:0xf bank_mask:0xf
	s_waitcnt lgkmcnt(0)
	s_nop 1
	v_add_f32_dpp v156, v156, v156 quad_perm:[1,0,3,2] row_mask:0xf bank_mask:0xf
	s_waitcnt lgkmcnt(0)
	s_nop 1
	v_add_f32_dpp v155, v155, v155 quad_perm:[2,3,0,1] row_mask:0xf bank_mask:0xf
	s_waitcnt lgkmcnt(0)
	s_nop 1
	v_add_f32_dpp v159, v159, v159 quad_perm:[2,3,0,1] row_mask:0xf bank_mask:0xf
	s_waitcnt lgkmcnt(0)
	s_nop 1
	v_add_f32_dpp v156, v156, v156 quad_perm:[2,3,0,1] row_mask:0xf bank_mask:0xf
	s_waitcnt lgkmcnt(0)
	s_nop 1
	v_add_f32_dpp v155, v155, v155 row_half_mirror row_mask:0xf bank_mask:0xf
	s_waitcnt lgkmcnt(0)
	s_nop 1
	v_add_f32_dpp v159, v159, v159 row_half_mirror row_mask:0xf bank_mask:0xf
	s_waitcnt lgkmcnt(0)
	s_nop 1
	v_add_f32_dpp v156, v156, v156 row_half_mirror row_mask:0xf bank_mask:0xf
	s_waitcnt lgkmcnt(0)
	s_nop 1
	v_add_f32_dpp v155, v155, v155 row_mirror row_mask:0xf bank_mask:0xf
	s_waitcnt lgkmcnt(0)
	s_nop 1
	v_add_f32_dpp v159, v159, v159 row_mirror row_mask:0xf bank_mask:0xf
	s_waitcnt lgkmcnt(0)
	s_nop 1
	v_add_f32_dpp v156, v156, v156 row_mirror row_mask:0xf bank_mask:0xf
	s_waitcnt lgkmcnt(0)
	v_mov_b32_e32 v158, v155
	s_nop 1
	v_permlane16_swap_b32_e32 v155, v158
	v_add_f32_e32 v155, v155, v158
	s_waitcnt lgkmcnt(0)
	v_mov_b32_e32 v160, v159
	s_nop 1
	v_permlane16_swap_b32_e32 v159, v160
	v_add_f32_e32 v159, v159, v160
	s_waitcnt lgkmcnt(0)
	v_mov_b32_e32 v157, v156
	s_nop 1
	v_permlane16_swap_b32_e32 v156, v157
	v_add_f32_e32 v156, v156, v157
	s_waitcnt lgkmcnt(0)
	v_mov_b32_e32 v158, v155
	s_nop 1
	v_permlane32_swap_b32_e32 v155, v158
	v_add_f32_e32 v155, v155, v158
	v_fmamk_f32 v155, v155, 0x3a800000, v153
	s_waitcnt lgkmcnt(1)
	v_mov_b32_e32 v160, v159
	s_nop 1
	v_permlane32_swap_b32_e32 v159, v160
	v_add_f32_e32 v158, v159, v160
	v_mul_f32_e32 v159, 0x4f800000, v155
	v_cmp_gt_f32_e32 vcc, s25, v155
	v_fmamk_f32 v158, v158, 0x3a800000, v153
	s_waitcnt lgkmcnt(0)
	v_mov_b32_e32 v157, v156
	s_nop 1
	v_permlane32_swap_b32_e32 v156, v157
	v_add_f32_e32 v156, v156, v157
	v_cndmask_b32_e32 v155, v155, v159, vcc
	v_mul_f32_e32 v157, 0x4f800000, v158
	v_cmp_gt_f32_e64 s[6:7], s25, v158
	v_sqrt_f32_e32 v159, v155
	v_fmamk_f32 v156, v156, 0x3a800000, v153
	v_cndmask_b32_e64 v157, v158, v157, s[6:7]
	v_mul_f32_e32 v158, 0x4f800000, v156
	v_cmp_gt_f32_e64 s[8:9], s25, v156
	v_sqrt_f32_e32 v160, v157
	v_add_u32_e32 v161, -1, v159
	v_cndmask_b32_e64 v156, v156, v158, s[8:9]
	v_sqrt_f32_e32 v158, v156
	v_add_u32_e32 v162, 1, v159
	v_fma_f32 v163, -v161, v159, v155
	v_fma_f32 v164, -v162, v159, v155
	v_add_u32_e32 v165, -1, v160
	v_cmp_ge_f32_e64 s[10:11], 0, v163
	v_pk_add_f32 v[146:147], v[166:167], v[176:177]
	v_add_u32_e32 v166, 1, v160
	v_cndmask_b32_e64 v159, v159, v161, s[10:11]
	v_fma_f32 v161, -v165, v160, v157
	v_cmp_lt_f32_e64 s[10:11], 0, v164
	v_fma_f32 v163, -v166, v160, v157
	v_add_u32_e32 v167, -1, v158
	v_cndmask_b32_e64 v159, v159, v162, s[10:11]
	v_cmp_ge_f32_e64 s[10:11], 0, v161
	v_add_u32_e32 v168, 1, v158
	v_fma_f32 v161, -v167, v158, v156
	v_cndmask_b32_e64 v160, v160, v165, s[10:11]
	v_cmp_lt_f32_e64 s[10:11], 0, v163
	v_fma_f32 v162, -v168, v158, v156
	v_mul_f32_e32 v163, 0x37800000, v159
	v_cndmask_b32_e64 v160, v160, v166, s[10:11]
	v_cmp_ge_f32_e64 s[10:11], 0, v161
	v_cndmask_b32_e32 v159, v159, v163, vcc
	v_cmp_class_f32_e32 vcc, v155, v154
	v_cndmask_b32_e64 v158, v158, v167, s[10:11]
	v_cmp_lt_f32_e64 s[10:11], 0, v162
	v_mul_f32_e32 v161, 0x37800000, v160
	v_cndmask_b32_e32 v155, v159, v155, vcc
	v_cndmask_b32_e64 v158, v158, v168, s[10:11]
	v_cndmask_b32_e64 v159, v160, v161, s[6:7]
	v_cmp_class_f32_e32 vcc, v157, v154
	v_mul_f32_e32 v160, 0x37800000, v158
	v_div_scale_f32 v161, s[6:7], v155, v155, 1.0
	v_cndmask_b32_e32 v157, v159, v157, vcc
	v_cndmask_b32_e64 v158, v158, v160, s[8:9]
	v_cmp_class_f32_e32 vcc, v156, v154
	v_rcp_f32_e32 v159, v161
	v_div_scale_f32 v160, s[8:9], v157, v157, 1.0
	v_cndmask_b32_e32 v158, v158, v156, vcc
	v_rcp_f32_e32 v164, v160
	v_div_scale_f32 v165, s[10:11], v158, v158, 1.0
	v_rcp_f32_e32 v167, v165
	v_fma_f32 v156, -v161, v159, 1.0
	v_div_scale_f32 v162, s[6:7], 1.0, v155, 1.0
	v_fmac_f32_e32 v159, v156, v159
	v_fma_f32 v156, -v160, v164, 1.0
	v_mul_f32_e32 v168, v162, v159
	v_div_scale_f32 v163, s[8:9], 1.0, v157, 1.0
	v_fmac_f32_e32 v164, v156, v164
	v_fma_f32 v156, -v165, v167, 1.0
	v_fma_f32 v169, -v161, v168, v162
	v_div_scale_f32 v166, s[10:11], 1.0, v158, 1.0
	v_mul_f32_e32 v170, v163, v164
	v_fmac_f32_e32 v167, v156, v167
	v_fmac_f32_e32 v168, v169, v159
	v_fma_f32 v156, -v160, v170, v163
	v_mul_f32_e32 v169, v166, v167
	v_fma_f32 v161, -v161, v168, v162
	s_mov_b64 vcc, s[6:7]
	v_fmac_f32_e32 v170, v156, v164
	v_fma_f32 v156, -v165, v169, v166
	v_div_fmas_f32 v159, v161, v159, v168
	v_fma_f32 v160, -v160, v170, v163
	v_fmac_f32_e32 v169, v156, v167
	v_div_fixup_f32 v156, v159, v155, 1.0
	s_mov_b64 vcc, s[8:9]
	v_div_fmas_f32 v155, v160, v164, v170
	v_fma_f32 v159, -v165, v169, v166
	v_pk_mul_f32 v[80:81], v[80:81], v[156:157] op_sel_hi:[1,0]
	v_pk_mul_f32 v[78:79], v[78:79], v[156:157] op_sel_hi:[1,0]
	s_mov_b64 vcc, s[10:11]
	v_pk_add_f32 v[88:89], v[88:89], 1.0 op_sel_hi:[1,0]
	v_pk_add_f32 v[86:87], v[86:87], 1.0 op_sel_hi:[1,0]
	v_pk_mul_f32 v[76:77], v[76:77], v[156:157] op_sel_hi:[1,0]
	v_pk_mul_f32 v[74:75], v[74:75], v[156:157] op_sel_hi:[1,0]
	v_pk_mul_f32 v[72:73], v[72:73], v[156:157] op_sel_hi:[1,0]
	v_pk_mul_f32 v[70:71], v[70:71], v[156:157] op_sel_hi:[1,0]
	v_pk_mul_f32 v[68:69], v[68:69], v[156:157] op_sel_hi:[1,0]
	v_pk_mul_f32 v[66:67], v[66:67], v[156:157] op_sel_hi:[1,0]
	v_div_fixup_f32 v156, v155, v157, 1.0
	v_div_fmas_f32 v155, v159, v167, v169
	v_pk_mul_f32 v[78:79], v[78:79], v[2:3]
	v_pk_mul_f32 v[80:81], v[80:81], v[4:5]
	v_pk_mul_f32 v[64:65], v[64:65], v[156:157] op_sel_hi:[1,0]
	v_pk_mul_f32 v[62:63], v[62:63], v[156:157] op_sel_hi:[1,0]
	v_pk_mul_f32 v[60:61], v[60:61], v[156:157] op_sel_hi:[1,0]
	v_pk_mul_f32 v[58:59], v[58:59], v[156:157] op_sel_hi:[1,0]
	v_pk_mul_f32 v[56:57], v[56:57], v[156:157] op_sel_hi:[1,0]
	v_pk_mul_f32 v[54:55], v[54:55], v[156:157] op_sel_hi:[1,0]
	v_pk_mul_f32 v[52:53], v[52:53], v[156:157] op_sel_hi:[1,0]
	v_pk_mul_f32 v[156:157], v[50:51], v[156:157] op_sel_hi:[1,0]
	v_div_fixup_f32 v50, v155, v158, 1.0
	v_pk_fma_f32 v[80:81], v[80:81], v[88:89], v[84:85]
	v_pk_fma_f32 v[78:79], v[78:79], v[86:87], v[82:83]
	v_pk_mul_f32 v[86:87], v[52:53], v[16:17]
	v_pk_mul_f32 v[48:49], v[48:49], v[50:51] op_sel_hi:[1,0]
	v_pk_mul_f32 v[46:47], v[46:47], v[50:51] op_sel_hi:[1,0]
	v_pk_mul_f32 v[82:83], v[54:55], v[10:11]
	v_pk_mul_f32 v[84:85], v[156:157], v[14:15]
	v_pk_mul_f32 v[88:89], v[46:47], v[2:3]
	v_pk_mul_f32 v[156:157], v[48:49], v[4:5]
	v_cvt_pk_bf16_f32 v46, v78, v79
	v_cvt_pk_bf16_f32 v47, v80, v81
	global_store_dwordx2 v[102:103], v[46:47], off
	global_load_dwordx4 v[46:49], v[134:135], off
	s_nop 0
	global_load_dwordx4 v[52:55], v[124:125], off offset:1024
	v_pk_mul_f32 v[74:75], v[74:75], v[6:7]
	v_pk_mul_f32 v[76:77], v[76:77], v[8:9]
	v_pk_mul_f32 v[70:71], v[70:71], v[10:11]
	v_pk_mul_f32 v[72:73], v[72:73], v[12:13]
	v_pk_mul_f32 v[66:67], v[66:67], v[14:15]
	v_pk_mul_f32 v[68:69], v[68:69], v[16:17]
	v_pk_mul_f32 v[62:63], v[62:63], v[2:3]
	v_pk_mul_f32 v[64:65], v[64:65], v[4:5]
	v_pk_mul_f32 v[58:59], v[58:59], v[6:7]
	v_pk_mul_f32 v[60:61], v[60:61], v[8:9]
	v_pk_mul_f32 v[56:57], v[56:57], v[12:13]
	v_mul_f32_e32 v178, v23, v23
	v_mul_f32_e32 v184, v25, v25
	v_mul_f32_e32 v195, v18, v18
	v_mul_f32_e32 v196, v19, v19
	v_mul_f32_e32 v197, v20, v20
	v_mul_f32_e32 v198, v21, v21
	v_pk_fma_f32 v[140:141], v[22:23], v[22:23], v[178:179] op_sel_hi:[1,1,0]
	v_pk_fma_f32 v[142:143], v[24:25], v[24:25], v[184:185] op_sel_hi:[1,1,0]
	v_mov_b32_e32 v141, v197
	v_mov_b32_e32 v143, v198
	v_lshl_add_u64 v[94:95], v[94:95], 0, s[18:19]
	s_mov_b32 s8, s30
	s_cmp_lt_i32 s30, s24
	s_waitcnt vmcnt(0) lgkmcnt(0)
	v_pk_add_f32 v[48:49], v[48:49], 1.0 op_sel_hi:[1,0]
	v_pk_add_f32 v[46:47], v[46:47], 1.0 op_sel_hi:[1,0]
	v_pk_fma_f32 v[48:49], v[76:77], v[48:49], v[54:55]
	v_pk_fma_f32 v[46:47], v[74:75], v[46:47], v[52:53]
	v_cvt_pk_bf16_f32 v46, v46, v47
	v_cvt_pk_bf16_f32 v47, v48, v49
	global_store_dwordx2 v[102:103], v[46:47], off offset:512
	global_load_dwordx4 v[46:49], v[130:131], off
	s_nop 0
	global_load_dwordx4 v[52:55], v[124:125], off offset:2048
	s_waitcnt vmcnt(0) lgkmcnt(0)
	v_pk_add_f32 v[48:49], v[48:49], 1.0 op_sel_hi:[1,0]
	v_pk_add_f32 v[46:47], v[46:47], 1.0 op_sel_hi:[1,0]
	v_pk_fma_f32 v[48:49], v[72:73], v[48:49], v[54:55]
	v_pk_fma_f32 v[46:47], v[70:71], v[46:47], v[52:53]
	v_cvt_pk_bf16_f32 v46, v46, v47
	v_cvt_pk_bf16_f32 v47, v48, v49
	global_store_dwordx2 v[102:103], v[46:47], off offset:1024
	global_load_dwordx4 v[46:49], v[128:129], off
	s_nop 0
	global_load_dwordx4 v[52:55], v[124:125], off offset:3072
	s_waitcnt vmcnt(0) lgkmcnt(0)
	v_pk_add_f32 v[48:49], v[48:49], 1.0 op_sel_hi:[1,0]
	v_pk_add_f32 v[46:47], v[46:47], 1.0 op_sel_hi:[1,0]
	v_pk_fma_f32 v[48:49], v[68:69], v[48:49], v[54:55]
	v_pk_fma_f32 v[46:47], v[66:67], v[46:47], v[52:53]
	v_cvt_pk_bf16_f32 v46, v46, v47
	v_cvt_pk_bf16_f32 v47, v48, v49
	global_store_dwordx2 v[102:103], v[46:47], off offset:1536
	global_load_dwordx4 v[46:49], v[126:127], off
	s_nop 0
	global_load_dwordx4 v[52:55], v[110:111], off
	s_waitcnt vmcnt(0) lgkmcnt(0)
	v_pk_add_f32 v[48:49], v[48:49], 1.0 op_sel_hi:[1,0]
	v_pk_add_f32 v[46:47], v[46:47], 1.0 op_sel_hi:[1,0]
	v_pk_fma_f32 v[48:49], v[64:65], v[48:49], v[54:55]
	v_pk_fma_f32 v[46:47], v[62:63], v[46:47], v[52:53]
	v_cvt_pk_bf16_f32 v46, v46, v47
	v_cvt_pk_bf16_f32 v47, v48, v49
	global_store_dwordx2 v[102:103], v[46:47], off offset:2048
	global_load_dwordx4 v[46:49], v[120:121], off
	s_nop 0
	global_load_dwordx4 v[52:55], v[110:111], off offset:1024
	s_waitcnt vmcnt(0) lgkmcnt(0)
	v_pk_add_f32 v[48:49], v[48:49], 1.0 op_sel_hi:[1,0]
	v_pk_add_f32 v[46:47], v[46:47], 1.0 op_sel_hi:[1,0]
	v_pk_fma_f32 v[48:49], v[60:61], v[48:49], v[54:55]
	v_pk_fma_f32 v[46:47], v[58:59], v[46:47], v[52:53]
	v_cvt_pk_bf16_f32 v46, v46, v47
	v_cvt_pk_bf16_f32 v47, v48, v49
	global_store_dwordx2 v[102:103], v[46:47], off offset:2560
	global_load_dwordx4 v[46:49], v[116:117], off
	s_nop 0
	global_load_dwordx4 v[52:55], v[110:111], off offset:2048
	v_pk_add_f32 v[58:59], v[146:147], v[146:147] op_sel:[0,1] op_sel_hi:[1,0]
	v_pk_add_f32 v[60:61], v[140:141], v[142:143]
	v_mov_b32_e32 v59, v196
	s_waitcnt vmcnt(0) lgkmcnt(0)
	v_pk_add_f32 v[48:49], v[48:49], 1.0 op_sel_hi:[1,0]
	v_pk_add_f32 v[46:47], v[46:47], 1.0 op_sel_hi:[1,0]
	v_pk_fma_f32 v[48:49], v[56:57], v[48:49], v[54:55]
	v_pk_fma_f32 v[46:47], v[82:83], v[46:47], v[52:53]
	v_cvt_pk_bf16_f32 v46, v46, v47
	v_cvt_pk_bf16_f32 v47, v48, v49
	global_store_dwordx2 v[102:103], v[46:47], off offset:3072
	global_load_dwordx4 v[46:49], v[112:113], off
	s_nop 0
	global_load_dwordx4 v[52:55], v[110:111], off offset:3072
	v_pk_add_f32 v[56:57], v[144:145], v[144:145] op_sel:[0,1] op_sel_hi:[1,0]
	s_waitcnt vmcnt(0) lgkmcnt(0)
	v_pk_add_f32 v[48:49], v[48:49], 1.0 op_sel_hi:[1,0]
	v_pk_add_f32 v[46:47], v[46:47], 1.0 op_sel_hi:[1,0]
	v_pk_fma_f32 v[48:49], v[86:87], v[48:49], v[54:55]
	v_pk_fma_f32 v[46:47], v[84:85], v[46:47], v[52:53]
	v_cvt_pk_bf16_f32 v46, v46, v47
	v_cvt_pk_bf16_f32 v47, v48, v49
	global_store_dwordx2 v[102:103], v[46:47], off offset:3584
	global_load_dwordx4 v[46:49], v[138:139], off
	s_nop 0
	global_load_dwordx4 v[52:55], v[108:109], off
	v_mov_b32_e32 v57, v195
	s_waitcnt vmcnt(0) lgkmcnt(0)
	v_pk_add_f32 v[48:49], v[48:49], 1.0 op_sel_hi:[1,0]
	v_pk_add_f32 v[46:47], v[46:47], 1.0 op_sel_hi:[1,0]
	v_pk_fma_f32 v[48:49], v[156:157], v[48:49], v[54:55]
	v_pk_fma_f32 v[46:47], v[88:89], v[46:47], v[52:53]
	v_bfe_u32 v51, v46, 16, 1
	v_bfe_u32 v52, v47, 16, 1
	v_add3_u32 v46, v46, v51, s26
	v_add3_u32 v47, v47, v52, s26
	v_lshrrev_b32_e32 v46, 16, v46
	v_and_or_b32 v46, v47, s27, v46
	v_cvt_pk_bf16_f32 v47, v48, v49
	global_store_dwordx2 v[104:105], v[46:47], off
	global_load_dwordx4 v[46:49], v[136:137], off
	s_nop 0
	global_load_dwordx4 v[52:55], v[108:109], off offset:1024
	v_pk_mul_f32 v[44:45], v[44:45], v[50:51] op_sel_hi:[1,0]
	v_pk_mul_f32 v[42:43], v[42:43], v[50:51] op_sel_hi:[1,0]
	v_pk_mul_f32 v[44:45], v[44:45], v[8:9]
	v_pk_mul_f32 v[42:43], v[42:43], v[6:7]
	s_waitcnt vmcnt(0) lgkmcnt(0)
	v_pk_add_f32 v[48:49], v[48:49], 1.0 op_sel_hi:[1,0]
	v_pk_add_f32 v[46:47], v[46:47], 1.0 op_sel_hi:[1,0]
	v_pk_fma_f32 v[44:45], v[44:45], v[48:49], v[54:55]
	v_pk_fma_f32 v[42:43], v[42:43], v[46:47], v[52:53]
	v_cvt_pk_bf16_f32 v42, v42, v43
	v_cvt_pk_bf16_f32 v43, v44, v45
	global_store_dwordx2 v[104:105], v[42:43], off offset:512
	global_load_dwordx4 v[42:45], v[132:133], off
	s_nop 0
	global_load_dwordx4 v[46:49], v[108:109], off offset:2048
	v_pk_add_f32 v[52:53], v[56:57], v[58:59]
	s_waitcnt vmcnt(0) lgkmcnt(0)
	v_pk_add_f32 v[44:45], v[44:45], 1.0 op_sel_hi:[1,0]
	v_pk_add_f32 v[52:53], v[52:53], v[60:61]
	v_pk_add_f32 v[42:43], v[42:43], 1.0 op_sel_hi:[1,0]
	v_add_f32_e32 v51, v52, v53
	s_waitcnt lgkmcnt(0)
	s_nop 1
	v_add_f32_dpp v51, v51, v51 quad_perm:[1,0,3,2] row_mask:0xf bank_mask:0xf
	ds_bpermute_b32 v52, v148, v51
	s_waitcnt lgkmcnt(0)
	v_add_f32_e32 v51, v51, v52
	v_pk_mul_f32 v[40:41], v[40:41], v[50:51] op_sel_hi:[1,0]
	v_pk_mul_f32 v[38:39], v[38:39], v[50:51] op_sel_hi:[1,0]
	v_pk_mul_f32 v[40:41], v[40:41], v[12:13]
	v_pk_mul_f32 v[38:39], v[38:39], v[10:11]
	v_pk_fma_f32 v[40:41], v[40:41], v[44:45], v[48:49]
	v_pk_fma_f32 v[38:39], v[38:39], v[42:43], v[46:47]
	v_cvt_pk_bf16_f32 v38, v38, v39
	v_cvt_pk_bf16_f32 v39, v40, v41
	global_store_dwordx2 v[104:105], v[38:39], off offset:1024
	global_load_dwordx4 v[38:41], v[122:123], off
	s_nop 0
	global_load_dwordx4 v[42:45], v[108:109], off offset:3072
	v_pk_mul_f32 v[36:37], v[36:37], v[50:51] op_sel_hi:[1,0]
	v_pk_mul_f32 v[34:35], v[34:35], v[50:51] op_sel_hi:[1,0]
	v_pk_mul_f32 v[36:37], v[36:37], v[16:17]
	v_pk_mul_f32 v[34:35], v[34:35], v[14:15]
	ds_bpermute_b32 v46, v149, v51
	s_waitcnt lgkmcnt(0)
	v_add_f32_e32 v46, v51, v46
	ds_bpermute_b32 v47, v150, v46
	s_waitcnt lgkmcnt(0)
	v_add_f32_e32 v46, v46, v47
	s_waitcnt lgkmcnt(0)
	v_mov_b32_e32 v47, v46
	s_nop 1
	v_permlane16_swap_b32_e32 v46, v47
	v_add_f32_e32 v46, v46, v47
	s_waitcnt lgkmcnt(0)
	v_mov_b32_e32 v47, v46
	s_nop 1
	v_permlane32_swap_b32_e32 v46, v47
	v_add_f32_e32 v46, v46, v47
	v_fmamk_f32 v46, v46, 0x3a800000, v153
	v_mul_f32_e32 v47, 0x4f800000, v46
	v_cmp_gt_f32_e32 vcc, s25, v46
	s_waitcnt vmcnt(0)
	v_pk_add_f32 v[40:41], v[40:41], 1.0 op_sel_hi:[1,0]
	v_pk_add_f32 v[38:39], v[38:39], 1.0 op_sel_hi:[1,0]
	v_pk_fma_f32 v[36:37], v[36:37], v[40:41], v[44:45]
	v_pk_fma_f32 v[34:35], v[34:35], v[38:39], v[42:43]
	v_cvt_pk_bf16_f32 v34, v34, v35
	v_cvt_pk_bf16_f32 v35, v36, v37
	global_store_dwordx2 v[104:105], v[34:35], off offset:1536
	global_load_dwordx4 v[34:37], v[118:119], off
	s_nop 0
	global_load_dwordx4 v[38:41], v[106:107], off
	v_cndmask_b32_e32 v42, v46, v47, vcc
	v_sqrt_f32_e32 v43, v42
	s_waitcnt vmcnt(0) lgkmcnt(0)
	v_pk_add_f32 v[36:37], v[36:37], 1.0 op_sel_hi:[1,0]
	v_add_u32_e32 v44, -1, v43
	v_add_u32_e32 v45, 1, v43
	v_fma_f32 v46, -v44, v43, v42
	v_fma_f32 v47, -v45, v43, v42
	v_cmp_ge_f32_e64 s[6:7], 0, v46
	v_pk_add_f32 v[34:35], v[34:35], 1.0 op_sel_hi:[1,0]
	s_nop 0
	v_cndmask_b32_e64 v43, v43, v44, s[6:7]
	v_cmp_lt_f32_e64 s[6:7], 0, v47
	s_nop 1
	v_cndmask_b32_e64 v43, v43, v45, s[6:7]
	v_mul_f32_e32 v44, 0x37800000, v43
	v_cndmask_b32_e32 v43, v43, v44, vcc
	v_cmp_class_f32_e32 vcc, v42, v154
	s_nop 1
	v_cndmask_b32_e32 v42, v43, v42, vcc
	v_div_scale_f32 v43, s[6:7], v42, v42, 1.0
	v_rcp_f32_e32 v45, v43
	v_div_scale_f32 v44, vcc, 1.0, v42, 1.0
	v_fma_f32 v46, -v43, v45, 1.0
	v_fmac_f32_e32 v45, v46, v45
	v_mul_f32_e32 v46, v44, v45
	v_fma_f32 v47, -v43, v46, v44
	v_fmac_f32_e32 v46, v47, v45
	v_fma_f32 v43, -v43, v46, v44
	v_div_fmas_f32 v43, v43, v45, v46
	v_div_fixup_f32 v42, v43, v42, 1.0
	v_pk_mul_f32 v[32:33], v[32:33], v[42:43] op_sel_hi:[1,0]
	v_pk_mul_f32 v[30:31], v[30:31], v[42:43] op_sel_hi:[1,0]
	v_pk_mul_f32 v[32:33], v[32:33], v[4:5]
	v_pk_mul_f32 v[30:31], v[30:31], v[2:3]
	v_pk_fma_f32 v[32:33], v[32:33], v[36:37], v[40:41]
	v_pk_fma_f32 v[30:31], v[30:31], v[34:35], v[38:39]
	v_cvt_pk_bf16_f32 v30, v30, v31
	v_cvt_pk_bf16_f32 v31, v32, v33
	global_store_dwordx2 v[104:105], v[30:31], off offset:2048
	global_load_dwordx4 v[30:33], v[114:115], off
	s_nop 0
	global_load_dwordx4 v[34:37], v[106:107], off offset:1024
	v_pk_mul_f32 v[28:29], v[28:29], v[42:43] op_sel_hi:[1,0]
	v_pk_mul_f32 v[26:27], v[26:27], v[42:43] op_sel_hi:[1,0]
	v_pk_mul_f32 v[28:29], v[28:29], v[8:9]
	v_pk_mul_f32 v[26:27], v[26:27], v[6:7]
	v_lshl_add_u64 v[38:39], s[22:23], 0, v[98:99]
	v_pk_mul_f32 v[24:25], v[24:25], v[42:43] op_sel_hi:[1,0]
	v_pk_mul_f32 v[22:23], v[22:23], v[42:43] op_sel_hi:[1,0]
	v_pk_mul_f32 v[24:25], v[24:25], v[12:13]
	v_pk_mul_f32 v[22:23], v[22:23], v[10:11]
	v_pk_mul_f32 v[20:21], v[20:21], v[42:43] op_sel_hi:[1,0]
	v_pk_mul_f32 v[18:19], v[18:19], v[42:43] op_sel_hi:[1,0]
	v_pk_mul_f32 v[20:21], v[20:21], v[16:17]
	v_pk_mul_f32 v[18:19], v[18:19], v[14:15]
	s_waitcnt vmcnt(0) lgkmcnt(0)
	v_pk_add_f32 v[32:33], v[32:33], 1.0 op_sel_hi:[1,0]
	v_pk_add_f32 v[30:31], v[30:31], 1.0 op_sel_hi:[1,0]
	v_pk_fma_f32 v[28:29], v[28:29], v[32:33], v[36:37]
	v_pk_fma_f32 v[26:27], v[26:27], v[30:31], v[34:35]
	v_cvt_pk_bf16_f32 v26, v26, v27
	v_cvt_pk_bf16_f32 v27, v28, v29
	global_store_dwordx2 v[104:105], v[26:27], off offset:2560
	global_load_dwordx4 v[26:29], v[38:39], off
	s_nop 0
	global_load_dwordx4 v[30:33], v[106:107], off offset:2048
	v_lshl_add_u64 v[34:35], s[22:23], 0, v[100:101]
	s_waitcnt vmcnt(0) lgkmcnt(0)
	v_pk_add_f32 v[28:29], v[28:29], 1.0 op_sel_hi:[1,0]
	v_pk_add_f32 v[26:27], v[26:27], 1.0 op_sel_hi:[1,0]
	v_pk_fma_f32 v[24:25], v[24:25], v[28:29], v[32:33]
	v_pk_fma_f32 v[22:23], v[22:23], v[26:27], v[30:31]
	v_cvt_pk_bf16_f32 v22, v22, v23
	v_cvt_pk_bf16_f32 v23, v24, v25
	global_store_dwordx2 v[104:105], v[22:23], off offset:3072
	global_load_dwordx4 v[22:25], v[34:35], off
	s_nop 0
	global_load_dwordx4 v[26:29], v[106:107], off offset:3072
	s_waitcnt vmcnt(0) lgkmcnt(0)
	v_pk_add_f32 v[24:25], v[24:25], 1.0 op_sel_hi:[1,0]
	v_pk_add_f32 v[22:23], v[22:23], 1.0 op_sel_hi:[1,0]
	v_pk_fma_f32 v[20:21], v[20:21], v[24:25], v[28:29]
	v_pk_fma_f32 v[18:19], v[18:19], v[22:23], v[26:27]
	v_cvt_pk_bf16_f32 v18, v18, v19
	v_cvt_pk_bf16_f32 v19, v20, v21
	global_store_dwordx2 v[104:105], v[18:19], off offset:3584
	s_cbranch_scc1 .LBB0_3341

.LBB0_3449:
	v_lshl_add_u64 v[18:19], s[38:39], 0, v[94:95]
	v_lshl_add_u64 v[22:23], s[38:39], 0, v[92:93]
	v_add_co_u32_e32 v20, vcc, 0x7800000, v18
	v_add_co_u32_e64 v102, s[6:7], s30, v22
	s_nop 0
	v_addc_co_u32_e32 v21, vcc, 0, v19, vcc
	v_addc_co_u32_e64 v103, s[6:7], 0, v23, s[6:7]
	v_add_co_u32_e64 v104, s[6:7], s31, v22
	v_add_co_u32_e32 v22, vcc, 0x7801000, v18
	s_nop 0
	v_addc_co_u32_e64 v105, s[6:7], 0, v23, s[6:7]
	global_load_dwordx4 v[78:81], v[20:21], off
	global_load_dwordx4 v[74:77], v[20:21], off offset:1024
	global_load_dwordx4 v[70:73], v[20:21], off offset:2048
	global_load_dwordx4 v[66:69], v[20:21], off offset:3072
	v_addc_co_u32_e32 v23, vcc, 0, v19, vcc
	v_add_co_u32_e32 v20, vcc, 0x7802000, v18
	global_load_dwordx4 v[62:65], v[22:23], off
	global_load_dwordx4 v[58:61], v[22:23], off offset:1024
	global_load_dwordx4 v[54:57], v[22:23], off offset:2048
	global_load_dwordx4 v[50:53], v[22:23], off offset:3072
	v_addc_co_u32_e32 v21, vcc, 0, v19, vcc
	global_load_dwordx4 v[46:49], v[20:21], off
	global_load_dwordx4 v[42:45], v[20:21], off offset:1024
	global_load_dwordx4 v[38:41], v[20:21], off offset:2048
	global_load_dwordx4 v[34:37], v[20:21], off offset:3072
	v_add_co_u32_e32 v18, vcc, 0x7803000, v18
	s_ashr_i32 s8, s20, 13
	s_nop 0
	v_addc_co_u32_e32 v19, vcc, 0, v19, vcc
	global_load_dwordx4 v[30:33], v[18:19], off
	global_load_dwordx4 v[26:29], v[18:19], off offset:1024
	global_load_dwordx4 v[22:25], v[18:19], off offset:2048
	s_nop 0
	global_load_dwordx4 v[18:21], v[18:19], off offset:3072
	s_add_i32 s9, s20, 0xffffc002
	s_cmpk_lt_i32 s20, 0x4000
	s_cselect_b32 s6, s8, s9
	s_addk_i32 s6, 0x82
	s_mul_hi_i32 s7, s6, 0x9000
	s_mul_i32 s6, s6, 0x9000
	s_add_u32 s6, s26, s6
	s_addc_u32 s7, s27, s7
	s_add_u32 s10, s6, 0x1000
	s_addc_u32 s11, s7, 0
	v_lshl_add_u64 v[122:123], s[6:7], 0, v[90:91]
	v_lshl_add_u64 v[86:87], s[10:11], 0, v[90:91]
	global_load_dwordx4 v[82:85], v[122:123], off
	s_add_i32 s6, s20, 0xffffc003
	global_load_dwordx4 v[86:89], v[86:87], off
	s_cmpk_lt_i32 s20, 0x3fff
	s_cselect_b32 s6, s8, s6
	s_addk_i32 s6, 0x82
	s_mul_hi_i32 s7, s6, 0x9000
	s_mul_i32 s6, s6, 0x9000
	s_add_u32 s6, s26, s6
	s_addc_u32 s7, s27, s7
	v_lshl_add_u64 v[138:139], s[10:11], 0, v[96:97]
	v_lshl_add_u64 v[134:135], s[10:11], 0, v[98:99]
	v_lshl_add_u64 v[128:129], s[10:11], 0, v[100:101]
	s_add_u32 s10, s6, 0x1000
	v_lshl_add_u64 v[110:111], s[6:7], 0, v[90:91]
	s_addc_u32 s11, s7, 0
	s_add_i32 s6, s20, 0xffffc004
	s_cmpk_lt_i32 s20, 0x3ffe
	s_cselect_b32 s6, s8, s6
	s_addk_i32 s6, 0x82
	s_mul_hi_i32 s7, s6, 0x9000
	s_mul_i32 s6, s6, 0x9000
	v_lshl_add_u64 v[124:125], s[10:11], 0, v[90:91]
	v_lshl_add_u64 v[118:119], s[10:11], 0, v[96:97]
	v_lshl_add_u64 v[114:115], s[10:11], 0, v[98:99]
	v_lshl_add_u64 v[112:113], s[10:11], 0, v[100:101]
	s_add_u32 s10, s26, s6
	s_addc_u32 s11, s27, s7
	s_add_u32 s6, s10, 0x1000
	s_addc_u32 s7, s11, 0
	s_add_i32 s9, s20, 0xffffc005
	s_cmpk_lt_i32 s20, 0x3ffd
	v_lshl_add_u64 v[142:143], s[6:7], 0, v[90:91]
	v_lshl_add_u64 v[140:141], s[6:7], 0, v[96:97]
	v_lshl_add_u64 v[136:137], s[6:7], 0, v[98:99]
	v_lshl_add_u64 v[126:127], s[6:7], 0, v[100:101]
	s_cselect_b32 s6, s8, s9
	s_addk_i32 s6, 0x82
	s_mul_hi_i32 s7, s6, 0x9000
	s_mul_i32 s6, s6, 0x9000
	s_add_u32 s6, s26, s6
	s_addc_u32 s7, s27, s7
	s_add_u32 s44, s6, 0x1000
	v_lshl_add_u64 v[106:107], s[6:7], 0, v[90:91]
	s_addc_u32 s45, s7, 0
	v_lshl_add_u64 v[108:109], s[10:11], 0, v[90:91]
	v_lshl_add_u64 v[120:121], s[44:45], 0, v[90:91]
	v_lshl_add_u64 v[116:117], s[44:45], 0, v[96:97]
	s_add_i32 s20, s20, 32
	v_lshl_add_u64 v[92:93], v[92:93], 0, s[22:23]
	s_waitcnt vmcnt(0) lgkmcnt(0)
	v_pk_mul_f32 v[144:145], v[80:81], v[80:81]
	v_pk_mul_f32 v[146:147], v[78:79], v[78:79]
	v_pk_mul_f32 v[148:149], v[76:77], v[76:77]
	v_pk_mul_f32 v[150:151], v[74:75], v[74:75]
	v_mul_f32_e32 v160, v71, v71
	v_mul_f32_e32 v162, v73, v73
	v_pk_mov_b32 v[164:165], v[146:147], v[144:145] op_sel:[1,0]
	v_mov_b32_e32 v147, v145
	v_pk_mov_b32 v[144:145], v[150:151], v[148:149] op_sel:[1,0]
	v_mov_b32_e32 v151, v149
	v_mul_f32_e32 v173, v68, v68
	v_mul_f32_e32 v175, v69, v69
	v_pk_fma_f32 v[148:149], v[70:71], v[70:71], v[160:161] op_sel_hi:[1,1,0]
	v_pk_fma_f32 v[160:161], v[72:73], v[72:73], v[162:163] op_sel_hi:[1,1,0]
	v_pk_mul_f32 v[162:163], v[64:65], v[64:65]
	v_pk_mul_f32 v[166:167], v[62:63], v[62:63]
	v_pk_mul_f32 v[168:169], v[60:61], v[60:61]
	v_pk_mul_f32 v[170:171], v[58:59], v[58:59]
	v_mul_f32_e32 v172, v55, v55
	v_mul_f32_e32 v174, v57, v57
	v_pk_add_f32 v[146:147], v[164:165], v[146:147]
	v_pk_add_f32 v[144:145], v[144:145], v[150:151]
	v_mul_f32_e32 v159, v66, v66
	v_mul_f32_e32 v183, v67, v67
	v_mov_b32_e32 v149, v173
	v_mov_b32_e32 v161, v175
	v_pk_mov_b32 v[150:151], v[166:167], v[162:163] op_sel:[1,0]
	v_mov_b32_e32 v167, v163
	v_pk_mov_b32 v[162:163], v[170:171], v[168:169] op_sel:[1,0]
	v_mov_b32_e32 v171, v169
	v_pk_fma_f32 v[164:165], v[54:55], v[54:55], v[172:173] op_sel_hi:[1,1,0]
	v_pk_fma_f32 v[168:169], v[56:57], v[56:57], v[174:175] op_sel_hi:[1,1,0]
	v_pk_mul_f32 v[172:173], v[48:49], v[48:49]
	v_pk_mul_f32 v[174:175], v[46:47], v[46:47]
	v_pk_add_f32 v[184:185], v[146:147], v[146:147] op_sel:[0,1] op_sel_hi:[1,0]
	v_pk_add_f32 v[186:187], v[144:145], v[144:145] op_sel:[0,1] op_sel_hi:[1,0]
	v_mul_f32_e32 v181, v52, v52
	v_pk_mul_f32 v[176:177], v[44:45], v[44:45]
	v_pk_mul_f32 v[178:179], v[42:43], v[42:43]
	v_mul_f32_e32 v180, v39, v39
	v_mul_f32_e32 v182, v41, v41
	v_pk_add_f32 v[160:161], v[148:149], v[160:161]
	v_pk_add_f32 v[144:145], v[150:151], v[166:167]
	v_pk_add_f32 v[146:147], v[162:163], v[170:171]
	v_pk_mov_b32 v[148:149], v[174:175], v[172:173] op_sel:[1,0]
	v_mov_b32_e32 v175, v173
	v_mov_b32_e32 v185, v159
	v_mov_b32_e32 v187, v183
	v_mul_f32_e32 v189, v50, v50
	v_mul_f32_e32 v194, v51, v51
	v_mul_f32_e32 v188, v53, v53
	v_mul_f32_e32 v197, v36, v36
	v_mul_f32_e32 v198, v37, v37
	v_pk_mov_b32 v[150:151], v[178:179], v[176:177] op_sel:[1,0]
	v_mov_b32_e32 v179, v177
	v_pk_fma_f32 v[162:163], v[38:39], v[38:39], v[180:181] op_sel_hi:[1,1,0]
	v_pk_fma_f32 v[166:167], v[40:41], v[40:41], v[182:183] op_sel_hi:[1,1,0]
	v_pk_add_f32 v[190:191], v[144:145], v[144:145] op_sel:[0,1] op_sel_hi:[1,0]
	v_pk_add_f32 v[192:193], v[146:147], v[146:147] op_sel:[0,1] op_sel_hi:[1,0]
	v_pk_add_f32 v[148:149], v[148:149], v[174:175]
	v_pk_add_f32 v[174:175], v[184:185], v[186:187]
	v_mov_b32_e32 v165, v181
	v_mov_b32_e32 v169, v188
	v_pk_mul_f32 v[170:171], v[32:33], v[32:33]
	v_pk_mul_f32 v[172:173], v[30:31], v[30:31]
	v_pk_mul_f32 v[176:177], v[28:29], v[28:29]
	v_pk_mul_f32 v[180:181], v[26:27], v[26:27]
	v_pk_add_f32 v[150:151], v[150:151], v[178:179]
	v_mov_b32_e32 v163, v197
	v_mov_b32_e32 v167, v198
	v_mov_b32_e32 v191, v189
	v_mov_b32_e32 v193, v194
	v_pk_add_f32 v[160:161], v[174:175], v[160:161]
	v_mul_f32_e32 v195, v34, v34
	v_mul_f32_e32 v196, v35, v35
	v_pk_add_f32 v[164:165], v[164:165], v[168:169]
	v_pk_mov_b32 v[168:169], v[172:173], v[170:171] op_sel:[1,0]
	v_mov_b32_e32 v173, v171
	v_pk_mov_b32 v[170:171], v[180:181], v[176:177] op_sel:[1,0]
	v_mov_b32_e32 v181, v177
	v_pk_add_f32 v[176:177], v[148:149], v[148:149] op_sel:[0,1] op_sel_hi:[1,0]
	v_pk_add_f32 v[178:179], v[150:151], v[150:151] op_sel:[0,1] op_sel_hi:[1,0]
	v_pk_add_f32 v[162:163], v[162:163], v[166:167]
	v_pk_add_f32 v[166:167], v[190:191], v[192:193]
	v_add_f32_e32 v159, v160, v161
	v_mov_b32_e32 v177, v195
	v_mov_b32_e32 v179, v196
	v_pk_add_f32 v[160:161], v[166:167], v[164:165]
	ds_bpermute_b32 v167, v133, v159
	v_pk_add_f32 v[164:165], v[176:177], v[178:179]
	v_add_f32_e32 v166, v160, v161
	v_pk_add_f32 v[160:161], v[164:165], v[162:163]
	v_add_f32_e32 v160, v160, v161
	s_waitcnt lgkmcnt(0)
	v_add_f32_e32 v159, v159, v167
	s_waitcnt lgkmcnt(0)
	s_nop 1
	v_add_f32_dpp v162, v166, v166 quad_perm:[1,0,3,2] row_mask:0xf bank_mask:0xf
	s_waitcnt lgkmcnt(0)
	s_nop 1
	v_add_f32_dpp v160, v160, v160 quad_perm:[1,0,3,2] row_mask:0xf bank_mask:0xf
	s_waitcnt lgkmcnt(0)
	s_nop 1
	v_add_f32_dpp v159, v159, v159 quad_perm:[2,3,0,1] row_mask:0xf bank_mask:0xf
	ds_bpermute_b32 v163, v153, v159
	s_waitcnt lgkmcnt(2)
	s_nop 1
	v_add_f32_dpp v162, v162, v162 quad_perm:[2,3,0,1] row_mask:0xf bank_mask:0xf
	s_waitcnt lgkmcnt(0)
	s_nop 1
	v_add_f32_dpp v160, v160, v160 quad_perm:[2,3,0,1] row_mask:0xf bank_mask:0xf
	s_waitcnt lgkmcnt(0)
	v_add_f32_e32 v159, v159, v163
	ds_bpermute_b32 v163, v154, v159
	s_waitcnt lgkmcnt(2)
	s_nop 1
	v_add_f32_dpp v162, v162, v162 row_half_mirror row_mask:0xf bank_mask:0xf
	s_waitcnt lgkmcnt(0)
	s_nop 1
	v_add_f32_dpp v160, v160, v160 row_half_mirror row_mask:0xf bank_mask:0xf
	s_waitcnt lgkmcnt(0)
	v_add_f32_e32 v159, v159, v163
	s_waitcnt lgkmcnt(0)
	s_nop 1
	v_add_f32_dpp v162, v162, v162 row_mirror row_mask:0xf bank_mask:0xf
	s_waitcnt lgkmcnt(0)
	s_nop 1
	v_add_f32_dpp v160, v160, v160 row_mirror row_mask:0xf bank_mask:0xf
	s_waitcnt lgkmcnt(0)
	v_mov_b32_e32 v163, v159
	s_nop 1
	v_permlane16_swap_b32_e32 v159, v163
	v_add_f32_e32 v159, v159, v163
	s_waitcnt lgkmcnt(0)
	v_mov_b32_e32 v164, v162
	s_nop 1
	v_permlane16_swap_b32_e32 v162, v164
	v_add_f32_e32 v162, v162, v164
	s_waitcnt lgkmcnt(0)
	v_mov_b32_e32 v161, v160
	s_nop 1
	v_permlane16_swap_b32_e32 v160, v161
	v_add_f32_e32 v160, v160, v161
	s_waitcnt lgkmcnt(0)
	v_mov_b32_e32 v163, v159
	s_nop 1
	v_permlane32_swap_b32_e32 v159, v163
	v_add_f32_e32 v159, v159, v163
	v_fmamk_f32 v159, v159, 0x3a800000, v157
	s_waitcnt lgkmcnt(1)
	v_mov_b32_e32 v164, v162
	s_nop 1
	v_permlane32_swap_b32_e32 v162, v164
	v_add_f32_e32 v162, v162, v164
	v_mul_f32_e32 v163, 0x4f800000, v159
	v_cmp_gt_f32_e32 vcc, s21, v159
	v_fmamk_f32 v162, v162, 0x3a800000, v157
	s_waitcnt lgkmcnt(0)
	v_mov_b32_e32 v161, v160
	s_nop 1
	v_permlane32_swap_b32_e32 v160, v161
	v_add_f32_e32 v160, v160, v161
	v_cndmask_b32_e32 v159, v159, v163, vcc
	v_mul_f32_e32 v161, 0x4f800000, v162
	v_cmp_gt_f32_e64 s[6:7], s21, v162
	v_sqrt_f32_e32 v163, v159
	v_fmamk_f32 v160, v160, 0x3a800000, v157
	v_cndmask_b32_e64 v161, v162, v161, s[6:7]
	v_mul_f32_e32 v162, 0x4f800000, v160
	v_cmp_gt_f32_e64 s[8:9], s21, v160
	v_sqrt_f32_e32 v164, v161
	v_add_u32_e32 v165, -1, v163
	v_cndmask_b32_e64 v160, v160, v162, s[8:9]
	v_sqrt_f32_e32 v162, v160
	v_add_u32_e32 v166, 1, v163
	v_fma_f32 v167, -v165, v163, v159
	v_pk_add_f32 v[148:149], v[168:169], v[172:173]
	v_fma_f32 v168, -v166, v163, v159
	v_add_u32_e32 v169, -1, v164
	v_cmp_ge_f32_e64 s[10:11], 0, v167
	v_pk_add_f32 v[150:151], v[170:171], v[180:181]
	v_add_u32_e32 v170, 1, v164
	v_cndmask_b32_e64 v163, v163, v165, s[10:11]
	v_fma_f32 v165, -v169, v164, v161
	v_cmp_lt_f32_e64 s[10:11], 0, v168
	v_fma_f32 v167, -v170, v164, v161
	v_add_u32_e32 v171, -1, v162
	v_cndmask_b32_e64 v163, v163, v166, s[10:11]
	v_cmp_ge_f32_e64 s[10:11], 0, v165
	v_add_u32_e32 v172, 1, v162
	v_fma_f32 v165, -v171, v162, v160
	v_cndmask_b32_e64 v164, v164, v169, s[10:11]
	v_cmp_lt_f32_e64 s[10:11], 0, v167
	v_fma_f32 v166, -v172, v162, v160
	v_mul_f32_e32 v167, 0x37800000, v163
	v_cndmask_b32_e64 v164, v164, v170, s[10:11]
	v_cmp_ge_f32_e64 s[10:11], 0, v165
	v_cndmask_b32_e32 v163, v163, v167, vcc
	v_cmp_class_f32_e32 vcc, v159, v158
	v_cndmask_b32_e64 v162, v162, v171, s[10:11]
	v_cmp_lt_f32_e64 s[10:11], 0, v166
	v_mul_f32_e32 v165, 0x37800000, v164
	v_cndmask_b32_e32 v159, v163, v159, vcc
	v_cndmask_b32_e64 v162, v162, v172, s[10:11]
	v_cndmask_b32_e64 v163, v164, v165, s[6:7]
	v_cmp_class_f32_e32 vcc, v161, v158
	v_mul_f32_e32 v164, 0x37800000, v162
	v_div_scale_f32 v165, s[6:7], v159, v159, 1.0
	v_cndmask_b32_e32 v161, v163, v161, vcc
	v_cndmask_b32_e64 v162, v162, v164, s[8:9]
	v_cmp_class_f32_e32 vcc, v160, v158
	v_rcp_f32_e32 v163, v165
	v_div_scale_f32 v164, s[8:9], v161, v161, 1.0
	v_cndmask_b32_e32 v162, v162, v160, vcc
	v_rcp_f32_e32 v168, v164
	v_div_scale_f32 v169, s[10:11], v162, v162, 1.0
	v_rcp_f32_e32 v171, v169
	v_fma_f32 v160, -v165, v163, 1.0
	v_div_scale_f32 v166, s[6:7], 1.0, v159, 1.0
	v_fmac_f32_e32 v163, v160, v163
	v_fma_f32 v160, -v164, v168, 1.0
	v_mul_f32_e32 v172, v166, v163
	v_div_scale_f32 v167, s[8:9], 1.0, v161, 1.0
	v_fmac_f32_e32 v168, v160, v168
	v_fma_f32 v160, -v169, v171, 1.0
	v_fma_f32 v173, -v165, v172, v166
	v_div_scale_f32 v170, s[10:11], 1.0, v162, 1.0
	v_mul_f32_e32 v174, v167, v168
	v_fmac_f32_e32 v171, v160, v171
	v_fmac_f32_e32 v172, v173, v163
	v_fma_f32 v160, -v164, v174, v167
	v_mul_f32_e32 v173, v170, v171
	v_fma_f32 v165, -v165, v172, v166
	s_mov_b64 vcc, s[6:7]
	v_fmac_f32_e32 v174, v160, v168
	v_fma_f32 v160, -v169, v173, v170
	v_div_fmas_f32 v163, v165, v163, v172
	v_fma_f32 v164, -v164, v174, v167
	v_fmac_f32_e32 v173, v160, v171
	v_div_fixup_f32 v160, v163, v159, 1.0
	s_mov_b64 vcc, s[8:9]
	v_div_fmas_f32 v159, v164, v168, v174
	v_fma_f32 v163, -v169, v173, v170
	v_pk_mul_f32 v[80:81], v[80:81], v[160:161] op_sel_hi:[1,0]
	v_pk_mul_f32 v[78:79], v[78:79], v[160:161] op_sel_hi:[1,0]
	s_mov_b64 vcc, s[10:11]
	v_pk_add_f32 v[88:89], v[88:89], 1.0 op_sel_hi:[1,0]
	v_pk_add_f32 v[86:87], v[86:87], 1.0 op_sel_hi:[1,0]
	v_pk_mul_f32 v[76:77], v[76:77], v[160:161] op_sel_hi:[1,0]
	v_pk_mul_f32 v[74:75], v[74:75], v[160:161] op_sel_hi:[1,0]
	v_pk_mul_f32 v[72:73], v[72:73], v[160:161] op_sel_hi:[1,0]
	v_pk_mul_f32 v[70:71], v[70:71], v[160:161] op_sel_hi:[1,0]
	v_pk_mul_f32 v[68:69], v[68:69], v[160:161] op_sel_hi:[1,0]
	v_pk_mul_f32 v[66:67], v[66:67], v[160:161] op_sel_hi:[1,0]
	v_div_fixup_f32 v160, v159, v161, 1.0
	v_div_fmas_f32 v159, v163, v171, v173
	v_pk_mul_f32 v[78:79], v[78:79], v[2:3]
	v_pk_mul_f32 v[80:81], v[80:81], v[4:5]
	v_pk_mul_f32 v[64:65], v[64:65], v[160:161] op_sel_hi:[1,0]
	v_pk_mul_f32 v[62:63], v[62:63], v[160:161] op_sel_hi:[1,0]
	v_pk_mul_f32 v[60:61], v[60:61], v[160:161] op_sel_hi:[1,0]
	v_pk_mul_f32 v[58:59], v[58:59], v[160:161] op_sel_hi:[1,0]
	v_pk_mul_f32 v[56:57], v[56:57], v[160:161] op_sel_hi:[1,0]
	v_pk_mul_f32 v[54:55], v[54:55], v[160:161] op_sel_hi:[1,0]
	v_pk_mul_f32 v[52:53], v[52:53], v[160:161] op_sel_hi:[1,0]
	v_pk_mul_f32 v[50:51], v[50:51], v[160:161] op_sel_hi:[1,0]
	v_div_fixup_f32 v160, v159, v162, 1.0
	v_pk_fma_f32 v[80:81], v[80:81], v[88:89], v[84:85]
	v_pk_fma_f32 v[78:79], v[78:79], v[86:87], v[82:83]
	v_pk_mul_f32 v[82:83], v[50:51], v[14:15]
	v_pk_mul_f32 v[84:85], v[52:53], v[16:17]
	v_pk_mul_f32 v[48:49], v[48:49], v[160:161] op_sel_hi:[1,0]
	v_pk_mul_f32 v[46:47], v[46:47], v[160:161] op_sel_hi:[1,0]
	v_pk_mul_f32 v[86:87], v[46:47], v[2:3]
	v_pk_mul_f32 v[88:89], v[48:49], v[4:5]
	v_cvt_pk_bf16_f32 v46, v78, v79
	v_cvt_pk_bf16_f32 v47, v80, v81
	global_store_dwordx2 v[102:103], v[46:47], off
	global_load_dwordx4 v[46:49], v[138:139], off
	s_nop 0
	global_load_dwordx4 v[50:53], v[122:123], off offset:1024
	v_pk_mul_f32 v[74:75], v[74:75], v[6:7]
	v_pk_mul_f32 v[76:77], v[76:77], v[8:9]
	v_pk_mul_f32 v[70:71], v[70:71], v[10:11]
	v_pk_mul_f32 v[72:73], v[72:73], v[12:13]
	v_pk_mul_f32 v[66:67], v[66:67], v[14:15]
	v_pk_mul_f32 v[68:69], v[68:69], v[16:17]
	v_pk_mul_f32 v[62:63], v[62:63], v[2:3]
	v_pk_mul_f32 v[64:65], v[64:65], v[4:5]
	v_pk_mul_f32 v[58:59], v[58:59], v[6:7]
	v_pk_mul_f32 v[60:61], v[60:61], v[8:9]
	v_pk_mul_f32 v[54:55], v[54:55], v[10:11]
	v_pk_mul_f32 v[56:57], v[56:57], v[12:13]
	v_pk_mul_f32 v[44:45], v[44:45], v[160:161] op_sel_hi:[1,0]
	v_pk_mul_f32 v[42:43], v[42:43], v[160:161] op_sel_hi:[1,0]
	v_pk_mul_f32 v[44:45], v[44:45], v[8:9]
	v_pk_mul_f32 v[42:43], v[42:43], v[6:7]
	v_pk_mul_f32 v[40:41], v[40:41], v[160:161] op_sel_hi:[1,0]
	v_pk_mul_f32 v[38:39], v[38:39], v[160:161] op_sel_hi:[1,0]
	v_pk_mul_f32 v[40:41], v[40:41], v[12:13]
	v_pk_mul_f32 v[38:39], v[38:39], v[10:11]
	v_pk_mul_f32 v[36:37], v[36:37], v[160:161] op_sel_hi:[1,0]
	v_pk_mul_f32 v[34:35], v[34:35], v[160:161] op_sel_hi:[1,0]
	v_pk_mul_f32 v[36:37], v[36:37], v[16:17]
	v_pk_mul_f32 v[34:35], v[34:35], v[14:15]
	v_mul_f32_e32 v182, v23, v23
	v_mul_f32_e32 v188, v25, v25
	v_mul_f32_e32 v199, v18, v18
	v_mul_f32_e32 v200, v19, v19
	v_mul_f32_e32 v201, v20, v20
	v_mul_f32_e32 v202, v21, v21
	v_pk_fma_f32 v[144:145], v[22:23], v[22:23], v[182:183] op_sel_hi:[1,1,0]
	v_pk_fma_f32 v[146:147], v[24:25], v[24:25], v[188:189] op_sel_hi:[1,1,0]
	v_mov_b32_e32 v145, v201
	v_mov_b32_e32 v147, v202
	v_lshl_add_u64 v[94:95], v[94:95], 0, s[24:25]
	s_cmp_lt_i32 s20, s13
	s_waitcnt vmcnt(0) lgkmcnt(0)
	v_pk_add_f32 v[48:49], v[48:49], 1.0 op_sel_hi:[1,0]
	v_pk_add_f32 v[46:47], v[46:47], 1.0 op_sel_hi:[1,0]
	v_pk_fma_f32 v[48:49], v[76:77], v[48:49], v[52:53]
	v_pk_fma_f32 v[46:47], v[74:75], v[46:47], v[50:51]
	v_cvt_pk_bf16_f32 v46, v46, v47
	v_cvt_pk_bf16_f32 v47, v48, v49
	global_store_dwordx2 v[102:103], v[46:47], off offset:512
	global_load_dwordx4 v[46:49], v[134:135], off
	s_nop 0
	global_load_dwordx4 v[50:53], v[122:123], off offset:2048
	s_waitcnt vmcnt(0) lgkmcnt(0)
	v_pk_add_f32 v[48:49], v[48:49], 1.0 op_sel_hi:[1,0]
	v_pk_add_f32 v[46:47], v[46:47], 1.0 op_sel_hi:[1,0]
	v_pk_fma_f32 v[48:49], v[72:73], v[48:49], v[52:53]
	v_pk_fma_f32 v[46:47], v[70:71], v[46:47], v[50:51]
	v_cvt_pk_bf16_f32 v46, v46, v47
	v_cvt_pk_bf16_f32 v47, v48, v49
	global_store_dwordx2 v[102:103], v[46:47], off offset:1024
	global_load_dwordx4 v[46:49], v[128:129], off
	s_nop 0
	global_load_dwordx4 v[50:53], v[122:123], off offset:3072
	s_waitcnt vmcnt(0) lgkmcnt(0)
	v_pk_add_f32 v[48:49], v[48:49], 1.0 op_sel_hi:[1,0]
	v_pk_add_f32 v[46:47], v[46:47], 1.0 op_sel_hi:[1,0]
	v_pk_fma_f32 v[48:49], v[68:69], v[48:49], v[52:53]
	v_pk_fma_f32 v[46:47], v[66:67], v[46:47], v[50:51]
	v_cvt_pk_bf16_f32 v46, v46, v47
	v_cvt_pk_bf16_f32 v47, v48, v49
	global_store_dwordx2 v[102:103], v[46:47], off offset:1536
	global_load_dwordx4 v[46:49], v[124:125], off
	s_nop 0
	global_load_dwordx4 v[50:53], v[110:111], off
	s_waitcnt vmcnt(0) lgkmcnt(0)
	v_pk_add_f32 v[48:49], v[48:49], 1.0 op_sel_hi:[1,0]
	v_pk_add_f32 v[46:47], v[46:47], 1.0 op_sel_hi:[1,0]
	v_pk_fma_f32 v[48:49], v[64:65], v[48:49], v[52:53]
	v_pk_fma_f32 v[46:47], v[62:63], v[46:47], v[50:51]
	v_cvt_pk_bf16_f32 v46, v46, v47
	v_cvt_pk_bf16_f32 v47, v48, v49
	global_store_dwordx2 v[102:103], v[46:47], off offset:2048
	global_load_dwordx4 v[46:49], v[118:119], off
	s_nop 0
	global_load_dwordx4 v[50:53], v[110:111], off offset:1024
	s_waitcnt vmcnt(0) lgkmcnt(0)
	v_pk_add_f32 v[48:49], v[48:49], 1.0 op_sel_hi:[1,0]
	v_pk_add_f32 v[46:47], v[46:47], 1.0 op_sel_hi:[1,0]
	v_pk_fma_f32 v[48:49], v[60:61], v[48:49], v[52:53]
	v_pk_fma_f32 v[46:47], v[58:59], v[46:47], v[50:51]
	v_cvt_pk_bf16_f32 v46, v46, v47
	v_cvt_pk_bf16_f32 v47, v48, v49
	global_store_dwordx2 v[102:103], v[46:47], off offset:2560
	global_load_dwordx4 v[46:49], v[114:115], off
	s_nop 0
	global_load_dwordx4 v[50:53], v[110:111], off offset:2048
	v_pk_add_f32 v[58:59], v[144:145], v[146:147]
	s_waitcnt vmcnt(0) lgkmcnt(0)
	v_pk_add_f32 v[48:49], v[48:49], 1.0 op_sel_hi:[1,0]
	v_pk_add_f32 v[46:47], v[46:47], 1.0 op_sel_hi:[1,0]
	v_pk_fma_f32 v[48:49], v[56:57], v[48:49], v[52:53]
	v_pk_fma_f32 v[46:47], v[54:55], v[46:47], v[50:51]
	v_cvt_pk_bf16_f32 v46, v46, v47
	v_cvt_pk_bf16_f32 v47, v48, v49
	global_store_dwordx2 v[102:103], v[46:47], off offset:3072
	global_load_dwordx4 v[46:49], v[112:113], off
	s_nop 0
	global_load_dwordx4 v[50:53], v[110:111], off offset:3072
	v_pk_add_f32 v[54:55], v[148:149], v[148:149] op_sel:[0,1] op_sel_hi:[1,0]
	v_pk_add_f32 v[56:57], v[150:151], v[150:151] op_sel:[0,1] op_sel_hi:[1,0]
	v_mov_b32_e32 v55, v199
	v_mov_b32_e32 v57, v200
	s_waitcnt vmcnt(0) lgkmcnt(0)
	v_pk_add_f32 v[48:49], v[48:49], 1.0 op_sel_hi:[1,0]
	v_pk_add_f32 v[46:47], v[46:47], 1.0 op_sel_hi:[1,0]
	v_pk_fma_f32 v[48:49], v[84:85], v[48:49], v[52:53]
	v_pk_fma_f32 v[46:47], v[82:83], v[46:47], v[50:51]
	v_cvt_pk_bf16_f32 v46, v46, v47
	v_cvt_pk_bf16_f32 v47, v48, v49
	global_store_dwordx2 v[102:103], v[46:47], off offset:3584
	global_load_dwordx4 v[46:49], v[142:143], off
	s_nop 0
	global_load_dwordx4 v[50:53], v[108:109], off
	s_waitcnt vmcnt(0) lgkmcnt(0)
	v_pk_add_f32 v[48:49], v[48:49], 1.0 op_sel_hi:[1,0]
	v_pk_add_f32 v[46:47], v[46:47], 1.0 op_sel_hi:[1,0]
	v_pk_fma_f32 v[48:49], v[88:89], v[48:49], v[52:53]
	v_pk_fma_f32 v[46:47], v[86:87], v[46:47], v[50:51]
	v_cvt_pk_bf16_f32 v46, v46, v47
	v_cvt_pk_bf16_f32 v47, v48, v49
	global_store_dwordx2 v[104:105], v[46:47], off
	global_load_dwordx4 v[46:49], v[140:141], off
	s_nop 0
	global_load_dwordx4 v[50:53], v[108:109], off offset:1024
	s_waitcnt vmcnt(0) lgkmcnt(0)
	v_pk_add_f32 v[48:49], v[48:49], 1.0 op_sel_hi:[1,0]
	v_pk_add_f32 v[46:47], v[46:47], 1.0 op_sel_hi:[1,0]
	v_pk_fma_f32 v[44:45], v[44:45], v[48:49], v[52:53]
	v_pk_fma_f32 v[42:43], v[42:43], v[46:47], v[50:51]
	v_cvt_pk_bf16_f32 v42, v42, v43
	v_cvt_pk_bf16_f32 v43, v44, v45
	global_store_dwordx2 v[104:105], v[42:43], off offset:512
	global_load_dwordx4 v[42:45], v[136:137], off
	s_nop 0
	global_load_dwordx4 v[46:49], v[108:109], off offset:2048
	v_pk_add_f32 v[50:51], v[54:55], v[56:57]
	s_waitcnt vmcnt(0) lgkmcnt(0)
	v_pk_add_f32 v[44:45], v[44:45], 1.0 op_sel_hi:[1,0]
	v_pk_add_f32 v[42:43], v[42:43], 1.0 op_sel_hi:[1,0]
	v_pk_fma_f32 v[40:41], v[40:41], v[44:45], v[48:49]
	v_pk_fma_f32 v[38:39], v[38:39], v[42:43], v[46:47]
	v_cvt_pk_bf16_f32 v38, v38, v39
	v_cvt_pk_bf16_f32 v39, v40, v41
	global_store_dwordx2 v[104:105], v[38:39], off offset:1024
	global_load_dwordx4 v[38:41], v[126:127], off
	s_nop 0
	global_load_dwordx4 v[42:45], v[108:109], off offset:3072
	v_pk_add_f32 v[50:51], v[50:51], v[58:59]
	s_waitcnt vmcnt(0) lgkmcnt(0)
	v_pk_add_f32 v[40:41], v[40:41], 1.0 op_sel_hi:[1,0]
	v_pk_add_f32 v[38:39], v[38:39], 1.0 op_sel_hi:[1,0]
	v_pk_fma_f32 v[36:37], v[36:37], v[40:41], v[44:45]
	v_pk_fma_f32 v[34:35], v[34:35], v[38:39], v[42:43]
	v_cvt_pk_bf16_f32 v34, v34, v35
	v_cvt_pk_bf16_f32 v35, v36, v37
	global_store_dwordx2 v[104:105], v[34:35], off offset:1536
	global_load_dwordx4 v[34:37], v[120:121], off
	s_nop 0
	global_load_dwordx4 v[38:41], v[106:107], off
	v_add_f32_e32 v50, v50, v51
	s_waitcnt lgkmcnt(0)
	s_nop 1
	v_add_f32_dpp v50, v50, v50 quad_perm:[1,0,3,2] row_mask:0xf bank_mask:0xf
	ds_bpermute_b32 v51, v152, v50
	s_waitcnt lgkmcnt(0)
	v_add_f32_e32 v50, v50, v51
	ds_bpermute_b32 v46, v153, v50
	s_waitcnt lgkmcnt(0)
	v_add_f32_e32 v46, v50, v46
	ds_bpermute_b32 v47, v154, v46
	s_waitcnt lgkmcnt(0)
	v_add_f32_e32 v46, v46, v47
	s_waitcnt lgkmcnt(0)
	v_mov_b32_e32 v47, v46
	s_nop 1
	v_permlane16_swap_b32_e32 v46, v47
	v_add_f32_e32 v46, v46, v47
	s_waitcnt lgkmcnt(0)
	v_mov_b32_e32 v47, v46
	s_nop 1
	v_permlane32_swap_b32_e32 v46, v47
	v_add_f32_e32 v46, v46, v47
	v_fmamk_f32 v46, v46, 0x3a800000, v157
	v_mul_f32_e32 v47, 0x4f800000, v46
	v_cmp_gt_f32_e32 vcc, s21, v46
	s_waitcnt vmcnt(0)
	v_pk_add_f32 v[36:37], v[36:37], 1.0 op_sel_hi:[1,0]
	v_cndmask_b32_e32 v42, v46, v47, vcc
	v_sqrt_f32_e32 v43, v42
	v_pk_add_f32 v[34:35], v[34:35], 1.0 op_sel_hi:[1,0]
	v_add_u32_e32 v44, -1, v43
	v_add_u32_e32 v45, 1, v43
	v_fma_f32 v46, -v44, v43, v42
	v_fma_f32 v47, -v45, v43, v42
	v_cmp_ge_f32_e64 s[6:7], 0, v46
	s_nop 1
	v_cndmask_b32_e64 v43, v43, v44, s[6:7]
	v_cmp_lt_f32_e64 s[6:7], 0, v47
	s_nop 1
	v_cndmask_b32_e64 v43, v43, v45, s[6:7]
	v_mul_f32_e32 v44, 0x37800000, v43
	v_cndmask_b32_e32 v43, v43, v44, vcc
	v_cmp_class_f32_e32 vcc, v42, v158
	s_nop 1
	v_cndmask_b32_e32 v42, v43, v42, vcc
	v_div_scale_f32 v43, s[6:7], v42, v42, 1.0
	v_rcp_f32_e32 v45, v43
	v_div_scale_f32 v44, vcc, 1.0, v42, 1.0
	v_fma_f32 v46, -v43, v45, 1.0
	v_fmac_f32_e32 v45, v46, v45
	v_mul_f32_e32 v46, v44, v45
	v_fma_f32 v47, -v43, v46, v44
	v_fmac_f32_e32 v46, v47, v45
	v_fma_f32 v43, -v43, v46, v44
	v_div_fmas_f32 v43, v43, v45, v46
	v_div_fixup_f32 v42, v43, v42, 1.0
	v_pk_mul_f32 v[32:33], v[32:33], v[42:43] op_sel_hi:[1,0]
	v_pk_mul_f32 v[30:31], v[30:31], v[42:43] op_sel_hi:[1,0]
	v_pk_mul_f32 v[32:33], v[32:33], v[4:5]
	v_pk_mul_f32 v[30:31], v[30:31], v[2:3]
	v_pk_fma_f32 v[32:33], v[32:33], v[36:37], v[40:41]
	v_pk_fma_f32 v[30:31], v[30:31], v[34:35], v[38:39]
	v_cvt_pk_bf16_f32 v30, v30, v31
	v_cvt_pk_bf16_f32 v31, v32, v33
	global_store_dwordx2 v[104:105], v[30:31], off offset:2048
	global_load_dwordx4 v[30:33], v[116:117], off
	s_nop 0
	global_load_dwordx4 v[34:37], v[106:107], off offset:1024
	v_pk_mul_f32 v[28:29], v[28:29], v[42:43] op_sel_hi:[1,0]
	v_pk_mul_f32 v[26:27], v[26:27], v[42:43] op_sel_hi:[1,0]
	v_pk_mul_f32 v[28:29], v[28:29], v[8:9]
	v_pk_mul_f32 v[26:27], v[26:27], v[6:7]
	v_lshl_add_u64 v[38:39], s[44:45], 0, v[98:99]
	v_pk_mul_f32 v[24:25], v[24:25], v[42:43] op_sel_hi:[1,0]
	v_pk_mul_f32 v[22:23], v[22:23], v[42:43] op_sel_hi:[1,0]
	v_pk_mul_f32 v[24:25], v[24:25], v[12:13]
	v_pk_mul_f32 v[22:23], v[22:23], v[10:11]
	v_pk_mul_f32 v[20:21], v[20:21], v[42:43] op_sel_hi:[1,0]
	v_pk_mul_f32 v[18:19], v[18:19], v[42:43] op_sel_hi:[1,0]
	v_pk_mul_f32 v[20:21], v[20:21], v[16:17]
	v_pk_mul_f32 v[18:19], v[18:19], v[14:15]
	s_waitcnt vmcnt(0) lgkmcnt(0)
	v_pk_add_f32 v[32:33], v[32:33], 1.0 op_sel_hi:[1,0]
	v_pk_add_f32 v[30:31], v[30:31], 1.0 op_sel_hi:[1,0]
	v_pk_fma_f32 v[28:29], v[28:29], v[32:33], v[36:37]
	v_pk_fma_f32 v[26:27], v[26:27], v[30:31], v[34:35]
	v_cvt_pk_bf16_f32 v26, v26, v27
	v_cvt_pk_bf16_f32 v27, v28, v29
	global_store_dwordx2 v[104:105], v[26:27], off offset:2560
	global_load_dwordx4 v[26:29], v[38:39], off
	s_nop 0
	global_load_dwordx4 v[30:33], v[106:107], off offset:2048
	v_lshl_add_u64 v[34:35], s[44:45], 0, v[100:101]
	s_waitcnt vmcnt(0) lgkmcnt(0)
	v_pk_add_f32 v[28:29], v[28:29], 1.0 op_sel_hi:[1,0]
	v_pk_add_f32 v[26:27], v[26:27], 1.0 op_sel_hi:[1,0]
	v_pk_fma_f32 v[24:25], v[24:25], v[28:29], v[32:33]
	v_pk_fma_f32 v[22:23], v[22:23], v[26:27], v[30:31]
	v_cvt_pk_bf16_f32 v22, v22, v23
	v_cvt_pk_bf16_f32 v23, v24, v25
	global_store_dwordx2 v[104:105], v[22:23], off offset:3072
	global_load_dwordx4 v[22:25], v[34:35], off
	s_nop 0
	global_load_dwordx4 v[26:29], v[106:107], off offset:3072
	s_waitcnt vmcnt(0) lgkmcnt(0)
	v_pk_add_f32 v[24:25], v[24:25], 1.0 op_sel_hi:[1,0]
	v_pk_add_f32 v[22:23], v[22:23], 1.0 op_sel_hi:[1,0]
	v_pk_fma_f32 v[20:21], v[20:21], v[24:25], v[28:29]
	v_pk_fma_f32 v[18:19], v[18:19], v[22:23], v[26:27]
	v_cvt_pk_bf16_f32 v18, v18, v19
	v_cvt_pk_bf16_f32 v19, v20, v21
	global_store_dwordx2 v[104:105], v[18:19], off offset:3584
	s_cbranch_scc1 .LBB0_3449

.LBB0_3611:
	v_lshl_add_u64 v[18:19], s[38:39], 0, v[94:95]
	v_lshl_add_u64 v[22:23], s[38:39], 0, v[92:93]
	v_add_co_u32_e32 v20, vcc, 0x7800000, v18
	v_add_co_u32_e64 v102, s[6:7], s23, v22
	s_nop 0
	v_addc_co_u32_e32 v21, vcc, 0, v19, vcc
	v_addc_co_u32_e64 v103, s[6:7], 0, v23, s[6:7]
	v_add_co_u32_e64 v104, s[6:7], s24, v22
	v_add_co_u32_e32 v22, vcc, 0x7801000, v18
	s_nop 0
	v_addc_co_u32_e64 v105, s[6:7], 0, v23, s[6:7]
	global_load_dwordx4 v[78:81], v[20:21], off
	global_load_dwordx4 v[74:77], v[20:21], off offset:1024
	global_load_dwordx4 v[70:73], v[20:21], off offset:2048
	global_load_dwordx4 v[66:69], v[20:21], off offset:3072
	v_addc_co_u32_e32 v23, vcc, 0, v19, vcc
	v_add_co_u32_e32 v20, vcc, 0x7802000, v18
	global_load_dwordx4 v[62:65], v[22:23], off
	global_load_dwordx4 v[58:61], v[22:23], off offset:1024
	global_load_dwordx4 v[54:57], v[22:23], off offset:2048
	global_load_dwordx4 v[50:53], v[22:23], off offset:3072
	v_addc_co_u32_e32 v21, vcc, 0, v19, vcc
	v_add_co_u32_e32 v82, vcc, 0x7803000, v18
	global_load_dwordx4 v[46:49], v[20:21], off
	global_load_dwordx4 v[42:45], v[20:21], off offset:1024
	global_load_dwordx4 v[38:41], v[20:21], off offset:2048
	global_load_dwordx4 v[34:37], v[20:21], off offset:3072
	v_addc_co_u32_e32 v83, vcc, 0, v19, vcc
	global_load_dwordx4 v[30:33], v[82:83], off
	global_load_dwordx4 v[26:29], v[82:83], off offset:1024
	global_load_dwordx4 v[22:25], v[82:83], off offset:2048
	global_load_dwordx4 v[18:21], v[82:83], off offset:3072
	s_add_i32 s25, s8, 32
	s_add_i32 s10, s8, 0xffffc022
	s_ashr_i32 s9, s25, 13
	s_cmpk_lt_i32 s25, 0x4000
	s_cselect_b32 s6, s9, s10
	s_addk_i32 s6, 0x82
	s_mul_hi_i32 s7, s6, 0x9000
	s_mul_i32 s6, s6, 0x9000
	s_add_u32 s6, s2, s6
	s_addc_u32 s7, s5, s7
	s_add_u32 s10, s6, 0x1000
	s_addc_u32 s11, s7, 0
	v_lshl_add_u64 v[124:125], s[6:7], 0, v[90:91]
	v_lshl_add_u64 v[86:87], s[10:11], 0, v[90:91]
	global_load_dwordx4 v[82:85], v[124:125], off
	s_add_i32 s6, s8, 0xffffc023
	global_load_dwordx4 v[86:89], v[86:87], off
	s_cmpk_lt_i32 s25, 0x3fff
	s_cselect_b32 s6, s9, s6
	s_addk_i32 s6, 0x82
	s_mul_hi_i32 s7, s6, 0x9000
	s_mul_i32 s6, s6, 0x9000
	s_add_u32 s6, s2, s6
	s_addc_u32 s7, s5, s7
	v_lshl_add_u64 v[138:139], s[10:11], 0, v[96:97]
	v_lshl_add_u64 v[134:135], s[10:11], 0, v[98:99]
	v_lshl_add_u64 v[128:129], s[10:11], 0, v[100:101]
	s_add_u32 s10, s6, 0x1000
	v_lshl_add_u64 v[110:111], s[6:7], 0, v[90:91]
	s_addc_u32 s11, s7, 0
	s_add_i32 s6, s8, 0xffffc024
	s_cmpk_lt_i32 s25, 0x3ffe
	s_cselect_b32 s6, s9, s6
	s_addk_i32 s6, 0x82
	s_mul_hi_i32 s7, s6, 0x9000
	s_mul_i32 s6, s6, 0x9000
	v_lshl_add_u64 v[126:127], s[10:11], 0, v[90:91]
	v_lshl_add_u64 v[120:121], s[10:11], 0, v[96:97]
	v_lshl_add_u64 v[116:117], s[10:11], 0, v[98:99]
	v_lshl_add_u64 v[112:113], s[10:11], 0, v[100:101]
	s_add_u32 s10, s2, s6
	s_addc_u32 s11, s5, s7
	s_add_u32 s6, s10, 0x1000
	s_addc_u32 s7, s11, 0
	s_addk_i32 s8, 0xc025
	s_cmpk_lt_i32 s25, 0x3ffd
	v_lshl_add_u64 v[142:143], s[6:7], 0, v[90:91]
	v_lshl_add_u64 v[140:141], s[6:7], 0, v[96:97]
	v_lshl_add_u64 v[136:137], s[6:7], 0, v[98:99]
	v_lshl_add_u64 v[122:123], s[6:7], 0, v[100:101]
	s_cselect_b32 s6, s9, s8
	s_addk_i32 s6, 0x82
	s_mul_hi_i32 s7, s6, 0x9000
	s_mul_i32 s6, s6, 0x9000
	s_add_u32 s6, s2, s6
	s_addc_u32 s7, s5, s7
	s_add_u32 s20, s6, 0x1000
	v_lshl_add_u64 v[106:107], s[6:7], 0, v[90:91]
	s_addc_u32 s21, s7, 0
	v_lshl_add_u64 v[108:109], s[10:11], 0, v[90:91]
	v_lshl_add_u64 v[118:119], s[20:21], 0, v[90:91]
	v_lshl_add_u64 v[114:115], s[20:21], 0, v[96:97]
	v_lshl_add_u64 v[92:93], v[92:93], 0, s[14:15]
	s_waitcnt vmcnt(0) lgkmcnt(0)
	v_pk_mul_f32 v[144:145], v[80:81], v[80:81]
	v_pk_mul_f32 v[146:147], v[78:79], v[78:79]
	v_pk_mul_f32 v[148:149], v[76:77], v[76:77]
	v_pk_mul_f32 v[150:151], v[74:75], v[74:75]
	v_mul_f32_e32 v158, v71, v71
	v_mul_f32_e32 v160, v73, v73
	v_mul_f32_e32 v171, v68, v68
	v_mul_f32_e32 v173, v69, v69
	v_pk_mov_b32 v[162:163], v[146:147], v[144:145] op_sel:[1,0]
	v_mov_b32_e32 v147, v145
	v_pk_mov_b32 v[144:145], v[150:151], v[148:149] op_sel:[1,0]
	v_mov_b32_e32 v151, v149
	v_pk_fma_f32 v[148:149], v[70:71], v[70:71], v[158:159] op_sel_hi:[1,1,0]
	v_pk_fma_f32 v[158:159], v[72:73], v[72:73], v[160:161] op_sel_hi:[1,1,0]
	v_pk_mul_f32 v[160:161], v[64:65], v[64:65]
	v_pk_mul_f32 v[164:165], v[62:63], v[62:63]
	v_pk_mul_f32 v[166:167], v[60:61], v[60:61]
	v_pk_mul_f32 v[168:169], v[58:59], v[58:59]
	v_mul_f32_e32 v170, v55, v55
	v_mul_f32_e32 v172, v57, v57
	v_pk_add_f32 v[146:147], v[162:163], v[146:147]
	v_pk_add_f32 v[144:145], v[144:145], v[150:151]
	v_mov_b32_e32 v149, v171
	v_mov_b32_e32 v159, v173
	v_pk_mov_b32 v[150:151], v[164:165], v[160:161] op_sel:[1,0]
	v_mov_b32_e32 v165, v161
	v_pk_mov_b32 v[160:161], v[168:169], v[166:167] op_sel:[1,0]
	v_mov_b32_e32 v169, v167
	v_pk_fma_f32 v[162:163], v[54:55], v[54:55], v[170:171] op_sel_hi:[1,1,0]
	v_pk_fma_f32 v[166:167], v[56:57], v[56:57], v[172:173] op_sel_hi:[1,1,0]
	v_pk_mul_f32 v[170:171], v[48:49], v[48:49]
	v_pk_mul_f32 v[172:173], v[46:47], v[46:47]
	v_pk_mul_f32 v[174:175], v[44:45], v[44:45]
	v_pk_mul_f32 v[176:177], v[42:43], v[42:43]
	v_mul_f32_e32 v157, v66, v66
	v_mul_f32_e32 v181, v67, v67
	v_mul_f32_e32 v179, v52, v52
	v_mul_f32_e32 v186, v53, v53
	v_mul_f32_e32 v178, v39, v39
	v_mul_f32_e32 v180, v41, v41
	v_pk_add_f32 v[182:183], v[146:147], v[146:147] op_sel:[0,1] op_sel_hi:[1,0]
	v_pk_add_f32 v[184:185], v[144:145], v[144:145] op_sel:[0,1] op_sel_hi:[1,0]
	v_pk_add_f32 v[158:159], v[148:149], v[158:159]
	v_pk_add_f32 v[144:145], v[150:151], v[164:165]
	v_pk_add_f32 v[146:147], v[160:161], v[168:169]
	v_pk_mov_b32 v[148:149], v[172:173], v[170:171] op_sel:[1,0]
	v_mov_b32_e32 v173, v171
	v_pk_mov_b32 v[150:151], v[176:177], v[174:175] op_sel:[1,0]
	v_mov_b32_e32 v177, v175
	v_mul_f32_e32 v187, v50, v50
	v_mul_f32_e32 v192, v51, v51
	v_mul_f32_e32 v195, v36, v36
	v_mul_f32_e32 v196, v37, v37
	v_mov_b32_e32 v163, v179
	v_mov_b32_e32 v167, v186
	v_pk_fma_f32 v[160:161], v[38:39], v[38:39], v[178:179] op_sel_hi:[1,1,0]
	v_pk_fma_f32 v[164:165], v[40:41], v[40:41], v[180:181] op_sel_hi:[1,1,0]
	v_pk_mul_f32 v[168:169], v[32:33], v[32:33]
	v_pk_mul_f32 v[170:171], v[30:31], v[30:31]
	v_pk_mul_f32 v[174:175], v[28:29], v[28:29]
	v_pk_mul_f32 v[178:179], v[26:27], v[26:27]
	v_mov_b32_e32 v183, v157
	v_mov_b32_e32 v185, v181
	v_pk_add_f32 v[188:189], v[144:145], v[144:145] op_sel:[0,1] op_sel_hi:[1,0]
	v_pk_add_f32 v[190:191], v[146:147], v[146:147] op_sel:[0,1] op_sel_hi:[1,0]
	v_pk_add_f32 v[148:149], v[148:149], v[172:173]
	v_pk_add_f32 v[150:151], v[150:151], v[176:177]
	v_mul_f32_e32 v193, v34, v34
	v_mul_f32_e32 v194, v35, v35
	v_pk_add_f32 v[162:163], v[162:163], v[166:167]
	v_mov_b32_e32 v161, v195
	v_mov_b32_e32 v165, v196
	v_pk_mov_b32 v[166:167], v[170:171], v[168:169] op_sel:[1,0]
	v_mov_b32_e32 v171, v169
	v_pk_mov_b32 v[168:169], v[178:179], v[174:175] op_sel:[1,0]
	v_mov_b32_e32 v179, v175
	v_pk_add_f32 v[172:173], v[182:183], v[184:185]
	v_mov_b32_e32 v189, v187
	v_mov_b32_e32 v191, v192
	v_pk_add_f32 v[174:175], v[148:149], v[148:149] op_sel:[0,1] op_sel_hi:[1,0]
	v_pk_add_f32 v[176:177], v[150:151], v[150:151] op_sel:[0,1] op_sel_hi:[1,0]
	v_pk_add_f32 v[160:161], v[160:161], v[164:165]
	v_pk_add_f32 v[158:159], v[172:173], v[158:159]
	v_pk_add_f32 v[164:165], v[188:189], v[190:191]
	v_mov_b32_e32 v175, v193
	v_mov_b32_e32 v177, v194
	v_add_f32_e32 v157, v158, v159
	v_pk_add_f32 v[158:159], v[164:165], v[162:163]
	v_pk_add_f32 v[162:163], v[174:175], v[176:177]
	v_add_f32_e32 v164, v158, v159
	v_pk_add_f32 v[158:159], v[162:163], v[160:161]
	v_add_f32_e32 v158, v158, v159
	v_pk_add_f32 v[148:149], v[166:167], v[170:171]
	s_waitcnt lgkmcnt(0)
	s_nop 1
	v_add_f32_dpp v157, v157, v157 quad_perm:[1,0,3,2] row_mask:0xf bank_mask:0xf
	s_waitcnt lgkmcnt(0)
	s_nop 1
	v_add_f32_dpp v161, v164, v164 quad_perm:[1,0,3,2] row_mask:0xf bank_mask:0xf
	s_waitcnt lgkmcnt(0)
	s_nop 1
	v_add_f32_dpp v158, v158, v158 quad_perm:[1,0,3,2] row_mask:0xf bank_mask:0xf
	s_waitcnt lgkmcnt(0)
	s_nop 1
	v_add_f32_dpp v157, v157, v157 quad_perm:[2,3,0,1] row_mask:0xf bank_mask:0xf
	s_waitcnt lgkmcnt(0)
	s_nop 1
	v_add_f32_dpp v161, v161, v161 quad_perm:[2,3,0,1] row_mask:0xf bank_mask:0xf
	s_waitcnt lgkmcnt(0)
	s_nop 1
	v_add_f32_dpp v158, v158, v158 quad_perm:[2,3,0,1] row_mask:0xf bank_mask:0xf
	s_waitcnt lgkmcnt(0)
	s_nop 1
	v_add_f32_dpp v157, v157, v157 row_half_mirror row_mask:0xf bank_mask:0xf
	s_waitcnt lgkmcnt(0)
	s_nop 1
	v_add_f32_dpp v161, v161, v161 row_half_mirror row_mask:0xf bank_mask:0xf
	s_waitcnt lgkmcnt(0)
	s_nop 1
	v_add_f32_dpp v158, v158, v158 row_half_mirror row_mask:0xf bank_mask:0xf
	s_waitcnt lgkmcnt(0)
	s_nop 1
	v_add_f32_dpp v157, v157, v157 row_mirror row_mask:0xf bank_mask:0xf
	s_waitcnt lgkmcnt(0)
	s_nop 1
	v_add_f32_dpp v161, v161, v161 row_mirror row_mask:0xf bank_mask:0xf
	s_waitcnt lgkmcnt(0)
	s_nop 1
	v_add_f32_dpp v158, v158, v158 row_mirror row_mask:0xf bank_mask:0xf
	s_waitcnt lgkmcnt(0)
	v_mov_b32_e32 v160, v157
	s_nop 1
	v_permlane16_swap_b32_e32 v157, v160
	v_add_f32_e32 v157, v157, v160
	s_waitcnt lgkmcnt(0)
	v_mov_b32_e32 v162, v161
	s_nop 1
	v_permlane16_swap_b32_e32 v161, v162
	v_add_f32_e32 v161, v161, v162
	s_waitcnt lgkmcnt(0)
	v_mov_b32_e32 v159, v158
	s_nop 1
	v_permlane16_swap_b32_e32 v158, v159
	v_add_f32_e32 v158, v158, v159
	s_waitcnt lgkmcnt(0)
	v_mov_b32_e32 v160, v157
	s_nop 1
	v_permlane32_swap_b32_e32 v157, v160
	v_add_f32_e32 v157, v157, v160
	v_fmamk_f32 v157, v157, 0x3a800000, v155
	s_waitcnt lgkmcnt(1)
	v_mov_b32_e32 v162, v161
	s_nop 1
	v_permlane32_swap_b32_e32 v161, v162
	v_add_f32_e32 v160, v161, v162
	v_mul_f32_e32 v161, 0x4f800000, v157
	v_cmp_gt_f32_e32 vcc, s3, v157
	v_fmamk_f32 v160, v160, 0x3a800000, v155
	s_waitcnt lgkmcnt(0)
	v_mov_b32_e32 v159, v158
	s_nop 1
	v_permlane32_swap_b32_e32 v158, v159
	v_add_f32_e32 v158, v158, v159
	v_cndmask_b32_e32 v157, v157, v161, vcc
	v_mul_f32_e32 v159, 0x4f800000, v160
	v_cmp_gt_f32_e64 s[6:7], s3, v160
	v_sqrt_f32_e32 v161, v157
	v_fmamk_f32 v158, v158, 0x3a800000, v155
	v_cndmask_b32_e64 v159, v160, v159, s[6:7]
	v_mul_f32_e32 v160, 0x4f800000, v158
	v_cmp_gt_f32_e64 s[8:9], s3, v158
	v_sqrt_f32_e32 v162, v159
	v_add_u32_e32 v163, -1, v161
	v_cndmask_b32_e64 v158, v158, v160, s[8:9]
	v_sqrt_f32_e32 v160, v158
	v_add_u32_e32 v164, 1, v161
	v_fma_f32 v165, -v163, v161, v157
	v_fma_f32 v166, -v164, v161, v157
	v_add_u32_e32 v167, -1, v162
	v_cmp_ge_f32_e64 s[10:11], 0, v165
	v_pk_add_f32 v[150:151], v[168:169], v[178:179]
	v_add_u32_e32 v168, 1, v162
	v_cndmask_b32_e64 v161, v161, v163, s[10:11]
	v_fma_f32 v163, -v167, v162, v159
	v_cmp_lt_f32_e64 s[10:11], 0, v166
	v_fma_f32 v165, -v168, v162, v159
	v_add_u32_e32 v169, -1, v160
	v_cndmask_b32_e64 v161, v161, v164, s[10:11]
	v_cmp_ge_f32_e64 s[10:11], 0, v163
	v_add_u32_e32 v170, 1, v160
	v_fma_f32 v163, -v169, v160, v158
	v_cndmask_b32_e64 v162, v162, v167, s[10:11]
	v_cmp_lt_f32_e64 s[10:11], 0, v165
	v_fma_f32 v164, -v170, v160, v158
	v_mul_f32_e32 v165, 0x37800000, v161
	v_cndmask_b32_e64 v162, v162, v168, s[10:11]
	v_cmp_ge_f32_e64 s[10:11], 0, v163
	v_cndmask_b32_e32 v161, v161, v165, vcc
	v_cmp_class_f32_e32 vcc, v157, v156
	v_cndmask_b32_e64 v160, v160, v169, s[10:11]
	v_cmp_lt_f32_e64 s[10:11], 0, v164
	v_mul_f32_e32 v163, 0x37800000, v162
	v_cndmask_b32_e32 v157, v161, v157, vcc
	v_cndmask_b32_e64 v160, v160, v170, s[10:11]
	v_cndmask_b32_e64 v161, v162, v163, s[6:7]
	v_cmp_class_f32_e32 vcc, v159, v156
	v_mul_f32_e32 v162, 0x37800000, v160
	v_div_scale_f32 v163, s[6:7], v157, v157, 1.0
	v_cndmask_b32_e32 v159, v161, v159, vcc
	v_cndmask_b32_e64 v160, v160, v162, s[8:9]
	v_cmp_class_f32_e32 vcc, v158, v156
	v_rcp_f32_e32 v161, v163
	v_div_scale_f32 v162, s[8:9], v159, v159, 1.0
	v_cndmask_b32_e32 v160, v160, v158, vcc
	v_rcp_f32_e32 v166, v162
	v_div_scale_f32 v167, s[10:11], v160, v160, 1.0
	v_rcp_f32_e32 v169, v167
	v_fma_f32 v158, -v163, v161, 1.0
	v_div_scale_f32 v164, s[6:7], 1.0, v157, 1.0
	v_fmac_f32_e32 v161, v158, v161
	v_fma_f32 v158, -v162, v166, 1.0
	v_mul_f32_e32 v170, v164, v161
	v_div_scale_f32 v165, s[8:9], 1.0, v159, 1.0
	v_fmac_f32_e32 v166, v158, v166
	v_fma_f32 v158, -v167, v169, 1.0
	v_fma_f32 v171, -v163, v170, v164
	v_div_scale_f32 v168, s[10:11], 1.0, v160, 1.0
	v_mul_f32_e32 v172, v165, v166
	v_fmac_f32_e32 v169, v158, v169
	v_fmac_f32_e32 v170, v171, v161
	v_fma_f32 v158, -v162, v172, v165
	v_mul_f32_e32 v171, v168, v169
	v_fma_f32 v163, -v163, v170, v164
	s_mov_b64 vcc, s[6:7]
	v_fmac_f32_e32 v172, v158, v166
	v_fma_f32 v158, -v167, v171, v168
	v_div_fmas_f32 v161, v163, v161, v170
	v_fma_f32 v162, -v162, v172, v165
	v_fmac_f32_e32 v171, v158, v169
	v_div_fixup_f32 v158, v161, v157, 1.0
	s_mov_b64 vcc, s[8:9]
	v_div_fmas_f32 v157, v162, v166, v172
	v_fma_f32 v161, -v167, v171, v168
	v_pk_mul_f32 v[80:81], v[80:81], v[158:159] op_sel_hi:[1,0]
	v_pk_mul_f32 v[78:79], v[78:79], v[158:159] op_sel_hi:[1,0]
	s_mov_b64 vcc, s[10:11]
	v_pk_add_f32 v[88:89], v[88:89], 1.0 op_sel_hi:[1,0]
	v_pk_add_f32 v[86:87], v[86:87], 1.0 op_sel_hi:[1,0]
	v_pk_mul_f32 v[76:77], v[76:77], v[158:159] op_sel_hi:[1,0]
	v_pk_mul_f32 v[74:75], v[74:75], v[158:159] op_sel_hi:[1,0]
	v_pk_mul_f32 v[72:73], v[72:73], v[158:159] op_sel_hi:[1,0]
	v_pk_mul_f32 v[70:71], v[70:71], v[158:159] op_sel_hi:[1,0]
	v_pk_mul_f32 v[68:69], v[68:69], v[158:159] op_sel_hi:[1,0]
	v_pk_mul_f32 v[66:67], v[66:67], v[158:159] op_sel_hi:[1,0]
	v_div_fixup_f32 v158, v157, v159, 1.0
	v_div_fmas_f32 v157, v161, v169, v171
	v_pk_mul_f32 v[78:79], v[78:79], v[2:3]
	v_pk_mul_f32 v[80:81], v[80:81], v[4:5]
	v_pk_mul_f32 v[64:65], v[64:65], v[158:159] op_sel_hi:[1,0]
	v_pk_mul_f32 v[62:63], v[62:63], v[158:159] op_sel_hi:[1,0]
	v_pk_mul_f32 v[60:61], v[60:61], v[158:159] op_sel_hi:[1,0]
	v_pk_mul_f32 v[58:59], v[58:59], v[158:159] op_sel_hi:[1,0]
	v_pk_mul_f32 v[56:57], v[56:57], v[158:159] op_sel_hi:[1,0]
	v_pk_mul_f32 v[54:55], v[54:55], v[158:159] op_sel_hi:[1,0]
	v_pk_mul_f32 v[52:53], v[52:53], v[158:159] op_sel_hi:[1,0]
	v_pk_mul_f32 v[158:159], v[50:51], v[158:159] op_sel_hi:[1,0]
	v_div_fixup_f32 v50, v157, v160, 1.0
	v_pk_fma_f32 v[80:81], v[80:81], v[88:89], v[84:85]
	v_pk_fma_f32 v[78:79], v[78:79], v[86:87], v[82:83]
	v_pk_mul_f32 v[86:87], v[52:53], v[16:17]
	v_pk_mul_f32 v[48:49], v[48:49], v[50:51] op_sel_hi:[1,0]
	v_pk_mul_f32 v[46:47], v[46:47], v[50:51] op_sel_hi:[1,0]
	v_pk_mul_f32 v[82:83], v[54:55], v[10:11]
	v_pk_mul_f32 v[84:85], v[158:159], v[14:15]
	v_pk_mul_f32 v[88:89], v[46:47], v[2:3]
	v_pk_mul_f32 v[158:159], v[48:49], v[4:5]
	v_cvt_pk_bf16_f32 v46, v78, v79
	v_cvt_pk_bf16_f32 v47, v80, v81
	global_store_dwordx2 v[102:103], v[46:47], off
	global_load_dwordx4 v[46:49], v[138:139], off
	s_nop 0
	global_load_dwordx4 v[52:55], v[124:125], off offset:1024
	v_pk_mul_f32 v[74:75], v[74:75], v[6:7]
	v_pk_mul_f32 v[76:77], v[76:77], v[8:9]
	v_pk_mul_f32 v[70:71], v[70:71], v[10:11]
	v_pk_mul_f32 v[72:73], v[72:73], v[12:13]
	v_pk_mul_f32 v[66:67], v[66:67], v[14:15]
	v_pk_mul_f32 v[68:69], v[68:69], v[16:17]
	v_pk_mul_f32 v[62:63], v[62:63], v[2:3]
	v_pk_mul_f32 v[64:65], v[64:65], v[4:5]
	v_pk_mul_f32 v[58:59], v[58:59], v[6:7]
	v_pk_mul_f32 v[60:61], v[60:61], v[8:9]
	v_pk_mul_f32 v[56:57], v[56:57], v[12:13]
	v_mul_f32_e32 v180, v23, v23
	v_mul_f32_e32 v186, v25, v25
	v_mul_f32_e32 v197, v18, v18
	v_mul_f32_e32 v198, v19, v19
	v_mul_f32_e32 v199, v20, v20
	v_mul_f32_e32 v200, v21, v21
	v_pk_fma_f32 v[144:145], v[22:23], v[22:23], v[180:181] op_sel_hi:[1,1,0]
	v_pk_fma_f32 v[146:147], v[24:25], v[24:25], v[186:187] op_sel_hi:[1,1,0]
	v_mov_b32_e32 v145, v199
	v_mov_b32_e32 v147, v200
	v_lshl_add_u64 v[94:95], v[94:95], 0, s[18:19]
	s_mov_b32 s8, s25
	s_cmp_lt_i32 s25, s13
	s_waitcnt vmcnt(0) lgkmcnt(0)
	v_pk_add_f32 v[48:49], v[48:49], 1.0 op_sel_hi:[1,0]
	v_pk_add_f32 v[46:47], v[46:47], 1.0 op_sel_hi:[1,0]
	v_pk_fma_f32 v[48:49], v[76:77], v[48:49], v[54:55]
	v_pk_fma_f32 v[46:47], v[74:75], v[46:47], v[52:53]
	v_cvt_pk_bf16_f32 v46, v46, v47
	v_cvt_pk_bf16_f32 v47, v48, v49
	global_store_dwordx2 v[102:103], v[46:47], off offset:512
	global_load_dwordx4 v[46:49], v[134:135], off
	s_nop 0
	global_load_dwordx4 v[52:55], v[124:125], off offset:2048
	s_waitcnt vmcnt(0) lgkmcnt(0)
	v_pk_add_f32 v[48:49], v[48:49], 1.0 op_sel_hi:[1,0]
	v_pk_add_f32 v[46:47], v[46:47], 1.0 op_sel_hi:[1,0]
	v_pk_fma_f32 v[48:49], v[72:73], v[48:49], v[54:55]
	v_pk_fma_f32 v[46:47], v[70:71], v[46:47], v[52:53]
	v_cvt_pk_bf16_f32 v46, v46, v47
	v_cvt_pk_bf16_f32 v47, v48, v49
	global_store_dwordx2 v[102:103], v[46:47], off offset:1024
	global_load_dwordx4 v[46:49], v[128:129], off
	s_nop 0
	global_load_dwordx4 v[52:55], v[124:125], off offset:3072
	s_waitcnt vmcnt(0) lgkmcnt(0)
	v_pk_add_f32 v[48:49], v[48:49], 1.0 op_sel_hi:[1,0]
	v_pk_add_f32 v[46:47], v[46:47], 1.0 op_sel_hi:[1,0]
	v_pk_fma_f32 v[48:49], v[68:69], v[48:49], v[54:55]
	v_pk_fma_f32 v[46:47], v[66:67], v[46:47], v[52:53]
	v_cvt_pk_bf16_f32 v46, v46, v47
	v_cvt_pk_bf16_f32 v47, v48, v49
	global_store_dwordx2 v[102:103], v[46:47], off offset:1536
	global_load_dwordx4 v[46:49], v[126:127], off
	s_nop 0
	global_load_dwordx4 v[52:55], v[110:111], off
	s_waitcnt vmcnt(0) lgkmcnt(0)
	v_pk_add_f32 v[48:49], v[48:49], 1.0 op_sel_hi:[1,0]
	v_pk_add_f32 v[46:47], v[46:47], 1.0 op_sel_hi:[1,0]
	v_pk_fma_f32 v[48:49], v[64:65], v[48:49], v[54:55]
	v_pk_fma_f32 v[46:47], v[62:63], v[46:47], v[52:53]
	v_cvt_pk_bf16_f32 v46, v46, v47
	v_cvt_pk_bf16_f32 v47, v48, v49
	global_store_dwordx2 v[102:103], v[46:47], off offset:2048
	global_load_dwordx4 v[46:49], v[120:121], off
	s_nop 0
	global_load_dwordx4 v[52:55], v[110:111], off offset:1024
	s_waitcnt vmcnt(0) lgkmcnt(0)
	v_pk_add_f32 v[48:49], v[48:49], 1.0 op_sel_hi:[1,0]
	v_pk_add_f32 v[46:47], v[46:47], 1.0 op_sel_hi:[1,0]
	v_pk_fma_f32 v[48:49], v[60:61], v[48:49], v[54:55]
	v_pk_fma_f32 v[46:47], v[58:59], v[46:47], v[52:53]
	v_cvt_pk_bf16_f32 v46, v46, v47
	v_cvt_pk_bf16_f32 v47, v48, v49
	global_store_dwordx2 v[102:103], v[46:47], off offset:2560
	global_load_dwordx4 v[46:49], v[116:117], off
	s_nop 0
	global_load_dwordx4 v[52:55], v[110:111], off offset:2048
	v_pk_add_f32 v[58:59], v[150:151], v[150:151] op_sel:[0,1] op_sel_hi:[1,0]
	v_pk_add_f32 v[60:61], v[144:145], v[146:147]
	v_mov_b32_e32 v59, v198
	s_waitcnt vmcnt(0) lgkmcnt(0)
	v_pk_add_f32 v[48:49], v[48:49], 1.0 op_sel_hi:[1,0]
	v_pk_add_f32 v[46:47], v[46:47], 1.0 op_sel_hi:[1,0]
	v_pk_fma_f32 v[48:49], v[56:57], v[48:49], v[54:55]
	v_pk_fma_f32 v[46:47], v[82:83], v[46:47], v[52:53]
	v_cvt_pk_bf16_f32 v46, v46, v47
	v_cvt_pk_bf16_f32 v47, v48, v49
	global_store_dwordx2 v[102:103], v[46:47], off offset:3072
	global_load_dwordx4 v[46:49], v[112:113], off
	s_nop 0
	global_load_dwordx4 v[52:55], v[110:111], off offset:3072
	v_pk_add_f32 v[56:57], v[148:149], v[148:149] op_sel:[0,1] op_sel_hi:[1,0]
	s_waitcnt vmcnt(0) lgkmcnt(0)
	v_pk_add_f32 v[48:49], v[48:49], 1.0 op_sel_hi:[1,0]
	v_pk_add_f32 v[46:47], v[46:47], 1.0 op_sel_hi:[1,0]
	v_pk_fma_f32 v[48:49], v[86:87], v[48:49], v[54:55]
	v_pk_fma_f32 v[46:47], v[84:85], v[46:47], v[52:53]
	v_cvt_pk_bf16_f32 v46, v46, v47
	v_cvt_pk_bf16_f32 v47, v48, v49
	global_store_dwordx2 v[102:103], v[46:47], off offset:3584
	global_load_dwordx4 v[46:49], v[142:143], off
	s_nop 0
	global_load_dwordx4 v[52:55], v[108:109], off
	v_mov_b32_e32 v57, v197
	s_waitcnt vmcnt(0) lgkmcnt(0)
	v_pk_add_f32 v[48:49], v[48:49], 1.0 op_sel_hi:[1,0]
	v_pk_add_f32 v[46:47], v[46:47], 1.0 op_sel_hi:[1,0]
	v_pk_fma_f32 v[48:49], v[158:159], v[48:49], v[54:55]
	v_pk_fma_f32 v[46:47], v[88:89], v[46:47], v[52:53]
	v_bfe_u32 v51, v46, 16, 1
	v_bfe_u32 v52, v47, 16, 1
	v_add3_u32 v46, v46, v51, s4
	v_add3_u32 v47, v47, v52, s4
	v_lshrrev_b32_e32 v46, 16, v46
	v_and_or_b32 v46, v47, s22, v46
	v_cvt_pk_bf16_f32 v47, v48, v49
	global_store_dwordx2 v[104:105], v[46:47], off
	global_load_dwordx4 v[46:49], v[140:141], off
	s_nop 0
	global_load_dwordx4 v[52:55], v[108:109], off offset:1024
	v_pk_mul_f32 v[44:45], v[44:45], v[50:51] op_sel_hi:[1,0]
	v_pk_mul_f32 v[42:43], v[42:43], v[50:51] op_sel_hi:[1,0]
	v_pk_mul_f32 v[44:45], v[44:45], v[8:9]
	v_pk_mul_f32 v[42:43], v[42:43], v[6:7]
	s_waitcnt vmcnt(0) lgkmcnt(0)
	v_pk_add_f32 v[48:49], v[48:49], 1.0 op_sel_hi:[1,0]
	v_pk_add_f32 v[46:47], v[46:47], 1.0 op_sel_hi:[1,0]
	v_pk_fma_f32 v[44:45], v[44:45], v[48:49], v[54:55]
	v_pk_fma_f32 v[42:43], v[42:43], v[46:47], v[52:53]
	v_cvt_pk_bf16_f32 v42, v42, v43
	v_cvt_pk_bf16_f32 v43, v44, v45
	global_store_dwordx2 v[104:105], v[42:43], off offset:512
	global_load_dwordx4 v[42:45], v[136:137], off
	s_nop 0
	global_load_dwordx4 v[46:49], v[108:109], off offset:2048
	v_pk_add_f32 v[52:53], v[56:57], v[58:59]
	s_waitcnt vmcnt(0) lgkmcnt(0)
	v_pk_add_f32 v[44:45], v[44:45], 1.0 op_sel_hi:[1,0]
	v_pk_add_f32 v[52:53], v[52:53], v[60:61]
	v_pk_add_f32 v[42:43], v[42:43], 1.0 op_sel_hi:[1,0]
	v_add_f32_e32 v51, v52, v53
	s_waitcnt lgkmcnt(0)
	s_nop 1
	v_add_f32_dpp v51, v51, v51 quad_perm:[1,0,3,2] row_mask:0xf bank_mask:0xf
	ds_bpermute_b32 v52, v131, v51
	s_waitcnt lgkmcnt(0)
	v_add_f32_e32 v51, v51, v52
	v_pk_mul_f32 v[40:41], v[40:41], v[50:51] op_sel_hi:[1,0]
	v_pk_mul_f32 v[38:39], v[38:39], v[50:51] op_sel_hi:[1,0]
	v_pk_mul_f32 v[40:41], v[40:41], v[12:13]
	v_pk_mul_f32 v[38:39], v[38:39], v[10:11]
	v_pk_fma_f32 v[40:41], v[40:41], v[44:45], v[48:49]
	v_pk_fma_f32 v[38:39], v[38:39], v[42:43], v[46:47]
	v_cvt_pk_bf16_f32 v38, v38, v39
	v_cvt_pk_bf16_f32 v39, v40, v41
	global_store_dwordx2 v[104:105], v[38:39], off offset:1024
	global_load_dwordx4 v[38:41], v[122:123], off
	s_nop 0
	global_load_dwordx4 v[42:45], v[108:109], off offset:3072
	v_pk_mul_f32 v[36:37], v[36:37], v[50:51] op_sel_hi:[1,0]
	v_pk_mul_f32 v[34:35], v[34:35], v[50:51] op_sel_hi:[1,0]
	v_pk_mul_f32 v[36:37], v[36:37], v[16:17]
	v_pk_mul_f32 v[34:35], v[34:35], v[14:15]
	ds_bpermute_b32 v46, v133, v51
	s_waitcnt lgkmcnt(0)
	v_add_f32_e32 v46, v51, v46
	ds_bpermute_b32 v47, v152, v46
	s_waitcnt lgkmcnt(0)
	v_add_f32_e32 v46, v46, v47
	s_waitcnt lgkmcnt(0)
	v_mov_b32_e32 v47, v46
	s_nop 1
	v_permlane16_swap_b32_e32 v46, v47
	v_add_f32_e32 v46, v46, v47
	s_waitcnt lgkmcnt(0)
	v_mov_b32_e32 v47, v46
	s_nop 1
	v_permlane32_swap_b32_e32 v46, v47
	v_add_f32_e32 v46, v46, v47
	v_fmamk_f32 v46, v46, 0x3a800000, v155
	v_mul_f32_e32 v47, 0x4f800000, v46
	v_cmp_gt_f32_e32 vcc, s3, v46
	s_waitcnt vmcnt(0)
	v_pk_add_f32 v[40:41], v[40:41], 1.0 op_sel_hi:[1,0]
	v_pk_add_f32 v[38:39], v[38:39], 1.0 op_sel_hi:[1,0]
	v_pk_fma_f32 v[36:37], v[36:37], v[40:41], v[44:45]
	v_pk_fma_f32 v[34:35], v[34:35], v[38:39], v[42:43]
	v_cvt_pk_bf16_f32 v34, v34, v35
	v_cvt_pk_bf16_f32 v35, v36, v37
	global_store_dwordx2 v[104:105], v[34:35], off offset:1536
	global_load_dwordx4 v[34:37], v[118:119], off
	s_nop 0
	global_load_dwordx4 v[38:41], v[106:107], off
	v_cndmask_b32_e32 v42, v46, v47, vcc
	v_sqrt_f32_e32 v43, v42
	s_waitcnt vmcnt(0) lgkmcnt(0)
	v_pk_add_f32 v[36:37], v[36:37], 1.0 op_sel_hi:[1,0]
	v_add_u32_e32 v44, -1, v43
	v_add_u32_e32 v45, 1, v43
	v_fma_f32 v46, -v44, v43, v42
	v_fma_f32 v47, -v45, v43, v42
	v_cmp_ge_f32_e64 s[6:7], 0, v46
	v_pk_add_f32 v[34:35], v[34:35], 1.0 op_sel_hi:[1,0]
	s_nop 0
	v_cndmask_b32_e64 v43, v43, v44, s[6:7]
	v_cmp_lt_f32_e64 s[6:7], 0, v47
	s_nop 1
	v_cndmask_b32_e64 v43, v43, v45, s[6:7]
	v_mul_f32_e32 v44, 0x37800000, v43
	v_cndmask_b32_e32 v43, v43, v44, vcc
	v_cmp_class_f32_e32 vcc, v42, v156
	s_nop 1
	v_cndmask_b32_e32 v42, v43, v42, vcc
	v_div_scale_f32 v43, s[6:7], v42, v42, 1.0
	v_rcp_f32_e32 v45, v43
	v_div_scale_f32 v44, vcc, 1.0, v42, 1.0
	v_fma_f32 v46, -v43, v45, 1.0
	v_fmac_f32_e32 v45, v46, v45
	v_mul_f32_e32 v46, v44, v45
	v_fma_f32 v47, -v43, v46, v44
	v_fmac_f32_e32 v46, v47, v45
	v_fma_f32 v43, -v43, v46, v44
	v_div_fmas_f32 v43, v43, v45, v46
	v_div_fixup_f32 v42, v43, v42, 1.0
	v_pk_mul_f32 v[32:33], v[32:33], v[42:43] op_sel_hi:[1,0]
	v_pk_mul_f32 v[30:31], v[30:31], v[42:43] op_sel_hi:[1,0]
	v_pk_mul_f32 v[32:33], v[32:33], v[4:5]
	v_pk_mul_f32 v[30:31], v[30:31], v[2:3]
	v_pk_fma_f32 v[32:33], v[32:33], v[36:37], v[40:41]
	v_pk_fma_f32 v[30:31], v[30:31], v[34:35], v[38:39]
	v_cvt_pk_bf16_f32 v30, v30, v31
	v_cvt_pk_bf16_f32 v31, v32, v33
	global_store_dwordx2 v[104:105], v[30:31], off offset:2048
	global_load_dwordx4 v[30:33], v[114:115], off
	s_nop 0
	global_load_dwordx4 v[34:37], v[106:107], off offset:1024
	v_pk_mul_f32 v[28:29], v[28:29], v[42:43] op_sel_hi:[1,0]
	v_pk_mul_f32 v[26:27], v[26:27], v[42:43] op_sel_hi:[1,0]
	v_pk_mul_f32 v[28:29], v[28:29], v[8:9]
	v_pk_mul_f32 v[26:27], v[26:27], v[6:7]
	v_lshl_add_u64 v[38:39], s[20:21], 0, v[98:99]
	v_pk_mul_f32 v[24:25], v[24:25], v[42:43] op_sel_hi:[1,0]
	v_pk_mul_f32 v[22:23], v[22:23], v[42:43] op_sel_hi:[1,0]
	v_pk_mul_f32 v[24:25], v[24:25], v[12:13]
	v_pk_mul_f32 v[22:23], v[22:23], v[10:11]
	v_pk_mul_f32 v[20:21], v[20:21], v[42:43] op_sel_hi:[1,0]
	v_pk_mul_f32 v[18:19], v[18:19], v[42:43] op_sel_hi:[1,0]
	v_pk_mul_f32 v[20:21], v[20:21], v[16:17]
	v_pk_mul_f32 v[18:19], v[18:19], v[14:15]
	s_waitcnt vmcnt(0) lgkmcnt(0)
	v_pk_add_f32 v[32:33], v[32:33], 1.0 op_sel_hi:[1,0]
	v_pk_add_f32 v[30:31], v[30:31], 1.0 op_sel_hi:[1,0]
	v_pk_fma_f32 v[28:29], v[28:29], v[32:33], v[36:37]
	v_pk_fma_f32 v[26:27], v[26:27], v[30:31], v[34:35]
	v_cvt_pk_bf16_f32 v26, v26, v27
	v_cvt_pk_bf16_f32 v27, v28, v29
	global_store_dwordx2 v[104:105], v[26:27], off offset:2560
	global_load_dwordx4 v[26:29], v[38:39], off
	s_nop 0
	global_load_dwordx4 v[30:33], v[106:107], off offset:2048
	v_lshl_add_u64 v[34:35], s[20:21], 0, v[100:101]
	s_waitcnt vmcnt(0) lgkmcnt(0)
	v_pk_add_f32 v[28:29], v[28:29], 1.0 op_sel_hi:[1,0]
	v_pk_add_f32 v[26:27], v[26:27], 1.0 op_sel_hi:[1,0]
	v_pk_fma_f32 v[24:25], v[24:25], v[28:29], v[32:33]
	v_pk_fma_f32 v[22:23], v[22:23], v[26:27], v[30:31]
	v_cvt_pk_bf16_f32 v22, v22, v23
	v_cvt_pk_bf16_f32 v23, v24, v25
	global_store_dwordx2 v[104:105], v[22:23], off offset:3072
	global_load_dwordx4 v[22:25], v[34:35], off
	s_nop 0
	global_load_dwordx4 v[26:29], v[106:107], off offset:3072
	s_waitcnt vmcnt(0) lgkmcnt(0)
	v_pk_add_f32 v[24:25], v[24:25], 1.0 op_sel_hi:[1,0]
	v_pk_add_f32 v[22:23], v[22:23], 1.0 op_sel_hi:[1,0]
	v_pk_fma_f32 v[20:21], v[20:21], v[24:25], v[28:29]
	v_pk_fma_f32 v[18:19], v[18:19], v[22:23], v[26:27]
	v_cvt_pk_bf16_f32 v18, v18, v19
	v_cvt_pk_bf16_f32 v19, v20, v21
	global_store_dwordx2 v[104:105], v[18:19], off offset:3584
	s_cbranch_scc1 .LBB0_3611

.LBB0_4257:
	v_add_u32_e32 v74, s21, v6
	v_mov_b32_e32 v43, s24
	ds_read2st64_b32 v[44:45], v74 offset1:2
	ds_read2st64_b32 v[46:47], v74 offset0:4 offset1:6
	ds_read2st64_b32 v[48:49], v74 offset0:8 offset1:10
	ds_read2_b32 v[50:51], v43 offset1:1
	ds_read2_b32 v[52:53], v43 offset0:2 offset1:3
	ds_read2_b32 v[54:55], v43 offset0:4 offset1:5
	ds_read2_b32 v[56:57], v43 offset0:6 offset1:7
	ds_read2st64_b32 v[58:59], v74 offset0:12 offset1:14
	ds_read2st64_b32 v[60:61], v74 offset0:16 offset1:18
	ds_read2st64_b32 v[62:63], v74 offset0:20 offset1:22
	ds_read2st64_b32 v[64:65], v74 offset0:24 offset1:26
	ds_read2_b32 v[66:67], v43 offset0:8 offset1:9
	ds_read2_b32 v[68:69], v43 offset0:10 offset1:11
	ds_read2_b32 v[70:71], v43 offset0:12 offset1:13
	ds_read2_b32 v[72:73], v43 offset0:14 offset1:15
	ds_read2st64_b32 v[74:75], v74 offset0:28 offset1:30
	s_waitcnt lgkmcnt(0)
	v_fmac_f32_e32 v42, v50, v44
	v_fmac_f32_e32 v42, v51, v45
	v_fmac_f32_e32 v42, v52, v46
	v_fmac_f32_e32 v42, v53, v47
	v_fmac_f32_e32 v42, v54, v48
	v_fmac_f32_e32 v42, v55, v49
	v_fmac_f32_e32 v42, v56, v58
	v_fmac_f32_e32 v42, v57, v59
	v_fmac_f32_e32 v42, v66, v60
	v_fmac_f32_e32 v42, v67, v61
	v_fmac_f32_e32 v42, v68, v62
	v_fmac_f32_e32 v42, v69, v63
	v_fmac_f32_e32 v42, v70, v64
	v_fmac_f32_e32 v42, v71, v65
	s_add_i32 s24, s24, 64
	s_addk_i32 s21, 0x2000
	v_fmac_f32_e32 v42, v72, v74
	s_cmpk_lg_u32 s21, 0x8000
	v_fmac_f32_e32 v42, v73, v75
	s_cbranch_scc1 .LBB0_4257
	v_mov_b32_e32 v43, s94
	ds_read_b32 v44, v6 offset:33536
	ds_read_b32 v43, v43 offset:34048
	v_cmp_lt_i32_e32 vcc, v36, v35
	s_waitcnt lgkmcnt(0)
	v_fmac_f32_e32 v42, v43, v44
	v_cndmask_b32_e32 v45, v1, v36, vcc
	v_lshlrev_b32_e32 v45, 2, v45
	v_mul_f32_e32 v43, v42, v42
	ds_bpermute_b32 v43, v45, v43
	v_cmp_lt_i32_e32 vcc, v37, v35
	s_waitcnt lgkmcnt(0)
	v_fmac_f32_e32 v43, v42, v42
	v_cndmask_b32_e32 v44, v1, v37, vcc
	v_lshlrev_b32_e32 v44, 2, v44
	ds_bpermute_b32 v44, v44, v43
	v_cmp_lt_i32_e32 vcc, v38, v35
	s_waitcnt lgkmcnt(0)
	v_add_f32_e32 v43, v43, v44
	v_cndmask_b32_e32 v45, v1, v38, vcc
	v_lshlrev_b32_e32 v45, 2, v45
	ds_bpermute_b32 v44, v45, v43
	v_cmp_lt_i32_e32 vcc, v39, v35
	s_waitcnt lgkmcnt(0)
	v_add_f32_e32 v43, v43, v44
	v_cndmask_b32_e32 v45, v1, v39, vcc
	v_lshlrev_b32_e32 v45, 2, v45
	ds_bpermute_b32 v44, v45, v43
	v_cmp_lt_i32_e32 vcc, v40, v35
	s_waitcnt lgkmcnt(0)
	v_add_f32_e32 v43, v43, v44
	v_cndmask_b32_e32 v45, v1, v40, vcc
	v_lshlrev_b32_e32 v45, 2, v45
	v_cmp_lt_i32_e32 vcc, v41, v35
	s_waitcnt lgkmcnt(0)
	v_mov_b32_e32 v44, v43
	s_nop 1
	v_permlane16_swap_b32_e32 v43, v44
	v_add_f32_e32 v43, v43, v44
	v_cndmask_b32_e32 v45, v1, v41, vcc
	v_lshlrev_b32_e32 v44, 2, v45
	ds_bpermute_b32 v44, v44, v43
	s_and_saveexec_b64 s[24:25], s[14:15]
	s_cbranch_execz .LBB0_4260
	s_waitcnt lgkmcnt(0)
	v_add_f32_e32 v43, v43, v44
	v_mov_b32_e32 v44, s26
	ds_write_b32 v44, v43 offset:34052

.LBB0_4898:
	s_cmp_lt_i32 s5, 4
	s_cselect_b64 s[20:21], -1, 0
	s_cmp_gt_i32 s5, 3
	s_waitcnt lgkmcnt(0)
	s_barrier
	s_cbranch_scc1 .LBB0_4900
	s_lshl_b32 s6, s5, 9
	s_add_i32 s6, s3, s6
	v_lshl_add_u32 v4, v1, 2, s6
	ds_read2st64_b32 v[2:3], v4 offset0:4 offset1:5
	v_and_b32_e32 v5, 64, v166
	v_xor_b32_e32 v6, 1, v166
	v_add_u32_e32 v5, 64, v5
	v_cmp_lt_i32_e32 vcc, v6, v5
	s_waitcnt lgkmcnt(0)
	v_max_f32_e32 v7, v3, v3
	v_max_f32_e32 v8, v2, v2
	v_cndmask_b32_e32 v6, v166, v6, vcc
	v_max_f32_e32 v7, v8, v7
	v_lshlrev_b32_e32 v6, 2, v6
	ds_bpermute_b32 v8, v6, v7
	v_xor_b32_e32 v9, 2, v166
	v_cmp_lt_i32_e32 vcc, v9, v5
	v_xor_b32_e32 v10, 4, v166
	v_xor_b32_e32 v11, 8, v166
	s_waitcnt lgkmcnt(0)
	v_max_f32_e32 v8, v8, v8
	v_max_f32_e32 v7, v7, v8
	v_cndmask_b32_e32 v8, v166, v9, vcc
	v_lshlrev_b32_e32 v8, 2, v8
	ds_bpermute_b32 v9, v8, v7
	v_cmp_lt_i32_e32 vcc, v10, v5
	v_xor_b32_e32 v12, 16, v166
	v_xor_b32_e32 v13, 32, v166
	s_waitcnt lgkmcnt(0)
	v_max_f32_e32 v9, v9, v9
	v_max_f32_e32 v7, v7, v9
	v_cndmask_b32_e32 v9, v166, v10, vcc
	v_lshlrev_b32_e32 v9, 2, v9
	ds_bpermute_b32 v10, v9, v7
	v_cmp_lt_i32_e32 vcc, v11, v5
	s_waitcnt lgkmcnt(0)
	v_max_f32_e32 v10, v10, v10
	v_max_f32_e32 v7, v7, v10
	v_cndmask_b32_e32 v10, v166, v11, vcc
	v_lshlrev_b32_e32 v10, 2, v10
	ds_bpermute_b32 v11, v10, v7
	v_cmp_lt_i32_e32 vcc, v12, v5
	s_waitcnt lgkmcnt(0)
	v_max_f32_e32 v11, v11, v11
	v_max_f32_e32 v7, v7, v11
	v_cndmask_b32_e32 v11, v166, v12, vcc
	v_lshlrev_b32_e32 v11, 2, v11
	ds_bpermute_b32 v12, v11, v7
	v_cmp_lt_i32_e32 vcc, v13, v5
	s_waitcnt lgkmcnt(0)
	v_max_f32_e32 v12, v12, v12
	v_cndmask_b32_e32 v5, v166, v13, vcc
	v_max_f32_e32 v7, v7, v12
	v_lshlrev_b32_e32 v5, 2, v5
	ds_bpermute_b32 v12, v5, v7
	s_waitcnt lgkmcnt(0)
	v_max_f32_e32 v12, v12, v12
	v_max_f32_e32 v7, v7, v12
	v_sub_f32_e32 v2, v2, v7
	v_sub_f32_e32 v3, v3, v7
	v_mul_f32_e32 v2, 0x3fb8aa3b, v2
	v_mul_f32_e32 v3, 0x3fb8aa3b, v3
	v_exp_f32_e32 v2, v2
	v_exp_f32_e32 v3, v3
	s_nop 0
	v_add_f32_e32 v7, v2, v3
	ds_bpermute_b32 v6, v6, v7
	s_waitcnt lgkmcnt(0)
	v_add_f32_e32 v6, v7, v6
	s_waitcnt lgkmcnt(0)
	s_nop 1
	v_add_f32_dpp v6, v6, v6 quad_perm:[2,3,0,1] row_mask:0xf bank_mask:0xf
	ds_bpermute_b32 v7, v9, v6
	s_waitcnt lgkmcnt(0)
	v_add_f32_e32 v6, v6, v7
	ds_bpermute_b32 v7, v10, v6
	s_waitcnt lgkmcnt(0)
	v_add_f32_e32 v6, v6, v7
	s_waitcnt lgkmcnt(0)
	v_mov_b32_e32 v7, v6
	s_nop 1
	v_permlane16_swap_b32_e32 v6, v7
	v_add_f32_e32 v6, v6, v7
	ds_bpermute_b32 v5, v5, v6
	s_waitcnt lgkmcnt(0)
	v_add_f32_e32 v5, v6, v5
	v_max_f32_e32 v5, 0xda24260, v5
	v_div_scale_f32 v6, s[6:7], v5, v5, 1.0
	v_rcp_f32_e32 v7, v6
	v_div_scale_f32 v8, vcc, 1.0, v5, 1.0
	v_fma_f32 v9, -v6, v7, 1.0
	v_fmac_f32_e32 v7, v9, v7
	v_mul_f32_e32 v9, v8, v7
	v_fma_f32 v10, -v6, v9, v8
	v_fmac_f32_e32 v9, v10, v7
	v_fma_f32 v6, -v6, v9, v8
	v_div_fmas_f32 v6, v6, v7, v9
	v_div_fixup_f32 v5, v6, v5, 1.0
	v_mul_f32_e32 v2, v2, v5
	v_mul_f32_e32 v3, v3, v5
	ds_write2st64_b32 v4, v2, v3 offset0:4 offset1:5

.LBB0_5341:
	s_lshr_b32 s10, s48, 2
	s_cmp_lt_u32 s48, 4
	s_cselect_b64 vcc, -1, 0
	s_cmp_eq_u32 s10, 2
	s_cselect_b32 s12, s31, s29
	s_cselect_b32 s13, s42, s30
	s_cmp_eq_u32 s10, 1
	s_cselect_b64 s[10:11], -1, 0
	v_cndmask_b32_e64 v66, v106, v108, s[10:11]
	v_cndmask_b32_e64 v67, v107, v109, s[10:11]
	s_and_b64 s[10:11], s[10:11], exec
	s_cselect_b32 s14, s27, s28
	s_and_b64 s[10:11], vcc, exec
	s_cselect_b32 s14, s26, s14
	s_sub_i32 s10, s43, 32
	s_and_b32 s15, s10, 32
	s_or_b32 s10, s15, s14
	v_add_u32_e32 v80, s10, v100
	v_add_u32_e32 v144, 16, v80
	v_cndmask_b32_e32 v78, v66, v104, vcc
	v_subrev_u32_e32 v66, s14, v144
	v_cndmask_b32_e32 v79, v67, v105, vcc
	v_ashrrev_i32_e32 v67, 31, v66
	v_lshlrev_b64 v[66:67], 10, v[66:67]
	v_lshl_add_u64 v[66:67], v[78:79], 0, v[66:67]
	v_mov_b32_e32 v82, s13
	v_cmp_gt_i32_e64 s[10:11], s44, v144
	v_mov_b32_e32 v83, s12
	v_add_u32_e32 v147, 20, v80
	v_cndmask_b32_e64 v67, v82, v67, s[10:11]
	v_cndmask_b32_e64 v66, v83, v66, s[10:11]
	v_lshl_add_u64 v[66:67], v[66:67], 0, v[98:99]
	v_add_u32_e32 v146, 24, v80
	v_add_u32_e32 v145, 28, v80
	global_load_dwordx4 v[94:97], v[66:67], off
	global_load_dwordx4 v[74:77], v[66:67], off offset:512
	v_subrev_u32_e32 v66, s14, v147
	v_subrev_u32_e32 v70, s14, v146
	v_subrev_u32_e32 v80, s14, v145
	v_ashrrev_i32_e32 v67, 31, v66
	v_ashrrev_i32_e32 v71, 31, v70
	v_ashrrev_i32_e32 v81, 31, v80
	v_lshlrev_b64 v[66:67], 10, v[66:67]
	v_lshlrev_b64 v[70:71], 10, v[70:71]
	v_lshlrev_b64 v[80:81], 10, v[80:81]
	v_lshl_add_u64 v[66:67], v[78:79], 0, v[66:67]
	v_lshl_add_u64 v[70:71], v[78:79], 0, v[70:71]
	v_lshl_add_u64 v[78:79], v[78:79], 0, v[80:81]
	s_waitcnt vmcnt(0) lgkmcnt(0)
	v_mul_f32_e32 v80, v11, v3
	v_fmac_f32_e32 v80, v10, v2
	v_fmac_f32_e32 v80, v12, v4
	v_fmac_f32_e32 v80, v13, v5
	v_cmp_gt_i32_e64 s[10:11], s44, v147
	v_mul_f32_e32 v148, v11, v27
	v_fmac_f32_e32 v148, v10, v26
	v_cndmask_b32_e64 v67, v82, v67, s[10:11]
	s_waitcnt lgkmcnt(0)
	v_add_f32_dpp v80, v80, v80 quad_perm:[1,0,3,2] row_mask:0xf bank_mask:0xf
	v_cndmask_b32_e64 v66, v83, v66, s[10:11]
	v_cmp_gt_i32_e64 s[10:11], s44, v146
	v_mul_f32_e32 v125, v23, v3
	v_cndmask_b32_e64 v71, v82, v71, s[10:11]
	v_cndmask_b32_e64 v70, v83, v70, s[10:11]
	v_cmp_gt_i32_e64 s[10:11], s44, v145
	s_waitcnt lgkmcnt(0)
	v_add_f32_dpp v80, v80, v80 quad_perm:[2,3,0,1] row_mask:0xf bank_mask:0xf
	v_cndmask_b32_e64 v79, v82, v79, s[10:11]
	v_mul_f32_e32 v82, v15, v3
	v_fmac_f32_e32 v82, v14, v2
	v_fmac_f32_e32 v82, v16, v4
	v_fmac_f32_e32 v82, v17, v5
	v_cndmask_b32_e64 v78, v83, v78, s[10:11]
	s_and_b32 s10, s48, 12
	s_waitcnt lgkmcnt(0)
	v_add_f32_dpp v118, v80, v80 row_half_mirror row_mask:0xf bank_mask:0xf
	s_cmp_eq_u32 s10, 4
	s_waitcnt lgkmcnt(0)
	v_add_f32_dpp v120, v82, v82 quad_perm:[1,0,3,2] row_mask:0xf bank_mask:0xf
	s_cselect_b32 s12, s27, s28
	s_and_b64 s[10:11], vcc, exec
	s_cselect_b32 s10, s26, s12
	s_or_b32 s10, s10, s15
	v_add_u32_e32 v156, s10, v100
	v_sub_u32_e32 v84, 0x800, v156
	s_waitcnt lgkmcnt(0)
	v_add_f32_dpp v118, v118, v118 row_mirror row_mask:0xf bank_mask:0xf
	s_waitcnt lgkmcnt(0)
	v_add_f32_dpp v119, v120, v120 quad_perm:[2,3,0,1] row_mask:0xf bank_mask:0xf
	v_cvt_f32_u32_e32 v124, v84
	v_cmp_gt_i32_e32 vcc, s2, v156
	v_fmac_f32_e32 v125, v22, v2
	v_fma_f32 v118, -v127, v124, v118
	v_cndmask_b32_e32 v169, v135, v118, vcc
	s_waitcnt lgkmcnt(0)
	v_add_f32_dpp v120, v119, v119 row_half_mirror row_mask:0xf bank_mask:0xf
	v_pk_mul_f32 v[118:119], v[12:13], v[28:29]
	v_fmac_f32_e32 v125, v24, v4
	v_add_f32_e32 v118, v118, v148
	v_add_f32_e32 v118, v119, v118
	v_fmac_f32_e32 v125, v25, v5
	v_mul_f32_e32 v150, v15, v27
	v_fmac_f32_e32 v150, v14, v26
	s_waitcnt lgkmcnt(0)
	v_add_f32_dpp v118, v118, v118 quad_perm:[1,0,3,2] row_mask:0xf bank_mask:0xf
	v_fmac_f32_e32 v150, v16, v28
	s_waitcnt lgkmcnt(0)
	v_add_f32_dpp v125, v125, v125 quad_perm:[1,0,3,2] row_mask:0xf bank_mask:0xf
	v_fmac_f32_e32 v150, v17, v29
	s_waitcnt lgkmcnt(0)
	v_add_f32_dpp v118, v118, v118 quad_perm:[2,3,0,1] row_mask:0xf bank_mask:0xf
	s_movk_i32 s10, 0x7fd
	s_waitcnt lgkmcnt(0)
	s_nop 1
	v_add_f32_dpp v148, v125, v125 quad_perm:[2,3,0,1] row_mask:0xf bank_mask:0xf
	v_sub_u32_e32 v125, 0x7fc, v156
	s_waitcnt lgkmcnt(0)
	v_add_f32_dpp v118, v118, v118 row_half_mirror row_mask:0xf bank_mask:0xf
	v_cvt_f32_u32_e32 v125, v125
	v_cmp_gt_i32_e64 s[10:11], s10, v156
	v_mul_f32_e32 v154, v11, v35
	v_fmac_f32_e32 v154, v10, v34
	s_waitcnt lgkmcnt(0)
	v_add_f32_dpp v118, v118, v118 row_mirror row_mask:0xf bank_mask:0xf
	v_add_f32_dpp v119, v150, v150 quad_perm:[1,0,3,2] row_mask:0xf bank_mask:0xf
	v_mul_f32_e32 v151, v19, v27
	v_fma_f32 v118, -v127, v125, v118
	v_fmac_f32_e32 v151, v18, v26
	v_fmac_f32_e32 v151, v20, v28
	v_cndmask_b32_e64 v172, v135, v118, s[10:11]
	s_waitcnt lgkmcnt(0)
	v_add_f32_dpp v118, v119, v119 quad_perm:[2,3,0,1] row_mask:0xf bank_mask:0xf
	v_fmac_f32_e32 v151, v21, v29
	v_lshl_add_u64 v[66:67], v[66:67], 0, v[98:99]
	v_lshl_add_u64 v[70:71], v[70:71], 0, v[98:99]
	v_lshl_add_u64 v[78:79], v[78:79], 0, v[98:99]
	s_waitcnt lgkmcnt(0)
	v_add_f32_dpp v164, v118, v118 row_half_mirror row_mask:0xf bank_mask:0xf
	v_pk_mul_f32 v[118:119], v[12:13], v[36:37]
	s_waitcnt lgkmcnt(0)
	v_add_f32_dpp v150, v151, v151 quad_perm:[1,0,3,2] row_mask:0xf bank_mask:0xf
	v_mul_f32_e32 v152, v23, v27
	v_add_f32_e32 v118, v118, v154
	v_fmac_f32_e32 v152, v22, v26
	v_add_f32_e32 v118, v119, v118
	v_fmac_f32_e32 v152, v24, v28
	v_fmac_f32_e32 v152, v25, v29
	global_load_dwordx4 v[90:93], v[66:67], off
	s_nop 0
	global_load_dwordx4 v[66:69], v[66:67], off offset:512
	s_waitcnt lgkmcnt(0)
	v_add_f32_dpp v118, v118, v118 quad_perm:[1,0,3,2] row_mask:0xf bank_mask:0xf
	v_add_f32_dpp v152, v152, v152 quad_perm:[1,0,3,2] row_mask:0xf bank_mask:0xf
	global_load_dwordx4 v[86:89], v[70:71], off
	s_nop 0
	global_load_dwordx4 v[70:73], v[70:71], off offset:512
	s_nop 0
	global_load_dwordx4 v[82:85], v[78:79], off
	s_nop 0
	global_load_dwordx4 v[78:81], v[78:79], off offset:512
	v_mul_f32_e32 v154, v15, v35
	s_waitcnt lgkmcnt(0)
	v_add_f32_dpp v118, v118, v118 quad_perm:[2,3,0,1] row_mask:0xf bank_mask:0xf
	v_fmac_f32_e32 v154, v14, v34
	v_fmac_f32_e32 v154, v16, v36
	v_add_f32_dpp v150, v150, v150 quad_perm:[2,3,0,1] row_mask:0xf bank_mask:0xf
	v_add_f32_dpp v152, v152, v152 quad_perm:[2,3,0,1] row_mask:0xf bank_mask:0xf
	v_fmac_f32_e32 v154, v17, v37
	s_waitcnt lgkmcnt(0)
	v_add_f32_dpp v118, v118, v118 row_half_mirror row_mask:0xf bank_mask:0xf
	v_add_f32_dpp v158, v150, v150 row_half_mirror row_mask:0xf bank_mask:0xf
	v_add_f32_dpp v150, v152, v152 row_half_mirror row_mask:0xf bank_mask:0xf
	v_sub_u32_e32 v152, 0x7f8, v156
	v_add_f32_dpp v154, v154, v154 quad_perm:[1,0,3,2] row_mask:0xf bank_mask:0xf
	v_cvt_f32_u32_e32 v152, v152
	v_or_b32_e32 v153, 8, v156
	s_waitcnt lgkmcnt(0)
	v_add_f32_dpp v118, v118, v118 row_mirror row_mask:0xf bank_mask:0xf
	v_fma_f32 v118, -v127, v152, v118
	v_cmp_gt_i32_e64 s[12:13], s2, v153
	v_mul_f32_e32 v153, v19, v35
	v_fmac_f32_e32 v153, v18, v34
	v_cndmask_b32_e64 v173, v135, v118, s[12:13]
	v_add_f32_dpp v118, v154, v154 quad_perm:[2,3,0,1] row_mask:0xf bank_mask:0xf
	v_mul_f32_e32 v155, v23, v35
	v_fmac_f32_e32 v155, v22, v34
	v_fmac_f32_e32 v153, v20, v36
	v_fmac_f32_e32 v155, v24, v36
	v_fmac_f32_e32 v153, v21, v37
	v_fmac_f32_e32 v155, v25, v37
	s_movk_i32 s14, 0x7f5
	v_cmp_gt_i32_e64 s[14:15], s14, v156
	s_waitcnt lgkmcnt(0)
	v_add_f32_dpp v153, v153, v153 quad_perm:[1,0,3,2] row_mask:0xf bank_mask:0xf
	s_nop 1
	v_add_f32_dpp v160, v155, v155 quad_perm:[1,0,3,2] row_mask:0xf bank_mask:0xf
	v_pk_mul_f32 v[154:155], v[10:11], v[46:47]
	v_add_f32_dpp v167, v118, v118 row_half_mirror row_mask:0xf bank_mask:0xf
	v_pk_mul_f32 v[118:119], v[12:13], v[48:49]
	v_add_f32_e32 v154, v154, v155
	v_add_f32_e32 v118, v118, v154
	v_add_f32_e32 v118, v119, v118
	v_mul_f32_e32 v122, v19, v3
	s_waitcnt lgkmcnt(0)
	v_add_f32_dpp v153, v153, v153 quad_perm:[2,3,0,1] row_mask:0xf bank_mask:0xf
	v_add_f32_dpp v155, v160, v160 quad_perm:[2,3,0,1] row_mask:0xf bank_mask:0xf
	v_add_f32_dpp v118, v118, v118 quad_perm:[1,0,3,2] row_mask:0xf bank_mask:0xf
	v_fmac_f32_e32 v122, v18, v2
	s_waitcnt lgkmcnt(0)
	v_add_f32_dpp v160, v153, v153 row_half_mirror row_mask:0xf bank_mask:0xf
	v_add_f32_dpp v153, v155, v155 row_half_mirror row_mask:0xf bank_mask:0xf
	v_mul_f32_e32 v162, v15, v47
	v_add_f32_dpp v118, v118, v118 quad_perm:[2,3,0,1] row_mask:0xf bank_mask:0xf
	v_fmac_f32_e32 v162, v14, v46
	v_fmac_f32_e32 v162, v16, v48
	v_fmac_f32_e32 v162, v17, v49
	v_sub_u32_e32 v155, 0x7f4, v156
	s_waitcnt lgkmcnt(0)
	v_add_f32_dpp v118, v118, v118 row_half_mirror row_mask:0xf bank_mask:0xf
	v_cvt_f32_u32_e32 v155, v155
	v_add_f32_dpp v162, v162, v162 quad_perm:[1,0,3,2] row_mask:0xf bank_mask:0xf
	v_mul_f32_e32 v156, v19, v47
	s_waitcnt lgkmcnt(0)
	v_add_f32_dpp v118, v118, v118 row_mirror row_mask:0xf bank_mask:0xf
	v_fma_f32 v118, -v127, v155, v118
	v_cndmask_b32_e64 v174, v135, v118, s[14:15]
	v_add_f32_dpp v118, v162, v162 quad_perm:[2,3,0,1] row_mask:0xf bank_mask:0xf
	v_mul_f32_e32 v163, v23, v47
	v_fmac_f32_e32 v156, v18, v46
	v_fmac_f32_e32 v163, v22, v46
	v_fmac_f32_e32 v122, v20, v4
	v_fmac_f32_e32 v156, v20, v48
	v_fmac_f32_e32 v163, v24, v48
	v_fmac_f32_e32 v122, v21, v5
	v_fmac_f32_e32 v156, v21, v49
	v_fmac_f32_e32 v163, v25, v49
	v_max3_f32 v157, v169, s33, v172
	s_waitcnt lgkmcnt(0)
	v_add_f32_dpp v122, v122, v122 quad_perm:[1,0,3,2] row_mask:0xf bank_mask:0xf
	v_add_f32_dpp v170, v118, v118 row_half_mirror row_mask:0xf bank_mask:0xf
	v_add_f32_dpp v118, v156, v156 quad_perm:[1,0,3,2] row_mask:0xf bank_mask:0xf
	v_add_f32_dpp v156, v163, v163 quad_perm:[1,0,3,2] row_mask:0xf bank_mask:0xf
	v_max3_f32 v157, v157, v173, v174
	ds_bpermute_b32 v163, v142, v157
	s_waitcnt lgkmcnt(0)
	v_add_f32_dpp v122, v122, v122 quad_perm:[2,3,0,1] row_mask:0xf bank_mask:0xf
	v_add_f32_dpp v118, v118, v118 quad_perm:[2,3,0,1] row_mask:0xf bank_mask:0xf
	v_add_f32_dpp v156, v156, v156 quad_perm:[2,3,0,1] row_mask:0xf bank_mask:0xf
	v_max_f32_e32 v162, v163, v163
	v_max_f32_e32 v176, v157, v162
	ds_bpermute_b32 v177, v143, v176
	s_waitcnt lgkmcnt(0)
	v_add_f32_dpp v122, v122, v122 row_half_mirror row_mask:0xf bank_mask:0xf
	v_add_f32_dpp v148, v148, v148 row_half_mirror row_mask:0xf bank_mask:0xf
	v_add_f32_dpp v162, v118, v118 row_half_mirror row_mask:0xf bank_mask:0xf
	v_add_f32_dpp v156, v156, v156 row_half_mirror row_mask:0xf bank_mask:0xf
	ds_bpermute_b32 v121, v141, v120
	ds_bpermute_b32 v123, v141, v122
	ds_bpermute_b32 v149, v141, v148
	ds_bpermute_b32 v165, v141, v164
	ds_bpermute_b32 v159, v141, v158
	ds_bpermute_b32 v151, v141, v150
	ds_bpermute_b32 v168, v141, v167
	ds_bpermute_b32 v161, v141, v160
	ds_bpermute_b32 v154, v141, v153
	ds_bpermute_b32 v171, v141, v170
	ds_bpermute_b32 v163, v141, v162
	ds_bpermute_b32 v157, v141, v156
	v_max_f32_e32 v118, v177, v177
	v_max_f32_e32 v175, v176, v118
	v_cmp_neq_f32_e64 s[16:17], s33, v175
	v_mov_b64_e32 v[118:119], v[112:113]
	s_and_saveexec_b64 s[22:23], s[16:17]
	s_cbranch_execz .LBB0_5343
	v_max_f32_e32 v118, v175, v175
	v_max_f32_e32 v119, v113, v113
	v_max_f32_e32 v119, v119, v118
	v_sub_f32_e32 v118, v169, v119
	v_mul_f32_e32 v118, 0x3fb8aa3b, v118
	v_exp_f32_e32 v118, v118
	v_sub_f32_e32 v113, v113, v119
	v_mul_f32_e32 v113, 0x3fb8aa3b, v113
	v_add_f32_e32 v169, 0, v118
	v_pk_fma_f32 v[176:177], v[8:9], v[118:119], 0 op_sel_hi:[1,0,0]
	v_pk_fma_f32 v[178:179], v[6:7], v[118:119], 0 op_sel_hi:[1,0,0]
	v_sub_f32_e32 v118, v172, v119
	v_mul_f32_e32 v118, 0x3fb8aa3b, v118
	v_exp_f32_e32 v118, v118
	s_nop 0
	v_add_f32_e32 v169, v118, v169
	v_pk_fma_f32 v[176:177], v[32:33], v[118:119], v[176:177] op_sel_hi:[1,0,1]
	v_pk_fma_f32 v[178:179], v[30:31], v[118:119], v[178:179] op_sel_hi:[1,0,1]
	v_sub_f32_e32 v118, v173, v119
	v_mul_f32_e32 v118, 0x3fb8aa3b, v118
	v_exp_f32_e32 v118, v118
	s_nop 0
	v_add_f32_e32 v169, v118, v169
	v_pk_fma_f32 v[172:173], v[38:39], v[118:119], v[178:179] op_sel_hi:[1,0,1]
	v_pk_fma_f32 v[176:177], v[40:41], v[118:119], v[176:177] op_sel_hi:[1,0,1]
	v_sub_f32_e32 v118, v174, v119
	v_mul_f32_e32 v118, 0x3fb8aa3b, v118
	v_exp_f32_e32 v118, v118
	s_nop 0
	v_add_f32_e32 v169, v118, v169
	v_pk_fma_f32 v[174:175], v[56:57], v[118:119], v[176:177] op_sel_hi:[1,0,1]
	v_exp_f32_e32 v176, v113
	ds_bpermute_b32 v113, v142, v169
	v_pk_fma_f32 v[172:173], v[54:55], v[118:119], v[172:173] op_sel_hi:[1,0,1]
	ds_bpermute_b32 v178, v142, v174
	ds_bpermute_b32 v179, v142, v175
	s_waitcnt lgkmcnt(0)
	v_add_f32_e32 v113, v169, v113
	v_pk_add_f32 v[174:175], v[174:175], v[178:179]
	ds_bpermute_b32 v178, v143, v174
	ds_bpermute_b32 v179, v143, v175
	s_waitcnt lgkmcnt(0)
	v_mov_b32_e32 v118, v113
	s_nop 1
	v_permlane32_swap_b32_e32 v113, v118
	v_add_f32_e32 v118, v113, v118
	v_fmac_f32_e32 v118, v112, v176
	ds_bpermute_b32 v112, v142, v172
	ds_bpermute_b32 v113, v142, v173
	s_waitcnt lgkmcnt(0)
	v_pk_add_f32 v[112:113], v[172:173], v[112:113]
	ds_bpermute_b32 v172, v143, v112
	ds_bpermute_b32 v173, v143, v113
	s_waitcnt lgkmcnt(0)
	v_pk_add_f32 v[112:113], v[112:113], v[172:173]
	v_pk_add_f32 v[172:173], v[174:175], v[178:179]
	v_pk_fma_f32 v[62:63], v[62:63], v[176:177], v[112:113] op_sel_hi:[1,0,1]
	v_pk_fma_f32 v[64:65], v[64:65], v[176:177], v[172:173] op_sel_hi:[1,0,1]
	v_mov_b32_e32 v112, v118
	v_mov_b32_e32 v113, v119
.LBB0_5343:
	s_or_b64 exec, exec, s[22:23]
	s_waitcnt lgkmcnt(0)
	v_add_f32_e32 v120, v120, v121
	v_fma_f32 v120, -v128, v124, v120
	v_add_f32_e32 v121, v167, v168
	v_cndmask_b32_e32 v172, v135, v120, vcc
	v_add_f32_e32 v120, v164, v165
	v_fma_f32 v121, -v128, v152, v121
	v_fma_f32 v120, -v128, v125, v120
	v_cndmask_b32_e64 v165, v135, v121, s[12:13]
	v_add_f32_e32 v121, v170, v171
	v_cndmask_b32_e64 v169, v135, v120, s[10:11]
	v_fma_f32 v121, -v128, v155, v121
	v_max3_f32 v120, v172, s33, v169
	v_cndmask_b32_e64 v164, v135, v121, s[14:15]
	v_max3_f32 v120, v120, v165, v164
	ds_bpermute_b32 v121, v142, v120
	s_waitcnt lgkmcnt(0)
	v_max_f32_e32 v121, v121, v121
	v_max_f32_e32 v120, v120, v121
	ds_bpermute_b32 v121, v143, v120
	s_waitcnt lgkmcnt(0)
	v_max_f32_e32 v121, v121, v121
	v_max_f32_e32 v167, v120, v121
	v_cmp_neq_f32_e64 s[16:17], s33, v167
	v_mov_b64_e32 v[120:121], v[116:117]
	s_and_saveexec_b64 s[22:23], s[16:17]
	s_cbranch_execz .LBB0_5345
	v_max_f32_e32 v120, v167, v167
	v_max_f32_e32 v121, v117, v117
	v_max_f32_e32 v121, v121, v120
	v_sub_f32_e32 v120, v172, v121
	v_mul_f32_e32 v120, 0x3fb8aa3b, v120
	v_exp_f32_e32 v120, v120
	v_sub_f32_e32 v117, v117, v121
	v_mul_f32_e32 v117, 0x3fb8aa3b, v117
	v_add_f32_e32 v167, 0, v120
	v_pk_fma_f32 v[170:171], v[8:9], v[120:121], 0 op_sel_hi:[1,0,0]
	v_pk_fma_f32 v[172:173], v[6:7], v[120:121], 0 op_sel_hi:[1,0,0]
	v_sub_f32_e32 v120, v169, v121
	v_mul_f32_e32 v120, 0x3fb8aa3b, v120
	v_exp_f32_e32 v120, v120
	s_nop 0
	v_add_f32_e32 v167, v120, v167
	v_pk_fma_f32 v[168:169], v[32:33], v[120:121], v[170:171] op_sel_hi:[1,0,1]
	v_pk_fma_f32 v[170:171], v[30:31], v[120:121], v[172:173] op_sel_hi:[1,0,1]
	v_sub_f32_e32 v120, v165, v121
	v_mul_f32_e32 v120, 0x3fb8aa3b, v120
	v_exp_f32_e32 v120, v120
	s_nop 0
	v_add_f32_e32 v165, v120, v167
	v_pk_fma_f32 v[170:171], v[38:39], v[120:121], v[170:171] op_sel_hi:[1,0,1]
	v_pk_fma_f32 v[168:169], v[40:41], v[120:121], v[168:169] op_sel_hi:[1,0,1]
	v_sub_f32_e32 v120, v164, v121
	v_mul_f32_e32 v120, 0x3fb8aa3b, v120
	v_exp_f32_e32 v120, v120
	s_nop 0
	v_add_f32_e32 v167, v120, v165
	v_pk_fma_f32 v[164:165], v[56:57], v[120:121], v[168:169] op_sel_hi:[1,0,1]
	v_pk_fma_f32 v[168:169], v[54:55], v[120:121], v[170:171] op_sel_hi:[1,0,1]
	v_exp_f32_e32 v170, v117
	ds_bpermute_b32 v117, v142, v167
	ds_bpermute_b32 v172, v142, v164
	ds_bpermute_b32 v173, v142, v165
	s_waitcnt lgkmcnt(0)
	v_add_f32_e32 v117, v167, v117
	v_pk_add_f32 v[164:165], v[164:165], v[172:173]
	ds_bpermute_b32 v172, v143, v164
	ds_bpermute_b32 v173, v143, v165
	s_waitcnt lgkmcnt(0)
	v_mov_b32_e32 v120, v117
	s_nop 1
	v_permlane32_swap_b32_e32 v117, v120
	v_add_f32_e32 v120, v117, v120
	v_fmac_f32_e32 v120, v116, v170
	ds_bpermute_b32 v116, v142, v168
	ds_bpermute_b32 v117, v142, v169
	v_pk_add_f32 v[164:165], v[164:165], v[172:173]
	s_waitcnt lgkmcnt(0)
	v_pk_add_f32 v[116:117], v[168:169], v[116:117]
	ds_bpermute_b32 v168, v143, v116
	ds_bpermute_b32 v169, v143, v117
	v_pk_fma_f32 v[60:61], v[60:61], v[170:171], v[164:165] op_sel_hi:[1,0,1]
	s_waitcnt lgkmcnt(0)
	v_pk_add_f32 v[116:117], v[116:117], v[168:169]
	s_nop 0
	v_pk_fma_f32 v[58:59], v[58:59], v[170:171], v[116:117] op_sel_hi:[1,0,1]
	v_mov_b32_e32 v116, v120
	v_mov_b32_e32 v117, v121
.LBB0_5345:
	s_or_b64 exec, exec, s[22:23]
	v_add_f32_e32 v122, v122, v123
	v_fma_f32 v122, -v129, v124, v122
	v_add_f32_e32 v123, v160, v161
	v_cndmask_b32_e32 v165, v135, v122, vcc
	v_add_f32_e32 v122, v158, v159
	v_fma_f32 v123, -v129, v152, v123
	v_fma_f32 v122, -v129, v125, v122
	v_cndmask_b32_e64 v159, v135, v123, s[12:13]
	v_add_f32_e32 v123, v162, v163
	v_cndmask_b32_e64 v164, v135, v122, s[10:11]
	v_fma_f32 v123, -v129, v155, v123
	v_max3_f32 v122, v165, s33, v164
	v_cndmask_b32_e64 v158, v135, v123, s[14:15]
	v_max3_f32 v122, v122, v159, v158
	ds_bpermute_b32 v123, v142, v122
	s_waitcnt lgkmcnt(0)
	v_max_f32_e32 v123, v123, v123
	v_max_f32_e32 v122, v122, v123
	ds_bpermute_b32 v123, v143, v122
	s_waitcnt lgkmcnt(0)
	v_max_f32_e32 v123, v123, v123
	v_max_f32_e32 v160, v122, v123
	v_cmp_neq_f32_e64 s[16:17], s33, v160
	v_mov_b64_e32 v[122:123], v[114:115]
	s_and_saveexec_b64 s[22:23], s[16:17]
	s_cbranch_execz .LBB0_5347
	v_max_f32_e32 v122, v160, v160
	v_max_f32_e32 v123, v115, v115
	v_max_f32_e32 v123, v123, v122
	v_sub_f32_e32 v122, v165, v123
	v_mul_f32_e32 v122, 0x3fb8aa3b, v122
	v_exp_f32_e32 v122, v122
	v_sub_f32_e32 v115, v115, v123
	v_mul_f32_e32 v115, 0x3fb8aa3b, v115
	v_add_f32_e32 v165, 0, v122
	v_pk_fma_f32 v[160:161], v[8:9], v[122:123], 0 op_sel_hi:[1,0,0]
	v_pk_fma_f32 v[162:163], v[6:7], v[122:123], 0 op_sel_hi:[1,0,0]
	v_sub_f32_e32 v122, v164, v123
	v_mul_f32_e32 v122, 0x3fb8aa3b, v122
	v_exp_f32_e32 v122, v122
	s_nop 0
	v_add_f32_e32 v164, v122, v165
	v_pk_fma_f32 v[160:161], v[32:33], v[122:123], v[160:161] op_sel_hi:[1,0,1]
	v_pk_fma_f32 v[162:163], v[30:31], v[122:123], v[162:163] op_sel_hi:[1,0,1]
	v_sub_f32_e32 v122, v159, v123
	v_mul_f32_e32 v122, 0x3fb8aa3b, v122
	v_exp_f32_e32 v122, v122
	s_nop 0
	v_add_f32_e32 v159, v122, v164
	v_pk_fma_f32 v[162:163], v[38:39], v[122:123], v[162:163] op_sel_hi:[1,0,1]
	v_pk_fma_f32 v[160:161], v[40:41], v[122:123], v[160:161] op_sel_hi:[1,0,1]
	v_sub_f32_e32 v122, v158, v123
	v_mul_f32_e32 v122, 0x3fb8aa3b, v122
	v_exp_f32_e32 v122, v122
	s_nop 0
	v_add_f32_e32 v164, v122, v159
	v_pk_fma_f32 v[158:159], v[56:57], v[122:123], v[160:161] op_sel_hi:[1,0,1]
	v_pk_fma_f32 v[160:161], v[54:55], v[122:123], v[162:163] op_sel_hi:[1,0,1]
	v_exp_f32_e32 v162, v115
	ds_bpermute_b32 v165, v142, v159
	s_waitcnt lgkmcnt(0)
	v_mov_b32_e32 v115, v164
	s_nop 1
	v_permlane16_swap_b32_e32 v164, v115
	v_add_f32_e32 v115, v164, v115
	ds_bpermute_b32 v164, v142, v158
	s_waitcnt lgkmcnt(0)
	v_mov_b32_e32 v122, v115
	s_nop 1
	v_permlane32_swap_b32_e32 v115, v122
	v_add_f32_e32 v122, v115, v122
	v_fmac_f32_e32 v122, v114, v162
	ds_bpermute_b32 v114, v142, v160
	ds_bpermute_b32 v115, v142, v161
	v_pk_add_f32 v[158:159], v[158:159], v[164:165]
	ds_bpermute_b32 v164, v143, v158
	ds_bpermute_b32 v165, v143, v159
	s_waitcnt lgkmcnt(0)
	v_pk_add_f32 v[114:115], v[160:161], v[114:115]
	ds_bpermute_b32 v160, v143, v114
	ds_bpermute_b32 v161, v143, v115
	v_pk_add_f32 v[158:159], v[158:159], v[164:165]
	s_waitcnt lgkmcnt(0)
	v_pk_add_f32 v[114:115], v[114:115], v[160:161]
	v_pk_fma_f32 v[52:53], v[52:53], v[162:163], v[158:159] op_sel_hi:[1,0,1]
	v_pk_fma_f32 v[50:51], v[50:51], v[162:163], v[114:115] op_sel_hi:[1,0,1]
	v_mov_b32_e32 v114, v122
	v_mov_b32_e32 v115, v123
.LBB0_5347:
	s_or_b64 exec, exec, s[22:23]
	v_add_f32_e32 v148, v148, v149
	v_fma_f32 v124, -v130, v124, v148
	v_cndmask_b32_e32 v158, v135, v124, vcc
	v_add_f32_e32 v124, v150, v151
	v_fma_f32 v124, -v130, v125, v124
	v_add_f32_e32 v125, v153, v154
	v_fma_f32 v125, -v130, v152, v125
	v_cndmask_b32_e64 v149, v135, v125, s[12:13]
	v_add_f32_e32 v125, v156, v157
	v_cndmask_b32_e64 v150, v135, v124, s[10:11]
	v_fma_f32 v125, -v130, v155, v125
	v_max3_f32 v124, v158, s33, v150
	v_cndmask_b32_e64 v148, v135, v125, s[14:15]
	v_max3_f32 v124, v124, v149, v148
	ds_bpermute_b32 v125, v142, v124
	s_waitcnt lgkmcnt(0)
	v_max_f32_e32 v125, v125, v125
	v_max_f32_e32 v124, v124, v125
	ds_bpermute_b32 v125, v143, v124
	s_waitcnt lgkmcnt(0)
	v_max_f32_e32 v125, v125, v125
	v_max_f32_e32 v151, v124, v125
	v_cmp_neq_f32_e32 vcc, s33, v151
	v_mov_b64_e32 v[124:125], v[110:111]
	s_and_saveexec_b64 s[10:11], vcc
	s_cbranch_execz .LBB0_5349
	v_max_f32_e32 v124, v151, v151
	v_max_f32_e32 v125, v111, v111
	v_max_f32_e32 v125, v125, v124
	v_sub_f32_e32 v124, v158, v125
	v_mul_f32_e32 v124, 0x3fb8aa3b, v124
	v_exp_f32_e32 v124, v124
	v_sub_f32_e32 v111, v111, v125
	v_mul_f32_e32 v111, 0x3fb8aa3b, v111
	v_add_f32_e32 v151, 0, v124
	v_pk_fma_f32 v[152:153], v[8:9], v[124:125], 0 op_sel_hi:[1,0,0]
	v_pk_fma_f32 v[154:155], v[6:7], v[124:125], 0 op_sel_hi:[1,0,0]
	v_sub_f32_e32 v124, v150, v125
	v_mul_f32_e32 v124, 0x3fb8aa3b, v124
	v_exp_f32_e32 v124, v124
	s_nop 0
	v_add_f32_e32 v156, v124, v151
	v_pk_fma_f32 v[150:151], v[32:33], v[124:125], v[152:153] op_sel_hi:[1,0,1]
	v_pk_fma_f32 v[152:153], v[30:31], v[124:125], v[154:155] op_sel_hi:[1,0,1]
	v_sub_f32_e32 v124, v149, v125
	v_mul_f32_e32 v124, 0x3fb8aa3b, v124
	v_exp_f32_e32 v124, v124
	s_nop 0
	v_add_f32_e32 v149, v124, v156
	v_pk_fma_f32 v[152:153], v[38:39], v[124:125], v[152:153] op_sel_hi:[1,0,1]
	v_pk_fma_f32 v[150:151], v[40:41], v[124:125], v[150:151] op_sel_hi:[1,0,1]
	v_sub_f32_e32 v124, v148, v125
	v_mul_f32_e32 v124, 0x3fb8aa3b, v124
	v_exp_f32_e32 v124, v124
	s_nop 0
	v_add_f32_e32 v154, v124, v149
	v_pk_fma_f32 v[148:149], v[56:57], v[124:125], v[150:151] op_sel_hi:[1,0,1]
	v_pk_fma_f32 v[150:151], v[54:55], v[124:125], v[152:153] op_sel_hi:[1,0,1]
	v_exp_f32_e32 v152, v111
	ds_bpermute_b32 v155, v142, v149
	s_waitcnt lgkmcnt(0)
	v_mov_b32_e32 v111, v154
	s_nop 1
	v_permlane16_swap_b32_e32 v154, v111
	v_add_f32_e32 v111, v154, v111
	ds_bpermute_b32 v154, v142, v148
	s_waitcnt lgkmcnt(0)
	v_mov_b32_e32 v124, v111
	s_nop 1
	v_permlane32_swap_b32_e32 v111, v124
	v_add_f32_e32 v124, v111, v124
	v_fmac_f32_e32 v124, v110, v152
	ds_bpermute_b32 v110, v142, v150
	ds_bpermute_b32 v111, v142, v151
	v_pk_add_f32 v[148:149], v[148:149], v[154:155]
	ds_bpermute_b32 v154, v143, v148
	ds_bpermute_b32 v155, v143, v149
	s_waitcnt lgkmcnt(0)
	v_pk_add_f32 v[110:111], v[150:151], v[110:111]
	ds_bpermute_b32 v150, v143, v110
	ds_bpermute_b32 v151, v143, v111
	v_pk_add_f32 v[148:149], v[148:149], v[154:155]
	s_waitcnt lgkmcnt(0)
	v_pk_add_f32 v[110:111], v[110:111], v[150:151]
	v_pk_fma_f32 v[44:45], v[44:45], v[152:153], v[148:149] op_sel_hi:[1,0,1]
	v_pk_fma_f32 v[42:43], v[42:43], v[152:153], v[110:111] op_sel_hi:[1,0,1]
	v_mov_b32_e32 v110, v124
	v_mov_b32_e32 v111, v125

.LBB0_5351:
	v_mul_f32_e32 v149, v11, v95
	v_fmac_f32_e32 v149, v10, v94
	v_fmac_f32_e32 v149, v12, v96
	v_fmac_f32_e32 v149, v13, v97
	v_sub_u32_e32 v148, 0x800, v144
	v_cvt_f32_u32_e32 v148, v148
	v_cmp_gt_i32_e32 vcc, s2, v144
	s_waitcnt vmcnt(0)
	v_pk_mul_f32 v[154:155], v[12:13], v[92:93]
	s_waitcnt lgkmcnt(0)
	v_add_f32_dpp v149, v149, v149 quad_perm:[1,0,3,2] row_mask:0xf bank_mask:0xf
	v_cmp_gt_i32_e64 s[10:11], s2, v147
	v_pk_mul_f32 v[158:159], v[12:13], v[88:89]
	v_cmp_gt_i32_e64 s[12:13], s2, v146
	v_pk_mul_f32 v[160:161], v[10:11], v[82:83]
	s_waitcnt lgkmcnt(0)
	v_add_f32_dpp v149, v149, v149 quad_perm:[2,3,0,1] row_mask:0xf bank_mask:0xf
	v_cmp_gt_i32_e64 s[14:15], s2, v145
	s_waitcnt lgkmcnt(0)
	v_add_f32_dpp v149, v149, v149 row_half_mirror row_mask:0xf bank_mask:0xf
	s_waitcnt lgkmcnt(0)
	s_nop 0
	v_add_f32_dpp v149, v149, v149 row_mirror row_mask:0xf bank_mask:0xf
	v_fma_f32 v149, -v127, v148, v149
	v_cndmask_b32_e32 v153, v135, v149, vcc
	v_mul_f32_e32 v149, v15, v95
	v_fmac_f32_e32 v149, v14, v94
	v_fmac_f32_e32 v149, v16, v96
	v_fmac_f32_e32 v149, v17, v97
	s_waitcnt lgkmcnt(0)
	s_nop 0
	v_add_f32_dpp v149, v149, v149 quad_perm:[1,0,3,2] row_mask:0xf bank_mask:0xf
	s_waitcnt lgkmcnt(0)
	s_nop 0
	v_add_f32_dpp v149, v149, v149 quad_perm:[2,3,0,1] row_mask:0xf bank_mask:0xf
	s_waitcnt lgkmcnt(0)
	s_nop 0
	v_add_f32_dpp v151, v149, v149 row_half_mirror row_mask:0xf bank_mask:0xf
	v_mul_f32_e32 v149, v19, v95
	v_mul_f32_e32 v95, v23, v95
	v_fmac_f32_e32 v149, v18, v94
	v_fmac_f32_e32 v95, v22, v94
	v_fmac_f32_e32 v149, v20, v96
	v_fmac_f32_e32 v95, v24, v96
	v_fmac_f32_e32 v149, v21, v97
	v_fmac_f32_e32 v95, v25, v97
	v_mul_f32_e32 v97, v11, v91
	v_fmac_f32_e32 v97, v10, v90
	v_add_f32_e32 v97, v154, v97
	v_add_f32_e32 v97, v155, v97
	ds_bpermute_b32 v152, v141, v151
	s_waitcnt lgkmcnt(0)
	v_add_f32_dpp v97, v97, v97 quad_perm:[1,0,3,2] row_mask:0xf bank_mask:0xf
	s_waitcnt lgkmcnt(0)
	s_nop 1
	v_add_f32_dpp v94, v95, v95 quad_perm:[1,0,3,2] row_mask:0xf bank_mask:0xf
	s_waitcnt lgkmcnt(0)
	v_add_f32_dpp v149, v149, v149 quad_perm:[1,0,3,2] row_mask:0xf bank_mask:0xf
	s_waitcnt lgkmcnt(0)
	v_add_f32_dpp v97, v97, v97 quad_perm:[2,3,0,1] row_mask:0xf bank_mask:0xf
	s_waitcnt lgkmcnt(0)
	v_add_f32_dpp v94, v94, v94 quad_perm:[2,3,0,1] row_mask:0xf bank_mask:0xf
	s_waitcnt lgkmcnt(0)
	v_add_f32_dpp v149, v149, v149 quad_perm:[2,3,0,1] row_mask:0xf bank_mask:0xf
	s_waitcnt lgkmcnt(0)
	v_add_f32_dpp v97, v97, v97 row_half_mirror row_mask:0xf bank_mask:0xf
	s_waitcnt lgkmcnt(0)
	v_add_f32_dpp v94, v94, v94 row_half_mirror row_mask:0xf bank_mask:0xf
	v_sub_u32_e32 v95, 0x7fc, v144
	v_cvt_f32_u32_e32 v95, v95
	s_waitcnt lgkmcnt(0)
	v_add_f32_dpp v149, v149, v149 row_half_mirror row_mask:0xf bank_mask:0xf
	s_waitcnt lgkmcnt(0)
	v_add_f32_dpp v97, v97, v97 row_mirror row_mask:0xf bank_mask:0xf
	ds_bpermute_b32 v150, v141, v149
	v_fma_f32 v97, -v127, v95, v97
	v_cndmask_b32_e64 v156, v135, v97, s[10:11]
	v_mul_f32_e32 v97, v15, v91
	v_fmac_f32_e32 v97, v14, v90
	v_fmac_f32_e32 v97, v16, v92
	v_fmac_f32_e32 v97, v17, v93
	v_max3_f32 v162, v153, s33, v156
	ds_bpermute_b32 v96, v141, v94
	s_waitcnt lgkmcnt(0)
	v_add_f32_dpp v97, v97, v97 quad_perm:[1,0,3,2] row_mask:0xf bank_mask:0xf
	s_waitcnt lgkmcnt(0)
	s_nop 0
	v_add_f32_dpp v97, v97, v97 quad_perm:[2,3,0,1] row_mask:0xf bank_mask:0xf
	s_waitcnt lgkmcnt(0)
	s_nop 0
	v_add_f32_dpp v154, v97, v97 row_half_mirror row_mask:0xf bank_mask:0xf
	v_mul_f32_e32 v97, v19, v91
	v_mul_f32_e32 v91, v23, v91
	v_fmac_f32_e32 v97, v18, v90
	v_fmac_f32_e32 v91, v22, v90
	v_fmac_f32_e32 v97, v20, v92
	v_fmac_f32_e32 v91, v24, v92
	v_fmac_f32_e32 v97, v21, v93
	v_fmac_f32_e32 v91, v25, v93
	v_mul_f32_e32 v93, v11, v87
	v_fmac_f32_e32 v93, v10, v86
	v_add_f32_e32 v93, v158, v93
	v_add_f32_e32 v93, v159, v93
	ds_bpermute_b32 v155, v141, v154
	s_waitcnt lgkmcnt(0)
	v_add_f32_dpp v93, v93, v93 quad_perm:[1,0,3,2] row_mask:0xf bank_mask:0xf
	s_waitcnt lgkmcnt(0)
	s_nop 1
	v_add_f32_dpp v90, v91, v91 quad_perm:[1,0,3,2] row_mask:0xf bank_mask:0xf
	s_waitcnt lgkmcnt(0)
	v_add_f32_dpp v97, v97, v97 quad_perm:[1,0,3,2] row_mask:0xf bank_mask:0xf
	s_waitcnt lgkmcnt(0)
	v_add_f32_dpp v93, v93, v93 quad_perm:[2,3,0,1] row_mask:0xf bank_mask:0xf
	s_waitcnt lgkmcnt(0)
	v_add_f32_dpp v90, v90, v90 quad_perm:[2,3,0,1] row_mask:0xf bank_mask:0xf
	ds_bpermute_b32 v91, v140, v90
	s_waitcnt lgkmcnt(0)
	v_add_f32_dpp v97, v97, v97 quad_perm:[2,3,0,1] row_mask:0xf bank_mask:0xf
	s_waitcnt lgkmcnt(0)
	v_add_f32_dpp v93, v93, v93 row_half_mirror row_mask:0xf bank_mask:0xf
	s_waitcnt lgkmcnt(0)
	v_add_f32_e32 v91, v90, v91
	v_sub_u32_e32 v90, 0x7f8, v144
	v_cvt_f32_u32_e32 v90, v90
	s_waitcnt lgkmcnt(0)
	v_add_f32_dpp v97, v97, v97 row_half_mirror row_mask:0xf bank_mask:0xf
	s_waitcnt lgkmcnt(0)
	v_add_f32_dpp v93, v93, v93 row_mirror row_mask:0xf bank_mask:0xf
	ds_bpermute_b32 v147, v141, v97
	v_fma_f32 v93, -v127, v90, v93
	v_cndmask_b32_e64 v159, v135, v93, s[12:13]
	v_mul_f32_e32 v93, v15, v87
	v_fmac_f32_e32 v93, v14, v86
	v_fmac_f32_e32 v93, v16, v88
	v_fmac_f32_e32 v93, v17, v89
	ds_bpermute_b32 v92, v141, v91
	s_waitcnt lgkmcnt(0)
	v_add_f32_dpp v93, v93, v93 quad_perm:[1,0,3,2] row_mask:0xf bank_mask:0xf
	s_waitcnt lgkmcnt(0)
	s_nop 0
	v_add_f32_dpp v93, v93, v93 quad_perm:[2,3,0,1] row_mask:0xf bank_mask:0xf
	s_waitcnt lgkmcnt(0)
	s_nop 0
	v_add_f32_dpp v157, v93, v93 row_half_mirror row_mask:0xf bank_mask:0xf
	v_mul_f32_e32 v93, v19, v87
	v_mul_f32_e32 v87, v23, v87
	v_fmac_f32_e32 v87, v22, v86
	v_fmac_f32_e32 v87, v24, v88
	v_fmac_f32_e32 v87, v25, v89
	v_fmac_f32_e32 v93, v18, v86
	v_fmac_f32_e32 v93, v20, v88
	v_fmac_f32_e32 v93, v21, v89
	v_add_f32_e32 v89, v160, v161
	s_waitcnt lgkmcnt(0)
	s_nop 1
	v_add_f32_dpp v86, v87, v87 quad_perm:[1,0,3,2] row_mask:0xf bank_mask:0xf
	ds_bpermute_b32 v158, v141, v157
	s_waitcnt lgkmcnt(0)
	v_add_f32_dpp v93, v93, v93 quad_perm:[1,0,3,2] row_mask:0xf bank_mask:0xf
	s_waitcnt lgkmcnt(0)
	v_add_f32_dpp v86, v86, v86 quad_perm:[2,3,0,1] row_mask:0xf bank_mask:0xf
	s_waitcnt lgkmcnt(0)
	v_add_f32_dpp v93, v93, v93 quad_perm:[2,3,0,1] row_mask:0xf bank_mask:0xf
	s_waitcnt lgkmcnt(0)
	v_add_f32_dpp v86, v86, v86 row_half_mirror row_mask:0xf bank_mask:0xf
	v_sub_u32_e32 v87, 0x7f4, v144
	v_pk_mul_f32 v[144:145], v[12:13], v[84:85]
	v_cvt_f32_u32_e32 v87, v87
	v_add_f32_e32 v89, v144, v89
	v_add_f32_e32 v89, v145, v89
	s_waitcnt lgkmcnt(0)
	v_add_f32_dpp v93, v93, v93 row_half_mirror row_mask:0xf bank_mask:0xf
	ds_bpermute_b32 v146, v141, v93
	ds_bpermute_b32 v88, v141, v86
	s_waitcnt lgkmcnt(0)
	v_add_f32_dpp v89, v89, v89 quad_perm:[1,0,3,2] row_mask:0xf bank_mask:0xf
	s_waitcnt lgkmcnt(0)
	s_nop 0
	v_add_f32_dpp v89, v89, v89 quad_perm:[2,3,0,1] row_mask:0xf bank_mask:0xf
	s_waitcnt lgkmcnt(0)
	s_nop 0
	v_add_f32_dpp v89, v89, v89 row_half_mirror row_mask:0xf bank_mask:0xf
	s_waitcnt lgkmcnt(0)
	s_nop 0
	v_add_f32_dpp v89, v89, v89 row_mirror row_mask:0xf bank_mask:0xf
	v_fma_f32 v89, -v127, v87, v89
	v_cndmask_b32_e64 v161, v135, v89, s[14:15]
	v_mul_f32_e32 v89, v15, v83
	v_fmac_f32_e32 v89, v14, v82
	v_fmac_f32_e32 v89, v16, v84
	v_fmac_f32_e32 v89, v17, v85
	v_max3_f32 v162, v162, v159, v161
	s_waitcnt lgkmcnt(0)
	v_add_f32_dpp v89, v89, v89 quad_perm:[1,0,3,2] row_mask:0xf bank_mask:0xf
	s_waitcnt lgkmcnt(0)
	s_nop 0
	v_add_f32_dpp v89, v89, v89 quad_perm:[2,3,0,1] row_mask:0xf bank_mask:0xf
	s_waitcnt lgkmcnt(0)
	s_nop 0
	v_add_f32_dpp v145, v89, v89 row_half_mirror row_mask:0xf bank_mask:0xf
	v_mul_f32_e32 v89, v19, v83
	v_mul_f32_e32 v83, v23, v83
	v_fmac_f32_e32 v89, v18, v82
	v_fmac_f32_e32 v83, v22, v82
	v_fmac_f32_e32 v89, v20, v84
	v_fmac_f32_e32 v83, v24, v84
	v_fmac_f32_e32 v89, v21, v85
	v_fmac_f32_e32 v83, v25, v85
	ds_bpermute_b32 v84, v142, v162
	ds_bpermute_b32 v160, v141, v145
	s_waitcnt lgkmcnt(0)
	v_add_f32_dpp v89, v89, v89 quad_perm:[1,0,3,2] row_mask:0xf bank_mask:0xf
	s_waitcnt lgkmcnt(0)
	s_nop 1
	v_add_f32_dpp v82, v83, v83 quad_perm:[1,0,3,2] row_mask:0xf bank_mask:0xf
	s_waitcnt lgkmcnt(0)
	v_max_f32_e32 v84, v84, v84
	v_max_f32_e32 v84, v162, v84
	ds_bpermute_b32 v85, v143, v84
	s_waitcnt lgkmcnt(0)
	v_add_f32_dpp v89, v89, v89 quad_perm:[2,3,0,1] row_mask:0xf bank_mask:0xf
	s_waitcnt lgkmcnt(0)
	v_add_f32_dpp v82, v82, v82 quad_perm:[2,3,0,1] row_mask:0xf bank_mask:0xf
	s_waitcnt lgkmcnt(0)
	v_max_f32_e32 v85, v85, v85
	v_max_f32_e32 v84, v84, v85
	v_cmp_neq_f32_e64 s[16:17], s33, v84
	s_waitcnt lgkmcnt(0)
	v_add_f32_dpp v89, v89, v89 row_half_mirror row_mask:0xf bank_mask:0xf
	s_waitcnt lgkmcnt(0)
	v_add_f32_dpp v82, v82, v82 row_half_mirror row_mask:0xf bank_mask:0xf
	ds_bpermute_b32 v144, v141, v89
	ds_bpermute_b32 v83, v141, v82
	s_and_saveexec_b64 s[24:25], s[16:17]
	s_cbranch_execz .LBB0_5353
	v_max_f32_e32 v84, v84, v84
	v_max_f32_e32 v85, v113, v113
	v_max_f32_e32 v119, v85, v84
	v_sub_f32_e32 v84, v113, v119
	v_mul_f32_e32 v113, 0x3fb8aa3b, v84
	v_sub_f32_e32 v84, v153, v119
	v_mul_f32_e32 v84, 0x3fb8aa3b, v84
	v_sub_f32_e32 v118, v156, v119
	v_exp_f32_e32 v84, v84
	v_mul_f32_e32 v118, 0x3fb8aa3b, v118
	v_exp_f32_e32 v118, v118
	v_exp_f32_e32 v156, v113
	v_add_f32_e32 v153, 0, v84
	v_pk_fma_f32 v[162:163], v[76:77], v[84:85], 0 op_sel_hi:[1,0,0]
	v_pk_fma_f32 v[84:85], v[74:75], v[84:85], 0 op_sel_hi:[1,0,0]
	v_add_f32_e32 v153, v118, v153
	v_pk_fma_f32 v[162:163], v[68:69], v[118:119], v[162:163] op_sel_hi:[1,0,1]
	v_pk_fma_f32 v[84:85], v[66:67], v[118:119], v[84:85] op_sel_hi:[1,0,1]
	v_sub_f32_e32 v118, v159, v119
	v_mul_f32_e32 v118, 0x3fb8aa3b, v118
	v_exp_f32_e32 v118, v118
	s_nop 0
	v_add_f32_e32 v153, v118, v153
	v_pk_fma_f32 v[84:85], v[70:71], v[118:119], v[84:85] op_sel_hi:[1,0,1]
	v_pk_fma_f32 v[162:163], v[72:73], v[118:119], v[162:163] op_sel_hi:[1,0,1]
	v_sub_f32_e32 v118, v161, v119
	v_mul_f32_e32 v118, 0x3fb8aa3b, v118
	v_exp_f32_e32 v118, v118
	s_nop 0
	v_add_f32_e32 v153, v118, v153
	ds_bpermute_b32 v113, v142, v153
	v_pk_fma_f32 v[162:163], v[80:81], v[118:119], v[162:163] op_sel_hi:[1,0,1]
	v_pk_fma_f32 v[84:85], v[78:79], v[118:119], v[84:85] op_sel_hi:[1,0,1]
	ds_bpermute_b32 v164, v142, v162
	ds_bpermute_b32 v165, v142, v163
	s_waitcnt lgkmcnt(0)
	v_add_f32_e32 v113, v153, v113
	s_waitcnt lgkmcnt(0)
	v_pk_add_f32 v[162:163], v[162:163], v[164:165]
	ds_bpermute_b32 v164, v143, v162
	s_waitcnt lgkmcnt(0)
	v_mov_b32_e32 v118, v113
	s_nop 1
	v_permlane32_swap_b32_e32 v113, v118
	v_add_f32_e32 v118, v113, v118
	v_fmac_f32_e32 v118, v112, v156
	ds_bpermute_b32 v112, v142, v84
	ds_bpermute_b32 v113, v142, v85
	ds_bpermute_b32 v165, v143, v163
	s_waitcnt lgkmcnt(0)
	v_pk_add_f32 v[84:85], v[84:85], v[112:113]
	ds_bpermute_b32 v112, v143, v84
	ds_bpermute_b32 v113, v143, v85
	s_waitcnt lgkmcnt(0)
	v_pk_add_f32 v[84:85], v[84:85], v[112:113]
	v_pk_add_f32 v[112:113], v[162:163], v[164:165]
	v_pk_fma_f32 v[62:63], v[62:63], v[156:157], v[84:85] op_sel_hi:[1,0,1]
	v_pk_fma_f32 v[64:65], v[64:65], v[156:157], v[112:113] op_sel_hi:[1,0,1]
	v_mov_b32_e32 v112, v118
	v_mov_b32_e32 v113, v119
.LBB0_5353:
	s_or_b64 exec, exec, s[24:25]
	v_add_f32_e32 v84, v151, v152
	v_fma_f32 v84, -v128, v148, v84
	v_cndmask_b32_e32 v152, v135, v84, vcc
	v_add_f32_e32 v84, v154, v155
	v_fma_f32 v84, -v128, v95, v84
	v_cndmask_b32_e64 v151, v135, v84, s[10:11]
	v_add_f32_e32 v84, v157, v158
	v_fma_f32 v84, -v128, v90, v84
	v_cndmask_b32_e64 v85, v135, v84, s[12:13]
	v_add_f32_e32 v84, v145, v160
	v_fma_f32 v84, -v128, v87, v84
	v_max3_f32 v153, v152, s33, v151
	v_cndmask_b32_e64 v84, v135, v84, s[14:15]
	v_max3_f32 v145, v153, v85, v84
	ds_bpermute_b32 v153, v142, v145
	s_waitcnt lgkmcnt(0)
	v_max_f32_e32 v153, v153, v153
	v_max_f32_e32 v145, v145, v153
	ds_bpermute_b32 v153, v143, v145
	s_waitcnt lgkmcnt(0)
	v_max_f32_e32 v153, v153, v153
	v_max_f32_e32 v145, v145, v153
	v_cmp_neq_f32_e64 s[16:17], s33, v145
	s_and_saveexec_b64 s[24:25], s[16:17]
	s_cbranch_execz .LBB0_5355
	v_max_f32_e32 v120, v145, v145
	v_max_f32_e32 v121, v117, v117
	v_max_f32_e32 v121, v121, v120
	v_sub_f32_e32 v120, v152, v121
	v_mul_f32_e32 v120, 0x3fb8aa3b, v120
	v_exp_f32_e32 v120, v120
	v_sub_f32_e32 v85, v85, v121
	v_mul_f32_e32 v85, 0x3fb8aa3b, v85
	v_sub_f32_e32 v84, v84, v121
	v_add_f32_e32 v145, 0, v120
	v_pk_fma_f32 v[152:153], v[76:77], v[120:121], 0 op_sel_hi:[1,0,0]
	v_pk_fma_f32 v[154:155], v[74:75], v[120:121], 0 op_sel_hi:[1,0,0]
	v_sub_f32_e32 v120, v151, v121
	v_mul_f32_e32 v120, 0x3fb8aa3b, v120
	v_exp_f32_e32 v120, v120
	v_mul_f32_e32 v84, 0x3fb8aa3b, v84
	v_exp_f32_e32 v84, v84
	v_sub_f32_e32 v117, v117, v121
	v_add_f32_e32 v145, v120, v145
	v_pk_fma_f32 v[152:153], v[68:69], v[120:121], v[152:153] op_sel_hi:[1,0,1]
	v_pk_fma_f32 v[154:155], v[66:67], v[120:121], v[154:155] op_sel_hi:[1,0,1]
	v_exp_f32_e32 v120, v85
	v_mul_f32_e32 v117, 0x3fb8aa3b, v117
	v_add_f32_e32 v85, v120, v145
	v_pk_fma_f32 v[154:155], v[70:71], v[120:121], v[154:155] op_sel_hi:[1,0,1]
	v_pk_fma_f32 v[152:153], v[72:73], v[120:121], v[152:153] op_sel_hi:[1,0,1]
	v_add_f32_e32 v120, v84, v85
	v_pk_fma_f32 v[152:153], v[80:81], v[84:85], v[152:153] op_sel_hi:[1,0,1]
	v_pk_fma_f32 v[84:85], v[78:79], v[84:85], v[154:155] op_sel_hi:[1,0,1]
	v_exp_f32_e32 v154, v117
	ds_bpermute_b32 v156, v142, v152
	ds_bpermute_b32 v157, v142, v153
	s_waitcnt lgkmcnt(0)
	v_mov_b32_e32 v117, v120
	s_nop 1
	v_permlane16_swap_b32_e32 v120, v117
	v_add_f32_e32 v117, v120, v117
	s_waitcnt lgkmcnt(0)
	v_pk_add_f32 v[152:153], v[152:153], v[156:157]
	ds_bpermute_b32 v156, v143, v152
	ds_bpermute_b32 v157, v143, v153
	s_waitcnt lgkmcnt(0)
	v_mov_b32_e32 v120, v117
	s_nop 1
	v_permlane32_swap_b32_e32 v117, v120
	v_add_f32_e32 v120, v117, v120
	v_fmac_f32_e32 v120, v116, v154
	ds_bpermute_b32 v116, v142, v84
	ds_bpermute_b32 v117, v142, v85
	s_waitcnt lgkmcnt(0)
	v_pk_add_f32 v[84:85], v[84:85], v[116:117]
	ds_bpermute_b32 v116, v143, v84
	ds_bpermute_b32 v117, v143, v85
	s_waitcnt lgkmcnt(0)
	v_pk_add_f32 v[84:85], v[84:85], v[116:117]
	v_pk_add_f32 v[116:117], v[152:153], v[156:157]
	v_pk_fma_f32 v[58:59], v[58:59], v[154:155], v[84:85] op_sel_hi:[1,0,1]
	v_pk_fma_f32 v[60:61], v[60:61], v[154:155], v[116:117] op_sel_hi:[1,0,1]
	v_mov_b32_e32 v116, v120
	v_mov_b32_e32 v117, v121
.LBB0_5355:
	s_or_b64 exec, exec, s[24:25]
	v_add_f32_e32 v84, v149, v150
	v_fma_f32 v84, -v129, v148, v84
	v_cndmask_b32_e32 v145, v135, v84, vcc
	v_add_f32_e32 v84, v97, v147
	v_fma_f32 v84, -v129, v95, v84
	v_cndmask_b32_e64 v97, v135, v84, s[10:11]
	v_add_f32_e32 v84, v93, v146
	v_fma_f32 v84, -v129, v90, v84
	v_cndmask_b32_e64 v85, v135, v84, s[12:13]
	v_add_f32_e32 v84, v89, v144
	v_fma_f32 v84, -v129, v87, v84
	v_max3_f32 v147, v145, s33, v97
	v_cndmask_b32_e64 v84, v135, v84, s[14:15]
	v_max3_f32 v89, v147, v85, v84
	ds_bpermute_b32 v93, v142, v89
	s_waitcnt lgkmcnt(0)
	v_max_f32_e32 v93, v93, v93
	v_max_f32_e32 v89, v89, v93
	ds_bpermute_b32 v93, v143, v89
	s_waitcnt lgkmcnt(0)
	v_max_f32_e32 v93, v93, v93
	v_max_f32_e32 v89, v89, v93
	v_cmp_neq_f32_e64 s[16:17], s33, v89
	s_and_saveexec_b64 s[24:25], s[16:17]
	s_cbranch_execz .LBB0_5357
	v_max_f32_e32 v89, v89, v89
	v_max_f32_e32 v93, v115, v115
	v_max_f32_e32 v123, v93, v89
	v_sub_f32_e32 v93, v145, v123
	v_mul_f32_e32 v93, 0x3fb8aa3b, v93
	v_exp_f32_e32 v122, v93
	v_sub_f32_e32 v97, v97, v123
	v_mul_f32_e32 v97, 0x3fb8aa3b, v97
	v_sub_f32_e32 v85, v85, v123
	v_add_f32_e32 v93, 0, v122
	v_pk_fma_f32 v[144:145], v[76:77], v[122:123], 0 op_sel_hi:[1,0,0]
	v_pk_fma_f32 v[146:147], v[74:75], v[122:123], 0 op_sel_hi:[1,0,0]
	v_exp_f32_e32 v122, v97
	v_mul_f32_e32 v85, 0x3fb8aa3b, v85
	v_sub_f32_e32 v84, v84, v123
	v_mul_f32_e32 v84, 0x3fb8aa3b, v84
	v_add_f32_e32 v93, v122, v93
	v_pk_fma_f32 v[144:145], v[68:69], v[122:123], v[144:145] op_sel_hi:[1,0,1]
	v_pk_fma_f32 v[146:147], v[66:67], v[122:123], v[146:147] op_sel_hi:[1,0,1]
	v_exp_f32_e32 v122, v85
	v_exp_f32_e32 v84, v84
	v_sub_f32_e32 v89, v115, v123
	v_mul_f32_e32 v89, 0x3fb8aa3b, v89
	v_add_f32_e32 v85, v122, v93
	v_pk_fma_f32 v[146:147], v[70:71], v[122:123], v[146:147] op_sel_hi:[1,0,1]
	v_pk_fma_f32 v[144:145], v[72:73], v[122:123], v[144:145] op_sel_hi:[1,0,1]
	v_add_f32_e32 v93, v84, v85
	v_pk_fma_f32 v[144:145], v[80:81], v[84:85], v[144:145] op_sel_hi:[1,0,1]
	v_pk_fma_f32 v[84:85], v[78:79], v[84:85], v[146:147] op_sel_hi:[1,0,1]
	v_exp_f32_e32 v146, v89
	ds_bpermute_b32 v115, v142, v85
	ds_bpermute_b32 v150, v142, v144
	ds_bpermute_b32 v151, v142, v145
	s_waitcnt lgkmcnt(0)
	v_mov_b32_e32 v89, v93
	s_nop 1
	v_permlane16_swap_b32_e32 v93, v89
	v_add_f32_e32 v89, v93, v89
	ds_bpermute_b32 v93, v143, v89
	s_waitcnt lgkmcnt(0)
	v_pk_add_f32 v[144:145], v[144:145], v[150:151]
	ds_bpermute_b32 v150, v143, v144
	ds_bpermute_b32 v151, v143, v145
	s_waitcnt lgkmcnt(0)
	v_add_f32_e32 v122, v89, v93
	v_fmac_f32_e32 v122, v114, v146
	ds_bpermute_b32 v114, v142, v84
	s_waitcnt lgkmcnt(0)
	v_pk_add_f32 v[84:85], v[84:85], v[114:115]
	ds_bpermute_b32 v114, v143, v84
	ds_bpermute_b32 v115, v143, v85
	s_waitcnt lgkmcnt(0)
	v_pk_add_f32 v[84:85], v[84:85], v[114:115]
	v_pk_add_f32 v[114:115], v[144:145], v[150:151]
	v_pk_fma_f32 v[50:51], v[50:51], v[146:147], v[84:85] op_sel_hi:[1,0,1]
	v_pk_fma_f32 v[52:53], v[52:53], v[146:147], v[114:115] op_sel_hi:[1,0,1]
	v_mov_b32_e32 v114, v122
	v_mov_b32_e32 v115, v123
.LBB0_5357:
	s_or_b64 exec, exec, s[24:25]
	v_add_f32_e32 v84, v94, v96
	v_fma_f32 v84, -v130, v148, v84
	v_cndmask_b32_e32 v89, v135, v84, vcc
	v_add_f32_e32 v84, v91, v92
	v_fma_f32 v84, -v130, v95, v84
	v_cndmask_b32_e64 v85, v135, v84, s[10:11]
	v_add_f32_e32 v84, v86, v88
	v_add_f32_e32 v82, v82, v83
	v_fma_f32 v84, -v130, v90, v84
	v_fma_f32 v82, -v130, v87, v82
	v_max3_f32 v91, v89, s33, v85
	v_cndmask_b32_e64 v84, v135, v84, s[12:13]
	v_cndmask_b32_e64 v82, v135, v82, s[14:15]
	v_max3_f32 v83, v91, v84, v82
	ds_bpermute_b32 v86, v142, v83
	s_waitcnt lgkmcnt(0)
	v_max_f32_e32 v86, v86, v86
	v_max_f32_e32 v83, v83, v86
	ds_bpermute_b32 v86, v143, v83
	s_waitcnt lgkmcnt(0)
	v_max_f32_e32 v86, v86, v86
	v_max_f32_e32 v83, v83, v86
	v_cmp_neq_f32_e32 vcc, s33, v83
	s_and_saveexec_b64 s[10:11], vcc
	s_cbranch_execz .LBB0_5359
	v_max_f32_e32 v83, v83, v83
	v_max_f32_e32 v86, v111, v111
	v_max_f32_e32 v125, v86, v83
	v_sub_f32_e32 v86, v89, v125
	v_mul_f32_e32 v86, 0x3fb8aa3b, v86
	v_exp_f32_e32 v86, v86
	v_sub_f32_e32 v85, v85, v125
	v_mul_f32_e32 v85, 0x3fb8aa3b, v85
	v_sub_f32_e32 v83, v111, v125
	v_add_f32_e32 v87, 0, v86
	v_pk_fma_f32 v[76:77], v[76:77], v[86:87], 0 op_sel_hi:[1,0,0]
	v_pk_fma_f32 v[74:75], v[74:75], v[86:87], 0 op_sel_hi:[1,0,0]
	v_exp_f32_e32 v86, v85
	v_mul_f32_e32 v83, 0x3fb8aa3b, v83
	v_mov_b32_e32 v111, v125
	v_pk_fma_f32 v[66:67], v[66:67], v[86:87], v[74:75] op_sel_hi:[1,0,1]
	v_sub_f32_e32 v74, v84, v125
	v_mul_f32_e32 v74, 0x3fb8aa3b, v74
	v_exp_f32_e32 v74, v74
	v_add_f32_e32 v85, v86, v87
	v_pk_fma_f32 v[68:69], v[68:69], v[86:87], v[76:77] op_sel_hi:[1,0,1]
	v_add_f32_e32 v75, v74, v85
	v_pk_fma_f32 v[66:67], v[70:71], v[74:75], v[66:67] op_sel_hi:[1,0,1]
	v_sub_f32_e32 v70, v82, v125
	v_mul_f32_e32 v70, 0x3fb8aa3b, v70
	v_exp_f32_e32 v70, v70
	v_pk_fma_f32 v[68:69], v[72:73], v[74:75], v[68:69] op_sel_hi:[1,0,1]
	v_add_f32_e32 v71, v70, v75
	v_pk_fma_f32 v[68:69], v[80:81], v[70:71], v[68:69] op_sel_hi:[1,0,1]
	v_pk_fma_f32 v[66:67], v[78:79], v[70:71], v[66:67] op_sel_hi:[1,0,1]
	ds_bpermute_b32 v73, v142, v67
	ds_bpermute_b32 v74, v142, v68
	s_waitcnt lgkmcnt(0)
	v_mov_b32_e32 v72, v71
	s_nop 1
	v_permlane16_swap_b32_e32 v71, v72
	v_add_f32_e32 v71, v71, v72
	ds_bpermute_b32 v72, v143, v71
	ds_bpermute_b32 v75, v142, v69
	v_exp_f32_e32 v70, v83
	s_waitcnt lgkmcnt(0)
	v_add_f32_e32 v124, v71, v72
	ds_bpermute_b32 v72, v142, v66
	s_waitcnt lgkmcnt(0)
	v_pk_add_f32 v[68:69], v[68:69], v[74:75]
	ds_bpermute_b32 v74, v143, v68
	ds_bpermute_b32 v75, v143, v69
	v_fmac_f32_e32 v124, v110, v70
	s_waitcnt lgkmcnt(0)
	v_pk_add_f32 v[66:67], v[66:67], v[72:73]
	ds_bpermute_b32 v72, v143, v66
	ds_bpermute_b32 v73, v143, v67
	s_waitcnt lgkmcnt(0)
	v_pk_add_f32 v[68:69], v[68:69], v[74:75]
	v_mov_b32_e32 v110, v124
	v_pk_fma_f32 v[44:45], v[44:45], v[70:71], v[68:69] op_sel_hi:[1,0,1]
	s_waitcnt lgkmcnt(0)
	v_pk_add_f32 v[66:67], v[66:67], v[72:73]
	s_nop 0
	v_pk_fma_f32 v[42:43], v[42:43], v[70:71], v[66:67] op_sel_hi:[1,0,1]

.LBB0_5544:
	v_lshl_add_u64 v[18:19], s[68:69], 0, v[94:95]
	v_lshl_add_u64 v[22:23], s[68:69], 0, v[92:93]
	v_add_co_u32_e32 v20, vcc, 0x7800000, v18
	v_add_co_u32_e64 v102, s[6:7], s24, v22
	s_nop 0
	v_addc_co_u32_e32 v21, vcc, 0, v19, vcc
	v_addc_co_u32_e64 v103, s[6:7], 0, v23, s[6:7]
	v_add_co_u32_e64 v104, s[6:7], s25, v22
	v_add_co_u32_e32 v22, vcc, 0x7801000, v18
	s_nop 0
	v_addc_co_u32_e64 v105, s[6:7], 0, v23, s[6:7]
	global_load_dwordx4 v[78:81], v[20:21], off
	global_load_dwordx4 v[74:77], v[20:21], off offset:1024
	global_load_dwordx4 v[70:73], v[20:21], off offset:2048
	global_load_dwordx4 v[66:69], v[20:21], off offset:3072
	v_addc_co_u32_e32 v23, vcc, 0, v19, vcc
	v_add_co_u32_e32 v20, vcc, 0x7802000, v18
	global_load_dwordx4 v[62:65], v[22:23], off
	global_load_dwordx4 v[58:61], v[22:23], off offset:1024
	global_load_dwordx4 v[54:57], v[22:23], off offset:2048
	global_load_dwordx4 v[50:53], v[22:23], off offset:3072
	v_addc_co_u32_e32 v21, vcc, 0, v19, vcc
	v_add_co_u32_e32 v82, vcc, 0x7803000, v18
	global_load_dwordx4 v[46:49], v[20:21], off
	global_load_dwordx4 v[42:45], v[20:21], off offset:1024
	global_load_dwordx4 v[38:41], v[20:21], off offset:2048
	global_load_dwordx4 v[34:37], v[20:21], off offset:3072
	v_addc_co_u32_e32 v83, vcc, 0, v19, vcc
	global_load_dwordx4 v[30:33], v[82:83], off
	global_load_dwordx4 v[26:29], v[82:83], off offset:1024
	global_load_dwordx4 v[22:25], v[82:83], off offset:2048
	global_load_dwordx4 v[18:21], v[82:83], off offset:3072
	s_ashr_i32 s8, s12, 13
	s_add_i32 s9, s12, 0xffffc002
	s_cmpk_lt_i32 s12, 0x4000
	s_cselect_b32 s6, s8, s9
	s_addk_i32 s6, 0x82
	s_mul_hi_i32 s7, s6, 0x9000
	s_mul_i32 s6, s6, 0x9000
	s_add_u32 s9, s3, s6
	s_addc_u32 s11, s4, s7
	s_add_u32 s6, s9, 0x6000
	s_addc_u32 s7, s11, 0
	s_add_u32 s10, s9, 0x7000
	s_addc_u32 s11, s11, 0
	v_lshl_add_u64 v[82:83], s[6:7], 0, v[90:91]
	v_lshl_add_u64 v[86:87], s[10:11], 0, v[90:91]
	global_load_dwordx4 v[82:85], v[82:83], off
	v_lshl_add_u64 v[148:149], s[6:7], 0, v[96:97]
	global_load_dwordx4 v[86:89], v[86:87], off
	v_lshl_add_u64 v[142:143], s[6:7], 0, v[98:99]
	v_lshl_add_u64 v[132:133], s[6:7], 0, v[100:101]
	s_add_i32 s6, s12, 0xffffc003
	s_cmpk_lt_i32 s12, 0x3fff
	s_cselect_b32 s6, s8, s6
	s_addk_i32 s6, 0x82
	s_mul_hi_i32 s7, s6, 0x9000
	s_mul_i32 s6, s6, 0x9000
	s_add_u32 s9, s3, s6
	v_lshl_add_u64 v[152:153], s[10:11], 0, v[96:97]
	v_lshl_add_u64 v[146:147], s[10:11], 0, v[98:99]
	v_lshl_add_u64 v[140:141], s[10:11], 0, v[100:101]
	s_addc_u32 s11, s4, s7
	s_add_u32 s6, s9, 0x6000
	s_addc_u32 s7, s11, 0
	s_add_u32 s10, s9, 0x7000
	v_lshl_add_u64 v[134:135], s[6:7], 0, v[90:91]
	v_lshl_add_u64 v[126:127], s[6:7], 0, v[96:97]
	v_lshl_add_u64 v[118:119], s[6:7], 0, v[98:99]
	v_lshl_add_u64 v[114:115], s[6:7], 0, v[100:101]
	s_addc_u32 s11, s11, 0
	s_add_i32 s6, s12, 0xffffc004
	s_cmpk_lt_i32 s12, 0x3ffe
	s_cselect_b32 s6, s8, s6
	s_addk_i32 s6, 0x82
	s_mul_hi_i32 s7, s6, 0x9000
	s_mul_i32 s6, s6, 0x9000
	s_add_u32 s6, s3, s6
	s_addc_u32 s7, s4, s7
	v_lshl_add_u64 v[136:137], s[10:11], 0, v[90:91]
	v_lshl_add_u64 v[130:131], s[10:11], 0, v[96:97]
	v_lshl_add_u64 v[122:123], s[10:11], 0, v[98:99]
	v_lshl_add_u64 v[116:117], s[10:11], 0, v[100:101]
	s_add_u32 s10, s6, 0x6000
	s_addc_u32 s11, s7, 0
	s_add_u32 s6, s6, 0x7000
	s_addc_u32 s7, s7, 0
	s_add_i32 s9, s12, 0xffffc005
	s_cmpk_lt_i32 s12, 0x3ffd
	v_lshl_add_u64 v[156:157], s[6:7], 0, v[90:91]
	v_lshl_add_u64 v[154:155], s[6:7], 0, v[96:97]
	v_lshl_add_u64 v[150:151], s[6:7], 0, v[98:99]
	v_lshl_add_u64 v[138:139], s[6:7], 0, v[100:101]
	s_cselect_b32 s6, s8, s9
	s_addk_i32 s6, 0x82
	s_waitcnt vmcnt(0) lgkmcnt(0)
	v_pk_mul_f32 v[158:159], v[80:81], v[80:81]
	v_pk_mul_f32 v[160:161], v[78:79], v[78:79]
	v_pk_mul_f32 v[162:163], v[76:77], v[76:77]
	v_pk_mul_f32 v[164:165], v[74:75], v[74:75]
	v_mul_f32_e32 v174, v71, v71
	v_mul_f32_e32 v176, v73, v73
	v_mul_f32_e32 v187, v68, v68
	v_mul_f32_e32 v189, v69, v69
	v_pk_mov_b32 v[178:179], v[160:161], v[158:159] op_sel:[1,0]
	v_mov_b32_e32 v161, v159
	v_pk_mov_b32 v[158:159], v[164:165], v[162:163] op_sel:[1,0]
	v_mov_b32_e32 v165, v163
	v_pk_fma_f32 v[162:163], v[70:71], v[70:71], v[174:175] op_sel_hi:[1,1,0]
	v_pk_fma_f32 v[174:175], v[72:73], v[72:73], v[176:177] op_sel_hi:[1,1,0]
	v_pk_mul_f32 v[176:177], v[64:65], v[64:65]
	v_pk_mul_f32 v[180:181], v[62:63], v[62:63]
	v_pk_mul_f32 v[182:183], v[60:61], v[60:61]
	v_pk_mul_f32 v[184:185], v[58:59], v[58:59]
	v_mul_f32_e32 v186, v55, v55
	v_mul_f32_e32 v188, v57, v57
	v_pk_add_f32 v[160:161], v[178:179], v[160:161]
	v_pk_add_f32 v[158:159], v[158:159], v[164:165]
	v_mov_b32_e32 v163, v187
	v_mov_b32_e32 v175, v189
	v_pk_mov_b32 v[164:165], v[180:181], v[176:177] op_sel:[1,0]
	v_mov_b32_e32 v181, v177
	v_pk_mov_b32 v[176:177], v[184:185], v[182:183] op_sel:[1,0]
	v_mov_b32_e32 v185, v183
	v_pk_fma_f32 v[178:179], v[54:55], v[54:55], v[186:187] op_sel_hi:[1,1,0]
	v_pk_fma_f32 v[182:183], v[56:57], v[56:57], v[188:189] op_sel_hi:[1,1,0]
	v_pk_mul_f32 v[186:187], v[48:49], v[48:49]
	v_pk_mul_f32 v[188:189], v[46:47], v[46:47]
	v_pk_mul_f32 v[190:191], v[44:45], v[44:45]
	v_pk_mul_f32 v[192:193], v[42:43], v[42:43]
	v_mul_f32_e32 v197, v66, v66
	v_mul_f32_e32 v203, v67, v67
	v_mul_f32_e32 v195, v52, v52
	v_mul_f32_e32 v202, v53, v53
	v_mul_f32_e32 v194, v39, v39
	v_mul_f32_e32 v196, v41, v41
	v_pk_add_f32 v[198:199], v[160:161], v[160:161] op_sel:[0,1] op_sel_hi:[1,0]
	v_pk_add_f32 v[200:201], v[158:159], v[158:159] op_sel:[0,1] op_sel_hi:[1,0]
	v_pk_add_f32 v[174:175], v[162:163], v[174:175]
	v_pk_add_f32 v[158:159], v[164:165], v[180:181]
	v_pk_add_f32 v[160:161], v[176:177], v[184:185]
	v_pk_mov_b32 v[162:163], v[188:189], v[186:187] op_sel:[1,0]
	v_mov_b32_e32 v189, v187
	v_pk_mov_b32 v[164:165], v[192:193], v[190:191] op_sel:[1,0]
	v_mov_b32_e32 v193, v191
	v_mul_f32_e32 v208, v50, v50
	v_mul_f32_e32 v209, v51, v51
	v_mul_f32_e32 v212, v36, v36
	v_mul_f32_e32 v213, v37, v37
	v_mov_b32_e32 v179, v195
	v_mov_b32_e32 v183, v202
	v_pk_fma_f32 v[176:177], v[38:39], v[38:39], v[194:195] op_sel_hi:[1,1,0]
	v_pk_fma_f32 v[180:181], v[40:41], v[40:41], v[196:197] op_sel_hi:[1,1,0]
	v_pk_mul_f32 v[184:185], v[32:33], v[32:33]
	v_pk_mul_f32 v[186:187], v[30:31], v[30:31]
	v_pk_mul_f32 v[190:191], v[28:29], v[28:29]
	v_pk_mul_f32 v[194:195], v[26:27], v[26:27]
	v_mov_b32_e32 v199, v197
	v_mov_b32_e32 v201, v203
	v_pk_add_f32 v[204:205], v[158:159], v[158:159] op_sel:[0,1] op_sel_hi:[1,0]
	v_pk_add_f32 v[206:207], v[160:161], v[160:161] op_sel:[0,1] op_sel_hi:[1,0]
	v_pk_add_f32 v[162:163], v[162:163], v[188:189]
	v_pk_add_f32 v[164:165], v[164:165], v[192:193]
	v_mul_f32_e32 v210, v34, v34
	v_mul_f32_e32 v211, v35, v35
	v_pk_add_f32 v[178:179], v[178:179], v[182:183]
	v_mov_b32_e32 v177, v212
	v_mov_b32_e32 v181, v213
	v_pk_mov_b32 v[182:183], v[186:187], v[184:185] op_sel:[1,0]
	v_mov_b32_e32 v187, v185
	v_pk_mov_b32 v[184:185], v[194:195], v[190:191] op_sel:[1,0]
	v_mov_b32_e32 v195, v191
	v_pk_add_f32 v[188:189], v[198:199], v[200:201]
	v_mov_b32_e32 v205, v208
	v_mov_b32_e32 v207, v209
	v_pk_add_f32 v[190:191], v[162:163], v[162:163] op_sel:[0,1] op_sel_hi:[1,0]
	v_pk_add_f32 v[192:193], v[164:165], v[164:165] op_sel:[0,1] op_sel_hi:[1,0]
	v_pk_add_f32 v[176:177], v[176:177], v[180:181]
	v_pk_add_f32 v[174:175], v[188:189], v[174:175]
	v_pk_add_f32 v[180:181], v[204:205], v[206:207]
	v_mov_b32_e32 v191, v210
	v_mov_b32_e32 v193, v211
	v_pk_add_f32 v[162:163], v[182:183], v[186:187]
	v_add_f32_e32 v182, v174, v175
	v_pk_add_f32 v[174:175], v[180:181], v[178:179]
	v_pk_add_f32 v[178:179], v[190:191], v[192:193]
	v_add_f32_e32 v180, v174, v175
	v_pk_add_f32 v[174:175], v[178:179], v[176:177]
	v_add_f32_e32 v174, v174, v175
	s_mul_hi_i32 s7, s6, 0x9000
	s_waitcnt lgkmcnt(0)
	s_nop 1
	v_add_f32_dpp v176, v182, v182 quad_perm:[1,0,3,2] row_mask:0xf bank_mask:0xf
	s_waitcnt lgkmcnt(0)
	s_nop 1
	v_add_f32_dpp v175, v180, v180 quad_perm:[1,0,3,2] row_mask:0xf bank_mask:0xf
	s_waitcnt lgkmcnt(0)
	s_nop 1
	v_add_f32_dpp v174, v174, v174 quad_perm:[1,0,3,2] row_mask:0xf bank_mask:0xf
	s_waitcnt lgkmcnt(0)
	s_nop 1
	v_add_f32_dpp v176, v176, v176 quad_perm:[2,3,0,1] row_mask:0xf bank_mask:0xf
	s_waitcnt lgkmcnt(0)
	s_nop 1
	v_add_f32_dpp v175, v175, v175 quad_perm:[2,3,0,1] row_mask:0xf bank_mask:0xf
	s_waitcnt lgkmcnt(0)
	s_nop 1
	v_add_f32_dpp v174, v174, v174 quad_perm:[2,3,0,1] row_mask:0xf bank_mask:0xf
	s_waitcnt lgkmcnt(0)
	s_nop 1
	v_add_f32_dpp v176, v176, v176 row_half_mirror row_mask:0xf bank_mask:0xf
	s_waitcnt lgkmcnt(0)
	s_nop 1
	v_add_f32_dpp v175, v175, v175 row_half_mirror row_mask:0xf bank_mask:0xf
	s_waitcnt lgkmcnt(0)
	s_nop 1
	v_add_f32_dpp v174, v174, v174 row_half_mirror row_mask:0xf bank_mask:0xf
	s_waitcnt lgkmcnt(0)
	s_nop 1
	v_add_f32_dpp v176, v176, v176 row_mirror row_mask:0xf bank_mask:0xf
	s_waitcnt lgkmcnt(0)
	s_nop 1
	v_add_f32_dpp v175, v175, v175 row_mirror row_mask:0xf bank_mask:0xf
	s_waitcnt lgkmcnt(0)
	s_nop 1
	v_add_f32_dpp v174, v174, v174 row_mirror row_mask:0xf bank_mask:0xf
	s_waitcnt lgkmcnt(0)
	v_mov_b32_e32 v178, v176
	s_nop 1
	v_permlane16_swap_b32_e32 v176, v178
	v_add_f32_e32 v176, v176, v178
	s_waitcnt lgkmcnt(0)
	v_mov_b32_e32 v179, v175
	s_nop 1
	v_permlane16_swap_b32_e32 v175, v179
	v_add_f32_e32 v175, v175, v179
	ds_bpermute_b32 v179, v171, v175
	s_mul_i32 s6, s6, 0x9000
	s_waitcnt lgkmcnt(2)
	v_mov_b32_e32 v177, v174
	s_nop 1
	v_permlane16_swap_b32_e32 v174, v177
	v_add_f32_e32 v174, v174, v177
	s_add_u32 s6, s3, s6
	ds_bpermute_b32 v177, v171, v174
	s_addc_u32 s7, s4, s7
	s_waitcnt lgkmcnt(2)
	v_mov_b32_e32 v178, v176
	s_nop 1
	v_permlane32_swap_b32_e32 v176, v178
	v_add_f32_e32 v176, v176, v178
	s_add_u32 s18, s6, 0x6000
	v_fmamk_f32 v176, v176, 0x3a800000, v172
	s_addc_u32 s19, s7, 0
	s_waitcnt lgkmcnt(1)
	v_add_f32_e32 v175, v175, v179
	v_mul_f32_e32 v178, 0x4f800000, v176
	v_cmp_gt_f32_e32 vcc, s13, v176
	s_add_u32 s20, s6, 0x7000
	v_fmamk_f32 v175, v175, 0x3a800000, v172
	v_cndmask_b32_e32 v176, v176, v178, vcc
	s_addc_u32 s21, s7, 0
	s_waitcnt lgkmcnt(0)
	v_add_f32_e32 v174, v174, v177
	v_mul_f32_e32 v177, 0x4f800000, v175
	v_cmp_gt_f32_e64 s[6:7], s13, v175
	v_sqrt_f32_e32 v178, v176
	v_fmamk_f32 v174, v174, 0x3a800000, v172
	v_cndmask_b32_e64 v175, v175, v177, s[6:7]
	v_mul_f32_e32 v177, 0x4f800000, v174
	v_cmp_gt_f32_e64 s[8:9], s13, v174
	v_sqrt_f32_e32 v179, v175
	v_add_u32_e32 v180, -1, v178
	v_cndmask_b32_e64 v174, v174, v177, s[8:9]
	v_sqrt_f32_e32 v177, v174
	v_add_u32_e32 v181, 1, v178
	v_fma_f32 v182, -v180, v178, v176
	v_lshl_add_u64 v[112:113], s[10:11], 0, v[90:91]
	v_lshl_add_u64 v[106:107], s[10:11], 0, v[96:97]
	v_lshl_add_u64 v[110:111], s[10:11], 0, v[98:99]
	v_lshl_add_u64 v[108:109], s[10:11], 0, v[100:101]
	v_pk_add_f32 v[164:165], v[184:185], v[194:195]
	v_fma_f32 v183, -v181, v178, v176
	v_add_u32_e32 v184, -1, v179
	v_cmp_ge_f32_e64 s[10:11], 0, v182
	v_add_u32_e32 v185, 1, v179
	v_fma_f32 v182, -v185, v179, v175
	v_cndmask_b32_e64 v178, v178, v180, s[10:11]
	v_fma_f32 v180, -v184, v179, v175
	v_cmp_lt_f32_e64 s[10:11], 0, v183
	v_add_u32_e32 v186, -1, v177
	v_add_u32_e32 v187, 1, v177
	v_cndmask_b32_e64 v178, v178, v181, s[10:11]
	v_cmp_ge_f32_e64 s[10:11], 0, v180
	v_fma_f32 v180, -v186, v177, v174
	v_fma_f32 v181, -v187, v177, v174
	v_cndmask_b32_e64 v179, v179, v184, s[10:11]
	v_cmp_lt_f32_e64 s[10:11], 0, v182
	v_mul_f32_e32 v182, 0x37800000, v178
	v_cndmask_b32_e32 v178, v178, v182, vcc
	v_cndmask_b32_e64 v179, v179, v185, s[10:11]
	v_cmp_ge_f32_e64 s[10:11], 0, v180
	v_cmp_class_f32_e32 vcc, v176, v173
	v_mul_f32_e32 v180, 0x37800000, v179
	v_cndmask_b32_e64 v177, v177, v186, s[10:11]
	v_cmp_lt_f32_e64 s[10:11], 0, v181
	v_cndmask_b32_e32 v176, v178, v176, vcc
	v_cndmask_b32_e64 v178, v179, v180, s[6:7]
	v_cndmask_b32_e64 v177, v177, v187, s[10:11]
	v_cmp_class_f32_e32 vcc, v175, v173
	v_mul_f32_e32 v179, 0x37800000, v177
	v_div_scale_f32 v180, s[6:7], v176, v176, 1.0
	v_cndmask_b32_e32 v175, v178, v175, vcc
	v_cndmask_b32_e64 v177, v177, v179, s[8:9]
	v_cmp_class_f32_e32 vcc, v174, v173
	v_rcp_f32_e32 v178, v180
	v_div_scale_f32 v179, s[8:9], v175, v175, 1.0
	v_cndmask_b32_e32 v177, v177, v174, vcc
	v_rcp_f32_e32 v183, v179
	v_div_scale_f32 v184, s[10:11], v177, v177, 1.0
	v_rcp_f32_e32 v186, v184
	v_fma_f32 v174, -v180, v178, 1.0
	v_div_scale_f32 v181, s[6:7], 1.0, v176, 1.0
	v_fmac_f32_e32 v178, v174, v178
	v_fma_f32 v174, -v179, v183, 1.0
	v_mul_f32_e32 v187, v181, v178
	v_div_scale_f32 v182, s[8:9], 1.0, v175, 1.0
	v_fmac_f32_e32 v183, v174, v183
	v_fma_f32 v174, -v184, v186, 1.0
	v_fma_f32 v188, -v180, v187, v181
	v_div_scale_f32 v185, s[10:11], 1.0, v177, 1.0
	v_mul_f32_e32 v189, v182, v183
	v_fmac_f32_e32 v186, v174, v186
	v_fmac_f32_e32 v187, v188, v178
	v_fma_f32 v174, -v179, v189, v182
	v_mul_f32_e32 v188, v185, v186
	v_fma_f32 v180, -v180, v187, v181
	s_mov_b64 vcc, s[6:7]
	v_fmac_f32_e32 v189, v174, v183
	v_fma_f32 v174, -v184, v188, v185
	v_div_fmas_f32 v178, v180, v178, v187
	v_fma_f32 v179, -v179, v189, v182
	v_fmac_f32_e32 v188, v174, v186
	v_div_fixup_f32 v174, v178, v176, 1.0
	s_mov_b64 vcc, s[8:9]
	v_div_fmas_f32 v176, v179, v183, v189
	v_fma_f32 v178, -v184, v188, v185
	v_pk_mul_f32 v[80:81], v[80:81], v[174:175] op_sel_hi:[1,0]
	v_pk_mul_f32 v[78:79], v[78:79], v[174:175] op_sel_hi:[1,0]
	s_mov_b64 vcc, s[10:11]
	v_pk_add_f32 v[88:89], v[88:89], 1.0 op_sel_hi:[1,0]
	v_pk_add_f32 v[86:87], v[86:87], 1.0 op_sel_hi:[1,0]
	v_pk_mul_f32 v[76:77], v[76:77], v[174:175] op_sel_hi:[1,0]
	v_pk_mul_f32 v[74:75], v[74:75], v[174:175] op_sel_hi:[1,0]
	v_pk_mul_f32 v[72:73], v[72:73], v[174:175] op_sel_hi:[1,0]
	v_pk_mul_f32 v[70:71], v[70:71], v[174:175] op_sel_hi:[1,0]
	v_pk_mul_f32 v[68:69], v[68:69], v[174:175] op_sel_hi:[1,0]
	v_pk_mul_f32 v[66:67], v[66:67], v[174:175] op_sel_hi:[1,0]
	v_div_fixup_f32 v174, v176, v175, 1.0
	v_div_fmas_f32 v176, v178, v186, v188
	v_pk_mul_f32 v[78:79], v[2:3], v[78:79]
	v_pk_mul_f32 v[80:81], v[4:5], v[80:81]
	v_pk_mul_f32 v[64:65], v[64:65], v[174:175] op_sel_hi:[1,0]
	v_pk_mul_f32 v[62:63], v[62:63], v[174:175] op_sel_hi:[1,0]
	v_pk_mul_f32 v[60:61], v[60:61], v[174:175] op_sel_hi:[1,0]
	v_pk_mul_f32 v[58:59], v[58:59], v[174:175] op_sel_hi:[1,0]
	v_pk_mul_f32 v[56:57], v[56:57], v[174:175] op_sel_hi:[1,0]
	v_pk_mul_f32 v[54:55], v[54:55], v[174:175] op_sel_hi:[1,0]
	v_pk_mul_f32 v[52:53], v[52:53], v[174:175] op_sel_hi:[1,0]
	v_pk_mul_f32 v[174:175], v[50:51], v[174:175] op_sel_hi:[1,0]
	v_div_fixup_f32 v50, v176, v177, 1.0
	v_pk_fma_f32 v[80:81], v[88:89], v[80:81], v[84:85]
	v_pk_fma_f32 v[78:79], v[86:87], v[78:79], v[82:83]
	v_pk_mul_f32 v[86:87], v[16:17], v[52:53]
	v_pk_mul_f32 v[48:49], v[48:49], v[50:51] op_sel_hi:[1,0]
	v_pk_mul_f32 v[46:47], v[46:47], v[50:51] op_sel_hi:[1,0]
	v_pk_mul_f32 v[82:83], v[10:11], v[54:55]
	v_pk_mul_f32 v[84:85], v[14:15], v[174:175]
	v_pk_mul_f32 v[88:89], v[2:3], v[46:47]
	v_pk_mul_f32 v[174:175], v[4:5], v[48:49]
	v_cvt_pk_bf16_f32 v46, v78, v79
	v_cvt_pk_bf16_f32 v47, v80, v81
	global_store_dwordx2 v[102:103], v[46:47], off
	global_load_dwordx4 v[46:49], v[152:153], off
	s_nop 0
	global_load_dwordx4 v[52:55], v[148:149], off
	v_pk_mul_f32 v[74:75], v[6:7], v[74:75]
	v_pk_mul_f32 v[76:77], v[8:9], v[76:77]
	v_pk_mul_f32 v[70:71], v[10:11], v[70:71]
	v_pk_mul_f32 v[72:73], v[12:13], v[72:73]
	v_pk_mul_f32 v[66:67], v[66:67], v[14:15]
	v_pk_mul_f32 v[68:69], v[68:69], v[16:17]
	v_pk_mul_f32 v[62:63], v[2:3], v[62:63]
	v_pk_mul_f32 v[64:65], v[4:5], v[64:65]
	v_pk_mul_f32 v[58:59], v[6:7], v[58:59]
	v_pk_mul_f32 v[60:61], v[8:9], v[60:61]
	v_pk_mul_f32 v[56:57], v[12:13], v[56:57]
	v_mul_f32_e32 v196, v23, v23
	v_mul_f32_e32 v202, v25, v25
	v_mul_f32_e32 v214, v18, v18
	v_mul_f32_e32 v215, v19, v19
	v_mul_f32_e32 v216, v20, v20
	v_mul_f32_e32 v217, v21, v21
	v_pk_fma_f32 v[158:159], v[22:23], v[22:23], v[196:197] op_sel_hi:[1,1,0]
	v_pk_fma_f32 v[160:161], v[24:25], v[24:25], v[202:203] op_sel_hi:[1,1,0]
	v_mov_b32_e32 v159, v216
	v_mov_b32_e32 v161, v217
	v_lshl_add_u64 v[144:145], s[20:21], 0, v[90:91]
	v_lshl_add_u64 v[128:129], s[18:19], 0, v[90:91]
	v_lshl_add_u64 v[124:125], s[20:21], 0, v[96:97]
	v_lshl_add_u64 v[120:121], s[18:19], 0, v[96:97]
	s_add_i32 s12, s12, 32
	v_lshl_add_u64 v[92:93], v[92:93], 0, s[14:15]
	v_lshl_add_u64 v[94:95], v[94:95], 0, s[16:17]
	s_cmp_lt_i32 s12, s2
	s_waitcnt vmcnt(0) lgkmcnt(0)
	v_pk_add_f32 v[48:49], v[48:49], 1.0 op_sel_hi:[1,0]
	v_pk_add_f32 v[46:47], v[46:47], 1.0 op_sel_hi:[1,0]
	v_pk_fma_f32 v[48:49], v[48:49], v[76:77], v[54:55]
	v_pk_fma_f32 v[46:47], v[46:47], v[74:75], v[52:53]
	v_cvt_pk_bf16_f32 v46, v46, v47
	v_cvt_pk_bf16_f32 v47, v48, v49
	global_store_dwordx2 v[102:103], v[46:47], off offset:512
	global_load_dwordx4 v[46:49], v[146:147], off
	s_nop 0
	global_load_dwordx4 v[52:55], v[142:143], off
	s_waitcnt vmcnt(0) lgkmcnt(0)
	v_pk_add_f32 v[48:49], v[48:49], 1.0 op_sel_hi:[1,0]
	v_pk_add_f32 v[46:47], v[46:47], 1.0 op_sel_hi:[1,0]
	v_pk_fma_f32 v[48:49], v[72:73], v[48:49], v[54:55]
	v_pk_fma_f32 v[46:47], v[70:71], v[46:47], v[52:53]
	v_cvt_pk_bf16_f32 v46, v46, v47
	v_cvt_pk_bf16_f32 v47, v48, v49
	global_store_dwordx2 v[102:103], v[46:47], off offset:1024
	global_load_dwordx4 v[46:49], v[140:141], off
	s_nop 0
	global_load_dwordx4 v[52:55], v[132:133], off
	s_waitcnt vmcnt(0) lgkmcnt(0)
	v_pk_add_f32 v[48:49], v[48:49], 1.0 op_sel_hi:[1,0]
	v_pk_add_f32 v[46:47], v[46:47], 1.0 op_sel_hi:[1,0]
	v_pk_fma_f32 v[48:49], v[68:69], v[48:49], v[54:55]
	v_pk_fma_f32 v[46:47], v[66:67], v[46:47], v[52:53]
	v_cvt_pk_bf16_f32 v46, v46, v47
	v_cvt_pk_bf16_f32 v47, v48, v49
	global_store_dwordx2 v[102:103], v[46:47], off offset:1536
	global_load_dwordx4 v[46:49], v[136:137], off
	s_nop 0
	global_load_dwordx4 v[52:55], v[134:135], off
	s_waitcnt vmcnt(0) lgkmcnt(0)
	v_pk_add_f32 v[48:49], v[48:49], 1.0 op_sel_hi:[1,0]
	v_pk_add_f32 v[46:47], v[46:47], 1.0 op_sel_hi:[1,0]
	v_pk_fma_f32 v[48:49], v[48:49], v[64:65], v[54:55]
	v_pk_fma_f32 v[46:47], v[46:47], v[62:63], v[52:53]
	v_cvt_pk_bf16_f32 v46, v46, v47
	v_cvt_pk_bf16_f32 v47, v48, v49
	global_store_dwordx2 v[102:103], v[46:47], off offset:2048
	global_load_dwordx4 v[46:49], v[130:131], off
	s_nop 0
	global_load_dwordx4 v[52:55], v[126:127], off
	s_waitcnt vmcnt(0) lgkmcnt(0)
	v_pk_add_f32 v[48:49], v[48:49], 1.0 op_sel_hi:[1,0]
	v_pk_add_f32 v[46:47], v[46:47], 1.0 op_sel_hi:[1,0]
	v_pk_fma_f32 v[48:49], v[48:49], v[60:61], v[54:55]
	v_pk_fma_f32 v[46:47], v[46:47], v[58:59], v[52:53]
	v_cvt_pk_bf16_f32 v46, v46, v47
	v_cvt_pk_bf16_f32 v47, v48, v49
	global_store_dwordx2 v[102:103], v[46:47], off offset:2560
	global_load_dwordx4 v[46:49], v[122:123], off
	s_nop 0
	global_load_dwordx4 v[52:55], v[118:119], off
	v_pk_add_f32 v[58:59], v[164:165], v[164:165] op_sel:[0,1] op_sel_hi:[1,0]
	v_pk_add_f32 v[60:61], v[158:159], v[160:161]
	v_mov_b32_e32 v59, v215
	s_waitcnt vmcnt(0) lgkmcnt(0)
	v_pk_add_f32 v[48:49], v[48:49], 1.0 op_sel_hi:[1,0]
	v_pk_add_f32 v[46:47], v[46:47], 1.0 op_sel_hi:[1,0]
	v_pk_fma_f32 v[48:49], v[48:49], v[56:57], v[54:55]
	v_pk_fma_f32 v[46:47], v[46:47], v[82:83], v[52:53]
	v_cvt_pk_bf16_f32 v46, v46, v47
	v_cvt_pk_bf16_f32 v47, v48, v49
	global_store_dwordx2 v[102:103], v[46:47], off offset:3072
	global_load_dwordx4 v[46:49], v[116:117], off
	s_nop 0
	global_load_dwordx4 v[52:55], v[114:115], off
	v_pk_add_f32 v[56:57], v[162:163], v[162:163] op_sel:[0,1] op_sel_hi:[1,0]
	s_waitcnt vmcnt(0) lgkmcnt(0)
	v_pk_add_f32 v[48:49], v[48:49], 1.0 op_sel_hi:[1,0]
	v_pk_add_f32 v[46:47], v[46:47], 1.0 op_sel_hi:[1,0]
	v_pk_fma_f32 v[48:49], v[86:87], v[48:49], v[54:55]
	v_pk_fma_f32 v[46:47], v[84:85], v[46:47], v[52:53]
	v_cvt_pk_bf16_f32 v46, v46, v47
	v_cvt_pk_bf16_f32 v47, v48, v49
	global_store_dwordx2 v[102:103], v[46:47], off offset:3584
	global_load_dwordx4 v[46:49], v[156:157], off
	s_nop 0
	global_load_dwordx4 v[52:55], v[112:113], off
	v_mov_b32_e32 v57, v214
	s_waitcnt vmcnt(0) lgkmcnt(0)
	v_pk_add_f32 v[48:49], v[48:49], 1.0 op_sel_hi:[1,0]
	v_pk_add_f32 v[46:47], v[46:47], 1.0 op_sel_hi:[1,0]
	v_pk_fma_f32 v[48:49], v[48:49], v[174:175], v[54:55]
	v_pk_fma_f32 v[46:47], v[46:47], v[88:89], v[52:53]
	v_bfe_u32 v51, v46, 16, 1
	v_bfe_u32 v52, v47, 16, 1
	v_add3_u32 v46, v46, v51, s22
	v_add3_u32 v47, v47, v52, s22
	v_lshrrev_b32_e32 v46, 16, v46
	v_and_or_b32 v46, v47, s23, v46
	v_cvt_pk_bf16_f32 v47, v48, v49
	global_store_dwordx2 v[104:105], v[46:47], off
	global_load_dwordx4 v[46:49], v[154:155], off
	s_nop 0
	global_load_dwordx4 v[52:55], v[106:107], off
	v_pk_mul_f32 v[44:45], v[44:45], v[50:51] op_sel_hi:[1,0]
	v_pk_mul_f32 v[42:43], v[42:43], v[50:51] op_sel_hi:[1,0]
	v_pk_mul_f32 v[44:45], v[8:9], v[44:45]
	v_pk_mul_f32 v[42:43], v[6:7], v[42:43]
	s_waitcnt vmcnt(0) lgkmcnt(0)
	v_pk_add_f32 v[48:49], v[48:49], 1.0 op_sel_hi:[1,0]
	v_pk_add_f32 v[46:47], v[46:47], 1.0 op_sel_hi:[1,0]
	v_pk_fma_f32 v[44:45], v[48:49], v[44:45], v[54:55]
	v_pk_fma_f32 v[42:43], v[46:47], v[42:43], v[52:53]
	v_cvt_pk_bf16_f32 v42, v42, v43
	v_cvt_pk_bf16_f32 v43, v44, v45
	global_store_dwordx2 v[104:105], v[42:43], off offset:512
	global_load_dwordx4 v[42:45], v[150:151], off
	s_nop 0
	global_load_dwordx4 v[46:49], v[110:111], off
	v_pk_add_f32 v[52:53], v[56:57], v[58:59]
	s_waitcnt vmcnt(0) lgkmcnt(0)
	v_pk_add_f32 v[44:45], v[44:45], 1.0 op_sel_hi:[1,0]
	v_pk_add_f32 v[52:53], v[52:53], v[60:61]
	v_pk_add_f32 v[42:43], v[42:43], 1.0 op_sel_hi:[1,0]
	v_add_f32_e32 v51, v52, v53
	s_waitcnt lgkmcnt(0)
	s_nop 1
	v_add_f32_dpp v51, v51, v51 quad_perm:[1,0,3,2] row_mask:0xf bank_mask:0xf
	ds_bpermute_b32 v52, v167, v51
	s_waitcnt lgkmcnt(0)
	v_add_f32_e32 v51, v51, v52
	v_pk_mul_f32 v[40:41], v[40:41], v[50:51] op_sel_hi:[1,0]
	v_pk_mul_f32 v[38:39], v[38:39], v[50:51] op_sel_hi:[1,0]
	v_pk_mul_f32 v[40:41], v[12:13], v[40:41]
	v_pk_mul_f32 v[38:39], v[10:11], v[38:39]
	v_pk_fma_f32 v[40:41], v[44:45], v[40:41], v[48:49]
	v_pk_fma_f32 v[38:39], v[42:43], v[38:39], v[46:47]
	v_cvt_pk_bf16_f32 v38, v38, v39
	v_cvt_pk_bf16_f32 v39, v40, v41
	global_store_dwordx2 v[104:105], v[38:39], off offset:1024
	global_load_dwordx4 v[38:41], v[138:139], off
	s_nop 0
	global_load_dwordx4 v[42:45], v[108:109], off
	v_pk_mul_f32 v[36:37], v[36:37], v[50:51] op_sel_hi:[1,0]
	v_pk_mul_f32 v[34:35], v[34:35], v[50:51] op_sel_hi:[1,0]
	v_pk_mul_f32 v[36:37], v[16:17], v[36:37]
	v_pk_mul_f32 v[34:35], v[14:15], v[34:35]
	ds_bpermute_b32 v46, v168, v51
	s_waitcnt lgkmcnt(0)
	v_add_f32_e32 v46, v51, v46
	ds_bpermute_b32 v47, v169, v46
	s_waitcnt lgkmcnt(0)
	v_add_f32_e32 v46, v46, v47
	s_waitcnt lgkmcnt(0)
	v_mov_b32_e32 v47, v46
	s_nop 1
	v_permlane16_swap_b32_e32 v46, v47
	v_add_f32_e32 v46, v46, v47
	s_waitcnt lgkmcnt(0)
	v_mov_b32_e32 v47, v46
	s_nop 1
	v_permlane32_swap_b32_e32 v46, v47
	v_add_f32_e32 v46, v46, v47
	v_fmamk_f32 v46, v46, 0x3a800000, v172
	v_mul_f32_e32 v47, 0x4f800000, v46
	v_cmp_gt_f32_e32 vcc, s13, v46
	s_waitcnt vmcnt(0)
	v_pk_add_f32 v[40:41], v[40:41], 1.0 op_sel_hi:[1,0]
	v_pk_add_f32 v[38:39], v[38:39], 1.0 op_sel_hi:[1,0]
	v_pk_fma_f32 v[36:37], v[36:37], v[40:41], v[44:45]
	v_pk_fma_f32 v[34:35], v[34:35], v[38:39], v[42:43]
	v_cvt_pk_bf16_f32 v34, v34, v35
	v_cvt_pk_bf16_f32 v35, v36, v37
	global_store_dwordx2 v[104:105], v[34:35], off offset:1536
	global_load_dwordx4 v[34:37], v[144:145], off
	s_nop 0
	global_load_dwordx4 v[38:41], v[128:129], off
	v_cndmask_b32_e32 v42, v46, v47, vcc
	v_sqrt_f32_e32 v43, v42
	s_waitcnt vmcnt(0) lgkmcnt(0)
	v_pk_add_f32 v[36:37], v[36:37], 1.0 op_sel_hi:[1,0]
	v_add_u32_e32 v44, -1, v43
	v_add_u32_e32 v45, 1, v43
	v_fma_f32 v46, -v44, v43, v42
	v_fma_f32 v47, -v45, v43, v42
	v_cmp_ge_f32_e64 s[6:7], 0, v46
	v_pk_add_f32 v[34:35], v[34:35], 1.0 op_sel_hi:[1,0]
	s_nop 0
	v_cndmask_b32_e64 v43, v43, v44, s[6:7]
	v_cmp_lt_f32_e64 s[6:7], 0, v47
	s_nop 1
	v_cndmask_b32_e64 v43, v43, v45, s[6:7]
	v_mul_f32_e32 v44, 0x37800000, v43
	v_cndmask_b32_e32 v43, v43, v44, vcc
	v_cmp_class_f32_e32 vcc, v42, v173
	s_nop 1
	v_cndmask_b32_e32 v42, v43, v42, vcc
	v_div_scale_f32 v43, s[6:7], v42, v42, 1.0
	v_rcp_f32_e32 v45, v43
	v_div_scale_f32 v44, vcc, 1.0, v42, 1.0
	v_fma_f32 v46, -v43, v45, 1.0
	v_fmac_f32_e32 v45, v46, v45
	v_mul_f32_e32 v46, v44, v45
	v_fma_f32 v47, -v43, v46, v44
	v_fmac_f32_e32 v46, v47, v45
	v_fma_f32 v43, -v43, v46, v44
	v_div_fmas_f32 v43, v43, v45, v46
	v_div_fixup_f32 v42, v43, v42, 1.0
	v_pk_mul_f32 v[32:33], v[32:33], v[42:43] op_sel_hi:[1,0]
	v_pk_mul_f32 v[30:31], v[30:31], v[42:43] op_sel_hi:[1,0]
	v_pk_mul_f32 v[32:33], v[4:5], v[32:33]
	v_pk_mul_f32 v[30:31], v[2:3], v[30:31]
	v_pk_fma_f32 v[32:33], v[36:37], v[32:33], v[40:41]
	v_pk_fma_f32 v[30:31], v[34:35], v[30:31], v[38:39]
	v_cvt_pk_bf16_f32 v30, v30, v31
	v_cvt_pk_bf16_f32 v31, v32, v33
	global_store_dwordx2 v[104:105], v[30:31], off offset:2048
	global_load_dwordx4 v[30:33], v[124:125], off
	s_nop 0
	global_load_dwordx4 v[34:37], v[120:121], off
	v_pk_mul_f32 v[28:29], v[28:29], v[42:43] op_sel_hi:[1,0]
	v_pk_mul_f32 v[26:27], v[26:27], v[42:43] op_sel_hi:[1,0]
	v_pk_mul_f32 v[28:29], v[8:9], v[28:29]
	v_pk_mul_f32 v[26:27], v[6:7], v[26:27]
	v_lshl_add_u64 v[40:41], s[20:21], 0, v[98:99]
	v_lshl_add_u64 v[38:39], s[18:19], 0, v[98:99]
	v_pk_mul_f32 v[24:25], v[24:25], v[42:43] op_sel_hi:[1,0]
	v_pk_mul_f32 v[22:23], v[22:23], v[42:43] op_sel_hi:[1,0]
	v_pk_mul_f32 v[24:25], v[12:13], v[24:25]
	v_pk_mul_f32 v[22:23], v[10:11], v[22:23]
	v_pk_mul_f32 v[20:21], v[20:21], v[42:43] op_sel_hi:[1,0]
	v_pk_mul_f32 v[18:19], v[18:19], v[42:43] op_sel_hi:[1,0]
	v_pk_mul_f32 v[20:21], v[16:17], v[20:21]
	v_pk_mul_f32 v[18:19], v[14:15], v[18:19]
	s_waitcnt vmcnt(0) lgkmcnt(0)
	v_pk_add_f32 v[32:33], v[32:33], 1.0 op_sel_hi:[1,0]
	v_pk_add_f32 v[30:31], v[30:31], 1.0 op_sel_hi:[1,0]
	v_pk_fma_f32 v[28:29], v[32:33], v[28:29], v[36:37]
	v_pk_fma_f32 v[26:27], v[30:31], v[26:27], v[34:35]
	v_cvt_pk_bf16_f32 v26, v26, v27
	v_cvt_pk_bf16_f32 v27, v28, v29
	global_store_dwordx2 v[104:105], v[26:27], off offset:2560
	global_load_dwordx4 v[26:29], v[40:41], off
	s_nop 0
	global_load_dwordx4 v[30:33], v[38:39], off
	v_lshl_add_u64 v[36:37], s[20:21], 0, v[100:101]
	v_lshl_add_u64 v[34:35], s[18:19], 0, v[100:101]
	s_waitcnt vmcnt(0) lgkmcnt(0)
	v_pk_add_f32 v[28:29], v[28:29], 1.0 op_sel_hi:[1,0]
	v_pk_add_f32 v[26:27], v[26:27], 1.0 op_sel_hi:[1,0]
	v_pk_fma_f32 v[24:25], v[28:29], v[24:25], v[32:33]
	v_pk_fma_f32 v[22:23], v[26:27], v[22:23], v[30:31]
	v_cvt_pk_bf16_f32 v22, v22, v23
	v_cvt_pk_bf16_f32 v23, v24, v25
	global_store_dwordx2 v[104:105], v[22:23], off offset:3072
	global_load_dwordx4 v[22:25], v[36:37], off
	s_nop 0
	global_load_dwordx4 v[26:29], v[34:35], off
	s_waitcnt vmcnt(0) lgkmcnt(0)
	v_pk_add_f32 v[24:25], v[24:25], 1.0 op_sel_hi:[1,0]
	v_pk_add_f32 v[22:23], v[22:23], 1.0 op_sel_hi:[1,0]
	v_pk_fma_f32 v[20:21], v[20:21], v[24:25], v[28:29]
	v_pk_fma_f32 v[18:19], v[18:19], v[22:23], v[26:27]
	v_cvt_pk_bf16_f32 v18, v18, v19
	v_cvt_pk_bf16_f32 v19, v20, v21
	global_store_dwordx2 v[104:105], v[18:19], off offset:3584
	s_cbranch_scc1 .LBB0_5544

.LBB0_5693:
	v_lshl_add_u64 v[18:19], s[68:69], 0, v[94:95]
	v_lshl_add_u64 v[22:23], s[68:69], 0, v[92:93]
	v_add_co_u32_e32 v20, vcc, 0x7800000, v18
	v_add_co_u32_e64 v102, s[6:7], s22, v22
	s_nop 0
	v_addc_co_u32_e32 v21, vcc, 0, v19, vcc
	v_addc_co_u32_e64 v103, s[6:7], 0, v23, s[6:7]
	v_add_co_u32_e64 v104, s[6:7], s23, v22
	v_add_co_u32_e32 v22, vcc, 0x7801000, v18
	s_nop 0
	v_addc_co_u32_e64 v105, s[6:7], 0, v23, s[6:7]
	global_load_dwordx4 v[78:81], v[20:21], off
	global_load_dwordx4 v[74:77], v[20:21], off offset:1024
	global_load_dwordx4 v[70:73], v[20:21], off offset:2048
	global_load_dwordx4 v[66:69], v[20:21], off offset:3072
	v_addc_co_u32_e32 v23, vcc, 0, v19, vcc
	v_add_co_u32_e32 v20, vcc, 0x7802000, v18
	global_load_dwordx4 v[62:65], v[22:23], off
	global_load_dwordx4 v[58:61], v[22:23], off offset:1024
	global_load_dwordx4 v[54:57], v[22:23], off offset:2048
	global_load_dwordx4 v[50:53], v[22:23], off offset:3072
	v_addc_co_u32_e32 v21, vcc, 0, v19, vcc
	v_add_co_u32_e32 v82, vcc, 0x7803000, v18
	global_load_dwordx4 v[46:49], v[20:21], off
	global_load_dwordx4 v[42:45], v[20:21], off offset:1024
	global_load_dwordx4 v[38:41], v[20:21], off offset:2048
	global_load_dwordx4 v[34:37], v[20:21], off offset:3072
	v_addc_co_u32_e32 v83, vcc, 0, v19, vcc
	global_load_dwordx4 v[30:33], v[82:83], off
	global_load_dwordx4 v[26:29], v[82:83], off offset:1024
	global_load_dwordx4 v[22:25], v[82:83], off offset:2048
	global_load_dwordx4 v[18:21], v[82:83], off offset:3072
	s_add_i32 s24, s8, 32
	s_add_i32 s10, s8, 0xffffc022
	s_ashr_i32 s9, s24, 13
	s_cmpk_lt_i32 s24, 0x4000
	s_cselect_b32 s6, s9, s10
	s_addk_i32 s6, 0x82
	s_mul_hi_i32 s7, s6, 0x9000
	s_mul_i32 s6, s6, 0x9000
	s_add_u32 s10, s4, s6
	s_addc_u32 s11, s5, s7
	s_add_u32 s6, s10, 0x6000
	s_addc_u32 s7, s11, 0
	s_add_u32 s10, s10, 0x7000
	s_addc_u32 s11, s11, 0
	v_lshl_add_u64 v[82:83], s[6:7], 0, v[90:91]
	v_lshl_add_u64 v[86:87], s[10:11], 0, v[90:91]
	global_load_dwordx4 v[82:85], v[82:83], off
	v_lshl_add_u64 v[148:149], s[6:7], 0, v[96:97]
	global_load_dwordx4 v[86:89], v[86:87], off
	v_lshl_add_u64 v[142:143], s[6:7], 0, v[98:99]
	v_lshl_add_u64 v[132:133], s[6:7], 0, v[100:101]
	s_add_i32 s6, s8, 0xffffc023
	s_cmpk_lt_i32 s24, 0x3fff
	s_cselect_b32 s6, s9, s6
	s_addk_i32 s6, 0x82
	s_mul_hi_i32 s7, s6, 0x9000
	s_mul_i32 s6, s6, 0x9000
	v_lshl_add_u64 v[152:153], s[10:11], 0, v[96:97]
	v_lshl_add_u64 v[146:147], s[10:11], 0, v[98:99]
	v_lshl_add_u64 v[140:141], s[10:11], 0, v[100:101]
	s_add_u32 s10, s4, s6
	s_addc_u32 s11, s5, s7
	s_add_u32 s6, s10, 0x6000
	s_addc_u32 s7, s11, 0
	s_add_u32 s10, s10, 0x7000
	v_lshl_add_u64 v[134:135], s[6:7], 0, v[90:91]
	v_lshl_add_u64 v[126:127], s[6:7], 0, v[96:97]
	v_lshl_add_u64 v[118:119], s[6:7], 0, v[98:99]
	v_lshl_add_u64 v[114:115], s[6:7], 0, v[100:101]
	s_addc_u32 s11, s11, 0
	s_add_i32 s6, s8, 0xffffc024
	s_cmpk_lt_i32 s24, 0x3ffe
	s_cselect_b32 s6, s9, s6
	s_addk_i32 s6, 0x82
	s_mul_hi_i32 s7, s6, 0x9000
	s_mul_i32 s6, s6, 0x9000
	s_add_u32 s6, s4, s6
	s_addc_u32 s7, s5, s7
	v_lshl_add_u64 v[136:137], s[10:11], 0, v[90:91]
	v_lshl_add_u64 v[130:131], s[10:11], 0, v[96:97]
	v_lshl_add_u64 v[122:123], s[10:11], 0, v[98:99]
	v_lshl_add_u64 v[116:117], s[10:11], 0, v[100:101]
	s_add_u32 s10, s6, 0x6000
	s_addc_u32 s11, s7, 0
	s_add_u32 s6, s6, 0x7000
	s_addc_u32 s7, s7, 0
	s_addk_i32 s8, 0xc025
	s_cmpk_lt_i32 s24, 0x3ffd
	v_lshl_add_u64 v[156:157], s[6:7], 0, v[90:91]
	v_lshl_add_u64 v[154:155], s[6:7], 0, v[96:97]
	v_lshl_add_u64 v[150:151], s[6:7], 0, v[98:99]
	v_lshl_add_u64 v[138:139], s[6:7], 0, v[100:101]
	s_cselect_b32 s6, s9, s8
	s_waitcnt vmcnt(0) lgkmcnt(0)
	v_pk_mul_f32 v[158:159], v[80:81], v[80:81]
	v_pk_mul_f32 v[160:161], v[78:79], v[78:79]
	v_pk_mul_f32 v[162:163], v[76:77], v[76:77]
	v_pk_mul_f32 v[164:165], v[74:75], v[74:75]
	v_mul_f32_e32 v174, v71, v71
	v_mul_f32_e32 v176, v73, v73
	v_mul_f32_e32 v187, v68, v68
	v_mul_f32_e32 v189, v69, v69
	v_pk_mov_b32 v[178:179], v[160:161], v[158:159] op_sel:[1,0]
	v_mov_b32_e32 v161, v159
	v_pk_mov_b32 v[158:159], v[164:165], v[162:163] op_sel:[1,0]
	v_mov_b32_e32 v165, v163
	v_pk_fma_f32 v[162:163], v[70:71], v[70:71], v[174:175] op_sel_hi:[1,1,0]
	v_pk_fma_f32 v[174:175], v[72:73], v[72:73], v[176:177] op_sel_hi:[1,1,0]
	v_pk_mul_f32 v[176:177], v[64:65], v[64:65]
	v_pk_mul_f32 v[180:181], v[62:63], v[62:63]
	v_pk_mul_f32 v[182:183], v[60:61], v[60:61]
	v_pk_mul_f32 v[184:185], v[58:59], v[58:59]
	v_mul_f32_e32 v186, v55, v55
	v_mul_f32_e32 v188, v57, v57
	v_pk_add_f32 v[160:161], v[178:179], v[160:161]
	v_pk_add_f32 v[158:159], v[158:159], v[164:165]
	v_mov_b32_e32 v163, v187
	v_mov_b32_e32 v175, v189
	v_pk_mov_b32 v[164:165], v[180:181], v[176:177] op_sel:[1,0]
	v_mov_b32_e32 v181, v177
	v_pk_mov_b32 v[176:177], v[184:185], v[182:183] op_sel:[1,0]
	v_mov_b32_e32 v185, v183
	v_pk_fma_f32 v[178:179], v[54:55], v[54:55], v[186:187] op_sel_hi:[1,1,0]
	v_pk_fma_f32 v[182:183], v[56:57], v[56:57], v[188:189] op_sel_hi:[1,1,0]
	v_pk_mul_f32 v[186:187], v[48:49], v[48:49]
	v_pk_mul_f32 v[188:189], v[46:47], v[46:47]
	v_pk_mul_f32 v[190:191], v[44:45], v[44:45]
	v_pk_mul_f32 v[192:193], v[42:43], v[42:43]
	v_mul_f32_e32 v173, v66, v66
	v_mul_f32_e32 v197, v67, v67
	v_mul_f32_e32 v195, v52, v52
	v_mul_f32_e32 v202, v53, v53
	v_mul_f32_e32 v194, v39, v39
	v_mul_f32_e32 v196, v41, v41
	v_pk_add_f32 v[198:199], v[160:161], v[160:161] op_sel:[0,1] op_sel_hi:[1,0]
	v_pk_add_f32 v[200:201], v[158:159], v[158:159] op_sel:[0,1] op_sel_hi:[1,0]
	v_pk_add_f32 v[174:175], v[162:163], v[174:175]
	v_pk_add_f32 v[158:159], v[164:165], v[180:181]
	v_pk_add_f32 v[160:161], v[176:177], v[184:185]
	v_pk_mov_b32 v[162:163], v[188:189], v[186:187] op_sel:[1,0]
	v_mov_b32_e32 v189, v187
	v_pk_mov_b32 v[164:165], v[192:193], v[190:191] op_sel:[1,0]
	v_mov_b32_e32 v193, v191
	v_mul_f32_e32 v203, v50, v50
	v_mul_f32_e32 v208, v51, v51
	v_mul_f32_e32 v211, v36, v36
	v_mul_f32_e32 v212, v37, v37
	v_mov_b32_e32 v179, v195
	v_mov_b32_e32 v183, v202
	v_pk_fma_f32 v[176:177], v[38:39], v[38:39], v[194:195] op_sel_hi:[1,1,0]
	v_pk_fma_f32 v[180:181], v[40:41], v[40:41], v[196:197] op_sel_hi:[1,1,0]
	v_pk_mul_f32 v[184:185], v[32:33], v[32:33]
	v_pk_mul_f32 v[186:187], v[30:31], v[30:31]
	v_pk_mul_f32 v[190:191], v[28:29], v[28:29]
	v_pk_mul_f32 v[194:195], v[26:27], v[26:27]
	v_mov_b32_e32 v199, v173
	v_mov_b32_e32 v201, v197
	v_pk_add_f32 v[204:205], v[158:159], v[158:159] op_sel:[0,1] op_sel_hi:[1,0]
	v_pk_add_f32 v[206:207], v[160:161], v[160:161] op_sel:[0,1] op_sel_hi:[1,0]
	v_pk_add_f32 v[162:163], v[162:163], v[188:189]
	v_pk_add_f32 v[164:165], v[164:165], v[192:193]
	v_mul_f32_e32 v209, v34, v34
	v_mul_f32_e32 v210, v35, v35
	v_pk_add_f32 v[178:179], v[178:179], v[182:183]
	v_mov_b32_e32 v177, v211
	v_mov_b32_e32 v181, v212
	v_pk_mov_b32 v[182:183], v[186:187], v[184:185] op_sel:[1,0]
	v_mov_b32_e32 v187, v185
	v_pk_mov_b32 v[184:185], v[194:195], v[190:191] op_sel:[1,0]
	v_mov_b32_e32 v195, v191
	v_pk_add_f32 v[188:189], v[198:199], v[200:201]
	v_mov_b32_e32 v205, v203
	v_mov_b32_e32 v207, v208
	v_pk_add_f32 v[190:191], v[162:163], v[162:163] op_sel:[0,1] op_sel_hi:[1,0]
	v_pk_add_f32 v[192:193], v[164:165], v[164:165] op_sel:[0,1] op_sel_hi:[1,0]
	v_pk_add_f32 v[176:177], v[176:177], v[180:181]
	v_pk_add_f32 v[174:175], v[188:189], v[174:175]
	v_pk_add_f32 v[180:181], v[204:205], v[206:207]
	v_mov_b32_e32 v191, v209
	v_mov_b32_e32 v193, v210
	v_add_f32_e32 v173, v174, v175
	v_pk_add_f32 v[174:175], v[180:181], v[178:179]
	v_pk_add_f32 v[178:179], v[190:191], v[192:193]
	v_add_f32_e32 v180, v174, v175
	v_pk_add_f32 v[174:175], v[178:179], v[176:177]
	v_add_f32_e32 v174, v174, v175
	s_addk_i32 s6, 0x82
	s_waitcnt lgkmcnt(0)
	s_nop 1
	v_add_f32_dpp v173, v173, v173 quad_perm:[1,0,3,2] row_mask:0xf bank_mask:0xf
	s_waitcnt lgkmcnt(0)
	s_nop 1
	v_add_f32_dpp v175, v180, v180 quad_perm:[1,0,3,2] row_mask:0xf bank_mask:0xf
	s_waitcnt lgkmcnt(0)
	s_nop 1
	v_add_f32_dpp v174, v174, v174 quad_perm:[1,0,3,2] row_mask:0xf bank_mask:0xf
	s_waitcnt lgkmcnt(0)
	s_nop 1
	v_add_f32_dpp v173, v173, v173 quad_perm:[2,3,0,1] row_mask:0xf bank_mask:0xf
	s_waitcnt lgkmcnt(0)
	s_nop 1
	v_add_f32_dpp v175, v175, v175 quad_perm:[2,3,0,1] row_mask:0xf bank_mask:0xf
	s_waitcnt lgkmcnt(0)
	s_nop 1
	v_add_f32_dpp v174, v174, v174 quad_perm:[2,3,0,1] row_mask:0xf bank_mask:0xf
	s_waitcnt lgkmcnt(0)
	s_nop 1
	v_add_f32_dpp v173, v173, v173 row_half_mirror row_mask:0xf bank_mask:0xf
	s_waitcnt lgkmcnt(0)
	s_nop 1
	v_add_f32_dpp v175, v175, v175 row_half_mirror row_mask:0xf bank_mask:0xf
	s_waitcnt lgkmcnt(0)
	s_nop 1
	v_add_f32_dpp v174, v174, v174 row_half_mirror row_mask:0xf bank_mask:0xf
	s_waitcnt lgkmcnt(0)
	s_nop 1
	v_add_f32_dpp v173, v173, v173 row_mirror row_mask:0xf bank_mask:0xf
	s_waitcnt lgkmcnt(0)
	s_nop 1
	v_add_f32_dpp v175, v175, v175 row_mirror row_mask:0xf bank_mask:0xf
	s_waitcnt lgkmcnt(0)
	s_nop 1
	v_add_f32_dpp v174, v174, v174 row_mirror row_mask:0xf bank_mask:0xf
	s_waitcnt lgkmcnt(0)
	v_mov_b32_e32 v176, v173
	s_nop 1
	v_permlane16_swap_b32_e32 v173, v176
	v_add_f32_e32 v173, v173, v176
	ds_bpermute_b32 v176, v170, v173
	s_waitcnt lgkmcnt(2)
	v_mov_b32_e32 v178, v175
	s_nop 1
	v_permlane16_swap_b32_e32 v175, v178
	v_add_f32_e32 v175, v175, v178
	ds_bpermute_b32 v178, v170, v175
	s_mul_hi_i32 s7, s6, 0x9000
	s_mul_i32 s6, s6, 0x9000
	s_waitcnt lgkmcnt(2)
	v_mov_b32_e32 v177, v174
	s_nop 1
	v_permlane16_swap_b32_e32 v174, v177
	v_add_f32_e32 v174, v174, v177
	s_add_u32 s6, s4, s6
	ds_bpermute_b32 v177, v170, v174
	s_addc_u32 s7, s5, s7
	s_waitcnt lgkmcnt(2)
	v_add_f32_e32 v173, v173, v176
	s_add_u32 s16, s6, 0x6000
	v_fmamk_f32 v173, v173, 0x3a800000, v171
	s_addc_u32 s17, s7, 0
	s_waitcnt lgkmcnt(1)
	v_add_f32_e32 v175, v175, v178
	v_mul_f32_e32 v176, 0x4f800000, v173
	v_cmp_gt_f32_e32 vcc, s2, v173
	s_add_u32 s18, s6, 0x7000
	v_fmamk_f32 v175, v175, 0x3a800000, v171
	v_cndmask_b32_e32 v173, v173, v176, vcc
	s_addc_u32 s19, s7, 0
	s_waitcnt lgkmcnt(0)
	v_add_f32_e32 v174, v174, v177
	v_mul_f32_e32 v176, 0x4f800000, v175
	v_cmp_gt_f32_e64 s[6:7], s2, v175
	v_sqrt_f32_e32 v177, v173
	v_fmamk_f32 v174, v174, 0x3a800000, v171
	v_cndmask_b32_e64 v175, v175, v176, s[6:7]
	v_mul_f32_e32 v176, 0x4f800000, v174
	v_cmp_gt_f32_e64 s[8:9], s2, v174
	v_sqrt_f32_e32 v178, v175
	v_add_u32_e32 v179, -1, v177
	v_cndmask_b32_e64 v174, v174, v176, s[8:9]
	v_sqrt_f32_e32 v176, v174
	v_add_u32_e32 v180, 1, v177
	v_fma_f32 v181, -v179, v177, v173
	v_lshl_add_u64 v[112:113], s[10:11], 0, v[90:91]
	v_lshl_add_u64 v[106:107], s[10:11], 0, v[96:97]
	v_lshl_add_u64 v[110:111], s[10:11], 0, v[98:99]
	v_lshl_add_u64 v[108:109], s[10:11], 0, v[100:101]
	v_pk_add_f32 v[162:163], v[182:183], v[186:187]
	v_fma_f32 v182, -v180, v177, v173
	v_add_u32_e32 v183, -1, v178
	v_cmp_ge_f32_e64 s[10:11], 0, v181
	v_pk_add_f32 v[164:165], v[184:185], v[194:195]
	v_add_u32_e32 v184, 1, v178
	v_cndmask_b32_e64 v177, v177, v179, s[10:11]
	v_fma_f32 v179, -v183, v178, v175
	v_cmp_lt_f32_e64 s[10:11], 0, v182
	v_fma_f32 v181, -v184, v178, v175
	v_add_u32_e32 v185, -1, v176
	v_cndmask_b32_e64 v177, v177, v180, s[10:11]
	v_cmp_ge_f32_e64 s[10:11], 0, v179
	v_add_u32_e32 v186, 1, v176
	v_fma_f32 v179, -v185, v176, v174
	v_cndmask_b32_e64 v178, v178, v183, s[10:11]
	v_cmp_lt_f32_e64 s[10:11], 0, v181
	v_fma_f32 v180, -v186, v176, v174
	v_mul_f32_e32 v181, 0x37800000, v177
	v_cndmask_b32_e64 v178, v178, v184, s[10:11]
	v_cmp_ge_f32_e64 s[10:11], 0, v179
	v_cndmask_b32_e32 v177, v177, v181, vcc
	v_cmp_class_f32_e32 vcc, v173, v172
	v_cndmask_b32_e64 v176, v176, v185, s[10:11]
	v_cmp_lt_f32_e64 s[10:11], 0, v180
	v_mul_f32_e32 v179, 0x37800000, v178
	v_cndmask_b32_e32 v173, v177, v173, vcc
	v_cndmask_b32_e64 v176, v176, v186, s[10:11]
	v_cndmask_b32_e64 v177, v178, v179, s[6:7]
	v_cmp_class_f32_e32 vcc, v175, v172
	v_mul_f32_e32 v178, 0x37800000, v176
	v_div_scale_f32 v179, s[6:7], v173, v173, 1.0
	v_cndmask_b32_e32 v175, v177, v175, vcc
	v_cndmask_b32_e64 v176, v176, v178, s[8:9]
	v_cmp_class_f32_e32 vcc, v174, v172
	v_rcp_f32_e32 v177, v179
	v_div_scale_f32 v178, s[8:9], v175, v175, 1.0
	v_cndmask_b32_e32 v176, v176, v174, vcc
	v_rcp_f32_e32 v182, v178
	v_div_scale_f32 v183, s[10:11], v176, v176, 1.0
	v_rcp_f32_e32 v185, v183
	v_fma_f32 v174, -v179, v177, 1.0
	v_div_scale_f32 v180, s[6:7], 1.0, v173, 1.0
	v_fmac_f32_e32 v177, v174, v177
	v_fma_f32 v174, -v178, v182, 1.0
	v_mul_f32_e32 v186, v180, v177
	v_div_scale_f32 v181, s[8:9], 1.0, v175, 1.0
	v_fmac_f32_e32 v182, v174, v182
	v_fma_f32 v174, -v183, v185, 1.0
	v_fma_f32 v187, -v179, v186, v180
	v_div_scale_f32 v184, s[10:11], 1.0, v176, 1.0
	v_mul_f32_e32 v188, v181, v182
	v_fmac_f32_e32 v185, v174, v185
	v_fmac_f32_e32 v186, v187, v177
	v_fma_f32 v174, -v178, v188, v181
	v_mul_f32_e32 v187, v184, v185
	v_fma_f32 v179, -v179, v186, v180
	s_mov_b64 vcc, s[6:7]
	v_fmac_f32_e32 v188, v174, v182
	v_fma_f32 v174, -v183, v187, v184
	v_div_fmas_f32 v177, v179, v177, v186
	v_fma_f32 v178, -v178, v188, v181
	v_fmac_f32_e32 v187, v174, v185
	v_div_fixup_f32 v174, v177, v173, 1.0
	s_mov_b64 vcc, s[8:9]
	v_div_fmas_f32 v173, v178, v182, v188
	v_fma_f32 v177, -v183, v187, v184
	v_pk_mul_f32 v[80:81], v[80:81], v[174:175] op_sel_hi:[1,0]
	v_pk_mul_f32 v[78:79], v[78:79], v[174:175] op_sel_hi:[1,0]
	s_mov_b64 vcc, s[10:11]
	v_pk_add_f32 v[88:89], v[88:89], 1.0 op_sel_hi:[1,0]
	v_pk_add_f32 v[86:87], v[86:87], 1.0 op_sel_hi:[1,0]
	v_pk_mul_f32 v[76:77], v[76:77], v[174:175] op_sel_hi:[1,0]
	v_pk_mul_f32 v[74:75], v[74:75], v[174:175] op_sel_hi:[1,0]
	v_pk_mul_f32 v[72:73], v[72:73], v[174:175] op_sel_hi:[1,0]
	v_pk_mul_f32 v[70:71], v[70:71], v[174:175] op_sel_hi:[1,0]
	v_pk_mul_f32 v[68:69], v[68:69], v[174:175] op_sel_hi:[1,0]
	v_pk_mul_f32 v[66:67], v[66:67], v[174:175] op_sel_hi:[1,0]
	v_div_fixup_f32 v174, v173, v175, 1.0
	v_div_fmas_f32 v173, v177, v185, v187
	v_pk_mul_f32 v[78:79], v[2:3], v[78:79]
	v_pk_mul_f32 v[80:81], v[4:5], v[80:81]
	v_pk_mul_f32 v[64:65], v[64:65], v[174:175] op_sel_hi:[1,0]
	v_pk_mul_f32 v[62:63], v[62:63], v[174:175] op_sel_hi:[1,0]
	v_pk_mul_f32 v[60:61], v[60:61], v[174:175] op_sel_hi:[1,0]
	v_pk_mul_f32 v[58:59], v[58:59], v[174:175] op_sel_hi:[1,0]
	v_pk_mul_f32 v[56:57], v[56:57], v[174:175] op_sel_hi:[1,0]
	v_pk_mul_f32 v[54:55], v[54:55], v[174:175] op_sel_hi:[1,0]
	v_pk_mul_f32 v[52:53], v[52:53], v[174:175] op_sel_hi:[1,0]
	v_pk_mul_f32 v[174:175], v[50:51], v[174:175] op_sel_hi:[1,0]
	v_div_fixup_f32 v50, v173, v176, 1.0
	v_pk_fma_f32 v[80:81], v[88:89], v[80:81], v[84:85]
	v_pk_fma_f32 v[78:79], v[86:87], v[78:79], v[82:83]
	v_pk_mul_f32 v[86:87], v[16:17], v[52:53]
	v_pk_mul_f32 v[48:49], v[48:49], v[50:51] op_sel_hi:[1,0]
	v_pk_mul_f32 v[46:47], v[46:47], v[50:51] op_sel_hi:[1,0]
	v_pk_mul_f32 v[82:83], v[10:11], v[54:55]
	v_pk_mul_f32 v[84:85], v[14:15], v[174:175]
	v_pk_mul_f32 v[88:89], v[2:3], v[46:47]
	v_pk_mul_f32 v[174:175], v[4:5], v[48:49]
	v_cvt_pk_bf16_f32 v46, v78, v79
	v_cvt_pk_bf16_f32 v47, v80, v81
	global_store_dwordx2 v[102:103], v[46:47], off
	global_load_dwordx4 v[46:49], v[152:153], off
	s_nop 0
	global_load_dwordx4 v[52:55], v[148:149], off
	v_pk_mul_f32 v[74:75], v[6:7], v[74:75]
	v_pk_mul_f32 v[76:77], v[8:9], v[76:77]
	v_pk_mul_f32 v[70:71], v[10:11], v[70:71]
	v_pk_mul_f32 v[72:73], v[12:13], v[72:73]
	v_pk_mul_f32 v[66:67], v[66:67], v[14:15]
	v_pk_mul_f32 v[68:69], v[68:69], v[16:17]
	v_pk_mul_f32 v[62:63], v[2:3], v[62:63]
	v_pk_mul_f32 v[64:65], v[4:5], v[64:65]
	v_pk_mul_f32 v[58:59], v[6:7], v[58:59]
	v_pk_mul_f32 v[60:61], v[8:9], v[60:61]
	v_pk_mul_f32 v[56:57], v[12:13], v[56:57]
	v_mul_f32_e32 v196, v23, v23
	v_mul_f32_e32 v202, v25, v25
	v_mul_f32_e32 v213, v18, v18
	v_mul_f32_e32 v214, v19, v19
	v_mul_f32_e32 v215, v20, v20
	v_mul_f32_e32 v216, v21, v21
	v_pk_fma_f32 v[158:159], v[22:23], v[22:23], v[196:197] op_sel_hi:[1,1,0]
	v_pk_fma_f32 v[160:161], v[24:25], v[24:25], v[202:203] op_sel_hi:[1,1,0]
	v_mov_b32_e32 v159, v215
	v_mov_b32_e32 v161, v216
	v_lshl_add_u64 v[144:145], s[18:19], 0, v[90:91]
	v_lshl_add_u64 v[128:129], s[16:17], 0, v[90:91]
	v_lshl_add_u64 v[124:125], s[18:19], 0, v[96:97]
	v_lshl_add_u64 v[120:121], s[16:17], 0, v[96:97]
	v_lshl_add_u64 v[92:93], v[92:93], 0, s[12:13]
	v_lshl_add_u64 v[94:95], v[94:95], 0, s[14:15]
	s_mov_b32 s8, s24
	s_cmp_lt_i32 s24, s20
	s_waitcnt vmcnt(0) lgkmcnt(0)
	v_pk_add_f32 v[48:49], v[48:49], 1.0 op_sel_hi:[1,0]
	v_pk_add_f32 v[46:47], v[46:47], 1.0 op_sel_hi:[1,0]
	v_pk_fma_f32 v[48:49], v[48:49], v[76:77], v[54:55]
	v_pk_fma_f32 v[46:47], v[46:47], v[74:75], v[52:53]
	v_cvt_pk_bf16_f32 v46, v46, v47
	v_cvt_pk_bf16_f32 v47, v48, v49
	global_store_dwordx2 v[102:103], v[46:47], off offset:512
	global_load_dwordx4 v[46:49], v[146:147], off
	s_nop 0
	global_load_dwordx4 v[52:55], v[142:143], off
	s_waitcnt vmcnt(0) lgkmcnt(0)
	v_pk_add_f32 v[48:49], v[48:49], 1.0 op_sel_hi:[1,0]
	v_pk_add_f32 v[46:47], v[46:47], 1.0 op_sel_hi:[1,0]
	v_pk_fma_f32 v[48:49], v[72:73], v[48:49], v[54:55]
	v_pk_fma_f32 v[46:47], v[70:71], v[46:47], v[52:53]
	v_cvt_pk_bf16_f32 v46, v46, v47
	v_cvt_pk_bf16_f32 v47, v48, v49
	global_store_dwordx2 v[102:103], v[46:47], off offset:1024
	global_load_dwordx4 v[46:49], v[140:141], off
	s_nop 0
	global_load_dwordx4 v[52:55], v[132:133], off
	s_waitcnt vmcnt(0) lgkmcnt(0)
	v_pk_add_f32 v[48:49], v[48:49], 1.0 op_sel_hi:[1,0]
	v_pk_add_f32 v[46:47], v[46:47], 1.0 op_sel_hi:[1,0]
	v_pk_fma_f32 v[48:49], v[68:69], v[48:49], v[54:55]
	v_pk_fma_f32 v[46:47], v[66:67], v[46:47], v[52:53]
	v_cvt_pk_bf16_f32 v46, v46, v47
	v_cvt_pk_bf16_f32 v47, v48, v49
	global_store_dwordx2 v[102:103], v[46:47], off offset:1536
	global_load_dwordx4 v[46:49], v[136:137], off
	s_nop 0
	global_load_dwordx4 v[52:55], v[134:135], off
	s_waitcnt vmcnt(0) lgkmcnt(0)
	v_pk_add_f32 v[48:49], v[48:49], 1.0 op_sel_hi:[1,0]
	v_pk_add_f32 v[46:47], v[46:47], 1.0 op_sel_hi:[1,0]
	v_pk_fma_f32 v[48:49], v[48:49], v[64:65], v[54:55]
	v_pk_fma_f32 v[46:47], v[46:47], v[62:63], v[52:53]
	v_cvt_pk_bf16_f32 v46, v46, v47
	v_cvt_pk_bf16_f32 v47, v48, v49
	global_store_dwordx2 v[102:103], v[46:47], off offset:2048
	global_load_dwordx4 v[46:49], v[130:131], off
	s_nop 0
	global_load_dwordx4 v[52:55], v[126:127], off
	s_waitcnt vmcnt(0) lgkmcnt(0)
	v_pk_add_f32 v[48:49], v[48:49], 1.0 op_sel_hi:[1,0]
	v_pk_add_f32 v[46:47], v[46:47], 1.0 op_sel_hi:[1,0]
	v_pk_fma_f32 v[48:49], v[48:49], v[60:61], v[54:55]
	v_pk_fma_f32 v[46:47], v[46:47], v[58:59], v[52:53]
	v_cvt_pk_bf16_f32 v46, v46, v47
	v_cvt_pk_bf16_f32 v47, v48, v49
	global_store_dwordx2 v[102:103], v[46:47], off offset:2560
	global_load_dwordx4 v[46:49], v[122:123], off
	s_nop 0
	global_load_dwordx4 v[52:55], v[118:119], off
	v_pk_add_f32 v[58:59], v[164:165], v[164:165] op_sel:[0,1] op_sel_hi:[1,0]
	v_pk_add_f32 v[60:61], v[158:159], v[160:161]
	v_mov_b32_e32 v59, v214
	s_waitcnt vmcnt(0) lgkmcnt(0)
	v_pk_add_f32 v[48:49], v[48:49], 1.0 op_sel_hi:[1,0]
	v_pk_add_f32 v[46:47], v[46:47], 1.0 op_sel_hi:[1,0]
	v_pk_fma_f32 v[48:49], v[48:49], v[56:57], v[54:55]
	v_pk_fma_f32 v[46:47], v[46:47], v[82:83], v[52:53]
	v_cvt_pk_bf16_f32 v46, v46, v47
	v_cvt_pk_bf16_f32 v47, v48, v49
	global_store_dwordx2 v[102:103], v[46:47], off offset:3072
	global_load_dwordx4 v[46:49], v[116:117], off
	s_nop 0
	global_load_dwordx4 v[52:55], v[114:115], off
	v_pk_add_f32 v[56:57], v[162:163], v[162:163] op_sel:[0,1] op_sel_hi:[1,0]
	s_waitcnt vmcnt(0) lgkmcnt(0)
	v_pk_add_f32 v[48:49], v[48:49], 1.0 op_sel_hi:[1,0]
	v_pk_add_f32 v[46:47], v[46:47], 1.0 op_sel_hi:[1,0]
	v_pk_fma_f32 v[48:49], v[86:87], v[48:49], v[54:55]
	v_pk_fma_f32 v[46:47], v[84:85], v[46:47], v[52:53]
	v_cvt_pk_bf16_f32 v46, v46, v47
	v_cvt_pk_bf16_f32 v47, v48, v49
	global_store_dwordx2 v[102:103], v[46:47], off offset:3584
	global_load_dwordx4 v[46:49], v[156:157], off
	s_nop 0
	global_load_dwordx4 v[52:55], v[112:113], off
	v_mov_b32_e32 v57, v213
	s_waitcnt vmcnt(0) lgkmcnt(0)
	v_pk_add_f32 v[48:49], v[48:49], 1.0 op_sel_hi:[1,0]
	v_pk_add_f32 v[46:47], v[46:47], 1.0 op_sel_hi:[1,0]
	v_pk_fma_f32 v[48:49], v[48:49], v[174:175], v[54:55]
	v_pk_fma_f32 v[46:47], v[46:47], v[88:89], v[52:53]
	v_bfe_u32 v51, v46, 16, 1
	v_bfe_u32 v52, v47, 16, 1
	v_add3_u32 v46, v46, v51, s3
	v_add3_u32 v47, v47, v52, s3
	v_lshrrev_b32_e32 v46, 16, v46
	v_and_or_b32 v46, v47, s21, v46
	v_cvt_pk_bf16_f32 v47, v48, v49
	global_store_dwordx2 v[104:105], v[46:47], off
	global_load_dwordx4 v[46:49], v[154:155], off
	s_nop 0
	global_load_dwordx4 v[52:55], v[106:107], off
	v_pk_mul_f32 v[44:45], v[44:45], v[50:51] op_sel_hi:[1,0]
	v_pk_mul_f32 v[42:43], v[42:43], v[50:51] op_sel_hi:[1,0]
	v_pk_mul_f32 v[44:45], v[8:9], v[44:45]
	v_pk_mul_f32 v[42:43], v[6:7], v[42:43]
	s_waitcnt vmcnt(0) lgkmcnt(0)
	v_pk_add_f32 v[48:49], v[48:49], 1.0 op_sel_hi:[1,0]
	v_pk_add_f32 v[46:47], v[46:47], 1.0 op_sel_hi:[1,0]
	v_pk_fma_f32 v[44:45], v[48:49], v[44:45], v[54:55]
	v_pk_fma_f32 v[42:43], v[46:47], v[42:43], v[52:53]
	v_cvt_pk_bf16_f32 v42, v42, v43
	v_cvt_pk_bf16_f32 v43, v44, v45
	global_store_dwordx2 v[104:105], v[42:43], off offset:512
	global_load_dwordx4 v[42:45], v[150:151], off
	s_nop 0
	global_load_dwordx4 v[46:49], v[110:111], off
	v_pk_add_f32 v[52:53], v[56:57], v[58:59]
	s_waitcnt vmcnt(0) lgkmcnt(0)
	v_pk_add_f32 v[44:45], v[44:45], 1.0 op_sel_hi:[1,0]
	v_pk_add_f32 v[52:53], v[52:53], v[60:61]
	v_pk_add_f32 v[42:43], v[42:43], 1.0 op_sel_hi:[1,0]
	v_add_f32_e32 v51, v52, v53
	s_waitcnt lgkmcnt(0)
	s_nop 1
	v_add_f32_dpp v51, v51, v51 quad_perm:[1,0,3,2] row_mask:0xf bank_mask:0xf
	ds_bpermute_b32 v52, v166, v51
	s_waitcnt lgkmcnt(0)
	v_add_f32_e32 v51, v51, v52
	v_pk_mul_f32 v[40:41], v[40:41], v[50:51] op_sel_hi:[1,0]
	v_pk_mul_f32 v[38:39], v[38:39], v[50:51] op_sel_hi:[1,0]
	v_pk_mul_f32 v[40:41], v[12:13], v[40:41]
	v_pk_mul_f32 v[38:39], v[10:11], v[38:39]
	v_pk_fma_f32 v[40:41], v[44:45], v[40:41], v[48:49]
	v_pk_fma_f32 v[38:39], v[42:43], v[38:39], v[46:47]
	v_cvt_pk_bf16_f32 v38, v38, v39
	v_cvt_pk_bf16_f32 v39, v40, v41
	global_store_dwordx2 v[104:105], v[38:39], off offset:1024
	global_load_dwordx4 v[38:41], v[138:139], off
	s_nop 0
	global_load_dwordx4 v[42:45], v[108:109], off
	v_pk_mul_f32 v[36:37], v[36:37], v[50:51] op_sel_hi:[1,0]
	v_pk_mul_f32 v[34:35], v[34:35], v[50:51] op_sel_hi:[1,0]
	v_pk_mul_f32 v[36:37], v[16:17], v[36:37]
	v_pk_mul_f32 v[34:35], v[14:15], v[34:35]
	ds_bpermute_b32 v46, v167, v51
	s_waitcnt lgkmcnt(0)
	v_add_f32_e32 v46, v51, v46
	ds_bpermute_b32 v47, v168, v46
	s_waitcnt lgkmcnt(0)
	v_add_f32_e32 v46, v46, v47
	s_waitcnt lgkmcnt(0)
	v_mov_b32_e32 v47, v46
	s_nop 1
	v_permlane16_swap_b32_e32 v46, v47
	v_add_f32_e32 v46, v46, v47
	s_waitcnt lgkmcnt(0)
	v_mov_b32_e32 v47, v46
	s_nop 1
	v_permlane32_swap_b32_e32 v46, v47
	v_add_f32_e32 v46, v46, v47
	v_fmamk_f32 v46, v46, 0x3a800000, v171
	v_mul_f32_e32 v47, 0x4f800000, v46
	v_cmp_gt_f32_e32 vcc, s2, v46
	s_waitcnt vmcnt(0)
	v_pk_add_f32 v[40:41], v[40:41], 1.0 op_sel_hi:[1,0]
	v_pk_add_f32 v[38:39], v[38:39], 1.0 op_sel_hi:[1,0]
	v_pk_fma_f32 v[36:37], v[36:37], v[40:41], v[44:45]
	v_pk_fma_f32 v[34:35], v[34:35], v[38:39], v[42:43]
	v_cvt_pk_bf16_f32 v34, v34, v35
	v_cvt_pk_bf16_f32 v35, v36, v37
	global_store_dwordx2 v[104:105], v[34:35], off offset:1536
	global_load_dwordx4 v[34:37], v[144:145], off
	s_nop 0
	global_load_dwordx4 v[38:41], v[128:129], off
	v_cndmask_b32_e32 v42, v46, v47, vcc
	v_sqrt_f32_e32 v43, v42
	s_waitcnt vmcnt(0) lgkmcnt(0)
	v_pk_add_f32 v[36:37], v[36:37], 1.0 op_sel_hi:[1,0]
	v_add_u32_e32 v44, -1, v43
	v_add_u32_e32 v45, 1, v43
	v_fma_f32 v46, -v44, v43, v42
	v_fma_f32 v47, -v45, v43, v42
	v_cmp_ge_f32_e64 s[6:7], 0, v46
	v_pk_add_f32 v[34:35], v[34:35], 1.0 op_sel_hi:[1,0]
	s_nop 0
	v_cndmask_b32_e64 v43, v43, v44, s[6:7]
	v_cmp_lt_f32_e64 s[6:7], 0, v47
	s_nop 1
	v_cndmask_b32_e64 v43, v43, v45, s[6:7]
	v_mul_f32_e32 v44, 0x37800000, v43
	v_cndmask_b32_e32 v43, v43, v44, vcc
	v_cmp_class_f32_e32 vcc, v42, v172
	s_nop 1
	v_cndmask_b32_e32 v42, v43, v42, vcc
	v_div_scale_f32 v43, s[6:7], v42, v42, 1.0
	v_rcp_f32_e32 v45, v43
	v_div_scale_f32 v44, vcc, 1.0, v42, 1.0
	v_fma_f32 v46, -v43, v45, 1.0
	v_fmac_f32_e32 v45, v46, v45
	v_mul_f32_e32 v46, v44, v45
	v_fma_f32 v47, -v43, v46, v44
	v_fmac_f32_e32 v46, v47, v45
	v_fma_f32 v43, -v43, v46, v44
	v_div_fmas_f32 v43, v43, v45, v46
	v_div_fixup_f32 v42, v43, v42, 1.0
	v_pk_mul_f32 v[32:33], v[32:33], v[42:43] op_sel_hi:[1,0]
	v_pk_mul_f32 v[30:31], v[30:31], v[42:43] op_sel_hi:[1,0]
	v_pk_mul_f32 v[32:33], v[4:5], v[32:33]
	v_pk_mul_f32 v[30:31], v[2:3], v[30:31]
	v_pk_fma_f32 v[32:33], v[36:37], v[32:33], v[40:41]
	v_pk_fma_f32 v[30:31], v[34:35], v[30:31], v[38:39]
	v_cvt_pk_bf16_f32 v30, v30, v31
	v_cvt_pk_bf16_f32 v31, v32, v33
	global_store_dwordx2 v[104:105], v[30:31], off offset:2048
	global_load_dwordx4 v[30:33], v[124:125], off
	s_nop 0
	global_load_dwordx4 v[34:37], v[120:121], off
	v_pk_mul_f32 v[28:29], v[28:29], v[42:43] op_sel_hi:[1,0]
	v_pk_mul_f32 v[26:27], v[26:27], v[42:43] op_sel_hi:[1,0]
	v_pk_mul_f32 v[28:29], v[8:9], v[28:29]
	v_pk_mul_f32 v[26:27], v[6:7], v[26:27]
	v_lshl_add_u64 v[40:41], s[18:19], 0, v[98:99]
	v_lshl_add_u64 v[38:39], s[16:17], 0, v[98:99]
	v_pk_mul_f32 v[24:25], v[24:25], v[42:43] op_sel_hi:[1,0]
	v_pk_mul_f32 v[22:23], v[22:23], v[42:43] op_sel_hi:[1,0]
	v_pk_mul_f32 v[24:25], v[12:13], v[24:25]
	v_pk_mul_f32 v[22:23], v[10:11], v[22:23]
	v_pk_mul_f32 v[20:21], v[20:21], v[42:43] op_sel_hi:[1,0]
	v_pk_mul_f32 v[18:19], v[18:19], v[42:43] op_sel_hi:[1,0]
	v_pk_mul_f32 v[20:21], v[16:17], v[20:21]
	v_pk_mul_f32 v[18:19], v[14:15], v[18:19]
	s_waitcnt vmcnt(0) lgkmcnt(0)
	v_pk_add_f32 v[32:33], v[32:33], 1.0 op_sel_hi:[1,0]
	v_pk_add_f32 v[30:31], v[30:31], 1.0 op_sel_hi:[1,0]
	v_pk_fma_f32 v[28:29], v[32:33], v[28:29], v[36:37]
	v_pk_fma_f32 v[26:27], v[30:31], v[26:27], v[34:35]
	v_cvt_pk_bf16_f32 v26, v26, v27
	v_cvt_pk_bf16_f32 v27, v28, v29
	global_store_dwordx2 v[104:105], v[26:27], off offset:2560
	global_load_dwordx4 v[26:29], v[40:41], off
	s_nop 0
	global_load_dwordx4 v[30:33], v[38:39], off
	v_lshl_add_u64 v[36:37], s[18:19], 0, v[100:101]
	v_lshl_add_u64 v[34:35], s[16:17], 0, v[100:101]
	s_waitcnt vmcnt(0) lgkmcnt(0)
	v_pk_add_f32 v[28:29], v[28:29], 1.0 op_sel_hi:[1,0]
	v_pk_add_f32 v[26:27], v[26:27], 1.0 op_sel_hi:[1,0]
	v_pk_fma_f32 v[24:25], v[28:29], v[24:25], v[32:33]
	v_pk_fma_f32 v[22:23], v[26:27], v[22:23], v[30:31]
	v_cvt_pk_bf16_f32 v22, v22, v23
	v_cvt_pk_bf16_f32 v23, v24, v25
	global_store_dwordx2 v[104:105], v[22:23], off offset:3072
	global_load_dwordx4 v[22:25], v[36:37], off
	s_nop 0
	global_load_dwordx4 v[26:29], v[34:35], off
	s_waitcnt vmcnt(0) lgkmcnt(0)
	v_pk_add_f32 v[24:25], v[24:25], 1.0 op_sel_hi:[1,0]
	v_pk_add_f32 v[22:23], v[22:23], 1.0 op_sel_hi:[1,0]
	v_pk_fma_f32 v[20:21], v[20:21], v[24:25], v[28:29]
	v_pk_fma_f32 v[18:19], v[18:19], v[22:23], v[26:27]
	v_cvt_pk_bf16_f32 v18, v18, v19
	v_cvt_pk_bf16_f32 v19, v20, v21
	global_store_dwordx2 v[104:105], v[18:19], off offset:3584
	s_cbranch_scc1 .LBB0_5693

.LBB0_5801:
	v_lshl_add_u64 v[18:19], v[84:85], 0, s[24:25]
	v_add_co_u32_e32 v20, vcc, 0x7800000, v18
	s_add_u32 s6, s38, s24
	s_nop 0
	v_addc_co_u32_e32 v21, vcc, 0, v19, vcc
	v_add_co_u32_e32 v22, vcc, 0x7801000, v18
	global_load_dwordx4 v[78:81], v[20:21], off
	global_load_dwordx4 v[70:73], v[20:21], off offset:1024
	global_load_dwordx4 v[66:69], v[20:21], off offset:3072
	global_load_dwordx4 v[74:77], v[20:21], off offset:2048
	v_addc_co_u32_e32 v23, vcc, 0, v19, vcc
	v_add_co_u32_e32 v20, vcc, 0x7802000, v18
	global_load_dwordx4 v[62:65], v[22:23], off
	global_load_dwordx4 v[54:57], v[22:23], off offset:1024
	global_load_dwordx4 v[50:53], v[22:23], off offset:3072
	global_load_dwordx4 v[58:61], v[22:23], off offset:2048
	v_addc_co_u32_e32 v21, vcc, 0, v19, vcc
	v_add_co_u32_e32 v86, vcc, 0x7803000, v18
	global_load_dwordx4 v[46:49], v[20:21], off
	global_load_dwordx4 v[42:45], v[20:21], off offset:1024
	global_load_dwordx4 v[38:41], v[20:21], off offset:2048
	global_load_dwordx4 v[34:37], v[20:21], off offset:3072
	v_addc_co_u32_e32 v87, vcc, 0, v19, vcc
	global_load_dwordx4 v[30:33], v[86:87], off
	global_load_dwordx4 v[26:29], v[86:87], off offset:1024
	global_load_dwordx4 v[22:25], v[86:87], off offset:2048
	global_load_dwordx4 v[18:21], v[86:87], off offset:3072
	s_addc_u32 s7, s39, s25
	s_add_i32 s22, s20, 0xffffc000
	s_lshl_b64 s[8:9], s[22:23], 12
	s_add_u32 s8, s28, s8
	s_addc_u32 s9, s29, s9
	s_cmpk_lt_i32 s20, 0x4000
	s_cselect_b32 s9, s7, s9
	s_cselect_b32 s8, s6, s8
	s_add_u32 s10, s6, 0x1000
	s_addc_u32 s11, s7, 0
	s_add_i32 s22, s20, 0xffffc001
	v_lshl_add_u64 v[92:93], s[8:9], 0, v[82:83]
	s_lshl_b64 s[8:9], s[22:23], 12
	s_add_u32 s8, s28, s8
	s_addc_u32 s9, s29, s9
	s_cmpk_lt_i32 s20, 0x3fff
	s_cselect_b32 s9, s11, s9
	s_cselect_b32 s8, s10, s8
	s_add_u32 s10, s6, 0x2000
	s_addc_u32 s11, s7, 0
	s_add_i32 s22, s20, 0xffffc002
	v_lshl_add_u64 v[90:91], s[8:9], 0, v[82:83]
	s_lshl_b64 s[8:9], s[22:23], 12
	s_add_u32 s8, s28, s8
	s_addc_u32 s9, s29, s9
	s_cmpk_lt_i32 s20, 0x3ffe
	s_cselect_b32 s9, s11, s9
	s_cselect_b32 s8, s10, s8
	s_add_u32 s10, s6, 0x3000
	v_lshl_add_u64 v[88:89], s[8:9], 0, v[82:83]
	s_addc_u32 s8, s7, 0
	s_add_i32 s22, s20, 0xffffc003
	s_lshl_b64 s[6:7], s[22:23], 12
	s_add_u32 s6, s28, s6
	s_addc_u32 s7, s29, s7
	s_cmpk_lt_i32 s20, 0x3ffd
	s_cselect_b32 s7, s8, s7
	s_cselect_b32 s6, s10, s6
	v_lshl_add_u64 v[86:87], s[6:7], 0, v[82:83]
	s_add_i32 s20, s20, 32
	s_add_u32 s38, s38, 0x20000
	s_addc_u32 s39, s39, 0
	v_lshl_add_u64 v[84:85], v[84:85], 0, s[26:27]
	s_cmp_lt_i32 s20, s5
	s_waitcnt vmcnt(0) lgkmcnt(0)
	v_pk_mul_f32 v[102:103], v[80:81], v[80:81]
	v_pk_mul_f32 v[104:105], v[78:79], v[78:79]
	v_pk_mul_f32 v[106:107], v[72:73], v[72:73]
	v_pk_mul_f32 v[108:109], v[70:71], v[70:71]
	v_mul_f32_e32 v110, v75, v75
	v_mul_f32_e32 v112, v77, v77
	v_pk_mov_b32 v[114:115], v[104:105], v[102:103] op_sel:[1,0]
	v_mov_b32_e32 v105, v103
	v_pk_mov_b32 v[102:103], v[108:109], v[106:107] op_sel:[1,0]
	v_mov_b32_e32 v109, v107
	v_mul_f32_e32 v123, v68, v68
	v_mul_f32_e32 v125, v69, v69
	v_pk_fma_f32 v[106:107], v[74:75], v[74:75], v[110:111] op_sel_hi:[1,1,0]
	v_pk_fma_f32 v[110:111], v[76:77], v[76:77], v[112:113] op_sel_hi:[1,1,0]
	v_pk_mul_f32 v[112:113], v[64:65], v[64:65]
	v_pk_mul_f32 v[116:117], v[62:63], v[62:63]
	v_pk_mul_f32 v[118:119], v[56:57], v[56:57]
	v_pk_mul_f32 v[120:121], v[54:55], v[54:55]
	v_mul_f32_e32 v122, v59, v59
	v_mul_f32_e32 v124, v61, v61
	v_pk_add_f32 v[104:105], v[114:115], v[104:105]
	v_pk_add_f32 v[102:103], v[102:103], v[108:109]
	v_mul_f32_e32 v101, v66, v66
	v_mul_f32_e32 v137, v67, v67
	v_mul_f32_e32 v131, v52, v52
	v_mul_f32_e32 v133, v53, v53
	v_mov_b32_e32 v107, v123
	v_mov_b32_e32 v111, v125
	v_pk_mov_b32 v[108:109], v[116:117], v[112:113] op_sel:[1,0]
	v_mov_b32_e32 v117, v113
	v_pk_mov_b32 v[112:113], v[120:121], v[118:119] op_sel:[1,0]
	v_mov_b32_e32 v121, v119
	v_pk_fma_f32 v[114:115], v[58:59], v[58:59], v[122:123] op_sel_hi:[1,1,0]
	v_pk_fma_f32 v[118:119], v[60:61], v[60:61], v[124:125] op_sel_hi:[1,1,0]
	v_pk_mul_f32 v[122:123], v[48:49], v[48:49]
	v_pk_mul_f32 v[124:125], v[46:47], v[46:47]
	v_pk_mul_f32 v[126:127], v[44:45], v[44:45]
	v_pk_mul_f32 v[128:129], v[42:43], v[42:43]
	v_mul_f32_e32 v130, v39, v39
	v_mul_f32_e32 v132, v41, v41
	v_pk_add_f32 v[104:105], v[104:105], v[104:105] op_sel:[0,1] op_sel_hi:[1,0]
	v_pk_add_f32 v[102:103], v[102:103], v[102:103] op_sel:[0,1] op_sel_hi:[1,0]
	v_mul_f32_e32 v143, v36, v36
	v_mul_f32_e32 v144, v37, v37
	v_pk_add_f32 v[106:107], v[106:107], v[110:111]
	v_pk_add_f32 v[108:109], v[108:109], v[116:117]
	v_pk_add_f32 v[110:111], v[112:113], v[120:121]
	v_mov_b32_e32 v115, v131
	v_mov_b32_e32 v119, v133
	v_pk_mov_b32 v[112:113], v[124:125], v[122:123] op_sel:[1,0]
	v_mov_b32_e32 v125, v123
	v_pk_mov_b32 v[116:117], v[128:129], v[126:127] op_sel:[1,0]
	v_mov_b32_e32 v129, v127
	v_pk_fma_f32 v[120:121], v[38:39], v[38:39], v[130:131] op_sel_hi:[1,1,0]
	v_pk_fma_f32 v[122:123], v[40:41], v[40:41], v[132:133] op_sel_hi:[1,1,0]
	v_pk_mul_f32 v[126:127], v[32:33], v[32:33]
	v_pk_mul_f32 v[130:131], v[30:31], v[30:31]
	v_pk_mul_f32 v[132:133], v[28:29], v[28:29]
	v_pk_mul_f32 v[134:135], v[26:27], v[26:27]
	v_mov_b32_e32 v105, v101
	v_mov_b32_e32 v103, v137
	v_mul_f32_e32 v139, v50, v50
	v_mul_f32_e32 v140, v51, v51
	v_pk_add_f32 v[108:109], v[108:109], v[108:109] op_sel:[0,1] op_sel_hi:[1,0]
	v_pk_add_f32 v[110:111], v[110:111], v[110:111] op_sel:[0,1] op_sel_hi:[1,0]
	v_pk_add_f32 v[114:115], v[114:115], v[118:119]
	v_pk_add_f32 v[112:113], v[112:113], v[124:125]
	v_pk_add_f32 v[116:117], v[116:117], v[128:129]
	v_mov_b32_e32 v121, v143
	v_mov_b32_e32 v123, v144
	v_pk_mov_b32 v[118:119], v[130:131], v[126:127] op_sel:[1,0]
	v_mov_b32_e32 v131, v127
	v_pk_mov_b32 v[124:125], v[134:135], v[132:133] op_sel:[1,0]
	v_mov_b32_e32 v135, v133
	v_pk_add_f32 v[102:103], v[104:105], v[102:103]
	v_mul_f32_e32 v141, v34, v34
	v_mul_f32_e32 v142, v35, v35
	v_mul_f32_e32 v136, v23, v23
	v_mul_f32_e32 v138, v25, v25
	v_mov_b32_e32 v109, v139
	v_mov_b32_e32 v111, v140
	v_pk_add_f32 v[104:105], v[112:113], v[112:113] op_sel:[0,1] op_sel_hi:[1,0]
	v_pk_add_f32 v[112:113], v[116:117], v[116:117] op_sel:[0,1] op_sel_hi:[1,0]
	v_pk_add_f32 v[116:117], v[120:121], v[122:123]
	v_pk_add_f32 v[118:119], v[118:119], v[130:131]
	v_pk_add_f32 v[120:121], v[124:125], v[134:135]
	v_pk_add_f32 v[102:103], v[102:103], v[106:107]
	v_mul_f32_e32 v145, v18, v18
	v_mul_f32_e32 v146, v19, v19
	v_mul_f32_e32 v147, v20, v20
	v_mul_f32_e32 v148, v21, v21
	v_pk_fma_f32 v[126:127], v[22:23], v[22:23], v[136:137] op_sel_hi:[1,1,0]
	v_pk_fma_f32 v[128:129], v[24:25], v[24:25], v[138:139] op_sel_hi:[1,1,0]
	v_pk_add_f32 v[106:107], v[108:109], v[110:111]
	v_mov_b32_e32 v105, v141
	v_mov_b32_e32 v113, v142
	v_pk_add_f32 v[108:109], v[118:119], v[118:119] op_sel:[0,1] op_sel_hi:[1,0]
	v_pk_add_f32 v[110:111], v[120:121], v[120:121] op_sel:[0,1] op_sel_hi:[1,0]
	v_add_f32_e32 v101, v102, v103
	v_mov_b32_e32 v127, v147
	v_mov_b32_e32 v129, v148
	v_pk_add_f32 v[102:103], v[106:107], v[114:115]
	v_pk_add_f32 v[104:105], v[104:105], v[112:113]
	v_mov_b32_e32 v109, v145
	v_mov_b32_e32 v111, v146
	ds_bpermute_b32 v107, v1, v101
	v_pk_add_f32 v[118:119], v[126:127], v[128:129]
	v_add_f32_e32 v106, v102, v103
	v_pk_add_f32 v[102:103], v[104:105], v[116:117]
	v_pk_add_f32 v[104:105], v[108:109], v[110:111]
	v_add_f32_e32 v108, v102, v103
	v_pk_add_f32 v[102:103], v[104:105], v[118:119]
	v_add_f32_e32 v102, v102, v103
	s_waitcnt lgkmcnt(0)
	v_add_f32_e32 v101, v101, v107
	s_waitcnt lgkmcnt(0)
	s_nop 1
	v_add_f32_dpp v104, v106, v106 quad_perm:[1,0,3,2] row_mask:0xf bank_mask:0xf
	s_waitcnt lgkmcnt(0)
	s_nop 1
	v_add_f32_dpp v103, v108, v108 quad_perm:[1,0,3,2] row_mask:0xf bank_mask:0xf
	s_waitcnt lgkmcnt(2)
	s_nop 1
	v_add_f32_dpp v102, v102, v102 quad_perm:[1,0,3,2] row_mask:0xf bank_mask:0xf
	s_waitcnt lgkmcnt(0)
	s_nop 1
	v_add_f32_dpp v101, v101, v101 quad_perm:[2,3,0,1] row_mask:0xf bank_mask:0xf
	ds_bpermute_b32 v107, v95, v101
	s_waitcnt lgkmcnt(3)
	s_nop 1
	v_add_f32_dpp v104, v104, v104 quad_perm:[2,3,0,1] row_mask:0xf bank_mask:0xf
	s_waitcnt lgkmcnt(0)
	s_nop 1
	v_add_f32_dpp v103, v103, v103 quad_perm:[2,3,0,1] row_mask:0xf bank_mask:0xf
	s_waitcnt lgkmcnt(2)
	s_nop 1
	v_add_f32_dpp v102, v102, v102 quad_perm:[2,3,0,1] row_mask:0xf bank_mask:0xf
	s_waitcnt lgkmcnt(0)
	v_add_f32_e32 v101, v101, v107
	ds_bpermute_b32 v107, v96, v101
	s_waitcnt lgkmcnt(3)
	s_nop 1
	v_add_f32_dpp v104, v104, v104 row_half_mirror row_mask:0xf bank_mask:0xf
	s_waitcnt lgkmcnt(0)
	s_nop 1
	v_add_f32_dpp v103, v103, v103 row_half_mirror row_mask:0xf bank_mask:0xf
	s_waitcnt lgkmcnt(2)
	s_nop 1
	v_add_f32_dpp v102, v102, v102 row_half_mirror row_mask:0xf bank_mask:0xf
	s_waitcnt lgkmcnt(0)
	v_add_f32_e32 v101, v101, v107
	ds_bpermute_b32 v107, v97, v101
	s_waitcnt lgkmcnt(3)
	s_nop 1
	v_add_f32_dpp v104, v104, v104 row_mirror row_mask:0xf bank_mask:0xf
	ds_bpermute_b32 v106, v97, v104
	s_waitcnt lgkmcnt(3)
	s_nop 1
	v_add_f32_dpp v103, v103, v103 row_mirror row_mask:0xf bank_mask:0xf
	s_waitcnt lgkmcnt(2)
	s_nop 1
	v_add_f32_dpp v102, v102, v102 row_mirror row_mask:0xf bank_mask:0xf
	s_waitcnt lgkmcnt(0)
	v_add_f32_e32 v101, v101, v107
	s_waitcnt lgkmcnt(0)
	v_add_f32_e32 v104, v104, v106
	s_waitcnt lgkmcnt(0)
	v_mov_b32_e32 v108, v103
	s_nop 1
	v_permlane16_swap_b32_e32 v103, v108
	v_add_f32_e32 v103, v103, v108
	s_waitcnt lgkmcnt(2)
	v_mov_b32_e32 v105, v102
	s_nop 1
	v_permlane16_swap_b32_e32 v102, v105
	v_add_f32_e32 v102, v102, v105
	ds_bpermute_b32 v105, v98, v102
	s_waitcnt lgkmcnt(0)
	v_mov_b32_e32 v107, v101
	s_nop 1
	v_permlane32_swap_b32_e32 v101, v107
	v_add_f32_e32 v101, v101, v107
	v_fmamk_f32 v101, v101, 0x3a800000, v99
	s_waitcnt lgkmcnt(2)
	v_mov_b32_e32 v106, v104
	s_nop 1
	v_permlane32_swap_b32_e32 v104, v106
	v_add_f32_e32 v104, v104, v106
	v_mul_f32_e32 v106, 0x4f800000, v101
	v_cmp_gt_f32_e32 vcc, s21, v101
	v_fmamk_f32 v104, v104, 0x3a800000, v99
	s_waitcnt lgkmcnt(1)
	v_mov_b32_e32 v108, v103
	s_nop 1
	v_permlane32_swap_b32_e32 v103, v108
	v_add_f32_e32 v103, v103, v108
	v_cndmask_b32_e32 v101, v101, v106, vcc
	v_mul_f32_e32 v106, 0x4f800000, v104
	v_cmp_gt_f32_e64 s[6:7], s21, v104
	s_waitcnt lgkmcnt(0)
	v_add_f32_e32 v102, v102, v105
	v_sqrt_f32_e32 v105, v101
	v_fmamk_f32 v103, v103, 0x3a800000, v99
	v_cndmask_b32_e64 v104, v104, v106, s[6:7]
	v_mul_f32_e32 v106, 0x4f800000, v103
	v_cmp_gt_f32_e64 s[8:9], s21, v103
	v_fmamk_f32 v102, v102, 0x3a800000, v99
	v_sqrt_f32_e32 v107, v104
	v_cndmask_b32_e64 v103, v103, v106, s[8:9]
	v_mul_f32_e32 v106, 0x4f800000, v102
	v_cmp_gt_f32_e64 s[10:11], s21, v102
	v_sqrt_f32_e32 v108, v103
	v_add_u32_e32 v109, -1, v105
	v_cndmask_b32_e64 v102, v102, v106, s[10:11]
	v_sqrt_f32_e32 v106, v102
	v_add_u32_e32 v110, 1, v105
	v_fma_f32 v111, -v109, v105, v101
	v_fma_f32 v112, -v110, v105, v101
	v_add_u32_e32 v113, -1, v107
	v_cmp_ge_f32_e64 s[12:13], 0, v111
	v_add_u32_e32 v114, 1, v107
	v_fma_f32 v111, -v114, v107, v104
	v_cndmask_b32_e64 v105, v105, v109, s[12:13]
	v_fma_f32 v109, -v113, v107, v104
	v_cmp_lt_f32_e64 s[12:13], 0, v112
	v_add_u32_e32 v115, -1, v108
	v_add_u32_e32 v116, 1, v108
	v_cndmask_b32_e64 v105, v105, v110, s[12:13]
	v_cmp_ge_f32_e64 s[12:13], 0, v109
	v_fma_f32 v109, -v115, v108, v103
	v_fma_f32 v110, -v116, v108, v103
	v_cndmask_b32_e64 v107, v107, v113, s[12:13]
	v_cmp_lt_f32_e64 s[12:13], 0, v111
	v_add_u32_e32 v111, -1, v106
	v_add_u32_e32 v112, 1, v106
	v_mul_f32_e32 v113, 0x37800000, v105
	v_cndmask_b32_e64 v107, v107, v114, s[12:13]
	v_cmp_ge_f32_e64 s[12:13], 0, v109
	v_fma_f32 v109, -v111, v106, v102
	v_cndmask_b32_e32 v105, v105, v113, vcc
	v_cndmask_b32_e64 v108, v108, v115, s[12:13]
	v_cmp_lt_f32_e64 s[12:13], 0, v110
	v_fma_f32 v110, -v112, v106, v102
	v_cmp_ge_f32_e32 vcc, 0, v109
	v_mul_f32_e32 v113, 0x37800000, v107
	v_cndmask_b32_e64 v108, v108, v116, s[12:13]
	v_cndmask_b32_e32 v106, v106, v111, vcc
	v_cmp_lt_f32_e32 vcc, 0, v110
	v_cmp_class_f32_e64 s[12:13], v101, v100
	s_nop 0
	v_cndmask_b32_e32 v106, v106, v112, vcc
	v_cndmask_b32_e64 v101, v105, v101, s[12:13]
	v_cndmask_b32_e64 v105, v107, v113, s[6:7]
	v_cmp_class_f32_e64 s[6:7], v104, v100
	v_mul_f32_e32 v107, 0x37800000, v108
	v_div_scale_f32 v109, s[12:13], v101, v101, 1.0
	v_cndmask_b32_e64 v111, v105, v104, s[6:7]
	v_cndmask_b32_e64 v104, v108, v107, s[8:9]
	v_cmp_class_f32_e64 s[6:7], v103, v100
	v_mul_f32_e32 v105, 0x37800000, v106
	v_rcp_f32_e32 v107, v109
	v_div_scale_f32 v108, s[8:9], v111, v111, 1.0
	v_cndmask_b32_e64 v113, v104, v103, s[6:7]
	v_cndmask_b32_e64 v103, v106, v105, s[10:11]
	v_cmp_class_f32_e64 s[6:7], v102, v100
	v_rcp_f32_e32 v104, v108
	v_div_scale_f32 v105, s[10:11], v113, v113, 1.0
	v_cndmask_b32_e64 v114, v103, v102, s[6:7]
	v_rcp_f32_e32 v115, v105
	v_div_scale_f32 v116, s[6:7], v114, v114, 1.0
	v_rcp_f32_e32 v118, v116
	v_fma_f32 v102, -v109, v107, 1.0
	v_div_scale_f32 v110, vcc, 1.0, v101, 1.0
	v_fmac_f32_e32 v107, v102, v107
	v_fma_f32 v102, -v108, v104, 1.0
	v_div_scale_f32 v112, s[8:9], 1.0, v111, 1.0
	v_mul_f32_e32 v103, v110, v107
	v_fmac_f32_e32 v104, v102, v104
	v_fma_f32 v102, -v105, v115, 1.0
	v_div_scale_f32 v106, s[10:11], 1.0, v113, 1.0
	v_fma_f32 v119, -v109, v103, v110
	v_mul_f32_e32 v120, v112, v104
	v_fmac_f32_e32 v115, v102, v115
	v_fma_f32 v102, -v116, v118, 1.0
	v_div_scale_f32 v117, s[6:7], 1.0, v114, 1.0
	v_fmac_f32_e32 v103, v119, v107
	v_fma_f32 v119, -v108, v120, v112
	v_mul_f32_e32 v121, v106, v115
	v_fmac_f32_e32 v118, v102, v118
	v_fma_f32 v102, -v109, v103, v110
	v_fmac_f32_e32 v120, v119, v104
	v_fma_f32 v109, -v105, v121, v106
	v_mul_f32_e32 v110, v117, v118
	v_div_fmas_f32 v102, v102, v107, v103
	v_fma_f32 v103, -v108, v120, v112
	v_fmac_f32_e32 v121, v109, v115
	v_fma_f32 v107, -v116, v110, v117
	s_mov_b64 vcc, s[8:9]
	v_div_fixup_f32 v102, v102, v101, 1.0
	v_div_fmas_f32 v101, v103, v104, v120
	v_fma_f32 v108, -v105, v121, v106
	v_fmac_f32_e32 v110, v107, v118
	s_mov_b64 vcc, s[10:11]
	v_pk_mul_f32 v[78:79], v[78:79], v[102:103] op_sel_hi:[1,0]
	v_pk_mul_f32 v[80:81], v[80:81], v[102:103] op_sel_hi:[1,0]
	v_pk_mul_f32 v[70:71], v[70:71], v[102:103] op_sel_hi:[1,0]
	v_pk_mul_f32 v[72:73], v[72:73], v[102:103] op_sel_hi:[1,0]
	v_pk_mul_f32 v[74:75], v[74:75], v[102:103] op_sel_hi:[1,0]
	v_pk_mul_f32 v[76:77], v[76:77], v[102:103] op_sel_hi:[1,0]
	v_pk_mul_f32 v[104:105], v[66:67], v[102:103] op_sel_hi:[1,0]
	v_pk_mul_f32 v[102:103], v[68:69], v[102:103] op_sel_hi:[1,0]
	v_div_fixup_f32 v106, v101, v111, 1.0
	v_div_fmas_f32 v101, v108, v115, v121
	v_fma_f32 v107, -v116, v110, v117
	s_mov_b64 vcc, s[6:7]
	v_pk_mul_f32 v[68:69], v[80:81], v[4:5]
	v_pk_mul_f32 v[66:67], v[78:79], v[2:3]
	v_pk_mul_f32 v[74:75], v[74:75], v[10:11]
	v_pk_mul_f32 v[80:81], v[102:103], v[16:17]
	v_pk_mul_f32 v[78:79], v[104:105], v[14:15]
	v_pk_mul_f32 v[62:63], v[62:63], v[106:107] op_sel_hi:[1,0]
	v_pk_mul_f32 v[64:65], v[64:65], v[106:107] op_sel_hi:[1,0]
	v_pk_mul_f32 v[54:55], v[54:55], v[106:107] op_sel_hi:[1,0]
	v_pk_mul_f32 v[56:57], v[56:57], v[106:107] op_sel_hi:[1,0]
	v_pk_mul_f32 v[58:59], v[58:59], v[106:107] op_sel_hi:[1,0]
	v_pk_mul_f32 v[60:61], v[60:61], v[106:107] op_sel_hi:[1,0]
	v_pk_mul_f32 v[102:103], v[50:51], v[106:107] op_sel_hi:[1,0]
	v_pk_mul_f32 v[104:105], v[52:53], v[106:107] op_sel_hi:[1,0]
	v_div_fixup_f32 v106, v101, v113, 1.0
	v_div_fmas_f32 v101, v107, v118, v110
	v_pk_mul_f32 v[72:73], v[72:73], v[8:9]
	v_pk_mul_f32 v[70:71], v[70:71], v[6:7]
	v_pk_mul_f32 v[76:77], v[76:77], v[12:13]
	global_store_dwordx4 v[92:93], v[66:69], off
	global_store_dwordx4 v[92:93], v[70:73], off offset:1024
	global_store_dwordx4 v[92:93], v[74:77], off offset:2048
	global_store_dwordx4 v[92:93], v[78:81], off offset:3072
	v_pk_mul_f32 v[52:53], v[64:65], v[4:5]
	v_div_fixup_f32 v74, v101, v114, 1.0
	v_pk_mul_f32 v[50:51], v[62:63], v[2:3]
	v_pk_mul_f32 v[56:57], v[56:57], v[8:9]
	v_pk_mul_f32 v[54:55], v[54:55], v[6:7]
	v_pk_mul_f32 v[46:47], v[46:47], v[106:107] op_sel_hi:[1,0]
	v_pk_mul_f32 v[48:49], v[48:49], v[106:107] op_sel_hi:[1,0]
	v_pk_mul_f32 v[30:31], v[30:31], v[74:75] op_sel_hi:[1,0]
	v_pk_mul_f32 v[32:33], v[32:33], v[74:75] op_sel_hi:[1,0]
	v_pk_mul_f32 v[60:61], v[60:61], v[12:13]
	v_pk_mul_f32 v[58:59], v[58:59], v[10:11]
	v_pk_mul_f32 v[64:65], v[104:105], v[16:17]
	v_pk_mul_f32 v[62:63], v[102:103], v[14:15]
	v_pk_mul_f32 v[42:43], v[42:43], v[106:107] op_sel_hi:[1,0]
	v_pk_mul_f32 v[44:45], v[44:45], v[106:107] op_sel_hi:[1,0]
	v_pk_mul_f32 v[66:67], v[38:39], v[106:107] op_sel_hi:[1,0]
	v_pk_mul_f32 v[68:69], v[40:41], v[106:107] op_sel_hi:[1,0]
	v_pk_mul_f32 v[70:71], v[34:35], v[106:107] op_sel_hi:[1,0]
	v_pk_mul_f32 v[72:73], v[36:37], v[106:107] op_sel_hi:[1,0]
	global_store_dwordx4 v[90:91], v[50:53], off
	global_store_dwordx4 v[90:91], v[54:57], off offset:1024
	global_store_dwordx4 v[90:91], v[58:61], off offset:2048
	global_store_dwordx4 v[90:91], v[62:65], off offset:3072
	v_pk_mul_f32 v[36:37], v[48:49], v[4:5]
	v_pk_mul_f32 v[34:35], v[46:47], v[2:3]
	v_pk_mul_f32 v[26:27], v[26:27], v[74:75] op_sel_hi:[1,0]
	v_pk_mul_f32 v[28:29], v[28:29], v[74:75] op_sel_hi:[1,0]
	v_pk_mul_f32 v[50:51], v[22:23], v[74:75] op_sel_hi:[1,0]
	v_pk_mul_f32 v[52:53], v[24:25], v[74:75] op_sel_hi:[1,0]
	v_pk_mul_f32 v[54:55], v[18:19], v[74:75] op_sel_hi:[1,0]
	v_pk_mul_f32 v[56:57], v[20:21], v[74:75] op_sel_hi:[1,0]
	v_pk_mul_f32 v[20:21], v[32:33], v[4:5]
	v_pk_mul_f32 v[18:19], v[30:31], v[2:3]
	v_pk_mul_f32 v[40:41], v[44:45], v[8:9]
	v_pk_mul_f32 v[38:39], v[42:43], v[6:7]
	v_pk_mul_f32 v[44:45], v[68:69], v[12:13]
	v_pk_mul_f32 v[42:43], v[66:67], v[10:11]
	v_pk_mul_f32 v[48:49], v[72:73], v[16:17]
	v_pk_mul_f32 v[46:47], v[70:71], v[14:15]
	global_store_dwordx4 v[88:89], v[34:37], off
	global_store_dwordx4 v[88:89], v[38:41], off offset:1024
	global_store_dwordx4 v[88:89], v[42:45], off offset:2048
	global_store_dwordx4 v[88:89], v[46:49], off offset:3072
	v_pk_mul_f32 v[24:25], v[28:29], v[8:9]
	v_pk_mul_f32 v[22:23], v[26:27], v[6:7]
	v_pk_mul_f32 v[28:29], v[52:53], v[12:13]
	v_pk_mul_f32 v[26:27], v[50:51], v[10:11]
	v_pk_mul_f32 v[32:33], v[56:57], v[16:17]
	v_pk_mul_f32 v[30:31], v[54:55], v[14:15]
	global_store_dwordx4 v[86:87], v[18:21], off
	global_store_dwordx4 v[86:87], v[22:25], off offset:1024
	global_store_dwordx4 v[86:87], v[26:29], off offset:2048
	global_store_dwordx4 v[86:87], v[30:33], off offset:3072
	s_cbranch_scc1 .LBB0_5801

.LBB0_5948:
	v_lshl_add_u64 v[16:17], v[82:83], 0, s[10:11]
	v_add_co_u32_e32 v18, vcc, 0x7800000, v16
	s_add_i32 s0, s17, 32
	s_nop 0
	v_addc_co_u32_e32 v19, vcc, 0, v17, vcc
	v_add_co_u32_e32 v20, vcc, 0x7801000, v16
	global_load_dwordx4 v[76:79], v[18:19], off
	global_load_dwordx4 v[68:71], v[18:19], off offset:1024
	global_load_dwordx4 v[64:67], v[18:19], off offset:3072
	global_load_dwordx4 v[72:75], v[18:19], off offset:2048
	v_addc_co_u32_e32 v21, vcc, 0, v17, vcc
	v_add_co_u32_e32 v18, vcc, 0x7802000, v16
	global_load_dwordx4 v[60:63], v[20:21], off
	global_load_dwordx4 v[52:55], v[20:21], off offset:1024
	global_load_dwordx4 v[48:51], v[20:21], off offset:3072
	global_load_dwordx4 v[56:59], v[20:21], off offset:2048
	v_addc_co_u32_e32 v19, vcc, 0, v17, vcc
	v_add_co_u32_e32 v84, vcc, 0x7803000, v16
	global_load_dwordx4 v[44:47], v[18:19], off
	global_load_dwordx4 v[40:43], v[18:19], off offset:1024
	global_load_dwordx4 v[36:39], v[18:19], off offset:2048
	global_load_dwordx4 v[32:35], v[18:19], off offset:3072
	v_addc_co_u32_e32 v85, vcc, 0, v17, vcc
	global_load_dwordx4 v[28:31], v[84:85], off
	global_load_dwordx4 v[24:27], v[84:85], off offset:1024
	global_load_dwordx4 v[20:23], v[84:85], off offset:2048
	global_load_dwordx4 v[16:19], v[84:85], off offset:3072
	s_add_u32 s1, s68, s10
	s_addc_u32 s4, s69, s11
	s_add_i32 s8, s17, 0xffffc020
	s_lshl_b64 s[2:3], s[8:9], 12
	s_add_u32 s2, s15, s2
	s_addc_u32 s3, s16, s3
	s_cmpk_lt_i32 s0, 0x4000
	s_cselect_b32 s3, s4, s3
	s_cselect_b32 s2, s1, s2
	s_add_u32 s5, s1, 0x1000
	s_addc_u32 s6, s4, 0
	s_add_i32 s8, s17, 0xffffc021
	v_lshl_add_u64 v[90:91], s[2:3], 0, v[80:81]
	s_lshl_b64 s[2:3], s[8:9], 12
	s_add_u32 s2, s15, s2
	s_addc_u32 s3, s16, s3
	s_cmpk_lt_i32 s0, 0x3fff
	s_cselect_b32 s3, s6, s3
	s_cselect_b32 s2, s5, s2
	s_add_u32 s5, s1, 0x2000
	s_addc_u32 s6, s4, 0
	s_add_i32 s8, s17, 0xffffc022
	v_lshl_add_u64 v[88:89], s[2:3], 0, v[80:81]
	s_lshl_b64 s[2:3], s[8:9], 12
	s_add_u32 s2, s15, s2
	s_addc_u32 s3, s16, s3
	s_cmpk_lt_i32 s0, 0x3ffe
	s_cselect_b32 s3, s6, s3
	s_cselect_b32 s2, s5, s2
	s_add_u32 s1, s1, 0x3000
	s_addc_u32 s4, s4, 0
	s_add_i32 s8, s17, 0xffffc023
	v_lshl_add_u64 v[84:85], s[2:3], 0, v[80:81]
	s_lshl_b64 s[2:3], s[8:9], 12
	s_add_u32 s2, s15, s2
	s_addc_u32 s3, s16, s3
	s_cmpk_lt_i32 s0, 0x3ffd
	s_cselect_b32 s3, s4, s3
	s_cselect_b32 s2, s1, s2
	s_add_u32 s68, s68, 0x20000
	s_addc_u32 s69, s69, 0
	s_mov_b32 s17, s0
	s_cmp_lt_i32 s0, s14
	v_lshl_add_u64 v[86:87], s[2:3], 0, v[80:81]
	v_lshl_add_u64 v[82:83], v[82:83], 0, s[12:13]
	s_waitcnt vmcnt(0) lgkmcnt(0)
	v_pk_mul_f32 v[100:101], v[78:79], v[78:79]
	v_pk_mul_f32 v[102:103], v[76:77], v[76:77]
	v_pk_mul_f32 v[104:105], v[70:71], v[70:71]
	v_pk_mul_f32 v[106:107], v[68:69], v[68:69]
	v_mul_f32_e32 v108, v73, v73
	v_mul_f32_e32 v110, v75, v75
	v_pk_mov_b32 v[112:113], v[102:103], v[100:101] op_sel:[1,0]
	v_mov_b32_e32 v103, v101
	v_pk_mov_b32 v[100:101], v[106:107], v[104:105] op_sel:[1,0]
	v_mov_b32_e32 v107, v105
	v_mul_f32_e32 v121, v66, v66
	v_mul_f32_e32 v123, v67, v67
	v_pk_fma_f32 v[104:105], v[72:73], v[72:73], v[108:109] op_sel_hi:[1,1,0]
	v_pk_fma_f32 v[108:109], v[74:75], v[74:75], v[110:111] op_sel_hi:[1,1,0]
	v_pk_mul_f32 v[110:111], v[62:63], v[62:63]
	v_pk_mul_f32 v[114:115], v[60:61], v[60:61]
	v_pk_mul_f32 v[116:117], v[54:55], v[54:55]
	v_pk_mul_f32 v[118:119], v[52:53], v[52:53]
	v_mul_f32_e32 v120, v57, v57
	v_mul_f32_e32 v122, v59, v59
	v_pk_add_f32 v[102:103], v[112:113], v[102:103]
	v_pk_add_f32 v[100:101], v[100:101], v[106:107]
	v_mul_f32_e32 v135, v64, v64
	v_mul_f32_e32 v137, v65, v65
	v_mul_f32_e32 v129, v50, v50
	v_mul_f32_e32 v131, v51, v51
	v_mov_b32_e32 v105, v121
	v_mov_b32_e32 v109, v123
	v_pk_mov_b32 v[106:107], v[114:115], v[110:111] op_sel:[1,0]
	v_mov_b32_e32 v115, v111
	v_pk_mov_b32 v[110:111], v[118:119], v[116:117] op_sel:[1,0]
	v_mov_b32_e32 v119, v117
	v_pk_fma_f32 v[112:113], v[56:57], v[56:57], v[120:121] op_sel_hi:[1,1,0]
	v_pk_fma_f32 v[116:117], v[58:59], v[58:59], v[122:123] op_sel_hi:[1,1,0]
	v_pk_mul_f32 v[120:121], v[46:47], v[46:47]
	v_pk_mul_f32 v[122:123], v[44:45], v[44:45]
	v_pk_mul_f32 v[124:125], v[42:43], v[42:43]
	v_pk_mul_f32 v[126:127], v[40:41], v[40:41]
	v_mul_f32_e32 v128, v37, v37
	v_mul_f32_e32 v130, v39, v39
	v_pk_add_f32 v[102:103], v[102:103], v[102:103] op_sel:[0,1] op_sel_hi:[1,0]
	v_pk_add_f32 v[100:101], v[100:101], v[100:101] op_sel:[0,1] op_sel_hi:[1,0]
	v_mul_f32_e32 v142, v34, v34
	v_mul_f32_e32 v143, v35, v35
	v_pk_add_f32 v[104:105], v[104:105], v[108:109]
	v_pk_add_f32 v[106:107], v[106:107], v[114:115]
	v_pk_add_f32 v[108:109], v[110:111], v[118:119]
	v_mov_b32_e32 v113, v129
	v_mov_b32_e32 v117, v131
	v_pk_mov_b32 v[110:111], v[122:123], v[120:121] op_sel:[1,0]
	v_mov_b32_e32 v123, v121
	v_pk_mov_b32 v[114:115], v[126:127], v[124:125] op_sel:[1,0]
	v_mov_b32_e32 v127, v125
	v_pk_fma_f32 v[118:119], v[36:37], v[36:37], v[128:129] op_sel_hi:[1,1,0]
	v_pk_fma_f32 v[120:121], v[38:39], v[38:39], v[130:131] op_sel_hi:[1,1,0]
	v_pk_mul_f32 v[124:125], v[30:31], v[30:31]
	v_pk_mul_f32 v[128:129], v[28:29], v[28:29]
	v_pk_mul_f32 v[130:131], v[26:27], v[26:27]
	v_pk_mul_f32 v[132:133], v[24:25], v[24:25]
	v_mov_b32_e32 v103, v135
	v_mov_b32_e32 v101, v137
	v_mul_f32_e32 v138, v48, v48
	v_mul_f32_e32 v139, v49, v49
	v_pk_add_f32 v[106:107], v[106:107], v[106:107] op_sel:[0,1] op_sel_hi:[1,0]
	v_pk_add_f32 v[108:109], v[108:109], v[108:109] op_sel:[0,1] op_sel_hi:[1,0]
	v_pk_add_f32 v[112:113], v[112:113], v[116:117]
	v_pk_add_f32 v[110:111], v[110:111], v[122:123]
	v_pk_add_f32 v[114:115], v[114:115], v[126:127]
	v_mov_b32_e32 v119, v142
	v_mov_b32_e32 v121, v143
	v_pk_mov_b32 v[116:117], v[128:129], v[124:125] op_sel:[1,0]
	v_mov_b32_e32 v129, v125
	v_pk_mov_b32 v[122:123], v[132:133], v[130:131] op_sel:[1,0]
	v_mov_b32_e32 v133, v131
	v_pk_add_f32 v[100:101], v[102:103], v[100:101]
	v_mul_f32_e32 v140, v32, v32
	v_mul_f32_e32 v141, v33, v33
	v_mul_f32_e32 v134, v21, v21
	v_mul_f32_e32 v136, v23, v23
	v_mov_b32_e32 v107, v138
	v_mov_b32_e32 v109, v139
	v_pk_add_f32 v[102:103], v[110:111], v[110:111] op_sel:[0,1] op_sel_hi:[1,0]
	v_pk_add_f32 v[110:111], v[114:115], v[114:115] op_sel:[0,1] op_sel_hi:[1,0]
	v_pk_add_f32 v[114:115], v[118:119], v[120:121]
	v_pk_add_f32 v[116:117], v[116:117], v[128:129]
	v_pk_add_f32 v[118:119], v[122:123], v[132:133]
	v_pk_add_f32 v[100:101], v[100:101], v[104:105]
	v_mul_f32_e32 v144, v16, v16
	v_mul_f32_e32 v145, v17, v17
	v_mul_f32_e32 v146, v18, v18
	v_mul_f32_e32 v147, v19, v19
	v_pk_fma_f32 v[124:125], v[20:21], v[20:21], v[134:135] op_sel_hi:[1,1,0]
	v_pk_fma_f32 v[126:127], v[22:23], v[22:23], v[136:137] op_sel_hi:[1,1,0]
	v_pk_add_f32 v[104:105], v[106:107], v[108:109]
	v_mov_b32_e32 v103, v140
	v_mov_b32_e32 v111, v141
	v_pk_add_f32 v[106:107], v[116:117], v[116:117] op_sel:[0,1] op_sel_hi:[1,0]
	v_pk_add_f32 v[108:109], v[118:119], v[118:119] op_sel:[0,1] op_sel_hi:[1,0]
	v_add_f32_e32 v118, v100, v101
	v_mov_b32_e32 v125, v146
	v_mov_b32_e32 v127, v147
	v_pk_add_f32 v[100:101], v[104:105], v[112:113]
	v_pk_add_f32 v[102:103], v[102:103], v[110:111]
	v_mov_b32_e32 v107, v144
	v_mov_b32_e32 v109, v145
	ds_bpermute_b32 v105, v92, v118
	v_pk_add_f32 v[116:117], v[124:125], v[126:127]
	v_add_f32_e32 v104, v100, v101
	v_pk_add_f32 v[100:101], v[102:103], v[114:115]
	v_pk_add_f32 v[102:103], v[106:107], v[108:109]
	v_add_f32_e32 v106, v100, v101
	v_pk_add_f32 v[100:101], v[102:103], v[116:117]
	v_add_f32_e32 v100, v100, v101
	s_waitcnt lgkmcnt(0)
	v_add_f32_e32 v105, v118, v105
	s_waitcnt lgkmcnt(0)
	s_nop 1
	v_add_f32_dpp v102, v104, v104 quad_perm:[1,0,3,2] row_mask:0xf bank_mask:0xf
	s_waitcnt lgkmcnt(0)
	s_nop 1
	v_add_f32_dpp v101, v106, v106 quad_perm:[1,0,3,2] row_mask:0xf bank_mask:0xf
	s_waitcnt lgkmcnt(2)
	s_nop 1
	v_add_f32_dpp v100, v100, v100 quad_perm:[1,0,3,2] row_mask:0xf bank_mask:0xf
	s_waitcnt lgkmcnt(0)
	s_nop 1
	v_add_f32_dpp v105, v105, v105 quad_perm:[2,3,0,1] row_mask:0xf bank_mask:0xf
	ds_bpermute_b32 v107, v94, v105
	s_waitcnt lgkmcnt(3)
	s_nop 1
	v_add_f32_dpp v102, v102, v102 quad_perm:[2,3,0,1] row_mask:0xf bank_mask:0xf
	s_waitcnt lgkmcnt(0)
	s_nop 1
	v_add_f32_dpp v101, v101, v101 quad_perm:[2,3,0,1] row_mask:0xf bank_mask:0xf
	s_waitcnt lgkmcnt(2)
	s_nop 1
	v_add_f32_dpp v100, v100, v100 quad_perm:[2,3,0,1] row_mask:0xf bank_mask:0xf
	s_waitcnt lgkmcnt(0)
	v_add_f32_e32 v105, v105, v107
	ds_bpermute_b32 v107, v95, v105
	s_waitcnt lgkmcnt(3)
	s_nop 1
	v_add_f32_dpp v102, v102, v102 row_half_mirror row_mask:0xf bank_mask:0xf
	s_waitcnt lgkmcnt(0)
	s_nop 1
	v_add_f32_dpp v101, v101, v101 row_half_mirror row_mask:0xf bank_mask:0xf
	s_waitcnt lgkmcnt(2)
	s_nop 1
	v_add_f32_dpp v100, v100, v100 row_half_mirror row_mask:0xf bank_mask:0xf
	s_waitcnt lgkmcnt(0)
	v_add_f32_e32 v105, v105, v107
	ds_bpermute_b32 v107, v96, v105
	s_waitcnt lgkmcnt(3)
	s_nop 1
	v_add_f32_dpp v102, v102, v102 row_mirror row_mask:0xf bank_mask:0xf
	ds_bpermute_b32 v104, v96, v102
	s_waitcnt lgkmcnt(3)
	s_nop 1
	v_add_f32_dpp v101, v101, v101 row_mirror row_mask:0xf bank_mask:0xf
	s_waitcnt lgkmcnt(2)
	s_nop 1
	v_add_f32_dpp v100, v100, v100 row_mirror row_mask:0xf bank_mask:0xf
	s_waitcnt lgkmcnt(0)
	v_add_f32_e32 v105, v105, v107
	s_waitcnt lgkmcnt(0)
	v_add_f32_e32 v102, v102, v104
	s_waitcnt lgkmcnt(0)
	v_mov_b32_e32 v106, v101
	s_nop 1
	v_permlane16_swap_b32_e32 v101, v106
	v_add_f32_e32 v101, v101, v106
	s_waitcnt lgkmcnt(2)
	v_mov_b32_e32 v103, v100
	s_nop 1
	v_permlane16_swap_b32_e32 v100, v103
	v_add_f32_e32 v100, v100, v103
	ds_bpermute_b32 v103, v97, v100
	s_waitcnt lgkmcnt(0)
	v_mov_b32_e32 v107, v105
	s_nop 1
	v_permlane32_swap_b32_e32 v105, v107
	v_add_f32_e32 v105, v105, v107
	v_fmamk_f32 v105, v105, 0x3a800000, v98
	s_waitcnt lgkmcnt(2)
	v_mov_b32_e32 v104, v102
	s_nop 1
	v_permlane32_swap_b32_e32 v102, v104
	v_add_f32_e32 v102, v102, v104
	v_mul_f32_e32 v104, 0x4f800000, v105
	v_cmp_gt_f32_e32 vcc, s18, v105
	v_fmamk_f32 v102, v102, 0x3a800000, v98
	s_waitcnt lgkmcnt(1)
	v_mov_b32_e32 v106, v101
	s_nop 1
	v_permlane32_swap_b32_e32 v101, v106
	v_add_f32_e32 v101, v101, v106
	v_cndmask_b32_e32 v104, v105, v104, vcc
	v_mul_f32_e32 v105, 0x4f800000, v102
	v_cmp_gt_f32_e64 s[0:1], s18, v102
	s_waitcnt lgkmcnt(0)
	v_add_f32_e32 v100, v100, v103
	v_sqrt_f32_e32 v103, v104
	v_fmamk_f32 v101, v101, 0x3a800000, v98
	v_cndmask_b32_e64 v102, v102, v105, s[0:1]
	v_mul_f32_e32 v105, 0x4f800000, v101
	v_cmp_gt_f32_e64 s[2:3], s18, v101
	v_fmamk_f32 v100, v100, 0x3a800000, v98
	v_sqrt_f32_e32 v106, v102
	v_cndmask_b32_e64 v101, v101, v105, s[2:3]
	v_mul_f32_e32 v105, 0x4f800000, v100
	v_cmp_gt_f32_e64 s[4:5], s18, v100
	v_sqrt_f32_e32 v107, v101
	v_add_u32_e32 v108, -1, v103
	v_cndmask_b32_e64 v100, v100, v105, s[4:5]
	v_sqrt_f32_e32 v105, v100
	v_add_u32_e32 v109, 1, v103
	v_fma_f32 v110, -v108, v103, v104
	v_fma_f32 v111, -v109, v103, v104
	v_add_u32_e32 v112, -1, v106
	v_cmp_ge_f32_e64 s[6:7], 0, v110
	v_add_u32_e32 v113, 1, v106
	v_fma_f32 v110, -v113, v106, v102
	v_cndmask_b32_e64 v103, v103, v108, s[6:7]
	v_fma_f32 v108, -v112, v106, v102
	v_cmp_lt_f32_e64 s[6:7], 0, v111
	v_add_u32_e32 v114, -1, v107
	v_add_u32_e32 v115, 1, v107
	v_cndmask_b32_e64 v103, v103, v109, s[6:7]
	v_cmp_ge_f32_e64 s[6:7], 0, v108
	v_fma_f32 v108, -v114, v107, v101
	v_fma_f32 v109, -v115, v107, v101
	v_cndmask_b32_e64 v106, v106, v112, s[6:7]
	v_cmp_lt_f32_e64 s[6:7], 0, v110
	v_add_u32_e32 v110, -1, v105
	v_add_u32_e32 v111, 1, v105
	v_mul_f32_e32 v112, 0x37800000, v103
	v_cndmask_b32_e64 v106, v106, v113, s[6:7]
	v_cmp_ge_f32_e64 s[6:7], 0, v108
	v_fma_f32 v108, -v110, v105, v100
	v_cndmask_b32_e32 v103, v103, v112, vcc
	v_cndmask_b32_e64 v107, v107, v114, s[6:7]
	v_cmp_lt_f32_e64 s[6:7], 0, v109
	v_fma_f32 v109, -v111, v105, v100
	v_cmp_ge_f32_e32 vcc, 0, v108
	v_mul_f32_e32 v112, 0x37800000, v106
	v_cndmask_b32_e64 v107, v107, v115, s[6:7]
	v_cndmask_b32_e32 v105, v105, v110, vcc
	v_cmp_lt_f32_e32 vcc, 0, v109
	v_cmp_class_f32_e64 s[6:7], v104, v99
	s_nop 0
	v_cndmask_b32_e32 v105, v105, v111, vcc
	v_cndmask_b32_e64 v103, v103, v104, s[6:7]
	v_cndmask_b32_e64 v104, v106, v112, s[0:1]
	v_cmp_class_f32_e64 s[0:1], v102, v99
	v_mul_f32_e32 v106, 0x37800000, v107
	v_div_scale_f32 v108, s[6:7], v103, v103, 1.0
	v_cndmask_b32_e64 v104, v104, v102, s[0:1]
	v_cndmask_b32_e64 v102, v107, v106, s[2:3]
	v_cmp_class_f32_e64 s[0:1], v101, v99
	v_mul_f32_e32 v106, 0x37800000, v105
	v_rcp_f32_e32 v107, v108
	v_div_scale_f32 v110, s[2:3], v104, v104, 1.0
	v_cndmask_b32_e64 v112, v102, v101, s[0:1]
	v_cndmask_b32_e64 v101, v105, v106, s[4:5]
	v_cmp_class_f32_e64 s[0:1], v100, v99
	v_rcp_f32_e32 v102, v110
	v_div_scale_f32 v105, s[4:5], v112, v112, 1.0
	v_cndmask_b32_e64 v113, v101, v100, s[0:1]
	v_rcp_f32_e32 v114, v105
	v_div_scale_f32 v115, s[0:1], v113, v113, 1.0
	v_rcp_f32_e32 v117, v115
	v_fma_f32 v100, -v108, v107, 1.0
	v_div_scale_f32 v109, vcc, 1.0, v103, 1.0
	v_fmac_f32_e32 v107, v100, v107
	v_fma_f32 v100, -v110, v102, 1.0
	v_div_scale_f32 v111, s[2:3], 1.0, v104, 1.0
	v_mul_f32_e32 v101, v109, v107
	v_fmac_f32_e32 v102, v100, v102
	v_fma_f32 v100, -v105, v114, 1.0
	v_div_scale_f32 v106, s[4:5], 1.0, v112, 1.0
	v_fma_f32 v118, -v108, v101, v109
	v_mul_f32_e32 v119, v111, v102
	v_fmac_f32_e32 v114, v100, v114
	v_fma_f32 v100, -v115, v117, 1.0
	v_div_scale_f32 v116, s[0:1], 1.0, v113, 1.0
	v_fmac_f32_e32 v101, v118, v107
	v_fma_f32 v118, -v110, v119, v111
	v_mul_f32_e32 v120, v106, v114
	v_fmac_f32_e32 v117, v100, v117
	v_fma_f32 v100, -v108, v101, v109
	v_fmac_f32_e32 v119, v118, v102
	v_fma_f32 v108, -v105, v120, v106
	v_mul_f32_e32 v109, v116, v117
	v_div_fmas_f32 v100, v100, v107, v101
	v_fma_f32 v101, -v110, v119, v111
	v_fmac_f32_e32 v120, v108, v114
	v_fma_f32 v107, -v115, v109, v116
	s_mov_b64 vcc, s[2:3]
	v_div_fixup_f32 v100, v100, v103, 1.0
	v_div_fmas_f32 v108, v101, v102, v119
	v_fma_f32 v105, -v105, v120, v106
	v_fmac_f32_e32 v109, v107, v117
	s_mov_b64 vcc, s[4:5]
	v_pk_mul_f32 v[76:77], v[76:77], v[100:101] op_sel_hi:[1,0]
	v_pk_mul_f32 v[78:79], v[78:79], v[100:101] op_sel_hi:[1,0]
	v_pk_mul_f32 v[68:69], v[68:69], v[100:101] op_sel_hi:[1,0]
	v_pk_mul_f32 v[70:71], v[70:71], v[100:101] op_sel_hi:[1,0]
	v_pk_mul_f32 v[72:73], v[72:73], v[100:101] op_sel_hi:[1,0]
	v_pk_mul_f32 v[74:75], v[74:75], v[100:101] op_sel_hi:[1,0]
	v_pk_mul_f32 v[102:103], v[64:65], v[100:101] op_sel_hi:[1,0]
	v_pk_mul_f32 v[100:101], v[66:67], v[100:101] op_sel_hi:[1,0]
	v_div_fixup_f32 v104, v108, v104, 1.0
	v_div_fmas_f32 v105, v105, v114, v120
	v_fma_f32 v106, -v115, v109, v116
	s_mov_b64 vcc, s[0:1]
	v_pk_mul_f32 v[66:67], v[78:79], v[2:3]
	v_pk_mul_f32 v[64:65], v[76:77], v[0:1]
	v_pk_mul_f32 v[72:73], v[72:73], v[8:9]
	v_pk_mul_f32 v[78:79], v[100:101], v[14:15]
	v_pk_mul_f32 v[76:77], v[102:103], v[12:13]
	v_pk_mul_f32 v[60:61], v[60:61], v[104:105] op_sel_hi:[1,0]
	v_pk_mul_f32 v[62:63], v[62:63], v[104:105] op_sel_hi:[1,0]
	v_pk_mul_f32 v[52:53], v[52:53], v[104:105] op_sel_hi:[1,0]
	v_pk_mul_f32 v[54:55], v[54:55], v[104:105] op_sel_hi:[1,0]
	v_pk_mul_f32 v[56:57], v[56:57], v[104:105] op_sel_hi:[1,0]
	v_pk_mul_f32 v[58:59], v[58:59], v[104:105] op_sel_hi:[1,0]
	v_pk_mul_f32 v[100:101], v[48:49], v[104:105] op_sel_hi:[1,0]
	v_pk_mul_f32 v[102:103], v[50:51], v[104:105] op_sel_hi:[1,0]
	v_div_fixup_f32 v104, v105, v112, 1.0
	v_div_fmas_f32 v105, v106, v117, v109
	v_pk_mul_f32 v[70:71], v[70:71], v[6:7]
	v_pk_mul_f32 v[68:69], v[68:69], v[4:5]
	v_pk_mul_f32 v[74:75], v[74:75], v[10:11]
	global_store_dwordx4 v[90:91], v[64:67], off
	global_store_dwordx4 v[90:91], v[68:71], off offset:1024
	global_store_dwordx4 v[90:91], v[72:75], off offset:2048
	global_store_dwordx4 v[90:91], v[76:79], off offset:3072
	v_pk_mul_f32 v[50:51], v[62:63], v[2:3]
	v_div_fixup_f32 v72, v105, v113, 1.0
	v_pk_mul_f32 v[48:49], v[60:61], v[0:1]
	v_pk_mul_f32 v[54:55], v[54:55], v[6:7]
	v_pk_mul_f32 v[52:53], v[52:53], v[4:5]
	v_pk_mul_f32 v[44:45], v[44:45], v[104:105] op_sel_hi:[1,0]
	v_pk_mul_f32 v[46:47], v[46:47], v[104:105] op_sel_hi:[1,0]
	v_pk_mul_f32 v[28:29], v[28:29], v[72:73] op_sel_hi:[1,0]
	v_pk_mul_f32 v[30:31], v[30:31], v[72:73] op_sel_hi:[1,0]
	v_pk_mul_f32 v[58:59], v[58:59], v[10:11]
	v_pk_mul_f32 v[56:57], v[56:57], v[8:9]
	v_pk_mul_f32 v[62:63], v[102:103], v[14:15]
	v_pk_mul_f32 v[60:61], v[100:101], v[12:13]
	v_pk_mul_f32 v[40:41], v[40:41], v[104:105] op_sel_hi:[1,0]
	v_pk_mul_f32 v[42:43], v[42:43], v[104:105] op_sel_hi:[1,0]
	v_pk_mul_f32 v[64:65], v[36:37], v[104:105] op_sel_hi:[1,0]
	v_pk_mul_f32 v[66:67], v[38:39], v[104:105] op_sel_hi:[1,0]
	v_pk_mul_f32 v[68:69], v[32:33], v[104:105] op_sel_hi:[1,0]
	v_pk_mul_f32 v[70:71], v[34:35], v[104:105] op_sel_hi:[1,0]
	global_store_dwordx4 v[88:89], v[48:51], off
	global_store_dwordx4 v[88:89], v[52:55], off offset:1024
	global_store_dwordx4 v[88:89], v[56:59], off offset:2048
	global_store_dwordx4 v[88:89], v[60:63], off offset:3072
	v_pk_mul_f32 v[34:35], v[46:47], v[2:3]
	v_pk_mul_f32 v[32:33], v[44:45], v[0:1]
	v_pk_mul_f32 v[24:25], v[24:25], v[72:73] op_sel_hi:[1,0]
	v_pk_mul_f32 v[26:27], v[26:27], v[72:73] op_sel_hi:[1,0]
	v_pk_mul_f32 v[48:49], v[20:21], v[72:73] op_sel_hi:[1,0]
	v_pk_mul_f32 v[50:51], v[22:23], v[72:73] op_sel_hi:[1,0]
	v_pk_mul_f32 v[52:53], v[16:17], v[72:73] op_sel_hi:[1,0]
	v_pk_mul_f32 v[54:55], v[18:19], v[72:73] op_sel_hi:[1,0]
	v_pk_mul_f32 v[18:19], v[30:31], v[2:3]
	v_pk_mul_f32 v[16:17], v[28:29], v[0:1]
	v_pk_mul_f32 v[38:39], v[42:43], v[6:7]
	v_pk_mul_f32 v[36:37], v[40:41], v[4:5]
	v_pk_mul_f32 v[42:43], v[66:67], v[10:11]
	v_pk_mul_f32 v[40:41], v[64:65], v[8:9]
	v_pk_mul_f32 v[46:47], v[70:71], v[14:15]
	v_pk_mul_f32 v[44:45], v[68:69], v[12:13]
	global_store_dwordx4 v[84:85], v[32:35], off
	global_store_dwordx4 v[84:85], v[36:39], off offset:1024
	global_store_dwordx4 v[84:85], v[40:43], off offset:2048
	global_store_dwordx4 v[84:85], v[44:47], off offset:3072
	v_pk_mul_f32 v[22:23], v[26:27], v[6:7]
	v_pk_mul_f32 v[20:21], v[24:25], v[4:5]
	v_pk_mul_f32 v[26:27], v[50:51], v[10:11]
	v_pk_mul_f32 v[24:25], v[48:49], v[8:9]
	v_pk_mul_f32 v[30:31], v[54:55], v[14:15]
	v_pk_mul_f32 v[28:29], v[52:53], v[12:13]
	global_store_dwordx4 v[86:87], v[16:19], off
	global_store_dwordx4 v[86:87], v[20:23], off offset:1024
	global_store_dwordx4 v[86:87], v[24:27], off offset:2048
	global_store_dwordx4 v[86:87], v[28:31], off offset:3072
	s_cbranch_scc1 .LBB0_5948
